# FFN-up: 16x16x32 MFMA K loop with next-tile prefetch in loop tail, compact SwiGLU epilogue (v_rcp_f32 sigmoid); FFN-down/w_in/w_o pipelined K loops
# speedup vs baseline: 1.0709x; 1.0288x over previous
; #define TIDX get_tid_()
; DI bf16_t f2bf(float x) { unsigned r; asm("v_cvt_pk_bf16_f32 %0, %1, %1" : "=v"(r) : "v"(x)); return (bf16_t)(r & 0xffffu); }
; DI int crow(int i, int h) { return (i & 3) + 8 * (i >> 2) + 4 * h; }
; DI float sigmoidf_(float x) { return 1.f / (1.f + __expf(-x)); }
; #define GEMM_ISSUE(kt_, st_) do { char* sb_ = lw + (st_) * STAGE_B; const char* ak_ = Ab + (size_t)(kt_) * 128; const char* bk_ = Bb + (size_t)(kt_) * 128; \
;     _Pragma("unroll") for (int i_ = 0; i_ < 4; ++i_) glds16(ak_ + avo[i_], sb_ + i_ * 8192); \
;     _Pragma("unroll") for (int i_ = 0; i_ < 2; ++i_) glds16(bk_ + bvo[i_], sb_ + 32768 + i_ * 8192); } while (0)
;     ...
;   if (PART != 2) {
;     GEMM_ISSUE(0, 0);
;     if (nk > 1) GEMM_ISSUE(1, 1);
;   }
;   DI void operator()(const f32x16 (&acc)[2][2], int m0, int n0) const {
;     const int tid = TIDX, lane = tid & 63, wid = tid >> 6, wr = wid >> 1, wc = wid & 1, r = lane & 31, h = lane >> 5;
;     const int hid = (n0 >> 7) * 64 + wc * 32 + r;
; #pragma unroll
;     for (int mi = 0; mi < 2; ++mi)
; #pragma unroll
;       for (int i = 0; i < 16; ++i) {
;         const int row = m0 + wr * 64 + mi * 32 + crow(i, h);
;         const float g = acc[mi][0][i], u = acc[mi][1][i];
;         ffh[(size_t)row * DFF + hid] = f2bf(g * sigmoidf_(g) * u);
;       }
;   }
.LBB0_54:
	s_andn2_b64 vcc, exec, s[54:55]
	s_cbranch_vccnz .LBB0_65
	v_mov_b32_e32 v0, v129
	s_add_u32 s10, s4, 0x1080000
	s_addc_u32 s11, s22, 0
	v_lshlrev_b32_e32 v1, 4, v0
	s_ashr_i32 s9, s8, 31
	v_xor_b32_e32 v2, v1, v0
	v_lshlrev_b32_e32 v0, 8, v0
	s_lshl_b64 s[26:27], s[8:9], 19
	v_and_b32_e32 v0, 0xfffff800, v0
	s_movk_i32 s9, 0x70
	v_add_u32_e32 v14, 0, v1
	s_add_u32 s26, s88, s26
	v_and_or_b32 v130, v2, s9, v0
	v_readfirstlane_b32 s9, v14
	v_add_u32_e32 v3, 0x2000, v14
	s_addc_u32 s27, s89, s27
	v_add_u32_e32 v2, 0x40000, v130
	s_mov_b32 m0, s9
	v_readfirstlane_b32 s9, v3
	v_mov_b32_e32 v3, v131
	v_lshl_add_u64 v[10:11], s[26:27], 0, v[2:3]
	v_add_u32_e32 v3, 0x4000, v14
	s_ashr_i32 s15, s14, 31
	v_add_u32_e32 v0, 0x20000, v130
	global_load_lds_dwordx4 v130, s[26:27]
	s_mov_b32 m0, s9
	v_readfirstlane_b32 s9, v3
	s_lshl_b64 s[30:31], s[14:15], 18
	v_add_u32_e32 v4, 0x60000, v130
	global_load_lds_dwordx4 v0, s[26:27]
	s_mov_b32 m0, s9
	v_mov_b32_e32 v5, v131
	s_add_u32 s30, s10, s30
	global_load_lds_dwordx4 v2, s[26:27]
	v_lshl_add_u64 v[2:3], s[26:27], 0, v[4:5]
	v_add_u32_e32 v5, 0x6000, v14
	s_addc_u32 s31, s11, s31
	v_mov_b32_e32 v1, v131
	v_readfirstlane_b32 s9, v5
	v_add_u32_e32 v12, 0x8000, v14
	v_lshl_add_u64 v[8:9], s[26:27], 0, v[0:1]
	s_mov_b32 m0, s9
	v_readfirstlane_b32 s9, v12
	v_lshl_add_u64 v[12:13], s[30:31], 0, v[0:1]
	v_add_u32_e32 v1, 0xa000, v14
	global_load_lds_dwordx4 v4, s[26:27]
	s_mov_b32 m0, s9
	v_readfirstlane_b32 s9, v1
	v_lshl_add_u64 v[6:7], s[26:27], 0, v[130:131]
	global_load_lds_dwordx4 v130, s[30:31]
	s_mov_b32 m0, s9
	v_add_u32_e32 v15, 0xc000, v14
	global_load_lds_dwordx4 v0, s[30:31]
	v_lshl_add_u64 v[0:1], v[6:7], 0, s[92:93]
	v_readfirstlane_b32 s9, v15
	v_add_u32_e32 v6, 0xe000, v14
	s_mov_b32 m0, s9
	v_readfirstlane_b32 s9, v6
	v_add_u32_e32 v6, 0x10000, v14
	global_load_lds_dwordx4 v[0:1], off
	v_lshl_add_u64 v[0:1], v[8:9], 0, s[92:93]
	s_mov_b32 m0, s9
	v_readfirstlane_b32 s9, v6
	global_load_lds_dwordx4 v[0:1], off
	v_lshl_add_u64 v[0:1], v[10:11], 0, s[92:93]
	s_mov_b32 m0, s9
	v_lshl_add_u64 v[4:5], s[30:31], 0, v[130:131]
	global_load_lds_dwordx4 v[0:1], off
	v_lshl_add_u64 v[0:1], v[2:3], 0, s[92:93]
	v_add_u32_e32 v2, 0x12000, v14
	s_nop 0
	v_readfirstlane_b32 s9, v2
	v_add_u32_e32 v2, 0x14000, v14
	s_mov_b32 m0, s9
	v_readfirstlane_b32 s9, v2
	v_add_u32_e32 v2, 0x16000, v14
	global_load_lds_dwordx4 v[0:1], off
	v_lshl_add_u64 v[0:1], v[4:5], 0, s[92:93]
	s_mov_b32 m0, s9
	v_readfirstlane_b32 s9, v2
	global_load_lds_dwordx4 v[0:1], off
	v_lshl_add_u64 v[0:1], v[12:13], 0, s[92:93]
	s_mov_b32 m0, s9
	s_nop 0
	global_load_lds_dwordx4 v[0:1], off
	s_mov_b32 s100, 0
	s_mov_b32 s101, 1
	s_branch .LBB0_57
.LBB0_56:
	v_lshrrev_b32_e32 v64, 7, v129
	v_bfe_u32 v65, v129, 4, 2
	v_lshlrev_b32_e32 v64, 6, v64
	v_lshl_add_u32 v64, v65, 2, v64
	v_mul_u32_u24_e32 v64, 0x1600, v64
	v_bfe_u32 v65, v129, 6, 1
	v_and_b32_e32 v66, 15, v129
	v_lshl_add_u32 v65, v65, 5, v66
	v_lshl_add_u32 v72, v65, 1, v64
	v_add_u32_e32 v73, 0x1600, v72
	v_add_u32_e32 v74, 0x2c00, v72
	v_add_u32_e32 v75, 0x4200, v72
	v_readlane_b32 s24, v253, 13
	v_readlane_b32 s25, v253, 14
	s_mul_i32 s26, s68, 0x160000
	s_lshl_b32 s27, s70, 7
	s_add_u32 s26, s26, s27
	s_add_u32 s24, s24, s26
	s_addc_u32 s25, s25, 0
	v_mul_f32_e32 v64, 0xbfb8aa3b, v0
	v_mul_f32_e32 v65, 0xbfb8aa3b, v1
	v_mul_f32_e32 v66, 0xbfb8aa3b, v2
	v_mul_f32_e32 v67, 0xbfb8aa3b, v3
	v_exp_f32_e32 v64, v64
	v_exp_f32_e32 v65, v65
	v_exp_f32_e32 v66, v66
	v_exp_f32_e32 v67, v67
	v_add_f32_e32 v64, 1.0, v64
	v_add_f32_e32 v65, 1.0, v65
	v_add_f32_e32 v66, 1.0, v66
	v_add_f32_e32 v67, 1.0, v67
	v_rcp_f32_e32 v64, v64
	v_rcp_f32_e32 v65, v65
	v_rcp_f32_e32 v66, v66
	v_rcp_f32_e32 v67, v67
	v_mul_f32_e32 v0, v0, v64
	v_mul_f32_e32 v1, v1, v65
	v_mul_f32_e32 v2, v2, v66
	v_mul_f32_e32 v3, v3, v67
	v_mul_f32_e32 v0, v8, v0
	v_mul_f32_e32 v1, v9, v1
	v_mul_f32_e32 v2, v10, v2
	v_mul_f32_e32 v3, v11, v3
	v_cvt_pk_bf16_f32 v64, v0, v1
	v_cvt_pk_bf16_f32 v65, v2, v3
	global_store_short v72, v64, s[24:25]
	global_store_short_d16_hi v73, v64, s[24:25]
	global_store_short v74, v65, s[24:25]
	global_store_short_d16_hi v75, v65, s[24:25]
	v_mul_f32_e32 v68, 0xbfb8aa3b, v4
	v_mul_f32_e32 v69, 0xbfb8aa3b, v5
	v_mul_f32_e32 v70, 0xbfb8aa3b, v6
	v_mul_f32_e32 v71, 0xbfb8aa3b, v7
	v_exp_f32_e32 v68, v68
	v_exp_f32_e32 v69, v69
	v_exp_f32_e32 v70, v70
	v_exp_f32_e32 v71, v71
	v_add_f32_e32 v68, 1.0, v68
	v_add_f32_e32 v69, 1.0, v69
	v_add_f32_e32 v70, 1.0, v70
	v_add_f32_e32 v71, 1.0, v71
	v_rcp_f32_e32 v68, v68
	v_rcp_f32_e32 v69, v69
	v_rcp_f32_e32 v70, v70
	v_rcp_f32_e32 v71, v71
	v_mul_f32_e32 v4, v4, v68
	v_mul_f32_e32 v5, v5, v69
	v_mul_f32_e32 v6, v6, v70
	v_mul_f32_e32 v7, v7, v71
	v_mul_f32_e32 v4, v12, v4
	v_mul_f32_e32 v5, v13, v5
	v_mul_f32_e32 v6, v14, v6
	v_mul_f32_e32 v7, v15, v7
	v_cvt_pk_bf16_f32 v68, v4, v5
	v_cvt_pk_bf16_f32 v69, v6, v7
	global_store_short v72, v68, s[24:25] offset:32
	global_store_short_d16_hi v73, v68, s[24:25] offset:32
	global_store_short v74, v69, s[24:25] offset:32
	global_store_short_d16_hi v75, v69, s[24:25] offset:32
	s_add_u32 s24, s24, 0x16000
	s_addc_u32 s25, s25, 0
	v_mul_f32_e32 v64, 0xbfb8aa3b, v16
	v_mul_f32_e32 v65, 0xbfb8aa3b, v17
	v_mul_f32_e32 v66, 0xbfb8aa3b, v18
	v_mul_f32_e32 v67, 0xbfb8aa3b, v19
	v_exp_f32_e32 v64, v64
	v_exp_f32_e32 v65, v65
	v_exp_f32_e32 v66, v66
	v_exp_f32_e32 v67, v67
	v_add_f32_e32 v64, 1.0, v64
	v_add_f32_e32 v65, 1.0, v65
	v_add_f32_e32 v66, 1.0, v66
	v_add_f32_e32 v67, 1.0, v67
	v_rcp_f32_e32 v64, v64
	v_rcp_f32_e32 v65, v65
	v_rcp_f32_e32 v66, v66
	v_rcp_f32_e32 v67, v67
	v_mul_f32_e32 v16, v16, v64
; #define TIDX get_tid_()
; DI bf16_t f2bf(float x) { unsigned r; asm("v_cvt_pk_bf16_f32 %0, %1, %1" : "=v"(r) : "v"(x)); return (bf16_t)(r & 0xffffu); }
; DI int crow(int i, int h) { return (i & 3) + 8 * (i >> 2) + 4 * h; }
; DI float sigmoidf_(float x) { return 1.f / (1.f + __expf(-x)); }
;   DI void operator()(const f32x16 (&acc)[2][2], int m0, int n0) const {
;     const int tid = TIDX, lane = tid & 63, wid = tid >> 6, wr = wid >> 1, wc = wid & 1, r = lane & 31, h = lane >> 5;
;     const int hid = (n0 >> 7) * 64 + wc * 32 + r;
; #pragma unroll
;     for (int mi = 0; mi < 2; ++mi)
; #pragma unroll
;       for (int i = 0; i < 16; ++i) {
;         const int row = m0 + wr * 64 + mi * 32 + crow(i, h);
;         const float g = acc[mi][0][i], u = acc[mi][1][i];
;         ffh[(size_t)row * DFF + hid] = f2bf(g * sigmoidf_(g) * u);
;       }
;   }
; template <class Epi>
; DI void gemm_phase(const bf16_t* A, int lda, const bf16_t* Bt, int ldb, int K, int MT, int NTl, int SN, const Epi& epi, char* lds, bool rev = false) {
;     ...
;   while (have) {
;     f32x16 acc[2][2];
;     zero_acc(acc);
;     const int cmt = mt, cnt = nt;
;     float rv[Epi::PRE ? 2 : 1][2][16];
;     if constexpr (Epi::PRE) epi.pre(rv, cmt * 256, cnt * 128);
;     gemm_core<2>(A + (size_t)cmt * 256 * lda, lda, Bt + (size_t)cnt * 128 * ldb, ldb, K, acc, lds);
;     have = false;
;     for (L += gridDim.x; L < lmax; L += gridDim.x) if (tile_map(L, MT, NTl, SN, mt, nt)) { have = true; if (rev) mt = MT - 1 - mt; break; }
;     if (have) gemm_core<1>(A + (size_t)mt * 256 * lda, lda, Bt + (size_t)nt * 128 * ldb, ldb, K, dummy, lds);
;     if constexpr (Epi::PRE) epi(acc, cmt * 256, cnt * 128, rv); else epi(acc, cmt * 256, cnt * 128);
	v_mul_f32_e32 v17, v17, v65
	v_mul_f32_e32 v18, v18, v66
	v_mul_f32_e32 v19, v19, v67
	v_mul_f32_e32 v16, v24, v16
	v_mul_f32_e32 v17, v25, v17
	v_mul_f32_e32 v18, v26, v18
	v_mul_f32_e32 v19, v27, v19
	v_cvt_pk_bf16_f32 v64, v16, v17
	v_cvt_pk_bf16_f32 v65, v18, v19
	global_store_short v72, v64, s[24:25]
	global_store_short_d16_hi v73, v64, s[24:25]
	global_store_short v74, v65, s[24:25]
	global_store_short_d16_hi v75, v65, s[24:25]
	v_mul_f32_e32 v68, 0xbfb8aa3b, v20
	v_mul_f32_e32 v69, 0xbfb8aa3b, v21
	v_mul_f32_e32 v70, 0xbfb8aa3b, v22
	v_mul_f32_e32 v71, 0xbfb8aa3b, v23
	v_exp_f32_e32 v68, v68
	v_exp_f32_e32 v69, v69
	v_exp_f32_e32 v70, v70
	v_exp_f32_e32 v71, v71
	v_add_f32_e32 v68, 1.0, v68
	v_add_f32_e32 v69, 1.0, v69
	v_add_f32_e32 v70, 1.0, v70
	v_add_f32_e32 v71, 1.0, v71
	v_rcp_f32_e32 v68, v68
	v_rcp_f32_e32 v69, v69
	v_rcp_f32_e32 v70, v70
	v_rcp_f32_e32 v71, v71
	v_mul_f32_e32 v20, v20, v68
	v_mul_f32_e32 v21, v21, v69
	v_mul_f32_e32 v22, v22, v70
	v_mul_f32_e32 v23, v23, v71
	v_mul_f32_e32 v20, v28, v20
	v_mul_f32_e32 v21, v29, v21
	v_mul_f32_e32 v22, v30, v22
	v_mul_f32_e32 v23, v31, v23
	v_cvt_pk_bf16_f32 v68, v20, v21
	v_cvt_pk_bf16_f32 v69, v22, v23
	global_store_short v72, v68, s[24:25] offset:32
	global_store_short_d16_hi v73, v68, s[24:25] offset:32
	global_store_short v74, v69, s[24:25] offset:32
	global_store_short_d16_hi v75, v69, s[24:25] offset:32
	s_add_u32 s24, s24, 0x16000
	s_addc_u32 s25, s25, 0
	v_mul_f32_e32 v64, 0xbfb8aa3b, v32
	v_mul_f32_e32 v65, 0xbfb8aa3b, v33
	v_mul_f32_e32 v66, 0xbfb8aa3b, v34
	v_mul_f32_e32 v67, 0xbfb8aa3b, v35
	v_exp_f32_e32 v64, v64
	v_exp_f32_e32 v65, v65
	v_exp_f32_e32 v66, v66
	v_exp_f32_e32 v67, v67
	v_add_f32_e32 v64, 1.0, v64
	v_add_f32_e32 v65, 1.0, v65
	v_add_f32_e32 v66, 1.0, v66
	v_add_f32_e32 v67, 1.0, v67
	v_rcp_f32_e32 v64, v64
	v_rcp_f32_e32 v65, v65
	v_rcp_f32_e32 v66, v66
	v_rcp_f32_e32 v67, v67
	v_mul_f32_e32 v32, v32, v64
	v_mul_f32_e32 v33, v33, v65
	v_mul_f32_e32 v34, v34, v66
	v_mul_f32_e32 v35, v35, v67
	v_mul_f32_e32 v32, v40, v32
	v_mul_f32_e32 v33, v41, v33
	v_mul_f32_e32 v34, v42, v34
	v_mul_f32_e32 v35, v43, v35
	v_cvt_pk_bf16_f32 v64, v32, v33
	v_cvt_pk_bf16_f32 v65, v34, v35
	global_store_short v72, v64, s[24:25]
	global_store_short_d16_hi v73, v64, s[24:25]
	global_store_short v74, v65, s[24:25]
	global_store_short_d16_hi v75, v65, s[24:25]
	v_mul_f32_e32 v68, 0xbfb8aa3b, v36
	v_mul_f32_e32 v69, 0xbfb8aa3b, v37
	v_mul_f32_e32 v70, 0xbfb8aa3b, v38
	v_mul_f32_e32 v71, 0xbfb8aa3b, v39
	v_exp_f32_e32 v68, v68
	v_exp_f32_e32 v69, v69
	v_exp_f32_e32 v70, v70
	v_exp_f32_e32 v71, v71
	v_add_f32_e32 v68, 1.0, v68
	v_add_f32_e32 v69, 1.0, v69
	v_add_f32_e32 v70, 1.0, v70
	v_add_f32_e32 v71, 1.0, v71
	v_rcp_f32_e32 v68, v68
	v_rcp_f32_e32 v69, v69
	v_rcp_f32_e32 v70, v70
	v_rcp_f32_e32 v71, v71
	v_mul_f32_e32 v36, v36, v68
	v_mul_f32_e32 v37, v37, v69
	v_mul_f32_e32 v38, v38, v70
	v_mul_f32_e32 v39, v39, v71
	v_mul_f32_e32 v36, v44, v36
	v_mul_f32_e32 v37, v45, v37
	v_mul_f32_e32 v38, v46, v38
	v_mul_f32_e32 v39, v47, v39
	v_cvt_pk_bf16_f32 v68, v36, v37
	v_cvt_pk_bf16_f32 v69, v38, v39
	global_store_short v72, v68, s[24:25] offset:32
	global_store_short_d16_hi v73, v68, s[24:25] offset:32
	global_store_short v74, v69, s[24:25] offset:32
	global_store_short_d16_hi v75, v69, s[24:25] offset:32
	s_add_u32 s24, s24, 0x16000
	s_addc_u32 s25, s25, 0
	v_mul_f32_e32 v64, 0xbfb8aa3b, v48
	v_mul_f32_e32 v65, 0xbfb8aa3b, v49
	v_mul_f32_e32 v66, 0xbfb8aa3b, v50
	v_mul_f32_e32 v67, 0xbfb8aa3b, v51
	v_exp_f32_e32 v64, v64
	v_exp_f32_e32 v65, v65
	v_exp_f32_e32 v66, v66
	v_exp_f32_e32 v67, v67
	v_add_f32_e32 v64, 1.0, v64
	v_add_f32_e32 v65, 1.0, v65
	v_add_f32_e32 v66, 1.0, v66
	v_add_f32_e32 v67, 1.0, v67
	v_rcp_f32_e32 v64, v64
	v_rcp_f32_e32 v65, v65
	v_rcp_f32_e32 v66, v66
	v_rcp_f32_e32 v67, v67
	v_mul_f32_e32 v48, v48, v64
	v_mul_f32_e32 v49, v49, v65
	v_mul_f32_e32 v50, v50, v66
	v_mul_f32_e32 v51, v51, v67
	v_mul_f32_e32 v48, v56, v48
	v_mul_f32_e32 v49, v57, v49
	v_mul_f32_e32 v50, v58, v50
	v_mul_f32_e32 v51, v59, v51
	v_cvt_pk_bf16_f32 v64, v48, v49
	v_cvt_pk_bf16_f32 v65, v50, v51
	global_store_short v72, v64, s[24:25]
	global_store_short_d16_hi v73, v64, s[24:25]
	global_store_short v74, v65, s[24:25]
	global_store_short_d16_hi v75, v65, s[24:25]
	v_mul_f32_e32 v68, 0xbfb8aa3b, v52
	v_mul_f32_e32 v69, 0xbfb8aa3b, v53
	v_mul_f32_e32 v70, 0xbfb8aa3b, v54
	v_mul_f32_e32 v71, 0xbfb8aa3b, v55
	v_exp_f32_e32 v68, v68
	v_exp_f32_e32 v69, v69
	v_exp_f32_e32 v70, v70
	v_exp_f32_e32 v71, v71
	v_add_f32_e32 v68, 1.0, v68
	v_add_f32_e32 v69, 1.0, v69
	v_add_f32_e32 v70, 1.0, v70
	v_add_f32_e32 v71, 1.0, v71
	v_rcp_f32_e32 v68, v68
	v_rcp_f32_e32 v69, v69
	v_rcp_f32_e32 v70, v70
	v_rcp_f32_e32 v71, v71
	v_mul_f32_e32 v52, v52, v68
	v_mul_f32_e32 v53, v53, v69
	v_mul_f32_e32 v54, v54, v70
	v_mul_f32_e32 v55, v55, v71
	v_mul_f32_e32 v52, v60, v52
	v_mul_f32_e32 v53, v61, v53
	v_mul_f32_e32 v54, v62, v54
	v_mul_f32_e32 v55, v63, v55
	v_cvt_pk_bf16_f32 v68, v52, v53
	v_cvt_pk_bf16_f32 v69, v54, v55
	global_store_short v72, v68, s[24:25] offset:32
	global_store_short_d16_hi v73, v68, s[24:25] offset:32
	global_store_short v74, v69, s[24:25] offset:32
	global_store_short_d16_hi v75, v69, s[24:25] offset:32
	s_xor_b64 s[54:55], s[54:55], -1
	s_and_b64 vcc, exec, s[54:55]
	s_cbranch_vccnz .LBB0_65
; #define TIDX get_tid_()
;   const int tid = TIDX, lane = tid & 63, wid = tid >> 6, wr = wid >> 1, wc = wid & 1, r = lane & 31, h = lane >> 5;
;   const int ch = (tid & 7) ^ ((tid >> 4) & 7);
;   unsigned avo[4], bvo[2];
; #pragma unroll
;   for (int i = 0; i < 4; ++i) avo[i] = (unsigned)(((tid >> 3) + 64 * i) * lda * 2 + ch * 16);
; #pragma unroll
;   for (int i = 0; i < 2; ++i) bvo[i] = (unsigned)(((tid >> 3) + 64 * i) * ldb * 2 + ch * 16);
;   const char* Ab = (const char*)A; const char* Bb = (const char*)Bt;
;   char* lw = lds + tid * 16;
;   const int nk = K >> 6;
;   const unsigned swz = (unsigned)((r >> 1) & 7);
;   const unsigned arow_u = (unsigned)((wr * 64 + r) * 128), brow_u = (unsigned)((wc * 64 + r) * 128);
;   const unsigned co0 = ((0u + h) ^ swz) << 4, co1 = ((2u + h) ^ swz) << 4, co2 = ((4u + h) ^ swz) << 4, co3 = ((6u + h) ^ swz) << 4;
; DI void zero_acc(f32x16 (&acc)[2][2]) {
; #pragma unroll
;   for (int a = 0; a < 2; ++a)
; #pragma unroll
;     for (int b = 0; b < 2; ++b)
; #pragma unroll
;       for (int i = 0; i < 16; ++i) acc[a][b][i] = 0.f;
; }
.LBB0_57:
	v_mov_b32_e32 v1, v129
	s_mov_b32 s68, s8
	v_lshlrev_b32_e32 v5, 4, v1
	v_lshrrev_b32_e32 v3, 5, v1
	v_xor_b32_e32 v0, v5, v1
	v_lshlrev_b32_e32 v2, 8, v1
	v_and_b32_e32 v6, 31, v1
	v_bfe_u32 v7, v1, 5, 1
	v_add_u32_e32 v116, 0, v5
	v_lshrrev_b32_e32 v5, 1, v1
	v_bfe_u32 v8, v1, 1, 3
	v_lshlrev_b32_e32 v1, 7, v1
	s_ashr_i32 s69, s8, 31
	v_and_b32_e32 v118, 0x2f80, v1
	v_bitop3_b32 v1, v3, v8, 1 bitop3:0x6c
	s_lshl_b64 s[26:27], s[68:69], 19
	v_lshlrev_b32_e32 v119, 4, v1
	v_bitop3_b32 v1, v7, v8, 2 bitop3:0x36
	s_add_u32 s30, s88, s26
	v_and_b32_e32 v2, 0xfffff800, v2
	s_movk_i32 s9, 0x70
	v_lshlrev_b32_e32 v120, 4, v1
	v_bitop3_b32 v1, v7, v8, 4 bitop3:0x36
	s_addc_u32 s31, s89, s27
	v_and_or_b32 v130, v0, s9, v2
	s_mov_b32 s9, 0x1ffffc0
	v_lshlrev_b32_e32 v121, 4, v1
	v_bitop3_b32 v1, v7, v8, 6 bitop3:0x36
	v_add_u32_e32 v8, 0x18000, v116
	v_add_u32_e32 v0, 0x20000, v130
	v_and_or_b32 v5, v5, s9, v6
	v_lshlrev_b32_e32 v122, 4, v1
	v_mov_b32_e32 v1, v131
	v_lshl_add_u64 v[64:65], s[30:31], 0, v[130:131]
	v_readfirstlane_b32 s9, v8
	v_add_u32_e32 v8, 0x1a000, v116
	v_lshl_add_u64 v[6:7], v[64:65], 0, s[78:79]
	v_lshl_add_u64 v[66:67], s[30:31], 0, v[0:1]
	v_readfirstlane_b32 s15, v8
	s_mov_b32 s70, s14
	s_ashr_i32 s71, s14, 31
	v_lshl_add_u64 v[6:7], v[66:67], 0, s[78:79]
	s_lshl_b64 s[26:27], s[70:71], 18
	v_add_u32_e32 v2, 0x40000, v130
	v_add_u32_e32 v4, 0x60000, v130
	v_lshlrev_b32_e32 v117, 7, v5
	v_mov_b32_e32 v3, v131
	v_mov_b32_e32 v5, v131
	v_add_u32_e32 v6, 0x1c000, v116
	s_add_u32 s54, s10, s26
	v_lshl_add_u64 v[68:69], s[30:31], 0, v[2:3]
	v_readfirstlane_b32 s26, v6
	v_lshl_add_u64 v[70:71], s[30:31], 0, v[4:5]
	v_add_u32_e32 v4, 0x1e000, v116
	s_addc_u32 s55, s11, s27
	v_lshl_add_u64 v[2:3], v[68:69], 0, s[78:79]
	v_readfirstlane_b32 s27, v4
	v_add_u32_e32 v4, 0x20000, v116
	v_lshl_add_u64 v[2:3], v[70:71], 0, s[78:79]
	v_lshl_add_u64 v[72:73], s[54:55], 0, v[130:131]
	v_readfirstlane_b32 s69, v4
	v_lshl_add_u64 v[2:3], v[72:73], 0, s[78:79]
	v_lshl_add_u64 v[74:75], s[54:55], 0, v[0:1]
	v_add_u32_e32 v2, 0x22000, v116
	s_cmp_lg_u32 0, -1
	v_readfirstlane_b32 s71, v2
	v_lshl_add_u64 v[0:1], v[74:75], 0, s[78:79]
	s_cselect_b32 s24, 0, 0
	s_mov_b32 s53, s52
	v_add_u32_e32 v0, s24, v117
	s_add_i32 s24, s24, 0x8000
	s_mov_b32 s54, s52
	s_mov_b32 s55, s52
	s_mov_b32 s56, s52
	s_mov_b32 s57, s52
	s_mov_b32 s58, s52
	s_mov_b32 s59, s52
	s_mov_b32 s60, s52
	s_mov_b32 s61, s52
	s_mov_b32 s62, s52
	s_mov_b32 s63, s52
	s_mov_b32 s64, s52
	s_mov_b32 s65, s52
	s_mov_b32 s66, s52
	s_mov_b32 s67, s52
	v_mov_b64_e32 v[32:33], s[52:53]
	v_add_u32_e32 v1, s24, v118
	v_mov_b64_e32 v[46:47], s[66:67]
	v_add_u32_e32 v76, v0, v119
	v_add_u32_e32 v77, v0, v120
	v_add_u32_e32 v78, v0, v121
	v_add_u32_e32 v79, v0, v122
	v_add_u32_e32 v80, v119, v1
	v_add_u32_e32 v81, v120, v1
	v_add_u32_e32 v82, v121, v1
	v_add_u32_e32 v83, v122, v1
	v_mov_b64_e32 v[34:35], s[54:55]
	v_mov_b64_e32 v[36:37], s[56:57]
	v_mov_b64_e32 v[38:39], s[58:59]
	v_mov_b64_e32 v[40:41], s[60:61]
	v_mov_b64_e32 v[42:43], s[62:63]
	v_mov_b64_e32 v[44:45], s[64:65]
	v_mov_b64_e32 v[62:63], v[46:47]
	v_mov_b64_e32 v[0:1], v[32:33]
	v_mov_b64_e32 v[16:17], v[32:33]
	v_mov_b64_e32 v[60:61], v[44:45]
	v_mov_b64_e32 v[58:59], v[42:43]
	v_mov_b64_e32 v[56:57], v[40:41]
	v_mov_b64_e32 v[54:55], v[38:39]
	v_mov_b64_e32 v[52:53], v[36:37]
	v_mov_b64_e32 v[50:51], v[34:35]
	v_mov_b64_e32 v[48:49], v[32:33]
	v_mov_b64_e32 v[2:3], v[34:35]
	v_mov_b64_e32 v[4:5], v[36:37]
	v_mov_b64_e32 v[6:7], v[38:39]
	v_mov_b64_e32 v[8:9], v[40:41]
	v_mov_b64_e32 v[10:11], v[42:43]
	v_mov_b64_e32 v[12:13], v[44:45]
	v_mov_b64_e32 v[14:15], v[46:47]
	v_mov_b64_e32 v[18:19], v[34:35]
	v_mov_b64_e32 v[20:21], v[36:37]
	v_mov_b64_e32 v[22:23], v[38:39]
	v_mov_b64_e32 v[24:25], v[40:41]
	v_mov_b64_e32 v[26:27], v[42:43]
	v_mov_b64_e32 v[28:29], v[44:45]
	v_mov_b64_e32 v[30:31], v[46:47]
	s_load_dword s9, s[0:1], 0x10
	s_waitcnt lgkmcnt(0)
	s_lshr_b32 s9, s9, 16
	s_cmp_lg_u32 s9, 0
	s_cselect_b64 s[26:27], -1, 0
	s_cmp_lg_u64 s[26:27], 0
	s_addc_u32 s9, s33, 0
	s_cmp_lg_u64 s[26:27], 0
	s_addc_u32 s23, s23, s33
	s_cmpk_gt_i32 s23, 0x15ff
	s_cbranch_scc0 .LBB0_59

; #define TIDX get_tid_()
;   const int tid = TIDX, lane = tid & 63, wid = tid >> 6, wr = wid >> 1, wc = wid & 1, r = lane & 31, h = lane >> 5;
;   const int ch = (tid & 7) ^ ((tid >> 4) & 7);
;   unsigned avo[4], bvo[2];
; #pragma unroll
;   for (int i = 0; i < 4; ++i) avo[i] = (unsigned)(((tid >> 3) + 64 * i) * lda * 2 + ch * 16);
; #pragma unroll
;   for (int i = 0; i < 2; ++i) bvo[i] = (unsigned)(((tid >> 3) + 64 * i) * ldb * 2 + ch * 16);
;   const char* Ab = (const char*)A; const char* Bb = (const char*)Bt;
;   char* lw = lds + tid * 16;
;   const int nk = K >> 6;
;   const unsigned swz = (unsigned)((r >> 1) & 7);
;   const unsigned arow_u = (unsigned)((wr * 64 + r) * 128), brow_u = (unsigned)((wc * 64 + r) * 128);
;   const unsigned co0 = ((0u + h) ^ swz) << 4, co1 = ((2u + h) ^ swz) << 4, co2 = ((4u + h) ^ swz) << 4, co3 = ((6u + h) ^ swz) << 4;
.Ly11_go:
	s_sub_i32 s56, s8, s68
	s_ashr_i32 s57, s56, 31
	s_lshl_b64 s[56:57], s[56:57], 19
	s_and_b64 s[56:57], s[56:57], s[54:55]
	s_sub_i32 s58, s14, s70
	s_ashr_i32 s59, s58, 31
	s_lshl_b64 s[58:59], s[58:59], 18
	s_and_b64 s[58:59], s[58:59], s[54:55]
	v_and_b32_e32 v84, 15, v129
	v_bfe_u32 v85, v129, 4, 2
	v_lshrrev_b32_e32 v86, 6, v129
	v_bfe_u32 v88, v129, 1, 3
	v_lshrrev_b32_e32 v87, 1, v86
	v_and_b32_e32 v86, 1, v86
	v_xor_b32_e32 v85, v85, v88
	v_lshl_add_u32 v87, v87, 6, v84
	v_lshl_add_u32 v86, v86, 6, v84
	v_lshlrev_b32_e32 v85, 4, v85
	v_lshlrev_b32_e32 v87, 7, v87
	v_lshlrev_b32_e32 v86, 7, v86
	v_add_u32_e32 v86, 0x8000, v86
	v_xor_b32_e32 v88, 0x40, v85
	v_add_u32_e32 v76, v87, v85
	v_add_u32_e32 v77, v87, v88
	v_add_u32_e32 v78, v86, v85
	v_add_u32_e32 v79, v86, v88
	v_add_u32_e32 v80, 0x18000, v76
	v_add_u32_e32 v82, 0x18000, v78
	v_add_u32_e32 v81, 0x18000, v77
	v_add_u32_e32 v83, 0x18000, v79
	v_lshlrev_b32_e32 v84, 4, v129
	s_nop 0
	v_readfirstlane_b32 s30, v84
	s_mov_b32 s25, 0
	s_cmp_eq_u32 s101, 1
	s_cbranch_scc1 .Ly11_first
	s_waitcnt vmcnt(38)
	s_branch .Ly11_w0

;     ...
;   for (int kt = 0; kt < nk; ++kt) {
;     if (kt + 1 < nk) asm volatile("s_waitcnt vmcnt(6)" ::: "memory");
;     else asm volatile("s_waitcnt vmcnt(0)" ::: "memory");
;     __builtin_amdgcn_s_barrier();
;     asm volatile("" ::: "memory");
;     if (kt + 2 < nk) { const int st2 = (st >= 1) ? st - 1 : 2; GEMM_ISSUE(kt + 2, st2); }
;     const char* la = lds + st * STAGE_B;
;     const char* lb = la + 32768;
;     const unsigned sa_u = (unsigned)(size_t)la + arow_u, sb_u = (unsigned)(size_t)lb + brow_u;
;     const unsigned a0 = sa_u + co0, a1 = sa_u + co1, a2 = sa_u + co2, a3 = sa_u + co3;
;     const unsigned b0 = sb_u + co0, b1 = sb_u + co1, b2 = sb_u + co2, b3 = sb_u + co3;
;     {
;       bf16x8 p0, p1, q0, q1, u0, u1, w0, w1;
;       asm volatile(
;         "ds_read_b128 %4, %12\n\tds_read_b128 %5, %12 offset:4096\n\tds_read_b128 %6, %16\n\tds_read_b128 %7, %16 offset:4096\n\t"
;         "ds_read_b128 %8, %13\n\tds_read_b128 %9, %13 offset:4096\n\tds_read_b128 %10, %17\n\tds_read_b128 %11, %17 offset:4096\n\t"
;         "s_waitcnt lgkmcnt(4)\n\t"
;         "v_mfma_f32_32x32x16_bf16 %0, %4, %6, %0\n\tv_mfma_f32_32x32x16_bf16 %1, %4, %7, %1\n\tv_mfma_f32_32x32x16_bf16 %2, %5, %6, %2\n\tv_mfma_f32_32x32x16_bf16 %3, %5, %7, %3\n\t"
;         "ds_read_b128 %4, %14\n\tds_read_b128 %5, %14 offset:4096\n\tds_read_b128 %6, %18\n\tds_read_b128 %7, %18 offset:4096\n\t"
;         "s_waitcnt lgkmcnt(4)\n\t"
;         "v_mfma_f32_32x32x16_bf16 %0, %8, %10, %0\n\tv_mfma_f32_32x32x16_bf16 %1, %8, %11, %1\n\tv_mfma_f32_32x32x16_bf16 %2, %9, %10, %2\n\tv_mfma_f32_32x32x16_bf16 %3, %9, %11, %3\n\t"
;         "ds_read_b128 %8, %15\n\tds_read_b128 %9, %15 offset:4096\n\tds_read_b128 %10, %19\n\tds_read_b128 %11, %19 offset:4096\n\t"
;         "s_waitcnt lgkmcnt(4)\n\t"
;         "v_mfma_f32_32x32x16_bf16 %0, %4, %6, %0\n\tv_mfma_f32_32x32x16_bf16 %1, %4, %7, %1\n\tv_mfma_f32_32x32x16_bf16 %2, %5, %6, %2\n\tv_mfma_f32_32x32x16_bf16 %3, %5, %7, %3\n\t"
;         "s_waitcnt lgkmcnt(0)\n\t"
;         "v_mfma_f32_32x32x16_bf16 %0, %8, %10, %0\n\tv_mfma_f32_32x32x16_bf16 %1, %8, %11, %1\n\tv_mfma_f32_32x32x16_bf16 %2, %9, %10, %2\n\tv_mfma_f32_32x32x16_bf16 %3, %9, %11, %3"
;         : "+v"(acc[0][0]), "+v"(acc[0][1]), "+v"(acc[1][0]), "+v"(acc[1][1]),
;           "=&v"(p0), "=&v"(p1), "=&v"(q0), "=&v"(q1), "=&v"(u0), "=&v"(u1), "=&v"(w0), "=&v"(w1)
.Ly11_w0:
	s_barrier
	s_cmp_eq_u32 s100, 1
	s_cbranch_scc1 .Ly11_v1
	s_cmp_eq_u32 s100, 2
	s_cbranch_scc1 .Ly11_v2
	ds_read_b128 v[84:87], v76
	ds_read_b128 v[88:91], v76 offset:2048
	ds_read_b128 v[92:95], v76 offset:4096
	ds_read_b128 v[96:99], v76 offset:6144
	ds_read_b128 v[100:103], v78
	ds_read_b128 v[104:107], v78 offset:2048
	ds_read_b128 v[108:111], v78 offset:4096
	ds_read_b128 v[112:115], v78 offset:6144
	s_mov_b32 s24, 0x100
	s_mov_b32 s25, 0
	s_add_u32 m0, s30, 0x18000
	v_lshl_add_u64 v[124:125], v[64:65], 0, s[24:25]
	global_load_lds_dwordx4 v[124:125], off
	s_add_u32 m0, s30, 0x1a000
	v_lshl_add_u64 v[126:127], v[66:67], 0, s[24:25]
	global_load_lds_dwordx4 v[126:127], off
	s_add_u32 m0, s30, 0x1c000
	v_lshl_add_u64 v[124:125], v[68:69], 0, s[24:25]
	global_load_lds_dwordx4 v[124:125], off
	ds_read_b128 v[136:139], v77
	ds_read_b128 v[140:143], v77 offset:2048
	ds_read_b128 v[144:147], v77 offset:4096
	ds_read_b128 v[148:151], v77 offset:6144
	ds_read_b128 v[152:155], v79
	ds_read_b128 v[156:159], v79 offset:2048
	ds_read_b128 v[160:163], v79 offset:4096
	ds_read_b128 v[164:167], v79 offset:6144
	s_waitcnt lgkmcnt(8)
	v_mfma_f32_16x16x32_bf16 v[0:3], v[84:87], v[100:103], v[0:3]
	v_mfma_f32_16x16x32_bf16 v[4:7], v[84:87], v[104:107], v[4:7]
	s_add_u32 m0, s30, 0x1e000
	v_lshl_add_u64 v[126:127], v[70:71], 0, s[24:25]
	global_load_lds_dwordx4 v[126:127], off
	v_mfma_f32_16x16x32_bf16 v[8:11], v[84:87], v[108:111], v[8:11]
	v_mfma_f32_16x16x32_bf16 v[12:15], v[84:87], v[112:115], v[12:15]
	v_mfma_f32_16x16x32_bf16 v[16:19], v[88:91], v[100:103], v[16:19]
	v_mfma_f32_16x16x32_bf16 v[20:23], v[88:91], v[104:107], v[20:23]
	v_mfma_f32_16x16x32_bf16 v[24:27], v[88:91], v[108:111], v[24:27]
	s_add_u32 m0, s30, 0x20000
	v_lshl_add_u64 v[124:125], v[72:73], 0, s[24:25]
	global_load_lds_dwordx4 v[124:125], off
	v_mfma_f32_16x16x32_bf16 v[28:31], v[88:91], v[112:115], v[28:31]
	v_mfma_f32_16x16x32_bf16 v[32:35], v[92:95], v[100:103], v[32:35]
	v_mfma_f32_16x16x32_bf16 v[36:39], v[92:95], v[104:107], v[36:39]
	v_mfma_f32_16x16x32_bf16 v[40:43], v[92:95], v[108:111], v[40:43]
	v_mfma_f32_16x16x32_bf16 v[44:47], v[92:95], v[112:115], v[44:47]
	s_add_u32 m0, s30, 0x22000
	v_lshl_add_u64 v[126:127], v[74:75], 0, s[24:25]
	global_load_lds_dwordx4 v[126:127], off
	v_mfma_f32_16x16x32_bf16 v[48:51], v[96:99], v[100:103], v[48:51]
	v_mfma_f32_16x16x32_bf16 v[52:55], v[96:99], v[104:107], v[52:55]
	v_mfma_f32_16x16x32_bf16 v[56:59], v[96:99], v[108:111], v[56:59]
	v_mfma_f32_16x16x32_bf16 v[60:63], v[96:99], v[112:115], v[60:63]
	s_waitcnt vmcnt(6) lgkmcnt(0)
	s_barrier
	ds_read_b128 v[84:87], v76 offset:49152
	ds_read_b128 v[88:91], v76 offset:51200
	ds_read_b128 v[92:95], v76 offset:53248
	ds_read_b128 v[96:99], v76 offset:55296
	ds_read_b128 v[100:103], v78 offset:49152
	ds_read_b128 v[104:107], v78 offset:51200
	ds_read_b128 v[108:111], v78 offset:53248
	ds_read_b128 v[112:115], v78 offset:55296
	v_mfma_f32_16x16x32_bf16 v[0:3], v[136:139], v[152:155], v[0:3]
	v_mfma_f32_16x16x32_bf16 v[4:7], v[136:139], v[156:159], v[4:7]
	s_mov_b32 s24, 0x180
	s_mov_b32 s25, 0
	s_mov_b32 m0, s30
	v_lshl_add_u64 v[124:125], v[64:65], 0, s[24:25]
	global_load_lds_dwordx4 v[124:125], off
	v_mfma_f32_16x16x32_bf16 v[8:11], v[136:139], v[160:163], v[8:11]
	v_mfma_f32_16x16x32_bf16 v[12:15], v[136:139], v[164:167], v[12:15]
	v_mfma_f32_16x16x32_bf16 v[16:19], v[140:143], v[152:155], v[16:19]
	v_mfma_f32_16x16x32_bf16 v[20:23], v[140:143], v[156:159], v[20:23]
	v_mfma_f32_16x16x32_bf16 v[24:27], v[140:143], v[160:163], v[24:27]
	s_add_u32 m0, s30, 0x2000
	v_lshl_add_u64 v[126:127], v[66:67], 0, s[24:25]
	global_load_lds_dwordx4 v[126:127], off
	v_mfma_f32_16x16x32_bf16 v[28:31], v[140:143], v[164:167], v[28:31]
	v_mfma_f32_16x16x32_bf16 v[32:35], v[144:147], v[152:155], v[32:35]
	v_mfma_f32_16x16x32_bf16 v[36:39], v[144:147], v[156:159], v[36:39]
	v_mfma_f32_16x16x32_bf16 v[40:43], v[144:147], v[160:163], v[40:43]
	v_mfma_f32_16x16x32_bf16 v[44:47], v[144:147], v[164:167], v[44:47]
	s_add_u32 m0, s30, 0x4000
	v_lshl_add_u64 v[124:125], v[68:69], 0, s[24:25]
	global_load_lds_dwordx4 v[124:125], off
	v_mfma_f32_16x16x32_bf16 v[48:51], v[148:151], v[152:155], v[48:51]
	v_mfma_f32_16x16x32_bf16 v[52:55], v[148:151], v[156:159], v[52:55]
	v_mfma_f32_16x16x32_bf16 v[56:59], v[148:151], v[160:163], v[56:59]
	v_mfma_f32_16x16x32_bf16 v[60:63], v[148:151], v[164:167], v[60:63]
	ds_read_b128 v[136:139], v77 offset:49152
	ds_read_b128 v[140:143], v77 offset:51200
	ds_read_b128 v[144:147], v77 offset:53248
	ds_read_b128 v[148:151], v77 offset:55296
	ds_read_b128 v[152:155], v79 offset:49152
	ds_read_b128 v[156:159], v79 offset:51200
	ds_read_b128 v[160:163], v79 offset:53248
	ds_read_b128 v[164:167], v79 offset:55296
	s_waitcnt lgkmcnt(8)
	v_mfma_f32_16x16x32_bf16 v[0:3], v[84:87], v[100:103], v[0:3]
	v_mfma_f32_16x16x32_bf16 v[4:7], v[84:87], v[104:107], v[4:7]
	s_add_u32 m0, s30, 0x6000
	v_lshl_add_u64 v[126:127], v[70:71], 0, s[24:25]
	global_load_lds_dwordx4 v[126:127], off
	v_mfma_f32_16x16x32_bf16 v[8:11], v[84:87], v[108:111], v[8:11]
	v_mfma_f32_16x16x32_bf16 v[12:15], v[84:87], v[112:115], v[12:15]
	v_mfma_f32_16x16x32_bf16 v[16:19], v[88:91], v[100:103], v[16:19]
	v_mfma_f32_16x16x32_bf16 v[20:23], v[88:91], v[104:107], v[20:23]
	v_mfma_f32_16x16x32_bf16 v[24:27], v[88:91], v[108:111], v[24:27]
	s_add_u32 m0, s30, 0x8000
	v_lshl_add_u64 v[124:125], v[72:73], 0, s[24:25]
	global_load_lds_dwordx4 v[124:125], off
	v_mfma_f32_16x16x32_bf16 v[28:31], v[88:91], v[112:115], v[28:31]
	v_mfma_f32_16x16x32_bf16 v[32:35], v[92:95], v[100:103], v[32:35]
	v_mfma_f32_16x16x32_bf16 v[36:39], v[92:95], v[104:107], v[36:39]
	v_mfma_f32_16x16x32_bf16 v[40:43], v[92:95], v[108:111], v[40:43]
	v_mfma_f32_16x16x32_bf16 v[44:47], v[92:95], v[112:115], v[44:47]
	s_add_u32 m0, s30, 0xa000
	v_lshl_add_u64 v[126:127], v[74:75], 0, s[24:25]
	global_load_lds_dwordx4 v[126:127], off
	v_mfma_f32_16x16x32_bf16 v[48:51], v[96:99], v[100:103], v[48:51]
	v_mfma_f32_16x16x32_bf16 v[52:55], v[96:99], v[104:107], v[52:55]
	v_mfma_f32_16x16x32_bf16 v[56:59], v[96:99], v[108:111], v[56:59]
	v_mfma_f32_16x16x32_bf16 v[60:63], v[96:99], v[112:115], v[60:63]
	s_waitcnt vmcnt(6) lgkmcnt(0)
	s_barrier
;     ...
;   for (int kt = 0; kt < nk; ++kt) {
;     if (kt + 1 < nk) asm volatile("s_waitcnt vmcnt(6)" ::: "memory");
;     else asm volatile("s_waitcnt vmcnt(0)" ::: "memory");
;     __builtin_amdgcn_s_barrier();
;     asm volatile("" ::: "memory");
;     if (kt + 2 < nk) { const int st2 = (st >= 1) ? st - 1 : 2; GEMM_ISSUE(kt + 2, st2); }
;     const char* la = lds + st * STAGE_B;
;     const char* lb = la + 32768;
;     const unsigned sa_u = (unsigned)(size_t)la + arow_u, sb_u = (unsigned)(size_t)lb + brow_u;
;     const unsigned a0 = sa_u + co0, a1 = sa_u + co1, a2 = sa_u + co2, a3 = sa_u + co3;
;     const unsigned b0 = sb_u + co0, b1 = sb_u + co1, b2 = sb_u + co2, b3 = sb_u + co3;
;     {
;       bf16x8 p0, p1, q0, q1, u0, u1, w0, w1;
;       asm volatile(
;         "ds_read_b128 %4, %12\n\tds_read_b128 %5, %12 offset:4096\n\tds_read_b128 %6, %16\n\tds_read_b128 %7, %16 offset:4096\n\t"
;         "ds_read_b128 %8, %13\n\tds_read_b128 %9, %13 offset:4096\n\tds_read_b128 %10, %17\n\tds_read_b128 %11, %17 offset:4096\n\t"
;         "s_waitcnt lgkmcnt(4)\n\t"
;         "v_mfma_f32_32x32x16_bf16 %0, %4, %6, %0\n\tv_mfma_f32_32x32x16_bf16 %1, %4, %7, %1\n\tv_mfma_f32_32x32x16_bf16 %2, %5, %6, %2\n\tv_mfma_f32_32x32x16_bf16 %3, %5, %7, %3\n\t"
;         "ds_read_b128 %4, %14\n\tds_read_b128 %5, %14 offset:4096\n\tds_read_b128 %6, %18\n\tds_read_b128 %7, %18 offset:4096\n\t"
;         "s_waitcnt lgkmcnt(4)\n\t"
;         "v_mfma_f32_32x32x16_bf16 %0, %8, %10, %0\n\tv_mfma_f32_32x32x16_bf16 %1, %8, %11, %1\n\tv_mfma_f32_32x32x16_bf16 %2, %9, %10, %2\n\tv_mfma_f32_32x32x16_bf16 %3, %9, %11, %3\n\t"
;         "ds_read_b128 %8, %15\n\tds_read_b128 %9, %15 offset:4096\n\tds_read_b128 %10, %19\n\tds_read_b128 %11, %19 offset:4096\n\t"
;         "s_waitcnt lgkmcnt(4)\n\t"
;         "v_mfma_f32_32x32x16_bf16 %0, %4, %6, %0\n\tv_mfma_f32_32x32x16_bf16 %1, %4, %7, %1\n\tv_mfma_f32_32x32x16_bf16 %2, %5, %6, %2\n\tv_mfma_f32_32x32x16_bf16 %3, %5, %7, %3\n\t"
;         "s_waitcnt lgkmcnt(0)\n\t"
;         "v_mfma_f32_32x32x16_bf16 %0, %8, %10, %0\n\tv_mfma_f32_32x32x16_bf16 %1, %8, %11, %1\n\tv_mfma_f32_32x32x16_bf16 %2, %9, %10, %2\n\tv_mfma_f32_32x32x16_bf16 %3, %9, %11, %3"
;         : "+v"(acc[0][0]), "+v"(acc[0][1]), "+v"(acc[1][0]), "+v"(acc[1][1]),
;           "=&v"(p0), "=&v"(p1), "=&v"(q0), "=&v"(q1), "=&v"(u0), "=&v"(u1), "=&v"(w0), "=&v"(w1)
	ds_read_b128 v[84:87], v80
	ds_read_b128 v[88:91], v80 offset:2048
	ds_read_b128 v[92:95], v80 offset:4096
	ds_read_b128 v[96:99], v80 offset:6144
	ds_read_b128 v[100:103], v82
	ds_read_b128 v[104:107], v82 offset:2048
	ds_read_b128 v[108:111], v82 offset:4096
	ds_read_b128 v[112:115], v82 offset:6144
	v_mfma_f32_16x16x32_bf16 v[0:3], v[136:139], v[152:155], v[0:3]
	v_mfma_f32_16x16x32_bf16 v[4:7], v[136:139], v[156:159], v[4:7]
	s_mov_b32 s24, 0x200
	s_mov_b32 s25, 0
	s_add_u32 m0, s30, 0xc000
	v_lshl_add_u64 v[124:125], v[64:65], 0, s[24:25]
	global_load_lds_dwordx4 v[124:125], off
	v_mfma_f32_16x16x32_bf16 v[8:11], v[136:139], v[160:163], v[8:11]
	v_mfma_f32_16x16x32_bf16 v[12:15], v[136:139], v[164:167], v[12:15]
	v_mfma_f32_16x16x32_bf16 v[16:19], v[140:143], v[152:155], v[16:19]
	v_mfma_f32_16x16x32_bf16 v[20:23], v[140:143], v[156:159], v[20:23]
	v_mfma_f32_16x16x32_bf16 v[24:27], v[140:143], v[160:163], v[24:27]
	s_add_u32 m0, s30, 0xe000
	v_lshl_add_u64 v[126:127], v[66:67], 0, s[24:25]
	global_load_lds_dwordx4 v[126:127], off
	v_mfma_f32_16x16x32_bf16 v[28:31], v[140:143], v[164:167], v[28:31]
	v_mfma_f32_16x16x32_bf16 v[32:35], v[144:147], v[152:155], v[32:35]
	v_mfma_f32_16x16x32_bf16 v[36:39], v[144:147], v[156:159], v[36:39]
	v_mfma_f32_16x16x32_bf16 v[40:43], v[144:147], v[160:163], v[40:43]
	v_mfma_f32_16x16x32_bf16 v[44:47], v[144:147], v[164:167], v[44:47]
	s_add_u32 m0, s30, 0x10000
	v_lshl_add_u64 v[124:125], v[68:69], 0, s[24:25]
	global_load_lds_dwordx4 v[124:125], off
	v_mfma_f32_16x16x32_bf16 v[48:51], v[148:151], v[152:155], v[48:51]
	v_mfma_f32_16x16x32_bf16 v[52:55], v[148:151], v[156:159], v[52:55]
	v_mfma_f32_16x16x32_bf16 v[56:59], v[148:151], v[160:163], v[56:59]
	v_mfma_f32_16x16x32_bf16 v[60:63], v[148:151], v[164:167], v[60:63]
	ds_read_b128 v[136:139], v81
	ds_read_b128 v[140:143], v81 offset:2048
	ds_read_b128 v[144:147], v81 offset:4096
	ds_read_b128 v[148:151], v81 offset:6144
	ds_read_b128 v[152:155], v83
	ds_read_b128 v[156:159], v83 offset:2048
	ds_read_b128 v[160:163], v83 offset:4096
	ds_read_b128 v[164:167], v83 offset:6144
	s_waitcnt lgkmcnt(8)
	v_mfma_f32_16x16x32_bf16 v[0:3], v[84:87], v[100:103], v[0:3]
	v_mfma_f32_16x16x32_bf16 v[4:7], v[84:87], v[104:107], v[4:7]
	s_add_u32 m0, s30, 0x12000
	v_lshl_add_u64 v[126:127], v[70:71], 0, s[24:25]
	global_load_lds_dwordx4 v[126:127], off
	v_mfma_f32_16x16x32_bf16 v[8:11], v[84:87], v[108:111], v[8:11]
	v_mfma_f32_16x16x32_bf16 v[12:15], v[84:87], v[112:115], v[12:15]
	v_mfma_f32_16x16x32_bf16 v[16:19], v[88:91], v[100:103], v[16:19]
	v_mfma_f32_16x16x32_bf16 v[20:23], v[88:91], v[104:107], v[20:23]
	v_mfma_f32_16x16x32_bf16 v[24:27], v[88:91], v[108:111], v[24:27]
	s_add_u32 m0, s30, 0x14000
	v_lshl_add_u64 v[124:125], v[72:73], 0, s[24:25]
	global_load_lds_dwordx4 v[124:125], off
	v_mfma_f32_16x16x32_bf16 v[28:31], v[88:91], v[112:115], v[28:31]
	v_mfma_f32_16x16x32_bf16 v[32:35], v[92:95], v[100:103], v[32:35]
	v_mfma_f32_16x16x32_bf16 v[36:39], v[92:95], v[104:107], v[36:39]
	v_mfma_f32_16x16x32_bf16 v[40:43], v[92:95], v[108:111], v[40:43]
	v_mfma_f32_16x16x32_bf16 v[44:47], v[92:95], v[112:115], v[44:47]
	s_add_u32 m0, s30, 0x16000
	v_lshl_add_u64 v[126:127], v[74:75], 0, s[24:25]
	global_load_lds_dwordx4 v[126:127], off
	v_mfma_f32_16x16x32_bf16 v[48:51], v[96:99], v[100:103], v[48:51]
	v_mfma_f32_16x16x32_bf16 v[52:55], v[96:99], v[104:107], v[52:55]
	v_mfma_f32_16x16x32_bf16 v[56:59], v[96:99], v[108:111], v[56:59]
	v_mfma_f32_16x16x32_bf16 v[60:63], v[96:99], v[112:115], v[60:63]
	s_waitcnt vmcnt(6) lgkmcnt(0)
	s_barrier
	ds_read_b128 v[84:87], v76
	ds_read_b128 v[88:91], v76 offset:2048
	ds_read_b128 v[92:95], v76 offset:4096
	ds_read_b128 v[96:99], v76 offset:6144
	ds_read_b128 v[100:103], v78
	ds_read_b128 v[104:107], v78 offset:2048
	ds_read_b128 v[108:111], v78 offset:4096
	ds_read_b128 v[112:115], v78 offset:6144
	v_mfma_f32_16x16x32_bf16 v[0:3], v[136:139], v[152:155], v[0:3]
	v_mfma_f32_16x16x32_bf16 v[4:7], v[136:139], v[156:159], v[4:7]
	s_mov_b32 s24, 0x280
	s_mov_b32 s25, 0
	s_add_u32 m0, s30, 0x18000
	v_lshl_add_u64 v[124:125], v[64:65], 0, s[24:25]
	global_load_lds_dwordx4 v[124:125], off
	v_mfma_f32_16x16x32_bf16 v[8:11], v[136:139], v[160:163], v[8:11]
	v_mfma_f32_16x16x32_bf16 v[12:15], v[136:139], v[164:167], v[12:15]
	v_mfma_f32_16x16x32_bf16 v[16:19], v[140:143], v[152:155], v[16:19]
	v_mfma_f32_16x16x32_bf16 v[20:23], v[140:143], v[156:159], v[20:23]
	v_mfma_f32_16x16x32_bf16 v[24:27], v[140:143], v[160:163], v[24:27]
	s_add_u32 m0, s30, 0x1a000
	v_lshl_add_u64 v[126:127], v[66:67], 0, s[24:25]
	global_load_lds_dwordx4 v[126:127], off
	v_mfma_f32_16x16x32_bf16 v[28:31], v[140:143], v[164:167], v[28:31]
	v_mfma_f32_16x16x32_bf16 v[32:35], v[144:147], v[152:155], v[32:35]
	v_mfma_f32_16x16x32_bf16 v[36:39], v[144:147], v[156:159], v[36:39]
	v_mfma_f32_16x16x32_bf16 v[40:43], v[144:147], v[160:163], v[40:43]
	v_mfma_f32_16x16x32_bf16 v[44:47], v[144:147], v[164:167], v[44:47]
	s_add_u32 m0, s30, 0x1c000
	v_lshl_add_u64 v[124:125], v[68:69], 0, s[24:25]
	global_load_lds_dwordx4 v[124:125], off
	v_mfma_f32_16x16x32_bf16 v[48:51], v[148:151], v[152:155], v[48:51]
	v_mfma_f32_16x16x32_bf16 v[52:55], v[148:151], v[156:159], v[52:55]
	v_mfma_f32_16x16x32_bf16 v[56:59], v[148:151], v[160:163], v[56:59]
	v_mfma_f32_16x16x32_bf16 v[60:63], v[148:151], v[164:167], v[60:63]
	ds_read_b128 v[136:139], v77
	ds_read_b128 v[140:143], v77 offset:2048
	ds_read_b128 v[144:147], v77 offset:4096
	ds_read_b128 v[148:151], v77 offset:6144
	ds_read_b128 v[152:155], v79
	ds_read_b128 v[156:159], v79 offset:2048
	ds_read_b128 v[160:163], v79 offset:4096
	ds_read_b128 v[164:167], v79 offset:6144
	s_waitcnt lgkmcnt(8)
;     ...
;   for (int kt = 0; kt < nk; ++kt) {
;     if (kt + 1 < nk) asm volatile("s_waitcnt vmcnt(6)" ::: "memory");
;     else asm volatile("s_waitcnt vmcnt(0)" ::: "memory");
;     __builtin_amdgcn_s_barrier();
;     asm volatile("" ::: "memory");
;     if (kt + 2 < nk) { const int st2 = (st >= 1) ? st - 1 : 2; GEMM_ISSUE(kt + 2, st2); }
;     const char* la = lds + st * STAGE_B;
;     const char* lb = la + 32768;
;     const unsigned sa_u = (unsigned)(size_t)la + arow_u, sb_u = (unsigned)(size_t)lb + brow_u;
;     const unsigned a0 = sa_u + co0, a1 = sa_u + co1, a2 = sa_u + co2, a3 = sa_u + co3;
;     const unsigned b0 = sb_u + co0, b1 = sb_u + co1, b2 = sb_u + co2, b3 = sb_u + co3;
;     {
;       bf16x8 p0, p1, q0, q1, u0, u1, w0, w1;
;       asm volatile(
;         "ds_read_b128 %4, %12\n\tds_read_b128 %5, %12 offset:4096\n\tds_read_b128 %6, %16\n\tds_read_b128 %7, %16 offset:4096\n\t"
;         "ds_read_b128 %8, %13\n\tds_read_b128 %9, %13 offset:4096\n\tds_read_b128 %10, %17\n\tds_read_b128 %11, %17 offset:4096\n\t"
;         "s_waitcnt lgkmcnt(4)\n\t"
;         "v_mfma_f32_32x32x16_bf16 %0, %4, %6, %0\n\tv_mfma_f32_32x32x16_bf16 %1, %4, %7, %1\n\tv_mfma_f32_32x32x16_bf16 %2, %5, %6, %2\n\tv_mfma_f32_32x32x16_bf16 %3, %5, %7, %3\n\t"
;         "ds_read_b128 %4, %14\n\tds_read_b128 %5, %14 offset:4096\n\tds_read_b128 %6, %18\n\tds_read_b128 %7, %18 offset:4096\n\t"
;         "s_waitcnt lgkmcnt(4)\n\t"
;         "v_mfma_f32_32x32x16_bf16 %0, %8, %10, %0\n\tv_mfma_f32_32x32x16_bf16 %1, %8, %11, %1\n\tv_mfma_f32_32x32x16_bf16 %2, %9, %10, %2\n\tv_mfma_f32_32x32x16_bf16 %3, %9, %11, %3\n\t"
;         "ds_read_b128 %8, %15\n\tds_read_b128 %9, %15 offset:4096\n\tds_read_b128 %10, %19\n\tds_read_b128 %11, %19 offset:4096\n\t"
;         "s_waitcnt lgkmcnt(4)\n\t"
;         "v_mfma_f32_32x32x16_bf16 %0, %4, %6, %0\n\tv_mfma_f32_32x32x16_bf16 %1, %4, %7, %1\n\tv_mfma_f32_32x32x16_bf16 %2, %5, %6, %2\n\tv_mfma_f32_32x32x16_bf16 %3, %5, %7, %3\n\t"
;         "s_waitcnt lgkmcnt(0)\n\t"
;         "v_mfma_f32_32x32x16_bf16 %0, %8, %10, %0\n\tv_mfma_f32_32x32x16_bf16 %1, %8, %11, %1\n\tv_mfma_f32_32x32x16_bf16 %2, %9, %10, %2\n\tv_mfma_f32_32x32x16_bf16 %3, %9, %11, %3"
;         : "+v"(acc[0][0]), "+v"(acc[0][1]), "+v"(acc[1][0]), "+v"(acc[1][1]),
;           "=&v"(p0), "=&v"(p1), "=&v"(q0), "=&v"(q1), "=&v"(u0), "=&v"(u1), "=&v"(w0), "=&v"(w1)
	v_mfma_f32_16x16x32_bf16 v[0:3], v[84:87], v[100:103], v[0:3]
	v_mfma_f32_16x16x32_bf16 v[4:7], v[84:87], v[104:107], v[4:7]
	s_add_u32 m0, s30, 0x1e000
	v_lshl_add_u64 v[126:127], v[70:71], 0, s[24:25]
	global_load_lds_dwordx4 v[126:127], off
	v_mfma_f32_16x16x32_bf16 v[8:11], v[84:87], v[108:111], v[8:11]
	v_mfma_f32_16x16x32_bf16 v[12:15], v[84:87], v[112:115], v[12:15]
	v_mfma_f32_16x16x32_bf16 v[16:19], v[88:91], v[100:103], v[16:19]
	v_mfma_f32_16x16x32_bf16 v[20:23], v[88:91], v[104:107], v[20:23]
	v_mfma_f32_16x16x32_bf16 v[24:27], v[88:91], v[108:111], v[24:27]
	s_add_u32 m0, s30, 0x20000
	v_lshl_add_u64 v[124:125], v[72:73], 0, s[24:25]
	global_load_lds_dwordx4 v[124:125], off
	v_mfma_f32_16x16x32_bf16 v[28:31], v[88:91], v[112:115], v[28:31]
	v_mfma_f32_16x16x32_bf16 v[32:35], v[92:95], v[100:103], v[32:35]
	v_mfma_f32_16x16x32_bf16 v[36:39], v[92:95], v[104:107], v[36:39]
	v_mfma_f32_16x16x32_bf16 v[40:43], v[92:95], v[108:111], v[40:43]
	v_mfma_f32_16x16x32_bf16 v[44:47], v[92:95], v[112:115], v[44:47]
	s_add_u32 m0, s30, 0x22000
	v_lshl_add_u64 v[126:127], v[74:75], 0, s[24:25]
	global_load_lds_dwordx4 v[126:127], off
	v_mfma_f32_16x16x32_bf16 v[48:51], v[96:99], v[100:103], v[48:51]
	v_mfma_f32_16x16x32_bf16 v[52:55], v[96:99], v[104:107], v[52:55]
	v_mfma_f32_16x16x32_bf16 v[56:59], v[96:99], v[108:111], v[56:59]
	v_mfma_f32_16x16x32_bf16 v[60:63], v[96:99], v[112:115], v[60:63]
	s_waitcnt vmcnt(6) lgkmcnt(0)
	s_barrier
	ds_read_b128 v[84:87], v76 offset:49152
	ds_read_b128 v[88:91], v76 offset:51200
	ds_read_b128 v[92:95], v76 offset:53248
	ds_read_b128 v[96:99], v76 offset:55296
	ds_read_b128 v[100:103], v78 offset:49152
	ds_read_b128 v[104:107], v78 offset:51200
	ds_read_b128 v[108:111], v78 offset:53248
	ds_read_b128 v[112:115], v78 offset:55296
	v_mfma_f32_16x16x32_bf16 v[0:3], v[136:139], v[152:155], v[0:3]
	v_mfma_f32_16x16x32_bf16 v[4:7], v[136:139], v[156:159], v[4:7]
	s_mov_b32 s24, 0x300
	s_mov_b32 s25, 0
	s_mov_b32 m0, s30
	v_lshl_add_u64 v[124:125], v[64:65], 0, s[24:25]
	global_load_lds_dwordx4 v[124:125], off
	v_mfma_f32_16x16x32_bf16 v[8:11], v[136:139], v[160:163], v[8:11]
	v_mfma_f32_16x16x32_bf16 v[12:15], v[136:139], v[164:167], v[12:15]
	v_mfma_f32_16x16x32_bf16 v[16:19], v[140:143], v[152:155], v[16:19]
	v_mfma_f32_16x16x32_bf16 v[20:23], v[140:143], v[156:159], v[20:23]
	v_mfma_f32_16x16x32_bf16 v[24:27], v[140:143], v[160:163], v[24:27]
	s_add_u32 m0, s30, 0x2000
	v_lshl_add_u64 v[126:127], v[66:67], 0, s[24:25]
	global_load_lds_dwordx4 v[126:127], off
	v_mfma_f32_16x16x32_bf16 v[28:31], v[140:143], v[164:167], v[28:31]
	v_mfma_f32_16x16x32_bf16 v[32:35], v[144:147], v[152:155], v[32:35]
	v_mfma_f32_16x16x32_bf16 v[36:39], v[144:147], v[156:159], v[36:39]
	v_mfma_f32_16x16x32_bf16 v[40:43], v[144:147], v[160:163], v[40:43]
	v_mfma_f32_16x16x32_bf16 v[44:47], v[144:147], v[164:167], v[44:47]
	s_add_u32 m0, s30, 0x4000
	v_lshl_add_u64 v[124:125], v[68:69], 0, s[24:25]
	global_load_lds_dwordx4 v[124:125], off
	v_mfma_f32_16x16x32_bf16 v[48:51], v[148:151], v[152:155], v[48:51]
	v_mfma_f32_16x16x32_bf16 v[52:55], v[148:151], v[156:159], v[52:55]
	v_mfma_f32_16x16x32_bf16 v[56:59], v[148:151], v[160:163], v[56:59]
	v_mfma_f32_16x16x32_bf16 v[60:63], v[148:151], v[164:167], v[60:63]
	ds_read_b128 v[136:139], v77 offset:49152
	ds_read_b128 v[140:143], v77 offset:51200
	ds_read_b128 v[144:147], v77 offset:53248
	ds_read_b128 v[148:151], v77 offset:55296
	ds_read_b128 v[152:155], v79 offset:49152
	ds_read_b128 v[156:159], v79 offset:51200
	ds_read_b128 v[160:163], v79 offset:53248
	ds_read_b128 v[164:167], v79 offset:55296
	s_waitcnt lgkmcnt(8)
	v_mfma_f32_16x16x32_bf16 v[0:3], v[84:87], v[100:103], v[0:3]
	v_mfma_f32_16x16x32_bf16 v[4:7], v[84:87], v[104:107], v[4:7]
	s_add_u32 m0, s30, 0x6000
	v_lshl_add_u64 v[126:127], v[70:71], 0, s[24:25]
	global_load_lds_dwordx4 v[126:127], off
	v_mfma_f32_16x16x32_bf16 v[8:11], v[84:87], v[108:111], v[8:11]
	v_mfma_f32_16x16x32_bf16 v[12:15], v[84:87], v[112:115], v[12:15]
	v_mfma_f32_16x16x32_bf16 v[16:19], v[88:91], v[100:103], v[16:19]
	v_mfma_f32_16x16x32_bf16 v[20:23], v[88:91], v[104:107], v[20:23]
	v_mfma_f32_16x16x32_bf16 v[24:27], v[88:91], v[108:111], v[24:27]
	s_add_u32 m0, s30, 0x8000
	v_lshl_add_u64 v[124:125], v[72:73], 0, s[24:25]
	global_load_lds_dwordx4 v[124:125], off
	v_mfma_f32_16x16x32_bf16 v[28:31], v[88:91], v[112:115], v[28:31]
	v_mfma_f32_16x16x32_bf16 v[32:35], v[92:95], v[100:103], v[32:35]
	v_mfma_f32_16x16x32_bf16 v[36:39], v[92:95], v[104:107], v[36:39]
	v_mfma_f32_16x16x32_bf16 v[40:43], v[92:95], v[108:111], v[40:43]
	v_mfma_f32_16x16x32_bf16 v[44:47], v[92:95], v[112:115], v[44:47]
	s_add_u32 m0, s30, 0xa000
	v_lshl_add_u64 v[126:127], v[74:75], 0, s[24:25]
	global_load_lds_dwordx4 v[126:127], off
	v_mfma_f32_16x16x32_bf16 v[48:51], v[96:99], v[100:103], v[48:51]
	v_mfma_f32_16x16x32_bf16 v[52:55], v[96:99], v[104:107], v[52:55]
	v_mfma_f32_16x16x32_bf16 v[56:59], v[96:99], v[108:111], v[56:59]
	v_mfma_f32_16x16x32_bf16 v[60:63], v[96:99], v[112:115], v[60:63]
	s_waitcnt vmcnt(6) lgkmcnt(0)
	s_barrier
;     ...
;   for (int kt = 0; kt < nk; ++kt) {
;     if (kt + 1 < nk) asm volatile("s_waitcnt vmcnt(6)" ::: "memory");
;     else asm volatile("s_waitcnt vmcnt(0)" ::: "memory");
;     __builtin_amdgcn_s_barrier();
;     asm volatile("" ::: "memory");
;     if (kt + 2 < nk) { const int st2 = (st >= 1) ? st - 1 : 2; GEMM_ISSUE(kt + 2, st2); }
;     const char* la = lds + st * STAGE_B;
;     const char* lb = la + 32768;
;     const unsigned sa_u = (unsigned)(size_t)la + arow_u, sb_u = (unsigned)(size_t)lb + brow_u;
;     const unsigned a0 = sa_u + co0, a1 = sa_u + co1, a2 = sa_u + co2, a3 = sa_u + co3;
;     const unsigned b0 = sb_u + co0, b1 = sb_u + co1, b2 = sb_u + co2, b3 = sb_u + co3;
;     {
;       bf16x8 p0, p1, q0, q1, u0, u1, w0, w1;
;       asm volatile(
;         "ds_read_b128 %4, %12\n\tds_read_b128 %5, %12 offset:4096\n\tds_read_b128 %6, %16\n\tds_read_b128 %7, %16 offset:4096\n\t"
;         "ds_read_b128 %8, %13\n\tds_read_b128 %9, %13 offset:4096\n\tds_read_b128 %10, %17\n\tds_read_b128 %11, %17 offset:4096\n\t"
;         "s_waitcnt lgkmcnt(4)\n\t"
;         "v_mfma_f32_32x32x16_bf16 %0, %4, %6, %0\n\tv_mfma_f32_32x32x16_bf16 %1, %4, %7, %1\n\tv_mfma_f32_32x32x16_bf16 %2, %5, %6, %2\n\tv_mfma_f32_32x32x16_bf16 %3, %5, %7, %3\n\t"
;         "ds_read_b128 %4, %14\n\tds_read_b128 %5, %14 offset:4096\n\tds_read_b128 %6, %18\n\tds_read_b128 %7, %18 offset:4096\n\t"
;         "s_waitcnt lgkmcnt(4)\n\t"
;         "v_mfma_f32_32x32x16_bf16 %0, %8, %10, %0\n\tv_mfma_f32_32x32x16_bf16 %1, %8, %11, %1\n\tv_mfma_f32_32x32x16_bf16 %2, %9, %10, %2\n\tv_mfma_f32_32x32x16_bf16 %3, %9, %11, %3\n\t"
;         "ds_read_b128 %8, %15\n\tds_read_b128 %9, %15 offset:4096\n\tds_read_b128 %10, %19\n\tds_read_b128 %11, %19 offset:4096\n\t"
;         "s_waitcnt lgkmcnt(4)\n\t"
;         "v_mfma_f32_32x32x16_bf16 %0, %4, %6, %0\n\tv_mfma_f32_32x32x16_bf16 %1, %4, %7, %1\n\tv_mfma_f32_32x32x16_bf16 %2, %5, %6, %2\n\tv_mfma_f32_32x32x16_bf16 %3, %5, %7, %3\n\t"
;         "s_waitcnt lgkmcnt(0)\n\t"
;         "v_mfma_f32_32x32x16_bf16 %0, %8, %10, %0\n\tv_mfma_f32_32x32x16_bf16 %1, %8, %11, %1\n\tv_mfma_f32_32x32x16_bf16 %2, %9, %10, %2\n\tv_mfma_f32_32x32x16_bf16 %3, %9, %11, %3"
;         : "+v"(acc[0][0]), "+v"(acc[0][1]), "+v"(acc[1][0]), "+v"(acc[1][1]),
;           "=&v"(p0), "=&v"(p1), "=&v"(q0), "=&v"(q1), "=&v"(u0), "=&v"(u1), "=&v"(w0), "=&v"(w1)
	ds_read_b128 v[84:87], v80
	ds_read_b128 v[88:91], v80 offset:2048
	ds_read_b128 v[92:95], v80 offset:4096
	ds_read_b128 v[96:99], v80 offset:6144
	ds_read_b128 v[100:103], v82
	ds_read_b128 v[104:107], v82 offset:2048
	ds_read_b128 v[108:111], v82 offset:4096
	ds_read_b128 v[112:115], v82 offset:6144
	v_mfma_f32_16x16x32_bf16 v[0:3], v[136:139], v[152:155], v[0:3]
	v_mfma_f32_16x16x32_bf16 v[4:7], v[136:139], v[156:159], v[4:7]
	s_mov_b32 s24, 0x380
	s_mov_b32 s25, 0
	s_add_u32 m0, s30, 0xc000
	v_lshl_add_u64 v[124:125], v[64:65], 0, s[24:25]
	global_load_lds_dwordx4 v[124:125], off
	v_mfma_f32_16x16x32_bf16 v[8:11], v[136:139], v[160:163], v[8:11]
	v_mfma_f32_16x16x32_bf16 v[12:15], v[136:139], v[164:167], v[12:15]
	v_mfma_f32_16x16x32_bf16 v[16:19], v[140:143], v[152:155], v[16:19]
	v_mfma_f32_16x16x32_bf16 v[20:23], v[140:143], v[156:159], v[20:23]
	v_mfma_f32_16x16x32_bf16 v[24:27], v[140:143], v[160:163], v[24:27]
	s_add_u32 m0, s30, 0xe000
	v_lshl_add_u64 v[126:127], v[66:67], 0, s[24:25]
	global_load_lds_dwordx4 v[126:127], off
	v_mfma_f32_16x16x32_bf16 v[28:31], v[140:143], v[164:167], v[28:31]
	v_mfma_f32_16x16x32_bf16 v[32:35], v[144:147], v[152:155], v[32:35]
	v_mfma_f32_16x16x32_bf16 v[36:39], v[144:147], v[156:159], v[36:39]
	v_mfma_f32_16x16x32_bf16 v[40:43], v[144:147], v[160:163], v[40:43]
	v_mfma_f32_16x16x32_bf16 v[44:47], v[144:147], v[164:167], v[44:47]
	s_add_u32 m0, s30, 0x10000
	v_lshl_add_u64 v[124:125], v[68:69], 0, s[24:25]
	global_load_lds_dwordx4 v[124:125], off
	v_mfma_f32_16x16x32_bf16 v[48:51], v[148:151], v[152:155], v[48:51]
	v_mfma_f32_16x16x32_bf16 v[52:55], v[148:151], v[156:159], v[52:55]
	v_mfma_f32_16x16x32_bf16 v[56:59], v[148:151], v[160:163], v[56:59]
	v_mfma_f32_16x16x32_bf16 v[60:63], v[148:151], v[164:167], v[60:63]
	ds_read_b128 v[136:139], v81
	ds_read_b128 v[140:143], v81 offset:2048
	ds_read_b128 v[144:147], v81 offset:4096
	ds_read_b128 v[148:151], v81 offset:6144
	ds_read_b128 v[152:155], v83
	ds_read_b128 v[156:159], v83 offset:2048
	ds_read_b128 v[160:163], v83 offset:4096
	ds_read_b128 v[164:167], v83 offset:6144
	s_waitcnt lgkmcnt(8)
	v_mfma_f32_16x16x32_bf16 v[0:3], v[84:87], v[100:103], v[0:3]
	v_mfma_f32_16x16x32_bf16 v[4:7], v[84:87], v[104:107], v[4:7]
	s_add_u32 m0, s30, 0x12000
	v_lshl_add_u64 v[126:127], v[70:71], 0, s[24:25]
	global_load_lds_dwordx4 v[126:127], off
	v_mfma_f32_16x16x32_bf16 v[8:11], v[84:87], v[108:111], v[8:11]
	v_mfma_f32_16x16x32_bf16 v[12:15], v[84:87], v[112:115], v[12:15]
	v_mfma_f32_16x16x32_bf16 v[16:19], v[88:91], v[100:103], v[16:19]
	v_mfma_f32_16x16x32_bf16 v[20:23], v[88:91], v[104:107], v[20:23]
	v_mfma_f32_16x16x32_bf16 v[24:27], v[88:91], v[108:111], v[24:27]
	s_add_u32 m0, s30, 0x14000
	v_lshl_add_u64 v[124:125], v[72:73], 0, s[24:25]
	global_load_lds_dwordx4 v[124:125], off
	v_mfma_f32_16x16x32_bf16 v[28:31], v[88:91], v[112:115], v[28:31]
	v_mfma_f32_16x16x32_bf16 v[32:35], v[92:95], v[100:103], v[32:35]
	v_mfma_f32_16x16x32_bf16 v[36:39], v[92:95], v[104:107], v[36:39]
	v_mfma_f32_16x16x32_bf16 v[40:43], v[92:95], v[108:111], v[40:43]
	v_mfma_f32_16x16x32_bf16 v[44:47], v[92:95], v[112:115], v[44:47]
	s_add_u32 m0, s30, 0x16000
	v_lshl_add_u64 v[126:127], v[74:75], 0, s[24:25]
	global_load_lds_dwordx4 v[126:127], off
	v_mfma_f32_16x16x32_bf16 v[48:51], v[96:99], v[100:103], v[48:51]
	v_mfma_f32_16x16x32_bf16 v[52:55], v[96:99], v[104:107], v[52:55]
	v_mfma_f32_16x16x32_bf16 v[56:59], v[96:99], v[108:111], v[56:59]
	v_mfma_f32_16x16x32_bf16 v[60:63], v[96:99], v[112:115], v[60:63]
	s_waitcnt vmcnt(6) lgkmcnt(0)
	s_barrier
	ds_read_b128 v[84:87], v76
	ds_read_b128 v[88:91], v76 offset:2048
	ds_read_b128 v[92:95], v76 offset:4096
	ds_read_b128 v[96:99], v76 offset:6144
	ds_read_b128 v[100:103], v78
	ds_read_b128 v[104:107], v78 offset:2048
	ds_read_b128 v[108:111], v78 offset:4096
	ds_read_b128 v[112:115], v78 offset:6144
	v_mfma_f32_16x16x32_bf16 v[0:3], v[136:139], v[152:155], v[0:3]
	v_mfma_f32_16x16x32_bf16 v[4:7], v[136:139], v[156:159], v[4:7]
	s_mov_b32 s24, 0x400
	s_mov_b32 s25, 0
	s_add_u32 m0, s30, 0x18000
	v_lshl_add_u64 v[124:125], v[64:65], 0, s[24:25]
	global_load_lds_dwordx4 v[124:125], off
	v_mfma_f32_16x16x32_bf16 v[8:11], v[136:139], v[160:163], v[8:11]
	v_mfma_f32_16x16x32_bf16 v[12:15], v[136:139], v[164:167], v[12:15]
	v_mfma_f32_16x16x32_bf16 v[16:19], v[140:143], v[152:155], v[16:19]
	v_mfma_f32_16x16x32_bf16 v[20:23], v[140:143], v[156:159], v[20:23]
	v_mfma_f32_16x16x32_bf16 v[24:27], v[140:143], v[160:163], v[24:27]
	s_add_u32 m0, s30, 0x1a000
	v_lshl_add_u64 v[126:127], v[66:67], 0, s[24:25]
	global_load_lds_dwordx4 v[126:127], off
	v_mfma_f32_16x16x32_bf16 v[28:31], v[140:143], v[164:167], v[28:31]
	v_mfma_f32_16x16x32_bf16 v[32:35], v[144:147], v[152:155], v[32:35]
	v_mfma_f32_16x16x32_bf16 v[36:39], v[144:147], v[156:159], v[36:39]
	v_mfma_f32_16x16x32_bf16 v[40:43], v[144:147], v[160:163], v[40:43]
	v_mfma_f32_16x16x32_bf16 v[44:47], v[144:147], v[164:167], v[44:47]
	s_add_u32 m0, s30, 0x1c000
	v_lshl_add_u64 v[124:125], v[68:69], 0, s[24:25]
	global_load_lds_dwordx4 v[124:125], off
	v_mfma_f32_16x16x32_bf16 v[48:51], v[148:151], v[152:155], v[48:51]
	v_mfma_f32_16x16x32_bf16 v[52:55], v[148:151], v[156:159], v[52:55]
	v_mfma_f32_16x16x32_bf16 v[56:59], v[148:151], v[160:163], v[56:59]
	v_mfma_f32_16x16x32_bf16 v[60:63], v[148:151], v[164:167], v[60:63]
	ds_read_b128 v[136:139], v77
	ds_read_b128 v[140:143], v77 offset:2048
	ds_read_b128 v[144:147], v77 offset:4096
	ds_read_b128 v[148:151], v77 offset:6144
	ds_read_b128 v[152:155], v79
	ds_read_b128 v[156:159], v79 offset:2048
	ds_read_b128 v[160:163], v79 offset:4096
	ds_read_b128 v[164:167], v79 offset:6144
	s_waitcnt lgkmcnt(8)
;     ...
;   for (int kt = 0; kt < nk; ++kt) {
;     if (kt + 1 < nk) asm volatile("s_waitcnt vmcnt(6)" ::: "memory");
;     else asm volatile("s_waitcnt vmcnt(0)" ::: "memory");
;     __builtin_amdgcn_s_barrier();
;     asm volatile("" ::: "memory");
;     if (kt + 2 < nk) { const int st2 = (st >= 1) ? st - 1 : 2; GEMM_ISSUE(kt + 2, st2); }
;     const char* la = lds + st * STAGE_B;
;     const char* lb = la + 32768;
;     const unsigned sa_u = (unsigned)(size_t)la + arow_u, sb_u = (unsigned)(size_t)lb + brow_u;
;     const unsigned a0 = sa_u + co0, a1 = sa_u + co1, a2 = sa_u + co2, a3 = sa_u + co3;
;     const unsigned b0 = sb_u + co0, b1 = sb_u + co1, b2 = sb_u + co2, b3 = sb_u + co3;
;     {
;       bf16x8 p0, p1, q0, q1, u0, u1, w0, w1;
;       asm volatile(
;         "ds_read_b128 %4, %12\n\tds_read_b128 %5, %12 offset:4096\n\tds_read_b128 %6, %16\n\tds_read_b128 %7, %16 offset:4096\n\t"
;         "ds_read_b128 %8, %13\n\tds_read_b128 %9, %13 offset:4096\n\tds_read_b128 %10, %17\n\tds_read_b128 %11, %17 offset:4096\n\t"
;         "s_waitcnt lgkmcnt(4)\n\t"
;         "v_mfma_f32_32x32x16_bf16 %0, %4, %6, %0\n\tv_mfma_f32_32x32x16_bf16 %1, %4, %7, %1\n\tv_mfma_f32_32x32x16_bf16 %2, %5, %6, %2\n\tv_mfma_f32_32x32x16_bf16 %3, %5, %7, %3\n\t"
;         "ds_read_b128 %4, %14\n\tds_read_b128 %5, %14 offset:4096\n\tds_read_b128 %6, %18\n\tds_read_b128 %7, %18 offset:4096\n\t"
;         "s_waitcnt lgkmcnt(4)\n\t"
;         "v_mfma_f32_32x32x16_bf16 %0, %8, %10, %0\n\tv_mfma_f32_32x32x16_bf16 %1, %8, %11, %1\n\tv_mfma_f32_32x32x16_bf16 %2, %9, %10, %2\n\tv_mfma_f32_32x32x16_bf16 %3, %9, %11, %3\n\t"
;         "ds_read_b128 %8, %15\n\tds_read_b128 %9, %15 offset:4096\n\tds_read_b128 %10, %19\n\tds_read_b128 %11, %19 offset:4096\n\t"
;         "s_waitcnt lgkmcnt(4)\n\t"
;         "v_mfma_f32_32x32x16_bf16 %0, %4, %6, %0\n\tv_mfma_f32_32x32x16_bf16 %1, %4, %7, %1\n\tv_mfma_f32_32x32x16_bf16 %2, %5, %6, %2\n\tv_mfma_f32_32x32x16_bf16 %3, %5, %7, %3\n\t"
;         "s_waitcnt lgkmcnt(0)\n\t"
;         "v_mfma_f32_32x32x16_bf16 %0, %8, %10, %0\n\tv_mfma_f32_32x32x16_bf16 %1, %8, %11, %1\n\tv_mfma_f32_32x32x16_bf16 %2, %9, %10, %2\n\tv_mfma_f32_32x32x16_bf16 %3, %9, %11, %3"
;         : "+v"(acc[0][0]), "+v"(acc[0][1]), "+v"(acc[1][0]), "+v"(acc[1][1]),
;           "=&v"(p0), "=&v"(p1), "=&v"(q0), "=&v"(q1), "=&v"(u0), "=&v"(u1), "=&v"(w0), "=&v"(w1)
	v_mfma_f32_16x16x32_bf16 v[0:3], v[84:87], v[100:103], v[0:3]
	v_mfma_f32_16x16x32_bf16 v[4:7], v[84:87], v[104:107], v[4:7]
	s_add_u32 m0, s30, 0x1e000
	v_lshl_add_u64 v[126:127], v[70:71], 0, s[24:25]
	global_load_lds_dwordx4 v[126:127], off
	v_mfma_f32_16x16x32_bf16 v[8:11], v[84:87], v[108:111], v[8:11]
	v_mfma_f32_16x16x32_bf16 v[12:15], v[84:87], v[112:115], v[12:15]
	v_mfma_f32_16x16x32_bf16 v[16:19], v[88:91], v[100:103], v[16:19]
	v_mfma_f32_16x16x32_bf16 v[20:23], v[88:91], v[104:107], v[20:23]
	v_mfma_f32_16x16x32_bf16 v[24:27], v[88:91], v[108:111], v[24:27]
	s_add_u32 m0, s30, 0x20000
	v_lshl_add_u64 v[124:125], v[72:73], 0, s[24:25]
	global_load_lds_dwordx4 v[124:125], off
	v_mfma_f32_16x16x32_bf16 v[28:31], v[88:91], v[112:115], v[28:31]
	v_mfma_f32_16x16x32_bf16 v[32:35], v[92:95], v[100:103], v[32:35]
	v_mfma_f32_16x16x32_bf16 v[36:39], v[92:95], v[104:107], v[36:39]
	v_mfma_f32_16x16x32_bf16 v[40:43], v[92:95], v[108:111], v[40:43]
	v_mfma_f32_16x16x32_bf16 v[44:47], v[92:95], v[112:115], v[44:47]
	s_add_u32 m0, s30, 0x22000
	v_lshl_add_u64 v[126:127], v[74:75], 0, s[24:25]
	global_load_lds_dwordx4 v[126:127], off
	v_mfma_f32_16x16x32_bf16 v[48:51], v[96:99], v[100:103], v[48:51]
	v_mfma_f32_16x16x32_bf16 v[52:55], v[96:99], v[104:107], v[52:55]
	v_mfma_f32_16x16x32_bf16 v[56:59], v[96:99], v[108:111], v[56:59]
	v_mfma_f32_16x16x32_bf16 v[60:63], v[96:99], v[112:115], v[60:63]
	s_waitcnt vmcnt(6) lgkmcnt(0)
	s_barrier
	ds_read_b128 v[84:87], v76 offset:49152
	ds_read_b128 v[88:91], v76 offset:51200
	ds_read_b128 v[92:95], v76 offset:53248
	ds_read_b128 v[96:99], v76 offset:55296
	ds_read_b128 v[100:103], v78 offset:49152
	ds_read_b128 v[104:107], v78 offset:51200
	ds_read_b128 v[108:111], v78 offset:53248
	ds_read_b128 v[112:115], v78 offset:55296
	v_mfma_f32_16x16x32_bf16 v[0:3], v[136:139], v[152:155], v[0:3]
	v_mfma_f32_16x16x32_bf16 v[4:7], v[136:139], v[156:159], v[4:7]
	s_mov_b32 s24, 0x480
	s_mov_b32 s25, 0
	s_mov_b32 m0, s30
	v_lshl_add_u64 v[124:125], v[64:65], 0, s[24:25]
	global_load_lds_dwordx4 v[124:125], off
	v_mfma_f32_16x16x32_bf16 v[8:11], v[136:139], v[160:163], v[8:11]
	v_mfma_f32_16x16x32_bf16 v[12:15], v[136:139], v[164:167], v[12:15]
	v_mfma_f32_16x16x32_bf16 v[16:19], v[140:143], v[152:155], v[16:19]
	v_mfma_f32_16x16x32_bf16 v[20:23], v[140:143], v[156:159], v[20:23]
	v_mfma_f32_16x16x32_bf16 v[24:27], v[140:143], v[160:163], v[24:27]
	s_add_u32 m0, s30, 0x2000
	v_lshl_add_u64 v[126:127], v[66:67], 0, s[24:25]
	global_load_lds_dwordx4 v[126:127], off
	v_mfma_f32_16x16x32_bf16 v[28:31], v[140:143], v[164:167], v[28:31]
	v_mfma_f32_16x16x32_bf16 v[32:35], v[144:147], v[152:155], v[32:35]
	v_mfma_f32_16x16x32_bf16 v[36:39], v[144:147], v[156:159], v[36:39]
	v_mfma_f32_16x16x32_bf16 v[40:43], v[144:147], v[160:163], v[40:43]
	v_mfma_f32_16x16x32_bf16 v[44:47], v[144:147], v[164:167], v[44:47]
	s_add_u32 m0, s30, 0x4000
	v_lshl_add_u64 v[124:125], v[68:69], 0, s[24:25]
	global_load_lds_dwordx4 v[124:125], off
	v_mfma_f32_16x16x32_bf16 v[48:51], v[148:151], v[152:155], v[48:51]
	v_mfma_f32_16x16x32_bf16 v[52:55], v[148:151], v[156:159], v[52:55]
	v_mfma_f32_16x16x32_bf16 v[56:59], v[148:151], v[160:163], v[56:59]
	v_mfma_f32_16x16x32_bf16 v[60:63], v[148:151], v[164:167], v[60:63]
	ds_read_b128 v[136:139], v77 offset:49152
	ds_read_b128 v[140:143], v77 offset:51200
	ds_read_b128 v[144:147], v77 offset:53248
	ds_read_b128 v[148:151], v77 offset:55296
	ds_read_b128 v[152:155], v79 offset:49152
	ds_read_b128 v[156:159], v79 offset:51200
	ds_read_b128 v[160:163], v79 offset:53248
	ds_read_b128 v[164:167], v79 offset:55296
	s_waitcnt lgkmcnt(8)
	v_mfma_f32_16x16x32_bf16 v[0:3], v[84:87], v[100:103], v[0:3]
	v_mfma_f32_16x16x32_bf16 v[4:7], v[84:87], v[104:107], v[4:7]
	s_add_u32 m0, s30, 0x6000
	v_lshl_add_u64 v[126:127], v[70:71], 0, s[24:25]
	global_load_lds_dwordx4 v[126:127], off
	v_mfma_f32_16x16x32_bf16 v[8:11], v[84:87], v[108:111], v[8:11]
	v_mfma_f32_16x16x32_bf16 v[12:15], v[84:87], v[112:115], v[12:15]
	v_mfma_f32_16x16x32_bf16 v[16:19], v[88:91], v[100:103], v[16:19]
	v_mfma_f32_16x16x32_bf16 v[20:23], v[88:91], v[104:107], v[20:23]
	v_mfma_f32_16x16x32_bf16 v[24:27], v[88:91], v[108:111], v[24:27]
	s_add_u32 m0, s30, 0x8000
	v_lshl_add_u64 v[124:125], v[72:73], 0, s[24:25]
	global_load_lds_dwordx4 v[124:125], off
	v_mfma_f32_16x16x32_bf16 v[28:31], v[88:91], v[112:115], v[28:31]
	v_mfma_f32_16x16x32_bf16 v[32:35], v[92:95], v[100:103], v[32:35]
	v_mfma_f32_16x16x32_bf16 v[36:39], v[92:95], v[104:107], v[36:39]
	v_mfma_f32_16x16x32_bf16 v[40:43], v[92:95], v[108:111], v[40:43]
	v_mfma_f32_16x16x32_bf16 v[44:47], v[92:95], v[112:115], v[44:47]
	s_add_u32 m0, s30, 0xa000
	v_lshl_add_u64 v[126:127], v[74:75], 0, s[24:25]
	global_load_lds_dwordx4 v[126:127], off
	v_mfma_f32_16x16x32_bf16 v[48:51], v[96:99], v[100:103], v[48:51]
	v_mfma_f32_16x16x32_bf16 v[52:55], v[96:99], v[104:107], v[52:55]
	v_mfma_f32_16x16x32_bf16 v[56:59], v[96:99], v[108:111], v[56:59]
	v_mfma_f32_16x16x32_bf16 v[60:63], v[96:99], v[112:115], v[60:63]
	s_waitcnt vmcnt(6) lgkmcnt(0)
	s_barrier
;     ...
;   for (int kt = 0; kt < nk; ++kt) {
;     if (kt + 1 < nk) asm volatile("s_waitcnt vmcnt(6)" ::: "memory");
;     else asm volatile("s_waitcnt vmcnt(0)" ::: "memory");
;     __builtin_amdgcn_s_barrier();
;     asm volatile("" ::: "memory");
;     if (kt + 2 < nk) { const int st2 = (st >= 1) ? st - 1 : 2; GEMM_ISSUE(kt + 2, st2); }
;     const char* la = lds + st * STAGE_B;
;     const char* lb = la + 32768;
;     const unsigned sa_u = (unsigned)(size_t)la + arow_u, sb_u = (unsigned)(size_t)lb + brow_u;
;     const unsigned a0 = sa_u + co0, a1 = sa_u + co1, a2 = sa_u + co2, a3 = sa_u + co3;
;     const unsigned b0 = sb_u + co0, b1 = sb_u + co1, b2 = sb_u + co2, b3 = sb_u + co3;
;     {
;       bf16x8 p0, p1, q0, q1, u0, u1, w0, w1;
;       asm volatile(
;         "ds_read_b128 %4, %12\n\tds_read_b128 %5, %12 offset:4096\n\tds_read_b128 %6, %16\n\tds_read_b128 %7, %16 offset:4096\n\t"
;         "ds_read_b128 %8, %13\n\tds_read_b128 %9, %13 offset:4096\n\tds_read_b128 %10, %17\n\tds_read_b128 %11, %17 offset:4096\n\t"
;         "s_waitcnt lgkmcnt(4)\n\t"
;         "v_mfma_f32_32x32x16_bf16 %0, %4, %6, %0\n\tv_mfma_f32_32x32x16_bf16 %1, %4, %7, %1\n\tv_mfma_f32_32x32x16_bf16 %2, %5, %6, %2\n\tv_mfma_f32_32x32x16_bf16 %3, %5, %7, %3\n\t"
;         "ds_read_b128 %4, %14\n\tds_read_b128 %5, %14 offset:4096\n\tds_read_b128 %6, %18\n\tds_read_b128 %7, %18 offset:4096\n\t"
;         "s_waitcnt lgkmcnt(4)\n\t"
;         "v_mfma_f32_32x32x16_bf16 %0, %8, %10, %0\n\tv_mfma_f32_32x32x16_bf16 %1, %8, %11, %1\n\tv_mfma_f32_32x32x16_bf16 %2, %9, %10, %2\n\tv_mfma_f32_32x32x16_bf16 %3, %9, %11, %3\n\t"
;         "ds_read_b128 %8, %15\n\tds_read_b128 %9, %15 offset:4096\n\tds_read_b128 %10, %19\n\tds_read_b128 %11, %19 offset:4096\n\t"
;         "s_waitcnt lgkmcnt(4)\n\t"
;         "v_mfma_f32_32x32x16_bf16 %0, %4, %6, %0\n\tv_mfma_f32_32x32x16_bf16 %1, %4, %7, %1\n\tv_mfma_f32_32x32x16_bf16 %2, %5, %6, %2\n\tv_mfma_f32_32x32x16_bf16 %3, %5, %7, %3\n\t"
;         "s_waitcnt lgkmcnt(0)\n\t"
;         "v_mfma_f32_32x32x16_bf16 %0, %8, %10, %0\n\tv_mfma_f32_32x32x16_bf16 %1, %8, %11, %1\n\tv_mfma_f32_32x32x16_bf16 %2, %9, %10, %2\n\tv_mfma_f32_32x32x16_bf16 %3, %9, %11, %3"
;         : "+v"(acc[0][0]), "+v"(acc[0][1]), "+v"(acc[1][0]), "+v"(acc[1][1]),
;           "=&v"(p0), "=&v"(p1), "=&v"(q0), "=&v"(q1), "=&v"(u0), "=&v"(u1), "=&v"(w0), "=&v"(w1)
	ds_read_b128 v[84:87], v80
	ds_read_b128 v[88:91], v80 offset:2048
	ds_read_b128 v[92:95], v80 offset:4096
	ds_read_b128 v[96:99], v80 offset:6144
	ds_read_b128 v[100:103], v82
	ds_read_b128 v[104:107], v82 offset:2048
	ds_read_b128 v[108:111], v82 offset:4096
	ds_read_b128 v[112:115], v82 offset:6144
	v_mfma_f32_16x16x32_bf16 v[0:3], v[136:139], v[152:155], v[0:3]
	v_mfma_f32_16x16x32_bf16 v[4:7], v[136:139], v[156:159], v[4:7]
	s_mov_b32 s24, 0x500
	s_mov_b32 s25, 0
	s_add_u32 m0, s30, 0xc000
	v_lshl_add_u64 v[124:125], v[64:65], 0, s[24:25]
	global_load_lds_dwordx4 v[124:125], off
	v_mfma_f32_16x16x32_bf16 v[8:11], v[136:139], v[160:163], v[8:11]
	v_mfma_f32_16x16x32_bf16 v[12:15], v[136:139], v[164:167], v[12:15]
	v_mfma_f32_16x16x32_bf16 v[16:19], v[140:143], v[152:155], v[16:19]
	v_mfma_f32_16x16x32_bf16 v[20:23], v[140:143], v[156:159], v[20:23]
	v_mfma_f32_16x16x32_bf16 v[24:27], v[140:143], v[160:163], v[24:27]
	s_add_u32 m0, s30, 0xe000
	v_lshl_add_u64 v[126:127], v[66:67], 0, s[24:25]
	global_load_lds_dwordx4 v[126:127], off
	v_mfma_f32_16x16x32_bf16 v[28:31], v[140:143], v[164:167], v[28:31]
	v_mfma_f32_16x16x32_bf16 v[32:35], v[144:147], v[152:155], v[32:35]
	v_mfma_f32_16x16x32_bf16 v[36:39], v[144:147], v[156:159], v[36:39]
	v_mfma_f32_16x16x32_bf16 v[40:43], v[144:147], v[160:163], v[40:43]
	v_mfma_f32_16x16x32_bf16 v[44:47], v[144:147], v[164:167], v[44:47]
	s_add_u32 m0, s30, 0x10000
	v_lshl_add_u64 v[124:125], v[68:69], 0, s[24:25]
	global_load_lds_dwordx4 v[124:125], off
	v_mfma_f32_16x16x32_bf16 v[48:51], v[148:151], v[152:155], v[48:51]
	v_mfma_f32_16x16x32_bf16 v[52:55], v[148:151], v[156:159], v[52:55]
	v_mfma_f32_16x16x32_bf16 v[56:59], v[148:151], v[160:163], v[56:59]
	v_mfma_f32_16x16x32_bf16 v[60:63], v[148:151], v[164:167], v[60:63]
	ds_read_b128 v[136:139], v81
	ds_read_b128 v[140:143], v81 offset:2048
	ds_read_b128 v[144:147], v81 offset:4096
	ds_read_b128 v[148:151], v81 offset:6144
	ds_read_b128 v[152:155], v83
	ds_read_b128 v[156:159], v83 offset:2048
	ds_read_b128 v[160:163], v83 offset:4096
	ds_read_b128 v[164:167], v83 offset:6144
	s_waitcnt lgkmcnt(8)
	v_mfma_f32_16x16x32_bf16 v[0:3], v[84:87], v[100:103], v[0:3]
	v_mfma_f32_16x16x32_bf16 v[4:7], v[84:87], v[104:107], v[4:7]
	s_add_u32 m0, s30, 0x12000
	v_lshl_add_u64 v[126:127], v[70:71], 0, s[24:25]
	global_load_lds_dwordx4 v[126:127], off
	v_mfma_f32_16x16x32_bf16 v[8:11], v[84:87], v[108:111], v[8:11]
	v_mfma_f32_16x16x32_bf16 v[12:15], v[84:87], v[112:115], v[12:15]
	v_mfma_f32_16x16x32_bf16 v[16:19], v[88:91], v[100:103], v[16:19]
	v_mfma_f32_16x16x32_bf16 v[20:23], v[88:91], v[104:107], v[20:23]
	v_mfma_f32_16x16x32_bf16 v[24:27], v[88:91], v[108:111], v[24:27]
	s_add_u32 m0, s30, 0x14000
	v_lshl_add_u64 v[124:125], v[72:73], 0, s[24:25]
	global_load_lds_dwordx4 v[124:125], off
	v_mfma_f32_16x16x32_bf16 v[28:31], v[88:91], v[112:115], v[28:31]
	v_mfma_f32_16x16x32_bf16 v[32:35], v[92:95], v[100:103], v[32:35]
	v_mfma_f32_16x16x32_bf16 v[36:39], v[92:95], v[104:107], v[36:39]
	v_mfma_f32_16x16x32_bf16 v[40:43], v[92:95], v[108:111], v[40:43]
	v_mfma_f32_16x16x32_bf16 v[44:47], v[92:95], v[112:115], v[44:47]
	s_add_u32 m0, s30, 0x16000
	v_lshl_add_u64 v[126:127], v[74:75], 0, s[24:25]
	global_load_lds_dwordx4 v[126:127], off
	v_mfma_f32_16x16x32_bf16 v[48:51], v[96:99], v[100:103], v[48:51]
	v_mfma_f32_16x16x32_bf16 v[52:55], v[96:99], v[104:107], v[52:55]
	v_mfma_f32_16x16x32_bf16 v[56:59], v[96:99], v[108:111], v[56:59]
	v_mfma_f32_16x16x32_bf16 v[60:63], v[96:99], v[112:115], v[60:63]
	s_waitcnt vmcnt(6) lgkmcnt(0)
	s_barrier
	ds_read_b128 v[84:87], v76
	ds_read_b128 v[88:91], v76 offset:2048
	ds_read_b128 v[92:95], v76 offset:4096
	ds_read_b128 v[96:99], v76 offset:6144
	ds_read_b128 v[100:103], v78
	ds_read_b128 v[104:107], v78 offset:2048
	ds_read_b128 v[108:111], v78 offset:4096
	ds_read_b128 v[112:115], v78 offset:6144
	v_mfma_f32_16x16x32_bf16 v[0:3], v[136:139], v[152:155], v[0:3]
	v_mfma_f32_16x16x32_bf16 v[4:7], v[136:139], v[156:159], v[4:7]
	s_mov_b32 s24, 0x580
	s_mov_b32 s25, 0
	s_add_u32 m0, s30, 0x18000
	v_lshl_add_u64 v[124:125], v[64:65], 0, s[24:25]
	global_load_lds_dwordx4 v[124:125], off
	v_mfma_f32_16x16x32_bf16 v[8:11], v[136:139], v[160:163], v[8:11]
	v_mfma_f32_16x16x32_bf16 v[12:15], v[136:139], v[164:167], v[12:15]
	v_mfma_f32_16x16x32_bf16 v[16:19], v[140:143], v[152:155], v[16:19]
	v_mfma_f32_16x16x32_bf16 v[20:23], v[140:143], v[156:159], v[20:23]
	v_mfma_f32_16x16x32_bf16 v[24:27], v[140:143], v[160:163], v[24:27]
	s_add_u32 m0, s30, 0x1a000
	v_lshl_add_u64 v[126:127], v[66:67], 0, s[24:25]
	global_load_lds_dwordx4 v[126:127], off
	v_mfma_f32_16x16x32_bf16 v[28:31], v[140:143], v[164:167], v[28:31]
	v_mfma_f32_16x16x32_bf16 v[32:35], v[144:147], v[152:155], v[32:35]
	v_mfma_f32_16x16x32_bf16 v[36:39], v[144:147], v[156:159], v[36:39]
	v_mfma_f32_16x16x32_bf16 v[40:43], v[144:147], v[160:163], v[40:43]
	v_mfma_f32_16x16x32_bf16 v[44:47], v[144:147], v[164:167], v[44:47]
	s_add_u32 m0, s30, 0x1c000
	v_lshl_add_u64 v[124:125], v[68:69], 0, s[24:25]
	global_load_lds_dwordx4 v[124:125], off
	v_mfma_f32_16x16x32_bf16 v[48:51], v[148:151], v[152:155], v[48:51]
	v_mfma_f32_16x16x32_bf16 v[52:55], v[148:151], v[156:159], v[52:55]
	v_mfma_f32_16x16x32_bf16 v[56:59], v[148:151], v[160:163], v[56:59]
	v_mfma_f32_16x16x32_bf16 v[60:63], v[148:151], v[164:167], v[60:63]
	ds_read_b128 v[136:139], v77
	ds_read_b128 v[140:143], v77 offset:2048
	ds_read_b128 v[144:147], v77 offset:4096
	ds_read_b128 v[148:151], v77 offset:6144
	ds_read_b128 v[152:155], v79
	ds_read_b128 v[156:159], v79 offset:2048
	ds_read_b128 v[160:163], v79 offset:4096
	ds_read_b128 v[164:167], v79 offset:6144
	s_waitcnt lgkmcnt(8)
;     ...
;   for (int kt = 0; kt < nk; ++kt) {
;     if (kt + 1 < nk) asm volatile("s_waitcnt vmcnt(6)" ::: "memory");
;     else asm volatile("s_waitcnt vmcnt(0)" ::: "memory");
;     __builtin_amdgcn_s_barrier();
;     asm volatile("" ::: "memory");
;     if (kt + 2 < nk) { const int st2 = (st >= 1) ? st - 1 : 2; GEMM_ISSUE(kt + 2, st2); }
;     const char* la = lds + st * STAGE_B;
;     const char* lb = la + 32768;
;     const unsigned sa_u = (unsigned)(size_t)la + arow_u, sb_u = (unsigned)(size_t)lb + brow_u;
;     const unsigned a0 = sa_u + co0, a1 = sa_u + co1, a2 = sa_u + co2, a3 = sa_u + co3;
;     const unsigned b0 = sb_u + co0, b1 = sb_u + co1, b2 = sb_u + co2, b3 = sb_u + co3;
;     {
;       bf16x8 p0, p1, q0, q1, u0, u1, w0, w1;
;       asm volatile(
;         "ds_read_b128 %4, %12\n\tds_read_b128 %5, %12 offset:4096\n\tds_read_b128 %6, %16\n\tds_read_b128 %7, %16 offset:4096\n\t"
;         "ds_read_b128 %8, %13\n\tds_read_b128 %9, %13 offset:4096\n\tds_read_b128 %10, %17\n\tds_read_b128 %11, %17 offset:4096\n\t"
;         "s_waitcnt lgkmcnt(4)\n\t"
;         "v_mfma_f32_32x32x16_bf16 %0, %4, %6, %0\n\tv_mfma_f32_32x32x16_bf16 %1, %4, %7, %1\n\tv_mfma_f32_32x32x16_bf16 %2, %5, %6, %2\n\tv_mfma_f32_32x32x16_bf16 %3, %5, %7, %3\n\t"
;         "ds_read_b128 %4, %14\n\tds_read_b128 %5, %14 offset:4096\n\tds_read_b128 %6, %18\n\tds_read_b128 %7, %18 offset:4096\n\t"
;         "s_waitcnt lgkmcnt(4)\n\t"
;         "v_mfma_f32_32x32x16_bf16 %0, %8, %10, %0\n\tv_mfma_f32_32x32x16_bf16 %1, %8, %11, %1\n\tv_mfma_f32_32x32x16_bf16 %2, %9, %10, %2\n\tv_mfma_f32_32x32x16_bf16 %3, %9, %11, %3\n\t"
;         "ds_read_b128 %8, %15\n\tds_read_b128 %9, %15 offset:4096\n\tds_read_b128 %10, %19\n\tds_read_b128 %11, %19 offset:4096\n\t"
;         "s_waitcnt lgkmcnt(4)\n\t"
;         "v_mfma_f32_32x32x16_bf16 %0, %4, %6, %0\n\tv_mfma_f32_32x32x16_bf16 %1, %4, %7, %1\n\tv_mfma_f32_32x32x16_bf16 %2, %5, %6, %2\n\tv_mfma_f32_32x32x16_bf16 %3, %5, %7, %3\n\t"
;         "s_waitcnt lgkmcnt(0)\n\t"
;         "v_mfma_f32_32x32x16_bf16 %0, %8, %10, %0\n\tv_mfma_f32_32x32x16_bf16 %1, %8, %11, %1\n\tv_mfma_f32_32x32x16_bf16 %2, %9, %10, %2\n\tv_mfma_f32_32x32x16_bf16 %3, %9, %11, %3"
;         : "+v"(acc[0][0]), "+v"(acc[0][1]), "+v"(acc[1][0]), "+v"(acc[1][1]),
;           "=&v"(p0), "=&v"(p1), "=&v"(q0), "=&v"(q1), "=&v"(u0), "=&v"(u1), "=&v"(w0), "=&v"(w1)
	v_mfma_f32_16x16x32_bf16 v[0:3], v[84:87], v[100:103], v[0:3]
	v_mfma_f32_16x16x32_bf16 v[4:7], v[84:87], v[104:107], v[4:7]
	s_add_u32 m0, s30, 0x1e000
	v_lshl_add_u64 v[126:127], v[70:71], 0, s[24:25]
	global_load_lds_dwordx4 v[126:127], off
	v_mfma_f32_16x16x32_bf16 v[8:11], v[84:87], v[108:111], v[8:11]
	v_mfma_f32_16x16x32_bf16 v[12:15], v[84:87], v[112:115], v[12:15]
	v_mfma_f32_16x16x32_bf16 v[16:19], v[88:91], v[100:103], v[16:19]
	v_mfma_f32_16x16x32_bf16 v[20:23], v[88:91], v[104:107], v[20:23]
	v_mfma_f32_16x16x32_bf16 v[24:27], v[88:91], v[108:111], v[24:27]
	s_add_u32 m0, s30, 0x20000
	v_lshl_add_u64 v[124:125], v[72:73], 0, s[24:25]
	global_load_lds_dwordx4 v[124:125], off
	v_mfma_f32_16x16x32_bf16 v[28:31], v[88:91], v[112:115], v[28:31]
	v_mfma_f32_16x16x32_bf16 v[32:35], v[92:95], v[100:103], v[32:35]
	v_mfma_f32_16x16x32_bf16 v[36:39], v[92:95], v[104:107], v[36:39]
	v_mfma_f32_16x16x32_bf16 v[40:43], v[92:95], v[108:111], v[40:43]
	v_mfma_f32_16x16x32_bf16 v[44:47], v[92:95], v[112:115], v[44:47]
	s_add_u32 m0, s30, 0x22000
	v_lshl_add_u64 v[126:127], v[74:75], 0, s[24:25]
	global_load_lds_dwordx4 v[126:127], off
	v_mfma_f32_16x16x32_bf16 v[48:51], v[96:99], v[100:103], v[48:51]
	v_mfma_f32_16x16x32_bf16 v[52:55], v[96:99], v[104:107], v[52:55]
	v_mfma_f32_16x16x32_bf16 v[56:59], v[96:99], v[108:111], v[56:59]
	v_mfma_f32_16x16x32_bf16 v[60:63], v[96:99], v[112:115], v[60:63]
	s_waitcnt vmcnt(6) lgkmcnt(0)
	s_barrier
	ds_read_b128 v[84:87], v76 offset:49152
	ds_read_b128 v[88:91], v76 offset:51200
	ds_read_b128 v[92:95], v76 offset:53248
	ds_read_b128 v[96:99], v76 offset:55296
	ds_read_b128 v[100:103], v78 offset:49152
	ds_read_b128 v[104:107], v78 offset:51200
	ds_read_b128 v[108:111], v78 offset:53248
	ds_read_b128 v[112:115], v78 offset:55296
	v_mfma_f32_16x16x32_bf16 v[0:3], v[136:139], v[152:155], v[0:3]
	v_mfma_f32_16x16x32_bf16 v[4:7], v[136:139], v[156:159], v[4:7]
	s_mov_b32 s24, 0x600
	s_mov_b32 s25, 0
	s_mov_b32 m0, s30
	v_lshl_add_u64 v[124:125], v[64:65], 0, s[24:25]
	global_load_lds_dwordx4 v[124:125], off
	v_mfma_f32_16x16x32_bf16 v[8:11], v[136:139], v[160:163], v[8:11]
	v_mfma_f32_16x16x32_bf16 v[12:15], v[136:139], v[164:167], v[12:15]
	v_mfma_f32_16x16x32_bf16 v[16:19], v[140:143], v[152:155], v[16:19]
	v_mfma_f32_16x16x32_bf16 v[20:23], v[140:143], v[156:159], v[20:23]
	v_mfma_f32_16x16x32_bf16 v[24:27], v[140:143], v[160:163], v[24:27]
	s_add_u32 m0, s30, 0x2000
	v_lshl_add_u64 v[126:127], v[66:67], 0, s[24:25]
	global_load_lds_dwordx4 v[126:127], off
	v_mfma_f32_16x16x32_bf16 v[28:31], v[140:143], v[164:167], v[28:31]
	v_mfma_f32_16x16x32_bf16 v[32:35], v[144:147], v[152:155], v[32:35]
	v_mfma_f32_16x16x32_bf16 v[36:39], v[144:147], v[156:159], v[36:39]
	v_mfma_f32_16x16x32_bf16 v[40:43], v[144:147], v[160:163], v[40:43]
	v_mfma_f32_16x16x32_bf16 v[44:47], v[144:147], v[164:167], v[44:47]
	s_add_u32 m0, s30, 0x4000
	v_lshl_add_u64 v[124:125], v[68:69], 0, s[24:25]
	global_load_lds_dwordx4 v[124:125], off
	v_mfma_f32_16x16x32_bf16 v[48:51], v[148:151], v[152:155], v[48:51]
	v_mfma_f32_16x16x32_bf16 v[52:55], v[148:151], v[156:159], v[52:55]
	v_mfma_f32_16x16x32_bf16 v[56:59], v[148:151], v[160:163], v[56:59]
	v_mfma_f32_16x16x32_bf16 v[60:63], v[148:151], v[164:167], v[60:63]
	ds_read_b128 v[136:139], v77 offset:49152
	ds_read_b128 v[140:143], v77 offset:51200
	ds_read_b128 v[144:147], v77 offset:53248
	ds_read_b128 v[148:151], v77 offset:55296
	ds_read_b128 v[152:155], v79 offset:49152
	ds_read_b128 v[156:159], v79 offset:51200
	ds_read_b128 v[160:163], v79 offset:53248
	ds_read_b128 v[164:167], v79 offset:55296
	s_waitcnt lgkmcnt(8)
	v_mfma_f32_16x16x32_bf16 v[0:3], v[84:87], v[100:103], v[0:3]
	v_mfma_f32_16x16x32_bf16 v[4:7], v[84:87], v[104:107], v[4:7]
	s_add_u32 m0, s30, 0x6000
	v_lshl_add_u64 v[126:127], v[70:71], 0, s[24:25]
	global_load_lds_dwordx4 v[126:127], off
	v_mfma_f32_16x16x32_bf16 v[8:11], v[84:87], v[108:111], v[8:11]
	v_mfma_f32_16x16x32_bf16 v[12:15], v[84:87], v[112:115], v[12:15]
	v_mfma_f32_16x16x32_bf16 v[16:19], v[88:91], v[100:103], v[16:19]
	v_mfma_f32_16x16x32_bf16 v[20:23], v[88:91], v[104:107], v[20:23]
	v_mfma_f32_16x16x32_bf16 v[24:27], v[88:91], v[108:111], v[24:27]
	s_add_u32 m0, s30, 0x8000
	v_lshl_add_u64 v[124:125], v[72:73], 0, s[24:25]
	global_load_lds_dwordx4 v[124:125], off
	v_mfma_f32_16x16x32_bf16 v[28:31], v[88:91], v[112:115], v[28:31]
	v_mfma_f32_16x16x32_bf16 v[32:35], v[92:95], v[100:103], v[32:35]
	v_mfma_f32_16x16x32_bf16 v[36:39], v[92:95], v[104:107], v[36:39]
	v_mfma_f32_16x16x32_bf16 v[40:43], v[92:95], v[108:111], v[40:43]
	v_mfma_f32_16x16x32_bf16 v[44:47], v[92:95], v[112:115], v[44:47]
	s_add_u32 m0, s30, 0xa000
	v_lshl_add_u64 v[126:127], v[74:75], 0, s[24:25]
	global_load_lds_dwordx4 v[126:127], off
	v_mfma_f32_16x16x32_bf16 v[48:51], v[96:99], v[100:103], v[48:51]
	v_mfma_f32_16x16x32_bf16 v[52:55], v[96:99], v[104:107], v[52:55]
	v_mfma_f32_16x16x32_bf16 v[56:59], v[96:99], v[108:111], v[56:59]
	v_mfma_f32_16x16x32_bf16 v[60:63], v[96:99], v[112:115], v[60:63]
	s_waitcnt vmcnt(6) lgkmcnt(0)
	s_barrier
;     ...
;   for (int kt = 0; kt < nk; ++kt) {
;     if (kt + 1 < nk) asm volatile("s_waitcnt vmcnt(6)" ::: "memory");
;     else asm volatile("s_waitcnt vmcnt(0)" ::: "memory");
;     __builtin_amdgcn_s_barrier();
;     asm volatile("" ::: "memory");
;     if (kt + 2 < nk) { const int st2 = (st >= 1) ? st - 1 : 2; GEMM_ISSUE(kt + 2, st2); }
;     const char* la = lds + st * STAGE_B;
;     const char* lb = la + 32768;
;     const unsigned sa_u = (unsigned)(size_t)la + arow_u, sb_u = (unsigned)(size_t)lb + brow_u;
;     const unsigned a0 = sa_u + co0, a1 = sa_u + co1, a2 = sa_u + co2, a3 = sa_u + co3;
;     const unsigned b0 = sb_u + co0, b1 = sb_u + co1, b2 = sb_u + co2, b3 = sb_u + co3;
;     {
;       bf16x8 p0, p1, q0, q1, u0, u1, w0, w1;
;       asm volatile(
;         "ds_read_b128 %4, %12\n\tds_read_b128 %5, %12 offset:4096\n\tds_read_b128 %6, %16\n\tds_read_b128 %7, %16 offset:4096\n\t"
;         "ds_read_b128 %8, %13\n\tds_read_b128 %9, %13 offset:4096\n\tds_read_b128 %10, %17\n\tds_read_b128 %11, %17 offset:4096\n\t"
;         "s_waitcnt lgkmcnt(4)\n\t"
;         "v_mfma_f32_32x32x16_bf16 %0, %4, %6, %0\n\tv_mfma_f32_32x32x16_bf16 %1, %4, %7, %1\n\tv_mfma_f32_32x32x16_bf16 %2, %5, %6, %2\n\tv_mfma_f32_32x32x16_bf16 %3, %5, %7, %3\n\t"
;         "ds_read_b128 %4, %14\n\tds_read_b128 %5, %14 offset:4096\n\tds_read_b128 %6, %18\n\tds_read_b128 %7, %18 offset:4096\n\t"
;         "s_waitcnt lgkmcnt(4)\n\t"
;         "v_mfma_f32_32x32x16_bf16 %0, %8, %10, %0\n\tv_mfma_f32_32x32x16_bf16 %1, %8, %11, %1\n\tv_mfma_f32_32x32x16_bf16 %2, %9, %10, %2\n\tv_mfma_f32_32x32x16_bf16 %3, %9, %11, %3\n\t"
;         "ds_read_b128 %8, %15\n\tds_read_b128 %9, %15 offset:4096\n\tds_read_b128 %10, %19\n\tds_read_b128 %11, %19 offset:4096\n\t"
;         "s_waitcnt lgkmcnt(4)\n\t"
;         "v_mfma_f32_32x32x16_bf16 %0, %4, %6, %0\n\tv_mfma_f32_32x32x16_bf16 %1, %4, %7, %1\n\tv_mfma_f32_32x32x16_bf16 %2, %5, %6, %2\n\tv_mfma_f32_32x32x16_bf16 %3, %5, %7, %3\n\t"
;         "s_waitcnt lgkmcnt(0)\n\t"
;         "v_mfma_f32_32x32x16_bf16 %0, %8, %10, %0\n\tv_mfma_f32_32x32x16_bf16 %1, %8, %11, %1\n\tv_mfma_f32_32x32x16_bf16 %2, %9, %10, %2\n\tv_mfma_f32_32x32x16_bf16 %3, %9, %11, %3"
;         : "+v"(acc[0][0]), "+v"(acc[0][1]), "+v"(acc[1][0]), "+v"(acc[1][1]),
;           "=&v"(p0), "=&v"(p1), "=&v"(q0), "=&v"(q1), "=&v"(u0), "=&v"(u1), "=&v"(w0), "=&v"(w1)
	ds_read_b128 v[84:87], v80
	ds_read_b128 v[88:91], v80 offset:2048
	ds_read_b128 v[92:95], v80 offset:4096
	ds_read_b128 v[96:99], v80 offset:6144
	ds_read_b128 v[100:103], v82
	ds_read_b128 v[104:107], v82 offset:2048
	ds_read_b128 v[108:111], v82 offset:4096
	ds_read_b128 v[112:115], v82 offset:6144
	v_mfma_f32_16x16x32_bf16 v[0:3], v[136:139], v[152:155], v[0:3]
	v_mfma_f32_16x16x32_bf16 v[4:7], v[136:139], v[156:159], v[4:7]
	s_mov_b32 s24, 0x680
	s_mov_b32 s25, 0
	s_add_u32 m0, s30, 0xc000
	v_lshl_add_u64 v[124:125], v[64:65], 0, s[24:25]
	global_load_lds_dwordx4 v[124:125], off
	v_mfma_f32_16x16x32_bf16 v[8:11], v[136:139], v[160:163], v[8:11]
	v_mfma_f32_16x16x32_bf16 v[12:15], v[136:139], v[164:167], v[12:15]
	v_mfma_f32_16x16x32_bf16 v[16:19], v[140:143], v[152:155], v[16:19]
	v_mfma_f32_16x16x32_bf16 v[20:23], v[140:143], v[156:159], v[20:23]
	v_mfma_f32_16x16x32_bf16 v[24:27], v[140:143], v[160:163], v[24:27]
	s_add_u32 m0, s30, 0xe000
	v_lshl_add_u64 v[126:127], v[66:67], 0, s[24:25]
	global_load_lds_dwordx4 v[126:127], off
	v_mfma_f32_16x16x32_bf16 v[28:31], v[140:143], v[164:167], v[28:31]
	v_mfma_f32_16x16x32_bf16 v[32:35], v[144:147], v[152:155], v[32:35]
	v_mfma_f32_16x16x32_bf16 v[36:39], v[144:147], v[156:159], v[36:39]
	v_mfma_f32_16x16x32_bf16 v[40:43], v[144:147], v[160:163], v[40:43]
	v_mfma_f32_16x16x32_bf16 v[44:47], v[144:147], v[164:167], v[44:47]
	s_add_u32 m0, s30, 0x10000
	v_lshl_add_u64 v[124:125], v[68:69], 0, s[24:25]
	global_load_lds_dwordx4 v[124:125], off
	v_mfma_f32_16x16x32_bf16 v[48:51], v[148:151], v[152:155], v[48:51]
	v_mfma_f32_16x16x32_bf16 v[52:55], v[148:151], v[156:159], v[52:55]
	v_mfma_f32_16x16x32_bf16 v[56:59], v[148:151], v[160:163], v[56:59]
	v_mfma_f32_16x16x32_bf16 v[60:63], v[148:151], v[164:167], v[60:63]
	ds_read_b128 v[136:139], v81
	ds_read_b128 v[140:143], v81 offset:2048
	ds_read_b128 v[144:147], v81 offset:4096
	ds_read_b128 v[148:151], v81 offset:6144
	ds_read_b128 v[152:155], v83
	ds_read_b128 v[156:159], v83 offset:2048
	ds_read_b128 v[160:163], v83 offset:4096
	ds_read_b128 v[164:167], v83 offset:6144
	s_waitcnt lgkmcnt(8)
	v_mfma_f32_16x16x32_bf16 v[0:3], v[84:87], v[100:103], v[0:3]
	v_mfma_f32_16x16x32_bf16 v[4:7], v[84:87], v[104:107], v[4:7]
	s_add_u32 m0, s30, 0x12000
	v_lshl_add_u64 v[126:127], v[70:71], 0, s[24:25]
	global_load_lds_dwordx4 v[126:127], off
	v_mfma_f32_16x16x32_bf16 v[8:11], v[84:87], v[108:111], v[8:11]
	v_mfma_f32_16x16x32_bf16 v[12:15], v[84:87], v[112:115], v[12:15]
	v_mfma_f32_16x16x32_bf16 v[16:19], v[88:91], v[100:103], v[16:19]
	v_mfma_f32_16x16x32_bf16 v[20:23], v[88:91], v[104:107], v[20:23]
	v_mfma_f32_16x16x32_bf16 v[24:27], v[88:91], v[108:111], v[24:27]
	s_add_u32 m0, s30, 0x14000
	v_lshl_add_u64 v[124:125], v[72:73], 0, s[24:25]
	global_load_lds_dwordx4 v[124:125], off
	v_mfma_f32_16x16x32_bf16 v[28:31], v[88:91], v[112:115], v[28:31]
	v_mfma_f32_16x16x32_bf16 v[32:35], v[92:95], v[100:103], v[32:35]
	v_mfma_f32_16x16x32_bf16 v[36:39], v[92:95], v[104:107], v[36:39]
	v_mfma_f32_16x16x32_bf16 v[40:43], v[92:95], v[108:111], v[40:43]
	v_mfma_f32_16x16x32_bf16 v[44:47], v[92:95], v[112:115], v[44:47]
	s_add_u32 m0, s30, 0x16000
	v_lshl_add_u64 v[126:127], v[74:75], 0, s[24:25]
	global_load_lds_dwordx4 v[126:127], off
	v_mfma_f32_16x16x32_bf16 v[48:51], v[96:99], v[100:103], v[48:51]
	v_mfma_f32_16x16x32_bf16 v[52:55], v[96:99], v[104:107], v[52:55]
	v_mfma_f32_16x16x32_bf16 v[56:59], v[96:99], v[108:111], v[56:59]
	v_mfma_f32_16x16x32_bf16 v[60:63], v[96:99], v[112:115], v[60:63]
	s_waitcnt vmcnt(6) lgkmcnt(0)
	s_barrier
	ds_read_b128 v[84:87], v76
	ds_read_b128 v[88:91], v76 offset:2048
	ds_read_b128 v[92:95], v76 offset:4096
	ds_read_b128 v[96:99], v76 offset:6144
	ds_read_b128 v[100:103], v78
	ds_read_b128 v[104:107], v78 offset:2048
	ds_read_b128 v[108:111], v78 offset:4096
	ds_read_b128 v[112:115], v78 offset:6144
	v_mfma_f32_16x16x32_bf16 v[0:3], v[136:139], v[152:155], v[0:3]
	v_mfma_f32_16x16x32_bf16 v[4:7], v[136:139], v[156:159], v[4:7]
	s_mov_b32 s24, 0x700
	s_mov_b32 s25, 0
	s_add_u32 m0, s30, 0x18000
	v_lshl_add_u64 v[124:125], v[64:65], 0, s[24:25]
	global_load_lds_dwordx4 v[124:125], off
	v_mfma_f32_16x16x32_bf16 v[8:11], v[136:139], v[160:163], v[8:11]
	v_mfma_f32_16x16x32_bf16 v[12:15], v[136:139], v[164:167], v[12:15]
	v_mfma_f32_16x16x32_bf16 v[16:19], v[140:143], v[152:155], v[16:19]
	v_mfma_f32_16x16x32_bf16 v[20:23], v[140:143], v[156:159], v[20:23]
	v_mfma_f32_16x16x32_bf16 v[24:27], v[140:143], v[160:163], v[24:27]
	s_add_u32 m0, s30, 0x1a000
	v_lshl_add_u64 v[126:127], v[66:67], 0, s[24:25]
	global_load_lds_dwordx4 v[126:127], off
	v_mfma_f32_16x16x32_bf16 v[28:31], v[140:143], v[164:167], v[28:31]
	v_mfma_f32_16x16x32_bf16 v[32:35], v[144:147], v[152:155], v[32:35]
	v_mfma_f32_16x16x32_bf16 v[36:39], v[144:147], v[156:159], v[36:39]
	v_mfma_f32_16x16x32_bf16 v[40:43], v[144:147], v[160:163], v[40:43]
	v_mfma_f32_16x16x32_bf16 v[44:47], v[144:147], v[164:167], v[44:47]
	s_add_u32 m0, s30, 0x1c000
	v_lshl_add_u64 v[124:125], v[68:69], 0, s[24:25]
	global_load_lds_dwordx4 v[124:125], off
	v_mfma_f32_16x16x32_bf16 v[48:51], v[148:151], v[152:155], v[48:51]
	v_mfma_f32_16x16x32_bf16 v[52:55], v[148:151], v[156:159], v[52:55]
	v_mfma_f32_16x16x32_bf16 v[56:59], v[148:151], v[160:163], v[56:59]
	v_mfma_f32_16x16x32_bf16 v[60:63], v[148:151], v[164:167], v[60:63]
	ds_read_b128 v[136:139], v77
	ds_read_b128 v[140:143], v77 offset:2048
	ds_read_b128 v[144:147], v77 offset:4096
	ds_read_b128 v[148:151], v77 offset:6144
	ds_read_b128 v[152:155], v79
	ds_read_b128 v[156:159], v79 offset:2048
	ds_read_b128 v[160:163], v79 offset:4096
	ds_read_b128 v[164:167], v79 offset:6144
	s_waitcnt lgkmcnt(8)
;     ...
;   for (int kt = 0; kt < nk; ++kt) {
;     if (kt + 1 < nk) asm volatile("s_waitcnt vmcnt(6)" ::: "memory");
;     else asm volatile("s_waitcnt vmcnt(0)" ::: "memory");
;     __builtin_amdgcn_s_barrier();
;     asm volatile("" ::: "memory");
;     if (kt + 2 < nk) { const int st2 = (st >= 1) ? st - 1 : 2; GEMM_ISSUE(kt + 2, st2); }
;     const char* la = lds + st * STAGE_B;
;     const char* lb = la + 32768;
;     const unsigned sa_u = (unsigned)(size_t)la + arow_u, sb_u = (unsigned)(size_t)lb + brow_u;
;     const unsigned a0 = sa_u + co0, a1 = sa_u + co1, a2 = sa_u + co2, a3 = sa_u + co3;
;     const unsigned b0 = sb_u + co0, b1 = sb_u + co1, b2 = sb_u + co2, b3 = sb_u + co3;
;     {
;       bf16x8 p0, p1, q0, q1, u0, u1, w0, w1;
;       asm volatile(
;         "ds_read_b128 %4, %12\n\tds_read_b128 %5, %12 offset:4096\n\tds_read_b128 %6, %16\n\tds_read_b128 %7, %16 offset:4096\n\t"
;         "ds_read_b128 %8, %13\n\tds_read_b128 %9, %13 offset:4096\n\tds_read_b128 %10, %17\n\tds_read_b128 %11, %17 offset:4096\n\t"
;         "s_waitcnt lgkmcnt(4)\n\t"
;         "v_mfma_f32_32x32x16_bf16 %0, %4, %6, %0\n\tv_mfma_f32_32x32x16_bf16 %1, %4, %7, %1\n\tv_mfma_f32_32x32x16_bf16 %2, %5, %6, %2\n\tv_mfma_f32_32x32x16_bf16 %3, %5, %7, %3\n\t"
;         "ds_read_b128 %4, %14\n\tds_read_b128 %5, %14 offset:4096\n\tds_read_b128 %6, %18\n\tds_read_b128 %7, %18 offset:4096\n\t"
;         "s_waitcnt lgkmcnt(4)\n\t"
;         "v_mfma_f32_32x32x16_bf16 %0, %8, %10, %0\n\tv_mfma_f32_32x32x16_bf16 %1, %8, %11, %1\n\tv_mfma_f32_32x32x16_bf16 %2, %9, %10, %2\n\tv_mfma_f32_32x32x16_bf16 %3, %9, %11, %3\n\t"
;         "ds_read_b128 %8, %15\n\tds_read_b128 %9, %15 offset:4096\n\tds_read_b128 %10, %19\n\tds_read_b128 %11, %19 offset:4096\n\t"
;         "s_waitcnt lgkmcnt(4)\n\t"
;         "v_mfma_f32_32x32x16_bf16 %0, %4, %6, %0\n\tv_mfma_f32_32x32x16_bf16 %1, %4, %7, %1\n\tv_mfma_f32_32x32x16_bf16 %2, %5, %6, %2\n\tv_mfma_f32_32x32x16_bf16 %3, %5, %7, %3\n\t"
;         "s_waitcnt lgkmcnt(0)\n\t"
;         "v_mfma_f32_32x32x16_bf16 %0, %8, %10, %0\n\tv_mfma_f32_32x32x16_bf16 %1, %8, %11, %1\n\tv_mfma_f32_32x32x16_bf16 %2, %9, %10, %2\n\tv_mfma_f32_32x32x16_bf16 %3, %9, %11, %3"
;         : "+v"(acc[0][0]), "+v"(acc[0][1]), "+v"(acc[1][0]), "+v"(acc[1][1]),
;           "=&v"(p0), "=&v"(p1), "=&v"(q0), "=&v"(q1), "=&v"(u0), "=&v"(u1), "=&v"(w0), "=&v"(w1)
	v_mfma_f32_16x16x32_bf16 v[0:3], v[84:87], v[100:103], v[0:3]
	v_mfma_f32_16x16x32_bf16 v[4:7], v[84:87], v[104:107], v[4:7]
	s_add_u32 m0, s30, 0x1e000
	v_lshl_add_u64 v[126:127], v[70:71], 0, s[24:25]
	global_load_lds_dwordx4 v[126:127], off
	v_mfma_f32_16x16x32_bf16 v[8:11], v[84:87], v[108:111], v[8:11]
	v_mfma_f32_16x16x32_bf16 v[12:15], v[84:87], v[112:115], v[12:15]
	v_mfma_f32_16x16x32_bf16 v[16:19], v[88:91], v[100:103], v[16:19]
	v_mfma_f32_16x16x32_bf16 v[20:23], v[88:91], v[104:107], v[20:23]
	v_mfma_f32_16x16x32_bf16 v[24:27], v[88:91], v[108:111], v[24:27]
	s_add_u32 m0, s30, 0x20000
	v_lshl_add_u64 v[124:125], v[72:73], 0, s[24:25]
	global_load_lds_dwordx4 v[124:125], off
	v_mfma_f32_16x16x32_bf16 v[28:31], v[88:91], v[112:115], v[28:31]
	v_mfma_f32_16x16x32_bf16 v[32:35], v[92:95], v[100:103], v[32:35]
	v_mfma_f32_16x16x32_bf16 v[36:39], v[92:95], v[104:107], v[36:39]
	v_mfma_f32_16x16x32_bf16 v[40:43], v[92:95], v[108:111], v[40:43]
	v_mfma_f32_16x16x32_bf16 v[44:47], v[92:95], v[112:115], v[44:47]
	s_add_u32 m0, s30, 0x22000
	v_lshl_add_u64 v[126:127], v[74:75], 0, s[24:25]
	global_load_lds_dwordx4 v[126:127], off
	v_mfma_f32_16x16x32_bf16 v[48:51], v[96:99], v[100:103], v[48:51]
	v_mfma_f32_16x16x32_bf16 v[52:55], v[96:99], v[104:107], v[52:55]
	v_mfma_f32_16x16x32_bf16 v[56:59], v[96:99], v[108:111], v[56:59]
	v_mfma_f32_16x16x32_bf16 v[60:63], v[96:99], v[112:115], v[60:63]
	s_waitcnt vmcnt(6) lgkmcnt(0)
	s_barrier
	ds_read_b128 v[84:87], v76 offset:49152
	ds_read_b128 v[88:91], v76 offset:51200
	ds_read_b128 v[92:95], v76 offset:53248
	ds_read_b128 v[96:99], v76 offset:55296
	ds_read_b128 v[100:103], v78 offset:49152
	ds_read_b128 v[104:107], v78 offset:51200
	ds_read_b128 v[108:111], v78 offset:53248
	ds_read_b128 v[112:115], v78 offset:55296
	v_mfma_f32_16x16x32_bf16 v[0:3], v[136:139], v[152:155], v[0:3]
	v_mfma_f32_16x16x32_bf16 v[4:7], v[136:139], v[156:159], v[4:7]
	s_mov_b32 s24, 0x780
	s_mov_b32 s25, 0
	s_mov_b32 m0, s30
	v_lshl_add_u64 v[124:125], v[64:65], 0, s[24:25]
	global_load_lds_dwordx4 v[124:125], off
	v_mfma_f32_16x16x32_bf16 v[8:11], v[136:139], v[160:163], v[8:11]
	v_mfma_f32_16x16x32_bf16 v[12:15], v[136:139], v[164:167], v[12:15]
	v_mfma_f32_16x16x32_bf16 v[16:19], v[140:143], v[152:155], v[16:19]
	v_mfma_f32_16x16x32_bf16 v[20:23], v[140:143], v[156:159], v[20:23]
	v_mfma_f32_16x16x32_bf16 v[24:27], v[140:143], v[160:163], v[24:27]
	s_add_u32 m0, s30, 0x2000
	v_lshl_add_u64 v[126:127], v[66:67], 0, s[24:25]
	global_load_lds_dwordx4 v[126:127], off
	v_mfma_f32_16x16x32_bf16 v[28:31], v[140:143], v[164:167], v[28:31]
	v_mfma_f32_16x16x32_bf16 v[32:35], v[144:147], v[152:155], v[32:35]
	v_mfma_f32_16x16x32_bf16 v[36:39], v[144:147], v[156:159], v[36:39]
	v_mfma_f32_16x16x32_bf16 v[40:43], v[144:147], v[160:163], v[40:43]
	v_mfma_f32_16x16x32_bf16 v[44:47], v[144:147], v[164:167], v[44:47]
	s_add_u32 m0, s30, 0x4000
	v_lshl_add_u64 v[124:125], v[68:69], 0, s[24:25]
	global_load_lds_dwordx4 v[124:125], off
	v_mfma_f32_16x16x32_bf16 v[48:51], v[148:151], v[152:155], v[48:51]
	v_mfma_f32_16x16x32_bf16 v[52:55], v[148:151], v[156:159], v[52:55]
	v_mfma_f32_16x16x32_bf16 v[56:59], v[148:151], v[160:163], v[56:59]
	v_mfma_f32_16x16x32_bf16 v[60:63], v[148:151], v[164:167], v[60:63]
	ds_read_b128 v[136:139], v77 offset:49152
	ds_read_b128 v[140:143], v77 offset:51200
	ds_read_b128 v[144:147], v77 offset:53248
	ds_read_b128 v[148:151], v77 offset:55296
	ds_read_b128 v[152:155], v79 offset:49152
	ds_read_b128 v[156:159], v79 offset:51200
	ds_read_b128 v[160:163], v79 offset:53248
	ds_read_b128 v[164:167], v79 offset:55296
	s_waitcnt lgkmcnt(8)
	v_mfma_f32_16x16x32_bf16 v[0:3], v[84:87], v[100:103], v[0:3]
	v_mfma_f32_16x16x32_bf16 v[4:7], v[84:87], v[104:107], v[4:7]
	s_add_u32 m0, s30, 0x6000
	v_lshl_add_u64 v[126:127], v[70:71], 0, s[24:25]
	global_load_lds_dwordx4 v[126:127], off
	v_mfma_f32_16x16x32_bf16 v[8:11], v[84:87], v[108:111], v[8:11]
	v_mfma_f32_16x16x32_bf16 v[12:15], v[84:87], v[112:115], v[12:15]
	v_mfma_f32_16x16x32_bf16 v[16:19], v[88:91], v[100:103], v[16:19]
	v_mfma_f32_16x16x32_bf16 v[20:23], v[88:91], v[104:107], v[20:23]
	v_mfma_f32_16x16x32_bf16 v[24:27], v[88:91], v[108:111], v[24:27]
	s_add_u32 m0, s30, 0x8000
	v_lshl_add_u64 v[124:125], v[72:73], 0, s[24:25]
	global_load_lds_dwordx4 v[124:125], off
	v_mfma_f32_16x16x32_bf16 v[28:31], v[88:91], v[112:115], v[28:31]
	v_mfma_f32_16x16x32_bf16 v[32:35], v[92:95], v[100:103], v[32:35]
	v_mfma_f32_16x16x32_bf16 v[36:39], v[92:95], v[104:107], v[36:39]
	v_mfma_f32_16x16x32_bf16 v[40:43], v[92:95], v[108:111], v[40:43]
	v_mfma_f32_16x16x32_bf16 v[44:47], v[92:95], v[112:115], v[44:47]
	s_add_u32 m0, s30, 0xa000
	v_lshl_add_u64 v[126:127], v[74:75], 0, s[24:25]
	global_load_lds_dwordx4 v[126:127], off
	v_mfma_f32_16x16x32_bf16 v[48:51], v[96:99], v[100:103], v[48:51]
	v_mfma_f32_16x16x32_bf16 v[52:55], v[96:99], v[104:107], v[52:55]
	v_mfma_f32_16x16x32_bf16 v[56:59], v[96:99], v[108:111], v[56:59]
	v_mfma_f32_16x16x32_bf16 v[60:63], v[96:99], v[112:115], v[60:63]
	s_waitcnt vmcnt(6) lgkmcnt(0)
	s_barrier
;     ...
;   for (int kt = 0; kt < nk; ++kt) {
;     if (kt + 1 < nk) asm volatile("s_waitcnt vmcnt(6)" ::: "memory");
;     else asm volatile("s_waitcnt vmcnt(0)" ::: "memory");
;     __builtin_amdgcn_s_barrier();
;     asm volatile("" ::: "memory");
;     if (kt + 2 < nk) { const int st2 = (st >= 1) ? st - 1 : 2; GEMM_ISSUE(kt + 2, st2); }
;     const char* la = lds + st * STAGE_B;
;     const char* lb = la + 32768;
;     const unsigned sa_u = (unsigned)(size_t)la + arow_u, sb_u = (unsigned)(size_t)lb + brow_u;
;     const unsigned a0 = sa_u + co0, a1 = sa_u + co1, a2 = sa_u + co2, a3 = sa_u + co3;
;     const unsigned b0 = sb_u + co0, b1 = sb_u + co1, b2 = sb_u + co2, b3 = sb_u + co3;
;     {
;       bf16x8 p0, p1, q0, q1, u0, u1, w0, w1;
;       asm volatile(
;         "ds_read_b128 %4, %12\n\tds_read_b128 %5, %12 offset:4096\n\tds_read_b128 %6, %16\n\tds_read_b128 %7, %16 offset:4096\n\t"
;         "ds_read_b128 %8, %13\n\tds_read_b128 %9, %13 offset:4096\n\tds_read_b128 %10, %17\n\tds_read_b128 %11, %17 offset:4096\n\t"
;         "s_waitcnt lgkmcnt(4)\n\t"
;         "v_mfma_f32_32x32x16_bf16 %0, %4, %6, %0\n\tv_mfma_f32_32x32x16_bf16 %1, %4, %7, %1\n\tv_mfma_f32_32x32x16_bf16 %2, %5, %6, %2\n\tv_mfma_f32_32x32x16_bf16 %3, %5, %7, %3\n\t"
;         "ds_read_b128 %4, %14\n\tds_read_b128 %5, %14 offset:4096\n\tds_read_b128 %6, %18\n\tds_read_b128 %7, %18 offset:4096\n\t"
;         "s_waitcnt lgkmcnt(4)\n\t"
;         "v_mfma_f32_32x32x16_bf16 %0, %8, %10, %0\n\tv_mfma_f32_32x32x16_bf16 %1, %8, %11, %1\n\tv_mfma_f32_32x32x16_bf16 %2, %9, %10, %2\n\tv_mfma_f32_32x32x16_bf16 %3, %9, %11, %3\n\t"
;         "ds_read_b128 %8, %15\n\tds_read_b128 %9, %15 offset:4096\n\tds_read_b128 %10, %19\n\tds_read_b128 %11, %19 offset:4096\n\t"
;         "s_waitcnt lgkmcnt(4)\n\t"
;         "v_mfma_f32_32x32x16_bf16 %0, %4, %6, %0\n\tv_mfma_f32_32x32x16_bf16 %1, %4, %7, %1\n\tv_mfma_f32_32x32x16_bf16 %2, %5, %6, %2\n\tv_mfma_f32_32x32x16_bf16 %3, %5, %7, %3\n\t"
;         "s_waitcnt lgkmcnt(0)\n\t"
;         "v_mfma_f32_32x32x16_bf16 %0, %8, %10, %0\n\tv_mfma_f32_32x32x16_bf16 %1, %8, %11, %1\n\tv_mfma_f32_32x32x16_bf16 %2, %9, %10, %2\n\tv_mfma_f32_32x32x16_bf16 %3, %9, %11, %3"
;         : "+v"(acc[0][0]), "+v"(acc[0][1]), "+v"(acc[1][0]), "+v"(acc[1][1]),
;           "=&v"(p0), "=&v"(p1), "=&v"(q0), "=&v"(q1), "=&v"(u0), "=&v"(u1), "=&v"(w0), "=&v"(w1)
	ds_read_b128 v[84:87], v80
	ds_read_b128 v[88:91], v80 offset:2048
	ds_read_b128 v[92:95], v80 offset:4096
	ds_read_b128 v[96:99], v80 offset:6144
	ds_read_b128 v[100:103], v82
	ds_read_b128 v[104:107], v82 offset:2048
	ds_read_b128 v[108:111], v82 offset:4096
	ds_read_b128 v[112:115], v82 offset:6144
	v_mfma_f32_16x16x32_bf16 v[0:3], v[136:139], v[152:155], v[0:3]
	v_mfma_f32_16x16x32_bf16 v[4:7], v[136:139], v[156:159], v[4:7]
	s_add_u32 s24, s56, 0x0
	s_addc_u32 s25, s57, 0
	s_add_u32 m0, s30, 0xc000
	v_lshl_add_u64 v[124:125], v[64:65], 0, s[24:25]
	global_load_lds_dwordx4 v[124:125], off
	v_mfma_f32_16x16x32_bf16 v[8:11], v[136:139], v[160:163], v[8:11]
	v_mfma_f32_16x16x32_bf16 v[12:15], v[136:139], v[164:167], v[12:15]
	v_mfma_f32_16x16x32_bf16 v[16:19], v[140:143], v[152:155], v[16:19]
	v_mfma_f32_16x16x32_bf16 v[20:23], v[140:143], v[156:159], v[20:23]
	v_mfma_f32_16x16x32_bf16 v[24:27], v[140:143], v[160:163], v[24:27]
	s_add_u32 m0, s30, 0xe000
	v_lshl_add_u64 v[126:127], v[66:67], 0, s[24:25]
	global_load_lds_dwordx4 v[126:127], off
	v_mfma_f32_16x16x32_bf16 v[28:31], v[140:143], v[164:167], v[28:31]
	v_mfma_f32_16x16x32_bf16 v[32:35], v[144:147], v[152:155], v[32:35]
	v_mfma_f32_16x16x32_bf16 v[36:39], v[144:147], v[156:159], v[36:39]
	v_mfma_f32_16x16x32_bf16 v[40:43], v[144:147], v[160:163], v[40:43]
	v_mfma_f32_16x16x32_bf16 v[44:47], v[144:147], v[164:167], v[44:47]
	s_add_u32 m0, s30, 0x10000
	v_lshl_add_u64 v[124:125], v[68:69], 0, s[24:25]
	global_load_lds_dwordx4 v[124:125], off
	v_mfma_f32_16x16x32_bf16 v[48:51], v[148:151], v[152:155], v[48:51]
	v_mfma_f32_16x16x32_bf16 v[52:55], v[148:151], v[156:159], v[52:55]
	v_mfma_f32_16x16x32_bf16 v[56:59], v[148:151], v[160:163], v[56:59]
	v_mfma_f32_16x16x32_bf16 v[60:63], v[148:151], v[164:167], v[60:63]
	ds_read_b128 v[136:139], v81
	ds_read_b128 v[140:143], v81 offset:2048
	ds_read_b128 v[144:147], v81 offset:4096
	ds_read_b128 v[148:151], v81 offset:6144
	ds_read_b128 v[152:155], v83
	ds_read_b128 v[156:159], v83 offset:2048
	ds_read_b128 v[160:163], v83 offset:4096
	ds_read_b128 v[164:167], v83 offset:6144
	s_waitcnt lgkmcnt(8)
	v_mfma_f32_16x16x32_bf16 v[0:3], v[84:87], v[100:103], v[0:3]
	v_mfma_f32_16x16x32_bf16 v[4:7], v[84:87], v[104:107], v[4:7]
	s_add_u32 m0, s30, 0x12000
	v_lshl_add_u64 v[126:127], v[70:71], 0, s[24:25]
	global_load_lds_dwordx4 v[126:127], off
	v_mfma_f32_16x16x32_bf16 v[8:11], v[84:87], v[108:111], v[8:11]
	v_mfma_f32_16x16x32_bf16 v[12:15], v[84:87], v[112:115], v[12:15]
	v_mfma_f32_16x16x32_bf16 v[16:19], v[88:91], v[100:103], v[16:19]
	v_mfma_f32_16x16x32_bf16 v[20:23], v[88:91], v[104:107], v[20:23]
	v_mfma_f32_16x16x32_bf16 v[24:27], v[88:91], v[108:111], v[24:27]
	s_add_u32 s24, s58, 0x0
	s_addc_u32 s25, s59, 0
	s_add_u32 m0, s30, 0x14000
	v_lshl_add_u64 v[124:125], v[72:73], 0, s[24:25]
	global_load_lds_dwordx4 v[124:125], off
	v_mfma_f32_16x16x32_bf16 v[28:31], v[88:91], v[112:115], v[28:31]
	v_mfma_f32_16x16x32_bf16 v[32:35], v[92:95], v[100:103], v[32:35]
	v_mfma_f32_16x16x32_bf16 v[36:39], v[92:95], v[104:107], v[36:39]
	v_mfma_f32_16x16x32_bf16 v[40:43], v[92:95], v[108:111], v[40:43]
	v_mfma_f32_16x16x32_bf16 v[44:47], v[92:95], v[112:115], v[44:47]
	s_add_u32 m0, s30, 0x16000
	v_lshl_add_u64 v[126:127], v[74:75], 0, s[24:25]
	global_load_lds_dwordx4 v[126:127], off
	v_mfma_f32_16x16x32_bf16 v[48:51], v[96:99], v[100:103], v[48:51]
	v_mfma_f32_16x16x32_bf16 v[52:55], v[96:99], v[104:107], v[52:55]
	v_mfma_f32_16x16x32_bf16 v[56:59], v[96:99], v[108:111], v[56:59]
	v_mfma_f32_16x16x32_bf16 v[60:63], v[96:99], v[112:115], v[60:63]
	s_waitcnt vmcnt(6) lgkmcnt(0)
	s_barrier
	ds_read_b128 v[84:87], v76
	ds_read_b128 v[88:91], v76 offset:2048
	ds_read_b128 v[92:95], v76 offset:4096
	ds_read_b128 v[96:99], v76 offset:6144
	ds_read_b128 v[100:103], v78
	ds_read_b128 v[104:107], v78 offset:2048
	ds_read_b128 v[108:111], v78 offset:4096
	ds_read_b128 v[112:115], v78 offset:6144
	v_mfma_f32_16x16x32_bf16 v[0:3], v[136:139], v[152:155], v[0:3]
	v_mfma_f32_16x16x32_bf16 v[4:7], v[136:139], v[156:159], v[4:7]
	s_add_u32 s24, s56, 0x80
	s_addc_u32 s25, s57, 0
	s_add_u32 m0, s30, 0x18000
	v_lshl_add_u64 v[124:125], v[64:65], 0, s[24:25]
	global_load_lds_dwordx4 v[124:125], off
	v_mfma_f32_16x16x32_bf16 v[8:11], v[136:139], v[160:163], v[8:11]
	v_mfma_f32_16x16x32_bf16 v[12:15], v[136:139], v[164:167], v[12:15]
	v_mfma_f32_16x16x32_bf16 v[16:19], v[140:143], v[152:155], v[16:19]
	v_mfma_f32_16x16x32_bf16 v[20:23], v[140:143], v[156:159], v[20:23]
	v_mfma_f32_16x16x32_bf16 v[24:27], v[140:143], v[160:163], v[24:27]
	s_add_u32 m0, s30, 0x1a000
	v_lshl_add_u64 v[126:127], v[66:67], 0, s[24:25]
	global_load_lds_dwordx4 v[126:127], off
	v_mfma_f32_16x16x32_bf16 v[28:31], v[140:143], v[164:167], v[28:31]
	v_mfma_f32_16x16x32_bf16 v[32:35], v[144:147], v[152:155], v[32:35]
	v_mfma_f32_16x16x32_bf16 v[36:39], v[144:147], v[156:159], v[36:39]
	v_mfma_f32_16x16x32_bf16 v[40:43], v[144:147], v[160:163], v[40:43]
	v_mfma_f32_16x16x32_bf16 v[44:47], v[144:147], v[164:167], v[44:47]
	s_add_u32 m0, s30, 0x1c000
	v_lshl_add_u64 v[124:125], v[68:69], 0, s[24:25]
	global_load_lds_dwordx4 v[124:125], off
	v_mfma_f32_16x16x32_bf16 v[48:51], v[148:151], v[152:155], v[48:51]
	v_mfma_f32_16x16x32_bf16 v[52:55], v[148:151], v[156:159], v[52:55]
	v_mfma_f32_16x16x32_bf16 v[56:59], v[148:151], v[160:163], v[56:59]
	v_mfma_f32_16x16x32_bf16 v[60:63], v[148:151], v[164:167], v[60:63]
	ds_read_b128 v[136:139], v77
	ds_read_b128 v[140:143], v77 offset:2048
	ds_read_b128 v[144:147], v77 offset:4096
	ds_read_b128 v[148:151], v77 offset:6144
	ds_read_b128 v[152:155], v79
	ds_read_b128 v[156:159], v79 offset:2048
	ds_read_b128 v[160:163], v79 offset:4096
	ds_read_b128 v[164:167], v79 offset:6144
	s_waitcnt lgkmcnt(8)
;     ...
;   for (int kt = 0; kt < nk; ++kt) {
;     if (kt + 1 < nk) asm volatile("s_waitcnt vmcnt(6)" ::: "memory");
;     else asm volatile("s_waitcnt vmcnt(0)" ::: "memory");
;     __builtin_amdgcn_s_barrier();
;     asm volatile("" ::: "memory");
;     if (kt + 2 < nk) { const int st2 = (st >= 1) ? st - 1 : 2; GEMM_ISSUE(kt + 2, st2); }
;     const char* la = lds + st * STAGE_B;
;     const char* lb = la + 32768;
;     const unsigned sa_u = (unsigned)(size_t)la + arow_u, sb_u = (unsigned)(size_t)lb + brow_u;
;     const unsigned a0 = sa_u + co0, a1 = sa_u + co1, a2 = sa_u + co2, a3 = sa_u + co3;
;     const unsigned b0 = sb_u + co0, b1 = sb_u + co1, b2 = sb_u + co2, b3 = sb_u + co3;
;     {
;       bf16x8 p0, p1, q0, q1, u0, u1, w0, w1;
;       asm volatile(
;         "ds_read_b128 %4, %12\n\tds_read_b128 %5, %12 offset:4096\n\tds_read_b128 %6, %16\n\tds_read_b128 %7, %16 offset:4096\n\t"
;         "ds_read_b128 %8, %13\n\tds_read_b128 %9, %13 offset:4096\n\tds_read_b128 %10, %17\n\tds_read_b128 %11, %17 offset:4096\n\t"
;         "s_waitcnt lgkmcnt(4)\n\t"
;         "v_mfma_f32_32x32x16_bf16 %0, %4, %6, %0\n\tv_mfma_f32_32x32x16_bf16 %1, %4, %7, %1\n\tv_mfma_f32_32x32x16_bf16 %2, %5, %6, %2\n\tv_mfma_f32_32x32x16_bf16 %3, %5, %7, %3\n\t"
;         "ds_read_b128 %4, %14\n\tds_read_b128 %5, %14 offset:4096\n\tds_read_b128 %6, %18\n\tds_read_b128 %7, %18 offset:4096\n\t"
;         "s_waitcnt lgkmcnt(4)\n\t"
;         "v_mfma_f32_32x32x16_bf16 %0, %8, %10, %0\n\tv_mfma_f32_32x32x16_bf16 %1, %8, %11, %1\n\tv_mfma_f32_32x32x16_bf16 %2, %9, %10, %2\n\tv_mfma_f32_32x32x16_bf16 %3, %9, %11, %3\n\t"
;         "ds_read_b128 %8, %15\n\tds_read_b128 %9, %15 offset:4096\n\tds_read_b128 %10, %19\n\tds_read_b128 %11, %19 offset:4096\n\t"
;         "s_waitcnt lgkmcnt(4)\n\t"
;         "v_mfma_f32_32x32x16_bf16 %0, %4, %6, %0\n\tv_mfma_f32_32x32x16_bf16 %1, %4, %7, %1\n\tv_mfma_f32_32x32x16_bf16 %2, %5, %6, %2\n\tv_mfma_f32_32x32x16_bf16 %3, %5, %7, %3\n\t"
;         "s_waitcnt lgkmcnt(0)\n\t"
;         "v_mfma_f32_32x32x16_bf16 %0, %8, %10, %0\n\tv_mfma_f32_32x32x16_bf16 %1, %8, %11, %1\n\tv_mfma_f32_32x32x16_bf16 %2, %9, %10, %2\n\tv_mfma_f32_32x32x16_bf16 %3, %9, %11, %3"
;         : "+v"(acc[0][0]), "+v"(acc[0][1]), "+v"(acc[1][0]), "+v"(acc[1][1]),
;           "=&v"(p0), "=&v"(p1), "=&v"(q0), "=&v"(q1), "=&v"(u0), "=&v"(u1), "=&v"(w0), "=&v"(w1)
	v_mfma_f32_16x16x32_bf16 v[0:3], v[84:87], v[100:103], v[0:3]
	v_mfma_f32_16x16x32_bf16 v[4:7], v[84:87], v[104:107], v[4:7]
	s_add_u32 m0, s30, 0x1e000
	v_lshl_add_u64 v[126:127], v[70:71], 0, s[24:25]
	global_load_lds_dwordx4 v[126:127], off
	v_mfma_f32_16x16x32_bf16 v[8:11], v[84:87], v[108:111], v[8:11]
	v_mfma_f32_16x16x32_bf16 v[12:15], v[84:87], v[112:115], v[12:15]
	v_mfma_f32_16x16x32_bf16 v[16:19], v[88:91], v[100:103], v[16:19]
	v_mfma_f32_16x16x32_bf16 v[20:23], v[88:91], v[104:107], v[20:23]
	v_mfma_f32_16x16x32_bf16 v[24:27], v[88:91], v[108:111], v[24:27]
	s_add_u32 s24, s58, 0x80
	s_addc_u32 s25, s59, 0
	s_add_u32 m0, s30, 0x20000
	v_lshl_add_u64 v[124:125], v[72:73], 0, s[24:25]
	global_load_lds_dwordx4 v[124:125], off
	v_mfma_f32_16x16x32_bf16 v[28:31], v[88:91], v[112:115], v[28:31]
	v_mfma_f32_16x16x32_bf16 v[32:35], v[92:95], v[100:103], v[32:35]
	v_mfma_f32_16x16x32_bf16 v[36:39], v[92:95], v[104:107], v[36:39]
	v_mfma_f32_16x16x32_bf16 v[40:43], v[92:95], v[108:111], v[40:43]
	v_mfma_f32_16x16x32_bf16 v[44:47], v[92:95], v[112:115], v[44:47]
	s_add_u32 m0, s30, 0x22000
	v_lshl_add_u64 v[126:127], v[74:75], 0, s[24:25]
	global_load_lds_dwordx4 v[126:127], off
	v_mfma_f32_16x16x32_bf16 v[48:51], v[96:99], v[100:103], v[48:51]
	v_mfma_f32_16x16x32_bf16 v[52:55], v[96:99], v[104:107], v[52:55]
	v_mfma_f32_16x16x32_bf16 v[56:59], v[96:99], v[108:111], v[56:59]
	v_mfma_f32_16x16x32_bf16 v[60:63], v[96:99], v[112:115], v[60:63]
	s_waitcnt lgkmcnt(0)
	v_mfma_f32_16x16x32_bf16 v[0:3], v[136:139], v[152:155], v[0:3]
	v_mfma_f32_16x16x32_bf16 v[4:7], v[136:139], v[156:159], v[4:7]
	v_mfma_f32_16x16x32_bf16 v[8:11], v[136:139], v[160:163], v[8:11]
	v_mfma_f32_16x16x32_bf16 v[12:15], v[136:139], v[164:167], v[12:15]
	v_mfma_f32_16x16x32_bf16 v[16:19], v[140:143], v[152:155], v[16:19]
	v_mfma_f32_16x16x32_bf16 v[20:23], v[140:143], v[156:159], v[20:23]
	v_mfma_f32_16x16x32_bf16 v[24:27], v[140:143], v[160:163], v[24:27]
	v_mfma_f32_16x16x32_bf16 v[28:31], v[140:143], v[164:167], v[28:31]
	v_mfma_f32_16x16x32_bf16 v[32:35], v[144:147], v[152:155], v[32:35]
	v_mfma_f32_16x16x32_bf16 v[36:39], v[144:147], v[156:159], v[36:39]
	v_mfma_f32_16x16x32_bf16 v[40:43], v[144:147], v[160:163], v[40:43]
	v_mfma_f32_16x16x32_bf16 v[44:47], v[144:147], v[164:167], v[44:47]
	v_mfma_f32_16x16x32_bf16 v[48:51], v[148:151], v[152:155], v[48:51]
	v_mfma_f32_16x16x32_bf16 v[52:55], v[148:151], v[156:159], v[52:55]
	v_mfma_f32_16x16x32_bf16 v[56:59], v[148:151], v[160:163], v[56:59]
	v_mfma_f32_16x16x32_bf16 v[60:63], v[148:151], v[164:167], v[60:63]
	s_branch .Ly11_done
.Ly11_v1:
	ds_read_b128 v[84:87], v76 offset:49152
	ds_read_b128 v[88:91], v76 offset:51200
	ds_read_b128 v[92:95], v76 offset:53248
	ds_read_b128 v[96:99], v76 offset:55296
	ds_read_b128 v[100:103], v78 offset:49152
	ds_read_b128 v[104:107], v78 offset:51200
	ds_read_b128 v[108:111], v78 offset:53248
	ds_read_b128 v[112:115], v78 offset:55296
	s_mov_b32 s24, 0x100
	s_mov_b32 s25, 0
	s_mov_b32 m0, s30
	v_lshl_add_u64 v[124:125], v[64:65], 0, s[24:25]
	global_load_lds_dwordx4 v[124:125], off
	s_add_u32 m0, s30, 0x2000
	v_lshl_add_u64 v[126:127], v[66:67], 0, s[24:25]
	global_load_lds_dwordx4 v[126:127], off
	s_add_u32 m0, s30, 0x4000
	v_lshl_add_u64 v[124:125], v[68:69], 0, s[24:25]
	global_load_lds_dwordx4 v[124:125], off
	ds_read_b128 v[136:139], v77 offset:49152
	ds_read_b128 v[140:143], v77 offset:51200
	ds_read_b128 v[144:147], v77 offset:53248
	ds_read_b128 v[148:151], v77 offset:55296
	ds_read_b128 v[152:155], v79 offset:49152
	ds_read_b128 v[156:159], v79 offset:51200
	ds_read_b128 v[160:163], v79 offset:53248
	ds_read_b128 v[164:167], v79 offset:55296
	s_waitcnt lgkmcnt(8)
	v_mfma_f32_16x16x32_bf16 v[0:3], v[84:87], v[100:103], v[0:3]
	v_mfma_f32_16x16x32_bf16 v[4:7], v[84:87], v[104:107], v[4:7]
	s_add_u32 m0, s30, 0x6000
	v_lshl_add_u64 v[126:127], v[70:71], 0, s[24:25]
	global_load_lds_dwordx4 v[126:127], off
	v_mfma_f32_16x16x32_bf16 v[8:11], v[84:87], v[108:111], v[8:11]
	v_mfma_f32_16x16x32_bf16 v[12:15], v[84:87], v[112:115], v[12:15]
	v_mfma_f32_16x16x32_bf16 v[16:19], v[88:91], v[100:103], v[16:19]
	v_mfma_f32_16x16x32_bf16 v[20:23], v[88:91], v[104:107], v[20:23]
	v_mfma_f32_16x16x32_bf16 v[24:27], v[88:91], v[108:111], v[24:27]
	s_add_u32 m0, s30, 0x8000
	v_lshl_add_u64 v[124:125], v[72:73], 0, s[24:25]
	global_load_lds_dwordx4 v[124:125], off
	v_mfma_f32_16x16x32_bf16 v[28:31], v[88:91], v[112:115], v[28:31]
	v_mfma_f32_16x16x32_bf16 v[32:35], v[92:95], v[100:103], v[32:35]
	v_mfma_f32_16x16x32_bf16 v[36:39], v[92:95], v[104:107], v[36:39]
	v_mfma_f32_16x16x32_bf16 v[40:43], v[92:95], v[108:111], v[40:43]
	v_mfma_f32_16x16x32_bf16 v[44:47], v[92:95], v[112:115], v[44:47]
	s_add_u32 m0, s30, 0xa000
	v_lshl_add_u64 v[126:127], v[74:75], 0, s[24:25]
	global_load_lds_dwordx4 v[126:127], off
	v_mfma_f32_16x16x32_bf16 v[48:51], v[96:99], v[100:103], v[48:51]
	v_mfma_f32_16x16x32_bf16 v[52:55], v[96:99], v[104:107], v[52:55]
	v_mfma_f32_16x16x32_bf16 v[56:59], v[96:99], v[108:111], v[56:59]
	v_mfma_f32_16x16x32_bf16 v[60:63], v[96:99], v[112:115], v[60:63]
	s_waitcnt vmcnt(6) lgkmcnt(0)
	s_barrier
;     ...
;   for (int kt = 0; kt < nk; ++kt) {
;     if (kt + 1 < nk) asm volatile("s_waitcnt vmcnt(6)" ::: "memory");
;     else asm volatile("s_waitcnt vmcnt(0)" ::: "memory");
;     __builtin_amdgcn_s_barrier();
;     asm volatile("" ::: "memory");
;     if (kt + 2 < nk) { const int st2 = (st >= 1) ? st - 1 : 2; GEMM_ISSUE(kt + 2, st2); }
;     const char* la = lds + st * STAGE_B;
;     const char* lb = la + 32768;
;     const unsigned sa_u = (unsigned)(size_t)la + arow_u, sb_u = (unsigned)(size_t)lb + brow_u;
;     const unsigned a0 = sa_u + co0, a1 = sa_u + co1, a2 = sa_u + co2, a3 = sa_u + co3;
;     const unsigned b0 = sb_u + co0, b1 = sb_u + co1, b2 = sb_u + co2, b3 = sb_u + co3;
;     {
;       bf16x8 p0, p1, q0, q1, u0, u1, w0, w1;
;       asm volatile(
;         "ds_read_b128 %4, %12\n\tds_read_b128 %5, %12 offset:4096\n\tds_read_b128 %6, %16\n\tds_read_b128 %7, %16 offset:4096\n\t"
;         "ds_read_b128 %8, %13\n\tds_read_b128 %9, %13 offset:4096\n\tds_read_b128 %10, %17\n\tds_read_b128 %11, %17 offset:4096\n\t"
;         "s_waitcnt lgkmcnt(4)\n\t"
;         "v_mfma_f32_32x32x16_bf16 %0, %4, %6, %0\n\tv_mfma_f32_32x32x16_bf16 %1, %4, %7, %1\n\tv_mfma_f32_32x32x16_bf16 %2, %5, %6, %2\n\tv_mfma_f32_32x32x16_bf16 %3, %5, %7, %3\n\t"
;         "ds_read_b128 %4, %14\n\tds_read_b128 %5, %14 offset:4096\n\tds_read_b128 %6, %18\n\tds_read_b128 %7, %18 offset:4096\n\t"
;         "s_waitcnt lgkmcnt(4)\n\t"
;         "v_mfma_f32_32x32x16_bf16 %0, %8, %10, %0\n\tv_mfma_f32_32x32x16_bf16 %1, %8, %11, %1\n\tv_mfma_f32_32x32x16_bf16 %2, %9, %10, %2\n\tv_mfma_f32_32x32x16_bf16 %3, %9, %11, %3\n\t"
;         "ds_read_b128 %8, %15\n\tds_read_b128 %9, %15 offset:4096\n\tds_read_b128 %10, %19\n\tds_read_b128 %11, %19 offset:4096\n\t"
;         "s_waitcnt lgkmcnt(4)\n\t"
;         "v_mfma_f32_32x32x16_bf16 %0, %4, %6, %0\n\tv_mfma_f32_32x32x16_bf16 %1, %4, %7, %1\n\tv_mfma_f32_32x32x16_bf16 %2, %5, %6, %2\n\tv_mfma_f32_32x32x16_bf16 %3, %5, %7, %3\n\t"
;         "s_waitcnt lgkmcnt(0)\n\t"
;         "v_mfma_f32_32x32x16_bf16 %0, %8, %10, %0\n\tv_mfma_f32_32x32x16_bf16 %1, %8, %11, %1\n\tv_mfma_f32_32x32x16_bf16 %2, %9, %10, %2\n\tv_mfma_f32_32x32x16_bf16 %3, %9, %11, %3"
;         : "+v"(acc[0][0]), "+v"(acc[0][1]), "+v"(acc[1][0]), "+v"(acc[1][1]),
;           "=&v"(p0), "=&v"(p1), "=&v"(q0), "=&v"(q1), "=&v"(u0), "=&v"(u1), "=&v"(w0), "=&v"(w1)
	ds_read_b128 v[84:87], v80
	ds_read_b128 v[88:91], v80 offset:2048
	ds_read_b128 v[92:95], v80 offset:4096
	ds_read_b128 v[96:99], v80 offset:6144
	ds_read_b128 v[100:103], v82
	ds_read_b128 v[104:107], v82 offset:2048
	ds_read_b128 v[108:111], v82 offset:4096
	ds_read_b128 v[112:115], v82 offset:6144
	v_mfma_f32_16x16x32_bf16 v[0:3], v[136:139], v[152:155], v[0:3]
	v_mfma_f32_16x16x32_bf16 v[4:7], v[136:139], v[156:159], v[4:7]
	s_mov_b32 s24, 0x180
	s_mov_b32 s25, 0
	s_add_u32 m0, s30, 0xc000
	v_lshl_add_u64 v[124:125], v[64:65], 0, s[24:25]
	global_load_lds_dwordx4 v[124:125], off
	v_mfma_f32_16x16x32_bf16 v[8:11], v[136:139], v[160:163], v[8:11]
	v_mfma_f32_16x16x32_bf16 v[12:15], v[136:139], v[164:167], v[12:15]
	v_mfma_f32_16x16x32_bf16 v[16:19], v[140:143], v[152:155], v[16:19]
	v_mfma_f32_16x16x32_bf16 v[20:23], v[140:143], v[156:159], v[20:23]
	v_mfma_f32_16x16x32_bf16 v[24:27], v[140:143], v[160:163], v[24:27]
	s_add_u32 m0, s30, 0xe000
	v_lshl_add_u64 v[126:127], v[66:67], 0, s[24:25]
	global_load_lds_dwordx4 v[126:127], off
	v_mfma_f32_16x16x32_bf16 v[28:31], v[140:143], v[164:167], v[28:31]
	v_mfma_f32_16x16x32_bf16 v[32:35], v[144:147], v[152:155], v[32:35]
	v_mfma_f32_16x16x32_bf16 v[36:39], v[144:147], v[156:159], v[36:39]
	v_mfma_f32_16x16x32_bf16 v[40:43], v[144:147], v[160:163], v[40:43]
	v_mfma_f32_16x16x32_bf16 v[44:47], v[144:147], v[164:167], v[44:47]
	s_add_u32 m0, s30, 0x10000
	v_lshl_add_u64 v[124:125], v[68:69], 0, s[24:25]
	global_load_lds_dwordx4 v[124:125], off
	v_mfma_f32_16x16x32_bf16 v[48:51], v[148:151], v[152:155], v[48:51]
	v_mfma_f32_16x16x32_bf16 v[52:55], v[148:151], v[156:159], v[52:55]
	v_mfma_f32_16x16x32_bf16 v[56:59], v[148:151], v[160:163], v[56:59]
	v_mfma_f32_16x16x32_bf16 v[60:63], v[148:151], v[164:167], v[60:63]
	ds_read_b128 v[136:139], v81
	ds_read_b128 v[140:143], v81 offset:2048
	ds_read_b128 v[144:147], v81 offset:4096
	ds_read_b128 v[148:151], v81 offset:6144
	ds_read_b128 v[152:155], v83
	ds_read_b128 v[156:159], v83 offset:2048
	ds_read_b128 v[160:163], v83 offset:4096
	ds_read_b128 v[164:167], v83 offset:6144
	s_waitcnt lgkmcnt(8)
	v_mfma_f32_16x16x32_bf16 v[0:3], v[84:87], v[100:103], v[0:3]
	v_mfma_f32_16x16x32_bf16 v[4:7], v[84:87], v[104:107], v[4:7]
	s_add_u32 m0, s30, 0x12000
	v_lshl_add_u64 v[126:127], v[70:71], 0, s[24:25]
	global_load_lds_dwordx4 v[126:127], off
	v_mfma_f32_16x16x32_bf16 v[8:11], v[84:87], v[108:111], v[8:11]
	v_mfma_f32_16x16x32_bf16 v[12:15], v[84:87], v[112:115], v[12:15]
	v_mfma_f32_16x16x32_bf16 v[16:19], v[88:91], v[100:103], v[16:19]
	v_mfma_f32_16x16x32_bf16 v[20:23], v[88:91], v[104:107], v[20:23]
	v_mfma_f32_16x16x32_bf16 v[24:27], v[88:91], v[108:111], v[24:27]
	s_add_u32 m0, s30, 0x14000
	v_lshl_add_u64 v[124:125], v[72:73], 0, s[24:25]
	global_load_lds_dwordx4 v[124:125], off
	v_mfma_f32_16x16x32_bf16 v[28:31], v[88:91], v[112:115], v[28:31]
	v_mfma_f32_16x16x32_bf16 v[32:35], v[92:95], v[100:103], v[32:35]
	v_mfma_f32_16x16x32_bf16 v[36:39], v[92:95], v[104:107], v[36:39]
	v_mfma_f32_16x16x32_bf16 v[40:43], v[92:95], v[108:111], v[40:43]
	v_mfma_f32_16x16x32_bf16 v[44:47], v[92:95], v[112:115], v[44:47]
	s_add_u32 m0, s30, 0x16000
	v_lshl_add_u64 v[126:127], v[74:75], 0, s[24:25]
	global_load_lds_dwordx4 v[126:127], off
	v_mfma_f32_16x16x32_bf16 v[48:51], v[96:99], v[100:103], v[48:51]
	v_mfma_f32_16x16x32_bf16 v[52:55], v[96:99], v[104:107], v[52:55]
	v_mfma_f32_16x16x32_bf16 v[56:59], v[96:99], v[108:111], v[56:59]
	v_mfma_f32_16x16x32_bf16 v[60:63], v[96:99], v[112:115], v[60:63]
	s_waitcnt vmcnt(6) lgkmcnt(0)
	s_barrier
	ds_read_b128 v[84:87], v76
	ds_read_b128 v[88:91], v76 offset:2048
	ds_read_b128 v[92:95], v76 offset:4096
	ds_read_b128 v[96:99], v76 offset:6144
	ds_read_b128 v[100:103], v78
	ds_read_b128 v[104:107], v78 offset:2048
	ds_read_b128 v[108:111], v78 offset:4096
	ds_read_b128 v[112:115], v78 offset:6144
	v_mfma_f32_16x16x32_bf16 v[0:3], v[136:139], v[152:155], v[0:3]
	v_mfma_f32_16x16x32_bf16 v[4:7], v[136:139], v[156:159], v[4:7]
	s_mov_b32 s24, 0x200
	s_mov_b32 s25, 0
	s_add_u32 m0, s30, 0x18000
	v_lshl_add_u64 v[124:125], v[64:65], 0, s[24:25]
	global_load_lds_dwordx4 v[124:125], off
	v_mfma_f32_16x16x32_bf16 v[8:11], v[136:139], v[160:163], v[8:11]
	v_mfma_f32_16x16x32_bf16 v[12:15], v[136:139], v[164:167], v[12:15]
	v_mfma_f32_16x16x32_bf16 v[16:19], v[140:143], v[152:155], v[16:19]
	v_mfma_f32_16x16x32_bf16 v[20:23], v[140:143], v[156:159], v[20:23]
	v_mfma_f32_16x16x32_bf16 v[24:27], v[140:143], v[160:163], v[24:27]
	s_add_u32 m0, s30, 0x1a000
	v_lshl_add_u64 v[126:127], v[66:67], 0, s[24:25]
	global_load_lds_dwordx4 v[126:127], off
	v_mfma_f32_16x16x32_bf16 v[28:31], v[140:143], v[164:167], v[28:31]
	v_mfma_f32_16x16x32_bf16 v[32:35], v[144:147], v[152:155], v[32:35]
	v_mfma_f32_16x16x32_bf16 v[36:39], v[144:147], v[156:159], v[36:39]
	v_mfma_f32_16x16x32_bf16 v[40:43], v[144:147], v[160:163], v[40:43]
	v_mfma_f32_16x16x32_bf16 v[44:47], v[144:147], v[164:167], v[44:47]
	s_add_u32 m0, s30, 0x1c000
	v_lshl_add_u64 v[124:125], v[68:69], 0, s[24:25]
	global_load_lds_dwordx4 v[124:125], off
	v_mfma_f32_16x16x32_bf16 v[48:51], v[148:151], v[152:155], v[48:51]
	v_mfma_f32_16x16x32_bf16 v[52:55], v[148:151], v[156:159], v[52:55]
	v_mfma_f32_16x16x32_bf16 v[56:59], v[148:151], v[160:163], v[56:59]
	v_mfma_f32_16x16x32_bf16 v[60:63], v[148:151], v[164:167], v[60:63]
	ds_read_b128 v[136:139], v77
	ds_read_b128 v[140:143], v77 offset:2048
	ds_read_b128 v[144:147], v77 offset:4096
	ds_read_b128 v[148:151], v77 offset:6144
	ds_read_b128 v[152:155], v79
	ds_read_b128 v[156:159], v79 offset:2048
	ds_read_b128 v[160:163], v79 offset:4096
	ds_read_b128 v[164:167], v79 offset:6144
	s_waitcnt lgkmcnt(8)
;     ...
;   for (int kt = 0; kt < nk; ++kt) {
;     if (kt + 1 < nk) asm volatile("s_waitcnt vmcnt(6)" ::: "memory");
;     else asm volatile("s_waitcnt vmcnt(0)" ::: "memory");
;     __builtin_amdgcn_s_barrier();
;     asm volatile("" ::: "memory");
;     if (kt + 2 < nk) { const int st2 = (st >= 1) ? st - 1 : 2; GEMM_ISSUE(kt + 2, st2); }
;     const char* la = lds + st * STAGE_B;
;     const char* lb = la + 32768;
;     const unsigned sa_u = (unsigned)(size_t)la + arow_u, sb_u = (unsigned)(size_t)lb + brow_u;
;     const unsigned a0 = sa_u + co0, a1 = sa_u + co1, a2 = sa_u + co2, a3 = sa_u + co3;
;     const unsigned b0 = sb_u + co0, b1 = sb_u + co1, b2 = sb_u + co2, b3 = sb_u + co3;
;     {
;       bf16x8 p0, p1, q0, q1, u0, u1, w0, w1;
;       asm volatile(
;         "ds_read_b128 %4, %12\n\tds_read_b128 %5, %12 offset:4096\n\tds_read_b128 %6, %16\n\tds_read_b128 %7, %16 offset:4096\n\t"
;         "ds_read_b128 %8, %13\n\tds_read_b128 %9, %13 offset:4096\n\tds_read_b128 %10, %17\n\tds_read_b128 %11, %17 offset:4096\n\t"
;         "s_waitcnt lgkmcnt(4)\n\t"
;         "v_mfma_f32_32x32x16_bf16 %0, %4, %6, %0\n\tv_mfma_f32_32x32x16_bf16 %1, %4, %7, %1\n\tv_mfma_f32_32x32x16_bf16 %2, %5, %6, %2\n\tv_mfma_f32_32x32x16_bf16 %3, %5, %7, %3\n\t"
;         "ds_read_b128 %4, %14\n\tds_read_b128 %5, %14 offset:4096\n\tds_read_b128 %6, %18\n\tds_read_b128 %7, %18 offset:4096\n\t"
;         "s_waitcnt lgkmcnt(4)\n\t"
;         "v_mfma_f32_32x32x16_bf16 %0, %8, %10, %0\n\tv_mfma_f32_32x32x16_bf16 %1, %8, %11, %1\n\tv_mfma_f32_32x32x16_bf16 %2, %9, %10, %2\n\tv_mfma_f32_32x32x16_bf16 %3, %9, %11, %3\n\t"
;         "ds_read_b128 %8, %15\n\tds_read_b128 %9, %15 offset:4096\n\tds_read_b128 %10, %19\n\tds_read_b128 %11, %19 offset:4096\n\t"
;         "s_waitcnt lgkmcnt(4)\n\t"
;         "v_mfma_f32_32x32x16_bf16 %0, %4, %6, %0\n\tv_mfma_f32_32x32x16_bf16 %1, %4, %7, %1\n\tv_mfma_f32_32x32x16_bf16 %2, %5, %6, %2\n\tv_mfma_f32_32x32x16_bf16 %3, %5, %7, %3\n\t"
;         "s_waitcnt lgkmcnt(0)\n\t"
;         "v_mfma_f32_32x32x16_bf16 %0, %8, %10, %0\n\tv_mfma_f32_32x32x16_bf16 %1, %8, %11, %1\n\tv_mfma_f32_32x32x16_bf16 %2, %9, %10, %2\n\tv_mfma_f32_32x32x16_bf16 %3, %9, %11, %3"
;         : "+v"(acc[0][0]), "+v"(acc[0][1]), "+v"(acc[1][0]), "+v"(acc[1][1]),
;           "=&v"(p0), "=&v"(p1), "=&v"(q0), "=&v"(q1), "=&v"(u0), "=&v"(u1), "=&v"(w0), "=&v"(w1)
	v_mfma_f32_16x16x32_bf16 v[0:3], v[84:87], v[100:103], v[0:3]
	v_mfma_f32_16x16x32_bf16 v[4:7], v[84:87], v[104:107], v[4:7]
	s_add_u32 m0, s30, 0x1e000
	v_lshl_add_u64 v[126:127], v[70:71], 0, s[24:25]
	global_load_lds_dwordx4 v[126:127], off
	v_mfma_f32_16x16x32_bf16 v[8:11], v[84:87], v[108:111], v[8:11]
	v_mfma_f32_16x16x32_bf16 v[12:15], v[84:87], v[112:115], v[12:15]
	v_mfma_f32_16x16x32_bf16 v[16:19], v[88:91], v[100:103], v[16:19]
	v_mfma_f32_16x16x32_bf16 v[20:23], v[88:91], v[104:107], v[20:23]
	v_mfma_f32_16x16x32_bf16 v[24:27], v[88:91], v[108:111], v[24:27]
	s_add_u32 m0, s30, 0x20000
	v_lshl_add_u64 v[124:125], v[72:73], 0, s[24:25]
	global_load_lds_dwordx4 v[124:125], off
	v_mfma_f32_16x16x32_bf16 v[28:31], v[88:91], v[112:115], v[28:31]
	v_mfma_f32_16x16x32_bf16 v[32:35], v[92:95], v[100:103], v[32:35]
	v_mfma_f32_16x16x32_bf16 v[36:39], v[92:95], v[104:107], v[36:39]
	v_mfma_f32_16x16x32_bf16 v[40:43], v[92:95], v[108:111], v[40:43]
	v_mfma_f32_16x16x32_bf16 v[44:47], v[92:95], v[112:115], v[44:47]
	s_add_u32 m0, s30, 0x22000
	v_lshl_add_u64 v[126:127], v[74:75], 0, s[24:25]
	global_load_lds_dwordx4 v[126:127], off
	v_mfma_f32_16x16x32_bf16 v[48:51], v[96:99], v[100:103], v[48:51]
	v_mfma_f32_16x16x32_bf16 v[52:55], v[96:99], v[104:107], v[52:55]
	v_mfma_f32_16x16x32_bf16 v[56:59], v[96:99], v[108:111], v[56:59]
	v_mfma_f32_16x16x32_bf16 v[60:63], v[96:99], v[112:115], v[60:63]
	s_waitcnt vmcnt(6) lgkmcnt(0)
	s_barrier
	ds_read_b128 v[84:87], v76 offset:49152
	ds_read_b128 v[88:91], v76 offset:51200
	ds_read_b128 v[92:95], v76 offset:53248
	ds_read_b128 v[96:99], v76 offset:55296
	ds_read_b128 v[100:103], v78 offset:49152
	ds_read_b128 v[104:107], v78 offset:51200
	ds_read_b128 v[108:111], v78 offset:53248
	ds_read_b128 v[112:115], v78 offset:55296
	v_mfma_f32_16x16x32_bf16 v[0:3], v[136:139], v[152:155], v[0:3]
	v_mfma_f32_16x16x32_bf16 v[4:7], v[136:139], v[156:159], v[4:7]
	s_mov_b32 s24, 0x280
	s_mov_b32 s25, 0
	s_mov_b32 m0, s30
	v_lshl_add_u64 v[124:125], v[64:65], 0, s[24:25]
	global_load_lds_dwordx4 v[124:125], off
	v_mfma_f32_16x16x32_bf16 v[8:11], v[136:139], v[160:163], v[8:11]
	v_mfma_f32_16x16x32_bf16 v[12:15], v[136:139], v[164:167], v[12:15]
	v_mfma_f32_16x16x32_bf16 v[16:19], v[140:143], v[152:155], v[16:19]
	v_mfma_f32_16x16x32_bf16 v[20:23], v[140:143], v[156:159], v[20:23]
	v_mfma_f32_16x16x32_bf16 v[24:27], v[140:143], v[160:163], v[24:27]
	s_add_u32 m0, s30, 0x2000
	v_lshl_add_u64 v[126:127], v[66:67], 0, s[24:25]
	global_load_lds_dwordx4 v[126:127], off
	v_mfma_f32_16x16x32_bf16 v[28:31], v[140:143], v[164:167], v[28:31]
	v_mfma_f32_16x16x32_bf16 v[32:35], v[144:147], v[152:155], v[32:35]
	v_mfma_f32_16x16x32_bf16 v[36:39], v[144:147], v[156:159], v[36:39]
	v_mfma_f32_16x16x32_bf16 v[40:43], v[144:147], v[160:163], v[40:43]
	v_mfma_f32_16x16x32_bf16 v[44:47], v[144:147], v[164:167], v[44:47]
	s_add_u32 m0, s30, 0x4000
	v_lshl_add_u64 v[124:125], v[68:69], 0, s[24:25]
	global_load_lds_dwordx4 v[124:125], off
	v_mfma_f32_16x16x32_bf16 v[48:51], v[148:151], v[152:155], v[48:51]
	v_mfma_f32_16x16x32_bf16 v[52:55], v[148:151], v[156:159], v[52:55]
	v_mfma_f32_16x16x32_bf16 v[56:59], v[148:151], v[160:163], v[56:59]
	v_mfma_f32_16x16x32_bf16 v[60:63], v[148:151], v[164:167], v[60:63]
	ds_read_b128 v[136:139], v77 offset:49152
	ds_read_b128 v[140:143], v77 offset:51200
	ds_read_b128 v[144:147], v77 offset:53248
	ds_read_b128 v[148:151], v77 offset:55296
	ds_read_b128 v[152:155], v79 offset:49152
	ds_read_b128 v[156:159], v79 offset:51200
	ds_read_b128 v[160:163], v79 offset:53248
	ds_read_b128 v[164:167], v79 offset:55296
	s_waitcnt lgkmcnt(8)
	v_mfma_f32_16x16x32_bf16 v[0:3], v[84:87], v[100:103], v[0:3]
	v_mfma_f32_16x16x32_bf16 v[4:7], v[84:87], v[104:107], v[4:7]
	s_add_u32 m0, s30, 0x6000
	v_lshl_add_u64 v[126:127], v[70:71], 0, s[24:25]
	global_load_lds_dwordx4 v[126:127], off
	v_mfma_f32_16x16x32_bf16 v[8:11], v[84:87], v[108:111], v[8:11]
	v_mfma_f32_16x16x32_bf16 v[12:15], v[84:87], v[112:115], v[12:15]
	v_mfma_f32_16x16x32_bf16 v[16:19], v[88:91], v[100:103], v[16:19]
	v_mfma_f32_16x16x32_bf16 v[20:23], v[88:91], v[104:107], v[20:23]
	v_mfma_f32_16x16x32_bf16 v[24:27], v[88:91], v[108:111], v[24:27]
	s_add_u32 m0, s30, 0x8000
	v_lshl_add_u64 v[124:125], v[72:73], 0, s[24:25]
	global_load_lds_dwordx4 v[124:125], off
	v_mfma_f32_16x16x32_bf16 v[28:31], v[88:91], v[112:115], v[28:31]
	v_mfma_f32_16x16x32_bf16 v[32:35], v[92:95], v[100:103], v[32:35]
	v_mfma_f32_16x16x32_bf16 v[36:39], v[92:95], v[104:107], v[36:39]
	v_mfma_f32_16x16x32_bf16 v[40:43], v[92:95], v[108:111], v[40:43]
	v_mfma_f32_16x16x32_bf16 v[44:47], v[92:95], v[112:115], v[44:47]
	s_add_u32 m0, s30, 0xa000
	v_lshl_add_u64 v[126:127], v[74:75], 0, s[24:25]
	global_load_lds_dwordx4 v[126:127], off
	v_mfma_f32_16x16x32_bf16 v[48:51], v[96:99], v[100:103], v[48:51]
	v_mfma_f32_16x16x32_bf16 v[52:55], v[96:99], v[104:107], v[52:55]
	v_mfma_f32_16x16x32_bf16 v[56:59], v[96:99], v[108:111], v[56:59]
	v_mfma_f32_16x16x32_bf16 v[60:63], v[96:99], v[112:115], v[60:63]
	s_waitcnt vmcnt(6) lgkmcnt(0)
	s_barrier
;     ...
;   for (int kt = 0; kt < nk; ++kt) {
;     if (kt + 1 < nk) asm volatile("s_waitcnt vmcnt(6)" ::: "memory");
;     else asm volatile("s_waitcnt vmcnt(0)" ::: "memory");
;     __builtin_amdgcn_s_barrier();
;     asm volatile("" ::: "memory");
;     if (kt + 2 < nk) { const int st2 = (st >= 1) ? st - 1 : 2; GEMM_ISSUE(kt + 2, st2); }
;     const char* la = lds + st * STAGE_B;
;     const char* lb = la + 32768;
;     const unsigned sa_u = (unsigned)(size_t)la + arow_u, sb_u = (unsigned)(size_t)lb + brow_u;
;     const unsigned a0 = sa_u + co0, a1 = sa_u + co1, a2 = sa_u + co2, a3 = sa_u + co3;
;     const unsigned b0 = sb_u + co0, b1 = sb_u + co1, b2 = sb_u + co2, b3 = sb_u + co3;
;     {
;       bf16x8 p0, p1, q0, q1, u0, u1, w0, w1;
;       asm volatile(
;         "ds_read_b128 %4, %12\n\tds_read_b128 %5, %12 offset:4096\n\tds_read_b128 %6, %16\n\tds_read_b128 %7, %16 offset:4096\n\t"
;         "ds_read_b128 %8, %13\n\tds_read_b128 %9, %13 offset:4096\n\tds_read_b128 %10, %17\n\tds_read_b128 %11, %17 offset:4096\n\t"
;         "s_waitcnt lgkmcnt(4)\n\t"
;         "v_mfma_f32_32x32x16_bf16 %0, %4, %6, %0\n\tv_mfma_f32_32x32x16_bf16 %1, %4, %7, %1\n\tv_mfma_f32_32x32x16_bf16 %2, %5, %6, %2\n\tv_mfma_f32_32x32x16_bf16 %3, %5, %7, %3\n\t"
;         "ds_read_b128 %4, %14\n\tds_read_b128 %5, %14 offset:4096\n\tds_read_b128 %6, %18\n\tds_read_b128 %7, %18 offset:4096\n\t"
;         "s_waitcnt lgkmcnt(4)\n\t"
;         "v_mfma_f32_32x32x16_bf16 %0, %8, %10, %0\n\tv_mfma_f32_32x32x16_bf16 %1, %8, %11, %1\n\tv_mfma_f32_32x32x16_bf16 %2, %9, %10, %2\n\tv_mfma_f32_32x32x16_bf16 %3, %9, %11, %3\n\t"
;         "ds_read_b128 %8, %15\n\tds_read_b128 %9, %15 offset:4096\n\tds_read_b128 %10, %19\n\tds_read_b128 %11, %19 offset:4096\n\t"
;         "s_waitcnt lgkmcnt(4)\n\t"
;         "v_mfma_f32_32x32x16_bf16 %0, %4, %6, %0\n\tv_mfma_f32_32x32x16_bf16 %1, %4, %7, %1\n\tv_mfma_f32_32x32x16_bf16 %2, %5, %6, %2\n\tv_mfma_f32_32x32x16_bf16 %3, %5, %7, %3\n\t"
;         "s_waitcnt lgkmcnt(0)\n\t"
;         "v_mfma_f32_32x32x16_bf16 %0, %8, %10, %0\n\tv_mfma_f32_32x32x16_bf16 %1, %8, %11, %1\n\tv_mfma_f32_32x32x16_bf16 %2, %9, %10, %2\n\tv_mfma_f32_32x32x16_bf16 %3, %9, %11, %3"
;         : "+v"(acc[0][0]), "+v"(acc[0][1]), "+v"(acc[1][0]), "+v"(acc[1][1]),
;           "=&v"(p0), "=&v"(p1), "=&v"(q0), "=&v"(q1), "=&v"(u0), "=&v"(u1), "=&v"(w0), "=&v"(w1)
	ds_read_b128 v[84:87], v80
	ds_read_b128 v[88:91], v80 offset:2048
	ds_read_b128 v[92:95], v80 offset:4096
	ds_read_b128 v[96:99], v80 offset:6144
	ds_read_b128 v[100:103], v82
	ds_read_b128 v[104:107], v82 offset:2048
	ds_read_b128 v[108:111], v82 offset:4096
	ds_read_b128 v[112:115], v82 offset:6144
	v_mfma_f32_16x16x32_bf16 v[0:3], v[136:139], v[152:155], v[0:3]
	v_mfma_f32_16x16x32_bf16 v[4:7], v[136:139], v[156:159], v[4:7]
	s_mov_b32 s24, 0x300
	s_mov_b32 s25, 0
	s_add_u32 m0, s30, 0xc000
	v_lshl_add_u64 v[124:125], v[64:65], 0, s[24:25]
	global_load_lds_dwordx4 v[124:125], off
	v_mfma_f32_16x16x32_bf16 v[8:11], v[136:139], v[160:163], v[8:11]
	v_mfma_f32_16x16x32_bf16 v[12:15], v[136:139], v[164:167], v[12:15]
	v_mfma_f32_16x16x32_bf16 v[16:19], v[140:143], v[152:155], v[16:19]
	v_mfma_f32_16x16x32_bf16 v[20:23], v[140:143], v[156:159], v[20:23]
	v_mfma_f32_16x16x32_bf16 v[24:27], v[140:143], v[160:163], v[24:27]
	s_add_u32 m0, s30, 0xe000
	v_lshl_add_u64 v[126:127], v[66:67], 0, s[24:25]
	global_load_lds_dwordx4 v[126:127], off
	v_mfma_f32_16x16x32_bf16 v[28:31], v[140:143], v[164:167], v[28:31]
	v_mfma_f32_16x16x32_bf16 v[32:35], v[144:147], v[152:155], v[32:35]
	v_mfma_f32_16x16x32_bf16 v[36:39], v[144:147], v[156:159], v[36:39]
	v_mfma_f32_16x16x32_bf16 v[40:43], v[144:147], v[160:163], v[40:43]
	v_mfma_f32_16x16x32_bf16 v[44:47], v[144:147], v[164:167], v[44:47]
	s_add_u32 m0, s30, 0x10000
	v_lshl_add_u64 v[124:125], v[68:69], 0, s[24:25]
	global_load_lds_dwordx4 v[124:125], off
	v_mfma_f32_16x16x32_bf16 v[48:51], v[148:151], v[152:155], v[48:51]
	v_mfma_f32_16x16x32_bf16 v[52:55], v[148:151], v[156:159], v[52:55]
	v_mfma_f32_16x16x32_bf16 v[56:59], v[148:151], v[160:163], v[56:59]
	v_mfma_f32_16x16x32_bf16 v[60:63], v[148:151], v[164:167], v[60:63]
	ds_read_b128 v[136:139], v81
	ds_read_b128 v[140:143], v81 offset:2048
	ds_read_b128 v[144:147], v81 offset:4096
	ds_read_b128 v[148:151], v81 offset:6144
	ds_read_b128 v[152:155], v83
	ds_read_b128 v[156:159], v83 offset:2048
	ds_read_b128 v[160:163], v83 offset:4096
	ds_read_b128 v[164:167], v83 offset:6144
	s_waitcnt lgkmcnt(8)
	v_mfma_f32_16x16x32_bf16 v[0:3], v[84:87], v[100:103], v[0:3]
	v_mfma_f32_16x16x32_bf16 v[4:7], v[84:87], v[104:107], v[4:7]
	s_add_u32 m0, s30, 0x12000
	v_lshl_add_u64 v[126:127], v[70:71], 0, s[24:25]
	global_load_lds_dwordx4 v[126:127], off
	v_mfma_f32_16x16x32_bf16 v[8:11], v[84:87], v[108:111], v[8:11]
	v_mfma_f32_16x16x32_bf16 v[12:15], v[84:87], v[112:115], v[12:15]
	v_mfma_f32_16x16x32_bf16 v[16:19], v[88:91], v[100:103], v[16:19]
	v_mfma_f32_16x16x32_bf16 v[20:23], v[88:91], v[104:107], v[20:23]
	v_mfma_f32_16x16x32_bf16 v[24:27], v[88:91], v[108:111], v[24:27]
	s_add_u32 m0, s30, 0x14000
	v_lshl_add_u64 v[124:125], v[72:73], 0, s[24:25]
	global_load_lds_dwordx4 v[124:125], off
	v_mfma_f32_16x16x32_bf16 v[28:31], v[88:91], v[112:115], v[28:31]
	v_mfma_f32_16x16x32_bf16 v[32:35], v[92:95], v[100:103], v[32:35]
	v_mfma_f32_16x16x32_bf16 v[36:39], v[92:95], v[104:107], v[36:39]
	v_mfma_f32_16x16x32_bf16 v[40:43], v[92:95], v[108:111], v[40:43]
	v_mfma_f32_16x16x32_bf16 v[44:47], v[92:95], v[112:115], v[44:47]
	s_add_u32 m0, s30, 0x16000
	v_lshl_add_u64 v[126:127], v[74:75], 0, s[24:25]
	global_load_lds_dwordx4 v[126:127], off
	v_mfma_f32_16x16x32_bf16 v[48:51], v[96:99], v[100:103], v[48:51]
	v_mfma_f32_16x16x32_bf16 v[52:55], v[96:99], v[104:107], v[52:55]
	v_mfma_f32_16x16x32_bf16 v[56:59], v[96:99], v[108:111], v[56:59]
	v_mfma_f32_16x16x32_bf16 v[60:63], v[96:99], v[112:115], v[60:63]
	s_waitcnt vmcnt(6) lgkmcnt(0)
	s_barrier
	ds_read_b128 v[84:87], v76
	ds_read_b128 v[88:91], v76 offset:2048
	ds_read_b128 v[92:95], v76 offset:4096
	ds_read_b128 v[96:99], v76 offset:6144
	ds_read_b128 v[100:103], v78
	ds_read_b128 v[104:107], v78 offset:2048
	ds_read_b128 v[108:111], v78 offset:4096
	ds_read_b128 v[112:115], v78 offset:6144
	v_mfma_f32_16x16x32_bf16 v[0:3], v[136:139], v[152:155], v[0:3]
	v_mfma_f32_16x16x32_bf16 v[4:7], v[136:139], v[156:159], v[4:7]
	s_mov_b32 s24, 0x380
	s_mov_b32 s25, 0
	s_add_u32 m0, s30, 0x18000
	v_lshl_add_u64 v[124:125], v[64:65], 0, s[24:25]
	global_load_lds_dwordx4 v[124:125], off
	v_mfma_f32_16x16x32_bf16 v[8:11], v[136:139], v[160:163], v[8:11]
	v_mfma_f32_16x16x32_bf16 v[12:15], v[136:139], v[164:167], v[12:15]
	v_mfma_f32_16x16x32_bf16 v[16:19], v[140:143], v[152:155], v[16:19]
	v_mfma_f32_16x16x32_bf16 v[20:23], v[140:143], v[156:159], v[20:23]
	v_mfma_f32_16x16x32_bf16 v[24:27], v[140:143], v[160:163], v[24:27]
	s_add_u32 m0, s30, 0x1a000
	v_lshl_add_u64 v[126:127], v[66:67], 0, s[24:25]
	global_load_lds_dwordx4 v[126:127], off
	v_mfma_f32_16x16x32_bf16 v[28:31], v[140:143], v[164:167], v[28:31]
	v_mfma_f32_16x16x32_bf16 v[32:35], v[144:147], v[152:155], v[32:35]
	v_mfma_f32_16x16x32_bf16 v[36:39], v[144:147], v[156:159], v[36:39]
	v_mfma_f32_16x16x32_bf16 v[40:43], v[144:147], v[160:163], v[40:43]
	v_mfma_f32_16x16x32_bf16 v[44:47], v[144:147], v[164:167], v[44:47]
	s_add_u32 m0, s30, 0x1c000
	v_lshl_add_u64 v[124:125], v[68:69], 0, s[24:25]
	global_load_lds_dwordx4 v[124:125], off
	v_mfma_f32_16x16x32_bf16 v[48:51], v[148:151], v[152:155], v[48:51]
	v_mfma_f32_16x16x32_bf16 v[52:55], v[148:151], v[156:159], v[52:55]
	v_mfma_f32_16x16x32_bf16 v[56:59], v[148:151], v[160:163], v[56:59]
	v_mfma_f32_16x16x32_bf16 v[60:63], v[148:151], v[164:167], v[60:63]
	ds_read_b128 v[136:139], v77
	ds_read_b128 v[140:143], v77 offset:2048
	ds_read_b128 v[144:147], v77 offset:4096
	ds_read_b128 v[148:151], v77 offset:6144
	ds_read_b128 v[152:155], v79
	ds_read_b128 v[156:159], v79 offset:2048
	ds_read_b128 v[160:163], v79 offset:4096
	ds_read_b128 v[164:167], v79 offset:6144
	s_waitcnt lgkmcnt(8)
;     ...
;   for (int kt = 0; kt < nk; ++kt) {
;     if (kt + 1 < nk) asm volatile("s_waitcnt vmcnt(6)" ::: "memory");
;     else asm volatile("s_waitcnt vmcnt(0)" ::: "memory");
;     __builtin_amdgcn_s_barrier();
;     asm volatile("" ::: "memory");
;     if (kt + 2 < nk) { const int st2 = (st >= 1) ? st - 1 : 2; GEMM_ISSUE(kt + 2, st2); }
;     const char* la = lds + st * STAGE_B;
;     const char* lb = la + 32768;
;     const unsigned sa_u = (unsigned)(size_t)la + arow_u, sb_u = (unsigned)(size_t)lb + brow_u;
;     const unsigned a0 = sa_u + co0, a1 = sa_u + co1, a2 = sa_u + co2, a3 = sa_u + co3;
;     const unsigned b0 = sb_u + co0, b1 = sb_u + co1, b2 = sb_u + co2, b3 = sb_u + co3;
;     {
;       bf16x8 p0, p1, q0, q1, u0, u1, w0, w1;
;       asm volatile(
;         "ds_read_b128 %4, %12\n\tds_read_b128 %5, %12 offset:4096\n\tds_read_b128 %6, %16\n\tds_read_b128 %7, %16 offset:4096\n\t"
;         "ds_read_b128 %8, %13\n\tds_read_b128 %9, %13 offset:4096\n\tds_read_b128 %10, %17\n\tds_read_b128 %11, %17 offset:4096\n\t"
;         "s_waitcnt lgkmcnt(4)\n\t"
;         "v_mfma_f32_32x32x16_bf16 %0, %4, %6, %0\n\tv_mfma_f32_32x32x16_bf16 %1, %4, %7, %1\n\tv_mfma_f32_32x32x16_bf16 %2, %5, %6, %2\n\tv_mfma_f32_32x32x16_bf16 %3, %5, %7, %3\n\t"
;         "ds_read_b128 %4, %14\n\tds_read_b128 %5, %14 offset:4096\n\tds_read_b128 %6, %18\n\tds_read_b128 %7, %18 offset:4096\n\t"
;         "s_waitcnt lgkmcnt(4)\n\t"
;         "v_mfma_f32_32x32x16_bf16 %0, %8, %10, %0\n\tv_mfma_f32_32x32x16_bf16 %1, %8, %11, %1\n\tv_mfma_f32_32x32x16_bf16 %2, %9, %10, %2\n\tv_mfma_f32_32x32x16_bf16 %3, %9, %11, %3\n\t"
;         "ds_read_b128 %8, %15\n\tds_read_b128 %9, %15 offset:4096\n\tds_read_b128 %10, %19\n\tds_read_b128 %11, %19 offset:4096\n\t"
;         "s_waitcnt lgkmcnt(4)\n\t"
;         "v_mfma_f32_32x32x16_bf16 %0, %4, %6, %0\n\tv_mfma_f32_32x32x16_bf16 %1, %4, %7, %1\n\tv_mfma_f32_32x32x16_bf16 %2, %5, %6, %2\n\tv_mfma_f32_32x32x16_bf16 %3, %5, %7, %3\n\t"
;         "s_waitcnt lgkmcnt(0)\n\t"
;         "v_mfma_f32_32x32x16_bf16 %0, %8, %10, %0\n\tv_mfma_f32_32x32x16_bf16 %1, %8, %11, %1\n\tv_mfma_f32_32x32x16_bf16 %2, %9, %10, %2\n\tv_mfma_f32_32x32x16_bf16 %3, %9, %11, %3"
;         : "+v"(acc[0][0]), "+v"(acc[0][1]), "+v"(acc[1][0]), "+v"(acc[1][1]),
;           "=&v"(p0), "=&v"(p1), "=&v"(q0), "=&v"(q1), "=&v"(u0), "=&v"(u1), "=&v"(w0), "=&v"(w1)
	v_mfma_f32_16x16x32_bf16 v[0:3], v[84:87], v[100:103], v[0:3]
	v_mfma_f32_16x16x32_bf16 v[4:7], v[84:87], v[104:107], v[4:7]
	s_add_u32 m0, s30, 0x1e000
	v_lshl_add_u64 v[126:127], v[70:71], 0, s[24:25]
	global_load_lds_dwordx4 v[126:127], off
	v_mfma_f32_16x16x32_bf16 v[8:11], v[84:87], v[108:111], v[8:11]
	v_mfma_f32_16x16x32_bf16 v[12:15], v[84:87], v[112:115], v[12:15]
	v_mfma_f32_16x16x32_bf16 v[16:19], v[88:91], v[100:103], v[16:19]
	v_mfma_f32_16x16x32_bf16 v[20:23], v[88:91], v[104:107], v[20:23]
	v_mfma_f32_16x16x32_bf16 v[24:27], v[88:91], v[108:111], v[24:27]
	s_add_u32 m0, s30, 0x20000
	v_lshl_add_u64 v[124:125], v[72:73], 0, s[24:25]
	global_load_lds_dwordx4 v[124:125], off
	v_mfma_f32_16x16x32_bf16 v[28:31], v[88:91], v[112:115], v[28:31]
	v_mfma_f32_16x16x32_bf16 v[32:35], v[92:95], v[100:103], v[32:35]
	v_mfma_f32_16x16x32_bf16 v[36:39], v[92:95], v[104:107], v[36:39]
	v_mfma_f32_16x16x32_bf16 v[40:43], v[92:95], v[108:111], v[40:43]
	v_mfma_f32_16x16x32_bf16 v[44:47], v[92:95], v[112:115], v[44:47]
	s_add_u32 m0, s30, 0x22000
	v_lshl_add_u64 v[126:127], v[74:75], 0, s[24:25]
	global_load_lds_dwordx4 v[126:127], off
	v_mfma_f32_16x16x32_bf16 v[48:51], v[96:99], v[100:103], v[48:51]
	v_mfma_f32_16x16x32_bf16 v[52:55], v[96:99], v[104:107], v[52:55]
	v_mfma_f32_16x16x32_bf16 v[56:59], v[96:99], v[108:111], v[56:59]
	v_mfma_f32_16x16x32_bf16 v[60:63], v[96:99], v[112:115], v[60:63]
	s_waitcnt vmcnt(6) lgkmcnt(0)
	s_barrier
	ds_read_b128 v[84:87], v76 offset:49152
	ds_read_b128 v[88:91], v76 offset:51200
	ds_read_b128 v[92:95], v76 offset:53248
	ds_read_b128 v[96:99], v76 offset:55296
	ds_read_b128 v[100:103], v78 offset:49152
	ds_read_b128 v[104:107], v78 offset:51200
	ds_read_b128 v[108:111], v78 offset:53248
	ds_read_b128 v[112:115], v78 offset:55296
	v_mfma_f32_16x16x32_bf16 v[0:3], v[136:139], v[152:155], v[0:3]
	v_mfma_f32_16x16x32_bf16 v[4:7], v[136:139], v[156:159], v[4:7]
	s_mov_b32 s24, 0x400
	s_mov_b32 s25, 0
	s_mov_b32 m0, s30
	v_lshl_add_u64 v[124:125], v[64:65], 0, s[24:25]
	global_load_lds_dwordx4 v[124:125], off
	v_mfma_f32_16x16x32_bf16 v[8:11], v[136:139], v[160:163], v[8:11]
	v_mfma_f32_16x16x32_bf16 v[12:15], v[136:139], v[164:167], v[12:15]
	v_mfma_f32_16x16x32_bf16 v[16:19], v[140:143], v[152:155], v[16:19]
	v_mfma_f32_16x16x32_bf16 v[20:23], v[140:143], v[156:159], v[20:23]
	v_mfma_f32_16x16x32_bf16 v[24:27], v[140:143], v[160:163], v[24:27]
	s_add_u32 m0, s30, 0x2000
	v_lshl_add_u64 v[126:127], v[66:67], 0, s[24:25]
	global_load_lds_dwordx4 v[126:127], off
	v_mfma_f32_16x16x32_bf16 v[28:31], v[140:143], v[164:167], v[28:31]
	v_mfma_f32_16x16x32_bf16 v[32:35], v[144:147], v[152:155], v[32:35]
	v_mfma_f32_16x16x32_bf16 v[36:39], v[144:147], v[156:159], v[36:39]
	v_mfma_f32_16x16x32_bf16 v[40:43], v[144:147], v[160:163], v[40:43]
	v_mfma_f32_16x16x32_bf16 v[44:47], v[144:147], v[164:167], v[44:47]
	s_add_u32 m0, s30, 0x4000
	v_lshl_add_u64 v[124:125], v[68:69], 0, s[24:25]
	global_load_lds_dwordx4 v[124:125], off
	v_mfma_f32_16x16x32_bf16 v[48:51], v[148:151], v[152:155], v[48:51]
	v_mfma_f32_16x16x32_bf16 v[52:55], v[148:151], v[156:159], v[52:55]
	v_mfma_f32_16x16x32_bf16 v[56:59], v[148:151], v[160:163], v[56:59]
	v_mfma_f32_16x16x32_bf16 v[60:63], v[148:151], v[164:167], v[60:63]
	ds_read_b128 v[136:139], v77 offset:49152
	ds_read_b128 v[140:143], v77 offset:51200
	ds_read_b128 v[144:147], v77 offset:53248
	ds_read_b128 v[148:151], v77 offset:55296
	ds_read_b128 v[152:155], v79 offset:49152
	ds_read_b128 v[156:159], v79 offset:51200
	ds_read_b128 v[160:163], v79 offset:53248
	ds_read_b128 v[164:167], v79 offset:55296
	s_waitcnt lgkmcnt(8)
	v_mfma_f32_16x16x32_bf16 v[0:3], v[84:87], v[100:103], v[0:3]
	v_mfma_f32_16x16x32_bf16 v[4:7], v[84:87], v[104:107], v[4:7]
	s_add_u32 m0, s30, 0x6000
	v_lshl_add_u64 v[126:127], v[70:71], 0, s[24:25]
	global_load_lds_dwordx4 v[126:127], off
	v_mfma_f32_16x16x32_bf16 v[8:11], v[84:87], v[108:111], v[8:11]
	v_mfma_f32_16x16x32_bf16 v[12:15], v[84:87], v[112:115], v[12:15]
	v_mfma_f32_16x16x32_bf16 v[16:19], v[88:91], v[100:103], v[16:19]
	v_mfma_f32_16x16x32_bf16 v[20:23], v[88:91], v[104:107], v[20:23]
	v_mfma_f32_16x16x32_bf16 v[24:27], v[88:91], v[108:111], v[24:27]
	s_add_u32 m0, s30, 0x8000
	v_lshl_add_u64 v[124:125], v[72:73], 0, s[24:25]
	global_load_lds_dwordx4 v[124:125], off
	v_mfma_f32_16x16x32_bf16 v[28:31], v[88:91], v[112:115], v[28:31]
	v_mfma_f32_16x16x32_bf16 v[32:35], v[92:95], v[100:103], v[32:35]
	v_mfma_f32_16x16x32_bf16 v[36:39], v[92:95], v[104:107], v[36:39]
	v_mfma_f32_16x16x32_bf16 v[40:43], v[92:95], v[108:111], v[40:43]
	v_mfma_f32_16x16x32_bf16 v[44:47], v[92:95], v[112:115], v[44:47]
	s_add_u32 m0, s30, 0xa000
	v_lshl_add_u64 v[126:127], v[74:75], 0, s[24:25]
	global_load_lds_dwordx4 v[126:127], off
	v_mfma_f32_16x16x32_bf16 v[48:51], v[96:99], v[100:103], v[48:51]
	v_mfma_f32_16x16x32_bf16 v[52:55], v[96:99], v[104:107], v[52:55]
	v_mfma_f32_16x16x32_bf16 v[56:59], v[96:99], v[108:111], v[56:59]
	v_mfma_f32_16x16x32_bf16 v[60:63], v[96:99], v[112:115], v[60:63]
	s_waitcnt vmcnt(6) lgkmcnt(0)
	s_barrier
;     ...
;   for (int kt = 0; kt < nk; ++kt) {
;     if (kt + 1 < nk) asm volatile("s_waitcnt vmcnt(6)" ::: "memory");
;     else asm volatile("s_waitcnt vmcnt(0)" ::: "memory");
;     __builtin_amdgcn_s_barrier();
;     asm volatile("" ::: "memory");
;     if (kt + 2 < nk) { const int st2 = (st >= 1) ? st - 1 : 2; GEMM_ISSUE(kt + 2, st2); }
;     const char* la = lds + st * STAGE_B;
;     const char* lb = la + 32768;
;     const unsigned sa_u = (unsigned)(size_t)la + arow_u, sb_u = (unsigned)(size_t)lb + brow_u;
;     const unsigned a0 = sa_u + co0, a1 = sa_u + co1, a2 = sa_u + co2, a3 = sa_u + co3;
;     const unsigned b0 = sb_u + co0, b1 = sb_u + co1, b2 = sb_u + co2, b3 = sb_u + co3;
;     {
;       bf16x8 p0, p1, q0, q1, u0, u1, w0, w1;
;       asm volatile(
;         "ds_read_b128 %4, %12\n\tds_read_b128 %5, %12 offset:4096\n\tds_read_b128 %6, %16\n\tds_read_b128 %7, %16 offset:4096\n\t"
;         "ds_read_b128 %8, %13\n\tds_read_b128 %9, %13 offset:4096\n\tds_read_b128 %10, %17\n\tds_read_b128 %11, %17 offset:4096\n\t"
;         "s_waitcnt lgkmcnt(4)\n\t"
;         "v_mfma_f32_32x32x16_bf16 %0, %4, %6, %0\n\tv_mfma_f32_32x32x16_bf16 %1, %4, %7, %1\n\tv_mfma_f32_32x32x16_bf16 %2, %5, %6, %2\n\tv_mfma_f32_32x32x16_bf16 %3, %5, %7, %3\n\t"
;         "ds_read_b128 %4, %14\n\tds_read_b128 %5, %14 offset:4096\n\tds_read_b128 %6, %18\n\tds_read_b128 %7, %18 offset:4096\n\t"
;         "s_waitcnt lgkmcnt(4)\n\t"
;         "v_mfma_f32_32x32x16_bf16 %0, %8, %10, %0\n\tv_mfma_f32_32x32x16_bf16 %1, %8, %11, %1\n\tv_mfma_f32_32x32x16_bf16 %2, %9, %10, %2\n\tv_mfma_f32_32x32x16_bf16 %3, %9, %11, %3\n\t"
;         "ds_read_b128 %8, %15\n\tds_read_b128 %9, %15 offset:4096\n\tds_read_b128 %10, %19\n\tds_read_b128 %11, %19 offset:4096\n\t"
;         "s_waitcnt lgkmcnt(4)\n\t"
;         "v_mfma_f32_32x32x16_bf16 %0, %4, %6, %0\n\tv_mfma_f32_32x32x16_bf16 %1, %4, %7, %1\n\tv_mfma_f32_32x32x16_bf16 %2, %5, %6, %2\n\tv_mfma_f32_32x32x16_bf16 %3, %5, %7, %3\n\t"
;         "s_waitcnt lgkmcnt(0)\n\t"
;         "v_mfma_f32_32x32x16_bf16 %0, %8, %10, %0\n\tv_mfma_f32_32x32x16_bf16 %1, %8, %11, %1\n\tv_mfma_f32_32x32x16_bf16 %2, %9, %10, %2\n\tv_mfma_f32_32x32x16_bf16 %3, %9, %11, %3"
;         : "+v"(acc[0][0]), "+v"(acc[0][1]), "+v"(acc[1][0]), "+v"(acc[1][1]),
;           "=&v"(p0), "=&v"(p1), "=&v"(q0), "=&v"(q1), "=&v"(u0), "=&v"(u1), "=&v"(w0), "=&v"(w1)
	ds_read_b128 v[84:87], v80
	ds_read_b128 v[88:91], v80 offset:2048
	ds_read_b128 v[92:95], v80 offset:4096
	ds_read_b128 v[96:99], v80 offset:6144
	ds_read_b128 v[100:103], v82
	ds_read_b128 v[104:107], v82 offset:2048
	ds_read_b128 v[108:111], v82 offset:4096
	ds_read_b128 v[112:115], v82 offset:6144
	v_mfma_f32_16x16x32_bf16 v[0:3], v[136:139], v[152:155], v[0:3]
	v_mfma_f32_16x16x32_bf16 v[4:7], v[136:139], v[156:159], v[4:7]
	s_mov_b32 s24, 0x480
	s_mov_b32 s25, 0
	s_add_u32 m0, s30, 0xc000
	v_lshl_add_u64 v[124:125], v[64:65], 0, s[24:25]
	global_load_lds_dwordx4 v[124:125], off
	v_mfma_f32_16x16x32_bf16 v[8:11], v[136:139], v[160:163], v[8:11]
	v_mfma_f32_16x16x32_bf16 v[12:15], v[136:139], v[164:167], v[12:15]
	v_mfma_f32_16x16x32_bf16 v[16:19], v[140:143], v[152:155], v[16:19]
	v_mfma_f32_16x16x32_bf16 v[20:23], v[140:143], v[156:159], v[20:23]
	v_mfma_f32_16x16x32_bf16 v[24:27], v[140:143], v[160:163], v[24:27]
	s_add_u32 m0, s30, 0xe000
	v_lshl_add_u64 v[126:127], v[66:67], 0, s[24:25]
	global_load_lds_dwordx4 v[126:127], off
	v_mfma_f32_16x16x32_bf16 v[28:31], v[140:143], v[164:167], v[28:31]
	v_mfma_f32_16x16x32_bf16 v[32:35], v[144:147], v[152:155], v[32:35]
	v_mfma_f32_16x16x32_bf16 v[36:39], v[144:147], v[156:159], v[36:39]
	v_mfma_f32_16x16x32_bf16 v[40:43], v[144:147], v[160:163], v[40:43]
	v_mfma_f32_16x16x32_bf16 v[44:47], v[144:147], v[164:167], v[44:47]
	s_add_u32 m0, s30, 0x10000
	v_lshl_add_u64 v[124:125], v[68:69], 0, s[24:25]
	global_load_lds_dwordx4 v[124:125], off
	v_mfma_f32_16x16x32_bf16 v[48:51], v[148:151], v[152:155], v[48:51]
	v_mfma_f32_16x16x32_bf16 v[52:55], v[148:151], v[156:159], v[52:55]
	v_mfma_f32_16x16x32_bf16 v[56:59], v[148:151], v[160:163], v[56:59]
	v_mfma_f32_16x16x32_bf16 v[60:63], v[148:151], v[164:167], v[60:63]
	ds_read_b128 v[136:139], v81
	ds_read_b128 v[140:143], v81 offset:2048
	ds_read_b128 v[144:147], v81 offset:4096
	ds_read_b128 v[148:151], v81 offset:6144
	ds_read_b128 v[152:155], v83
	ds_read_b128 v[156:159], v83 offset:2048
	ds_read_b128 v[160:163], v83 offset:4096
	ds_read_b128 v[164:167], v83 offset:6144
	s_waitcnt lgkmcnt(8)
	v_mfma_f32_16x16x32_bf16 v[0:3], v[84:87], v[100:103], v[0:3]
	v_mfma_f32_16x16x32_bf16 v[4:7], v[84:87], v[104:107], v[4:7]
	s_add_u32 m0, s30, 0x12000
	v_lshl_add_u64 v[126:127], v[70:71], 0, s[24:25]
	global_load_lds_dwordx4 v[126:127], off
	v_mfma_f32_16x16x32_bf16 v[8:11], v[84:87], v[108:111], v[8:11]
	v_mfma_f32_16x16x32_bf16 v[12:15], v[84:87], v[112:115], v[12:15]
	v_mfma_f32_16x16x32_bf16 v[16:19], v[88:91], v[100:103], v[16:19]
	v_mfma_f32_16x16x32_bf16 v[20:23], v[88:91], v[104:107], v[20:23]
	v_mfma_f32_16x16x32_bf16 v[24:27], v[88:91], v[108:111], v[24:27]
	s_add_u32 m0, s30, 0x14000
	v_lshl_add_u64 v[124:125], v[72:73], 0, s[24:25]
	global_load_lds_dwordx4 v[124:125], off
	v_mfma_f32_16x16x32_bf16 v[28:31], v[88:91], v[112:115], v[28:31]
	v_mfma_f32_16x16x32_bf16 v[32:35], v[92:95], v[100:103], v[32:35]
	v_mfma_f32_16x16x32_bf16 v[36:39], v[92:95], v[104:107], v[36:39]
	v_mfma_f32_16x16x32_bf16 v[40:43], v[92:95], v[108:111], v[40:43]
	v_mfma_f32_16x16x32_bf16 v[44:47], v[92:95], v[112:115], v[44:47]
	s_add_u32 m0, s30, 0x16000
	v_lshl_add_u64 v[126:127], v[74:75], 0, s[24:25]
	global_load_lds_dwordx4 v[126:127], off
	v_mfma_f32_16x16x32_bf16 v[48:51], v[96:99], v[100:103], v[48:51]
	v_mfma_f32_16x16x32_bf16 v[52:55], v[96:99], v[104:107], v[52:55]
	v_mfma_f32_16x16x32_bf16 v[56:59], v[96:99], v[108:111], v[56:59]
	v_mfma_f32_16x16x32_bf16 v[60:63], v[96:99], v[112:115], v[60:63]
	s_waitcnt vmcnt(6) lgkmcnt(0)
	s_barrier
	ds_read_b128 v[84:87], v76
	ds_read_b128 v[88:91], v76 offset:2048
	ds_read_b128 v[92:95], v76 offset:4096
	ds_read_b128 v[96:99], v76 offset:6144
	ds_read_b128 v[100:103], v78
	ds_read_b128 v[104:107], v78 offset:2048
	ds_read_b128 v[108:111], v78 offset:4096
	ds_read_b128 v[112:115], v78 offset:6144
	v_mfma_f32_16x16x32_bf16 v[0:3], v[136:139], v[152:155], v[0:3]
	v_mfma_f32_16x16x32_bf16 v[4:7], v[136:139], v[156:159], v[4:7]
	s_mov_b32 s24, 0x500
	s_mov_b32 s25, 0
	s_add_u32 m0, s30, 0x18000
	v_lshl_add_u64 v[124:125], v[64:65], 0, s[24:25]
	global_load_lds_dwordx4 v[124:125], off
	v_mfma_f32_16x16x32_bf16 v[8:11], v[136:139], v[160:163], v[8:11]
	v_mfma_f32_16x16x32_bf16 v[12:15], v[136:139], v[164:167], v[12:15]
	v_mfma_f32_16x16x32_bf16 v[16:19], v[140:143], v[152:155], v[16:19]
	v_mfma_f32_16x16x32_bf16 v[20:23], v[140:143], v[156:159], v[20:23]
	v_mfma_f32_16x16x32_bf16 v[24:27], v[140:143], v[160:163], v[24:27]
	s_add_u32 m0, s30, 0x1a000
	v_lshl_add_u64 v[126:127], v[66:67], 0, s[24:25]
	global_load_lds_dwordx4 v[126:127], off
	v_mfma_f32_16x16x32_bf16 v[28:31], v[140:143], v[164:167], v[28:31]
	v_mfma_f32_16x16x32_bf16 v[32:35], v[144:147], v[152:155], v[32:35]
	v_mfma_f32_16x16x32_bf16 v[36:39], v[144:147], v[156:159], v[36:39]
	v_mfma_f32_16x16x32_bf16 v[40:43], v[144:147], v[160:163], v[40:43]
	v_mfma_f32_16x16x32_bf16 v[44:47], v[144:147], v[164:167], v[44:47]
	s_add_u32 m0, s30, 0x1c000
	v_lshl_add_u64 v[124:125], v[68:69], 0, s[24:25]
	global_load_lds_dwordx4 v[124:125], off
	v_mfma_f32_16x16x32_bf16 v[48:51], v[148:151], v[152:155], v[48:51]
	v_mfma_f32_16x16x32_bf16 v[52:55], v[148:151], v[156:159], v[52:55]
	v_mfma_f32_16x16x32_bf16 v[56:59], v[148:151], v[160:163], v[56:59]
	v_mfma_f32_16x16x32_bf16 v[60:63], v[148:151], v[164:167], v[60:63]
	ds_read_b128 v[136:139], v77
	ds_read_b128 v[140:143], v77 offset:2048
	ds_read_b128 v[144:147], v77 offset:4096
	ds_read_b128 v[148:151], v77 offset:6144
	ds_read_b128 v[152:155], v79
	ds_read_b128 v[156:159], v79 offset:2048
	ds_read_b128 v[160:163], v79 offset:4096
	ds_read_b128 v[164:167], v79 offset:6144
	s_waitcnt lgkmcnt(8)
;     ...
;   for (int kt = 0; kt < nk; ++kt) {
;     if (kt + 1 < nk) asm volatile("s_waitcnt vmcnt(6)" ::: "memory");
;     else asm volatile("s_waitcnt vmcnt(0)" ::: "memory");
;     __builtin_amdgcn_s_barrier();
;     asm volatile("" ::: "memory");
;     if (kt + 2 < nk) { const int st2 = (st >= 1) ? st - 1 : 2; GEMM_ISSUE(kt + 2, st2); }
;     const char* la = lds + st * STAGE_B;
;     const char* lb = la + 32768;
;     const unsigned sa_u = (unsigned)(size_t)la + arow_u, sb_u = (unsigned)(size_t)lb + brow_u;
;     const unsigned a0 = sa_u + co0, a1 = sa_u + co1, a2 = sa_u + co2, a3 = sa_u + co3;
;     const unsigned b0 = sb_u + co0, b1 = sb_u + co1, b2 = sb_u + co2, b3 = sb_u + co3;
;     {
;       bf16x8 p0, p1, q0, q1, u0, u1, w0, w1;
;       asm volatile(
;         "ds_read_b128 %4, %12\n\tds_read_b128 %5, %12 offset:4096\n\tds_read_b128 %6, %16\n\tds_read_b128 %7, %16 offset:4096\n\t"
;         "ds_read_b128 %8, %13\n\tds_read_b128 %9, %13 offset:4096\n\tds_read_b128 %10, %17\n\tds_read_b128 %11, %17 offset:4096\n\t"
;         "s_waitcnt lgkmcnt(4)\n\t"
;         "v_mfma_f32_32x32x16_bf16 %0, %4, %6, %0\n\tv_mfma_f32_32x32x16_bf16 %1, %4, %7, %1\n\tv_mfma_f32_32x32x16_bf16 %2, %5, %6, %2\n\tv_mfma_f32_32x32x16_bf16 %3, %5, %7, %3\n\t"
;         "ds_read_b128 %4, %14\n\tds_read_b128 %5, %14 offset:4096\n\tds_read_b128 %6, %18\n\tds_read_b128 %7, %18 offset:4096\n\t"
;         "s_waitcnt lgkmcnt(4)\n\t"
;         "v_mfma_f32_32x32x16_bf16 %0, %8, %10, %0\n\tv_mfma_f32_32x32x16_bf16 %1, %8, %11, %1\n\tv_mfma_f32_32x32x16_bf16 %2, %9, %10, %2\n\tv_mfma_f32_32x32x16_bf16 %3, %9, %11, %3\n\t"
;         "ds_read_b128 %8, %15\n\tds_read_b128 %9, %15 offset:4096\n\tds_read_b128 %10, %19\n\tds_read_b128 %11, %19 offset:4096\n\t"
;         "s_waitcnt lgkmcnt(4)\n\t"
;         "v_mfma_f32_32x32x16_bf16 %0, %4, %6, %0\n\tv_mfma_f32_32x32x16_bf16 %1, %4, %7, %1\n\tv_mfma_f32_32x32x16_bf16 %2, %5, %6, %2\n\tv_mfma_f32_32x32x16_bf16 %3, %5, %7, %3\n\t"
;         "s_waitcnt lgkmcnt(0)\n\t"
;         "v_mfma_f32_32x32x16_bf16 %0, %8, %10, %0\n\tv_mfma_f32_32x32x16_bf16 %1, %8, %11, %1\n\tv_mfma_f32_32x32x16_bf16 %2, %9, %10, %2\n\tv_mfma_f32_32x32x16_bf16 %3, %9, %11, %3"
;         : "+v"(acc[0][0]), "+v"(acc[0][1]), "+v"(acc[1][0]), "+v"(acc[1][1]),
;           "=&v"(p0), "=&v"(p1), "=&v"(q0), "=&v"(q1), "=&v"(u0), "=&v"(u1), "=&v"(w0), "=&v"(w1)
	v_mfma_f32_16x16x32_bf16 v[0:3], v[84:87], v[100:103], v[0:3]
	v_mfma_f32_16x16x32_bf16 v[4:7], v[84:87], v[104:107], v[4:7]
	s_add_u32 m0, s30, 0x1e000
	v_lshl_add_u64 v[126:127], v[70:71], 0, s[24:25]
	global_load_lds_dwordx4 v[126:127], off
	v_mfma_f32_16x16x32_bf16 v[8:11], v[84:87], v[108:111], v[8:11]
	v_mfma_f32_16x16x32_bf16 v[12:15], v[84:87], v[112:115], v[12:15]
	v_mfma_f32_16x16x32_bf16 v[16:19], v[88:91], v[100:103], v[16:19]
	v_mfma_f32_16x16x32_bf16 v[20:23], v[88:91], v[104:107], v[20:23]
	v_mfma_f32_16x16x32_bf16 v[24:27], v[88:91], v[108:111], v[24:27]
	s_add_u32 m0, s30, 0x20000
	v_lshl_add_u64 v[124:125], v[72:73], 0, s[24:25]
	global_load_lds_dwordx4 v[124:125], off
	v_mfma_f32_16x16x32_bf16 v[28:31], v[88:91], v[112:115], v[28:31]
	v_mfma_f32_16x16x32_bf16 v[32:35], v[92:95], v[100:103], v[32:35]
	v_mfma_f32_16x16x32_bf16 v[36:39], v[92:95], v[104:107], v[36:39]
	v_mfma_f32_16x16x32_bf16 v[40:43], v[92:95], v[108:111], v[40:43]
	v_mfma_f32_16x16x32_bf16 v[44:47], v[92:95], v[112:115], v[44:47]
	s_add_u32 m0, s30, 0x22000
	v_lshl_add_u64 v[126:127], v[74:75], 0, s[24:25]
	global_load_lds_dwordx4 v[126:127], off
	v_mfma_f32_16x16x32_bf16 v[48:51], v[96:99], v[100:103], v[48:51]
	v_mfma_f32_16x16x32_bf16 v[52:55], v[96:99], v[104:107], v[52:55]
	v_mfma_f32_16x16x32_bf16 v[56:59], v[96:99], v[108:111], v[56:59]
	v_mfma_f32_16x16x32_bf16 v[60:63], v[96:99], v[112:115], v[60:63]
	s_waitcnt vmcnt(6) lgkmcnt(0)
	s_barrier
	ds_read_b128 v[84:87], v76 offset:49152
	ds_read_b128 v[88:91], v76 offset:51200
	ds_read_b128 v[92:95], v76 offset:53248
	ds_read_b128 v[96:99], v76 offset:55296
	ds_read_b128 v[100:103], v78 offset:49152
	ds_read_b128 v[104:107], v78 offset:51200
	ds_read_b128 v[108:111], v78 offset:53248
	ds_read_b128 v[112:115], v78 offset:55296
	v_mfma_f32_16x16x32_bf16 v[0:3], v[136:139], v[152:155], v[0:3]
	v_mfma_f32_16x16x32_bf16 v[4:7], v[136:139], v[156:159], v[4:7]
	s_mov_b32 s24, 0x580
	s_mov_b32 s25, 0
	s_mov_b32 m0, s30
	v_lshl_add_u64 v[124:125], v[64:65], 0, s[24:25]
	global_load_lds_dwordx4 v[124:125], off
	v_mfma_f32_16x16x32_bf16 v[8:11], v[136:139], v[160:163], v[8:11]
	v_mfma_f32_16x16x32_bf16 v[12:15], v[136:139], v[164:167], v[12:15]
	v_mfma_f32_16x16x32_bf16 v[16:19], v[140:143], v[152:155], v[16:19]
	v_mfma_f32_16x16x32_bf16 v[20:23], v[140:143], v[156:159], v[20:23]
	v_mfma_f32_16x16x32_bf16 v[24:27], v[140:143], v[160:163], v[24:27]
	s_add_u32 m0, s30, 0x2000
	v_lshl_add_u64 v[126:127], v[66:67], 0, s[24:25]
	global_load_lds_dwordx4 v[126:127], off
	v_mfma_f32_16x16x32_bf16 v[28:31], v[140:143], v[164:167], v[28:31]
	v_mfma_f32_16x16x32_bf16 v[32:35], v[144:147], v[152:155], v[32:35]
	v_mfma_f32_16x16x32_bf16 v[36:39], v[144:147], v[156:159], v[36:39]
	v_mfma_f32_16x16x32_bf16 v[40:43], v[144:147], v[160:163], v[40:43]
	v_mfma_f32_16x16x32_bf16 v[44:47], v[144:147], v[164:167], v[44:47]
	s_add_u32 m0, s30, 0x4000
	v_lshl_add_u64 v[124:125], v[68:69], 0, s[24:25]
	global_load_lds_dwordx4 v[124:125], off
	v_mfma_f32_16x16x32_bf16 v[48:51], v[148:151], v[152:155], v[48:51]
	v_mfma_f32_16x16x32_bf16 v[52:55], v[148:151], v[156:159], v[52:55]
	v_mfma_f32_16x16x32_bf16 v[56:59], v[148:151], v[160:163], v[56:59]
	v_mfma_f32_16x16x32_bf16 v[60:63], v[148:151], v[164:167], v[60:63]
	ds_read_b128 v[136:139], v77 offset:49152
	ds_read_b128 v[140:143], v77 offset:51200
	ds_read_b128 v[144:147], v77 offset:53248
	ds_read_b128 v[148:151], v77 offset:55296
	ds_read_b128 v[152:155], v79 offset:49152
	ds_read_b128 v[156:159], v79 offset:51200
	ds_read_b128 v[160:163], v79 offset:53248
	ds_read_b128 v[164:167], v79 offset:55296
	s_waitcnt lgkmcnt(8)
	v_mfma_f32_16x16x32_bf16 v[0:3], v[84:87], v[100:103], v[0:3]
	v_mfma_f32_16x16x32_bf16 v[4:7], v[84:87], v[104:107], v[4:7]
	s_add_u32 m0, s30, 0x6000
	v_lshl_add_u64 v[126:127], v[70:71], 0, s[24:25]
	global_load_lds_dwordx4 v[126:127], off
	v_mfma_f32_16x16x32_bf16 v[8:11], v[84:87], v[108:111], v[8:11]
	v_mfma_f32_16x16x32_bf16 v[12:15], v[84:87], v[112:115], v[12:15]
	v_mfma_f32_16x16x32_bf16 v[16:19], v[88:91], v[100:103], v[16:19]
	v_mfma_f32_16x16x32_bf16 v[20:23], v[88:91], v[104:107], v[20:23]
	v_mfma_f32_16x16x32_bf16 v[24:27], v[88:91], v[108:111], v[24:27]
	s_add_u32 m0, s30, 0x8000
	v_lshl_add_u64 v[124:125], v[72:73], 0, s[24:25]
	global_load_lds_dwordx4 v[124:125], off
	v_mfma_f32_16x16x32_bf16 v[28:31], v[88:91], v[112:115], v[28:31]
	v_mfma_f32_16x16x32_bf16 v[32:35], v[92:95], v[100:103], v[32:35]
	v_mfma_f32_16x16x32_bf16 v[36:39], v[92:95], v[104:107], v[36:39]
	v_mfma_f32_16x16x32_bf16 v[40:43], v[92:95], v[108:111], v[40:43]
	v_mfma_f32_16x16x32_bf16 v[44:47], v[92:95], v[112:115], v[44:47]
	s_add_u32 m0, s30, 0xa000
	v_lshl_add_u64 v[126:127], v[74:75], 0, s[24:25]
	global_load_lds_dwordx4 v[126:127], off
	v_mfma_f32_16x16x32_bf16 v[48:51], v[96:99], v[100:103], v[48:51]
	v_mfma_f32_16x16x32_bf16 v[52:55], v[96:99], v[104:107], v[52:55]
	v_mfma_f32_16x16x32_bf16 v[56:59], v[96:99], v[108:111], v[56:59]
	v_mfma_f32_16x16x32_bf16 v[60:63], v[96:99], v[112:115], v[60:63]
	s_waitcnt vmcnt(6) lgkmcnt(0)
	s_barrier
;     ...
;   for (int kt = 0; kt < nk; ++kt) {
;     if (kt + 1 < nk) asm volatile("s_waitcnt vmcnt(6)" ::: "memory");
;     else asm volatile("s_waitcnt vmcnt(0)" ::: "memory");
;     __builtin_amdgcn_s_barrier();
;     asm volatile("" ::: "memory");
;     if (kt + 2 < nk) { const int st2 = (st >= 1) ? st - 1 : 2; GEMM_ISSUE(kt + 2, st2); }
;     const char* la = lds + st * STAGE_B;
;     const char* lb = la + 32768;
;     const unsigned sa_u = (unsigned)(size_t)la + arow_u, sb_u = (unsigned)(size_t)lb + brow_u;
;     const unsigned a0 = sa_u + co0, a1 = sa_u + co1, a2 = sa_u + co2, a3 = sa_u + co3;
;     const unsigned b0 = sb_u + co0, b1 = sb_u + co1, b2 = sb_u + co2, b3 = sb_u + co3;
;     {
;       bf16x8 p0, p1, q0, q1, u0, u1, w0, w1;
;       asm volatile(
;         "ds_read_b128 %4, %12\n\tds_read_b128 %5, %12 offset:4096\n\tds_read_b128 %6, %16\n\tds_read_b128 %7, %16 offset:4096\n\t"
;         "ds_read_b128 %8, %13\n\tds_read_b128 %9, %13 offset:4096\n\tds_read_b128 %10, %17\n\tds_read_b128 %11, %17 offset:4096\n\t"
;         "s_waitcnt lgkmcnt(4)\n\t"
;         "v_mfma_f32_32x32x16_bf16 %0, %4, %6, %0\n\tv_mfma_f32_32x32x16_bf16 %1, %4, %7, %1\n\tv_mfma_f32_32x32x16_bf16 %2, %5, %6, %2\n\tv_mfma_f32_32x32x16_bf16 %3, %5, %7, %3\n\t"
;         "ds_read_b128 %4, %14\n\tds_read_b128 %5, %14 offset:4096\n\tds_read_b128 %6, %18\n\tds_read_b128 %7, %18 offset:4096\n\t"
;         "s_waitcnt lgkmcnt(4)\n\t"
;         "v_mfma_f32_32x32x16_bf16 %0, %8, %10, %0\n\tv_mfma_f32_32x32x16_bf16 %1, %8, %11, %1\n\tv_mfma_f32_32x32x16_bf16 %2, %9, %10, %2\n\tv_mfma_f32_32x32x16_bf16 %3, %9, %11, %3\n\t"
;         "ds_read_b128 %8, %15\n\tds_read_b128 %9, %15 offset:4096\n\tds_read_b128 %10, %19\n\tds_read_b128 %11, %19 offset:4096\n\t"
;         "s_waitcnt lgkmcnt(4)\n\t"
;         "v_mfma_f32_32x32x16_bf16 %0, %4, %6, %0\n\tv_mfma_f32_32x32x16_bf16 %1, %4, %7, %1\n\tv_mfma_f32_32x32x16_bf16 %2, %5, %6, %2\n\tv_mfma_f32_32x32x16_bf16 %3, %5, %7, %3\n\t"
;         "s_waitcnt lgkmcnt(0)\n\t"
;         "v_mfma_f32_32x32x16_bf16 %0, %8, %10, %0\n\tv_mfma_f32_32x32x16_bf16 %1, %8, %11, %1\n\tv_mfma_f32_32x32x16_bf16 %2, %9, %10, %2\n\tv_mfma_f32_32x32x16_bf16 %3, %9, %11, %3"
;         : "+v"(acc[0][0]), "+v"(acc[0][1]), "+v"(acc[1][0]), "+v"(acc[1][1]),
;           "=&v"(p0), "=&v"(p1), "=&v"(q0), "=&v"(q1), "=&v"(u0), "=&v"(u1), "=&v"(w0), "=&v"(w1)
	ds_read_b128 v[84:87], v80
	ds_read_b128 v[88:91], v80 offset:2048
	ds_read_b128 v[92:95], v80 offset:4096
	ds_read_b128 v[96:99], v80 offset:6144
	ds_read_b128 v[100:103], v82
	ds_read_b128 v[104:107], v82 offset:2048
	ds_read_b128 v[108:111], v82 offset:4096
	ds_read_b128 v[112:115], v82 offset:6144
	v_mfma_f32_16x16x32_bf16 v[0:3], v[136:139], v[152:155], v[0:3]
	v_mfma_f32_16x16x32_bf16 v[4:7], v[136:139], v[156:159], v[4:7]
	s_mov_b32 s24, 0x600
	s_mov_b32 s25, 0
	s_add_u32 m0, s30, 0xc000
	v_lshl_add_u64 v[124:125], v[64:65], 0, s[24:25]
	global_load_lds_dwordx4 v[124:125], off
	v_mfma_f32_16x16x32_bf16 v[8:11], v[136:139], v[160:163], v[8:11]
	v_mfma_f32_16x16x32_bf16 v[12:15], v[136:139], v[164:167], v[12:15]
	v_mfma_f32_16x16x32_bf16 v[16:19], v[140:143], v[152:155], v[16:19]
	v_mfma_f32_16x16x32_bf16 v[20:23], v[140:143], v[156:159], v[20:23]
	v_mfma_f32_16x16x32_bf16 v[24:27], v[140:143], v[160:163], v[24:27]
	s_add_u32 m0, s30, 0xe000
	v_lshl_add_u64 v[126:127], v[66:67], 0, s[24:25]
	global_load_lds_dwordx4 v[126:127], off
	v_mfma_f32_16x16x32_bf16 v[28:31], v[140:143], v[164:167], v[28:31]
	v_mfma_f32_16x16x32_bf16 v[32:35], v[144:147], v[152:155], v[32:35]
	v_mfma_f32_16x16x32_bf16 v[36:39], v[144:147], v[156:159], v[36:39]
	v_mfma_f32_16x16x32_bf16 v[40:43], v[144:147], v[160:163], v[40:43]
	v_mfma_f32_16x16x32_bf16 v[44:47], v[144:147], v[164:167], v[44:47]
	s_add_u32 m0, s30, 0x10000
	v_lshl_add_u64 v[124:125], v[68:69], 0, s[24:25]
	global_load_lds_dwordx4 v[124:125], off
	v_mfma_f32_16x16x32_bf16 v[48:51], v[148:151], v[152:155], v[48:51]
	v_mfma_f32_16x16x32_bf16 v[52:55], v[148:151], v[156:159], v[52:55]
	v_mfma_f32_16x16x32_bf16 v[56:59], v[148:151], v[160:163], v[56:59]
	v_mfma_f32_16x16x32_bf16 v[60:63], v[148:151], v[164:167], v[60:63]
	ds_read_b128 v[136:139], v81
	ds_read_b128 v[140:143], v81 offset:2048
	ds_read_b128 v[144:147], v81 offset:4096
	ds_read_b128 v[148:151], v81 offset:6144
	ds_read_b128 v[152:155], v83
	ds_read_b128 v[156:159], v83 offset:2048
	ds_read_b128 v[160:163], v83 offset:4096
	ds_read_b128 v[164:167], v83 offset:6144
	s_waitcnt lgkmcnt(8)
	v_mfma_f32_16x16x32_bf16 v[0:3], v[84:87], v[100:103], v[0:3]
	v_mfma_f32_16x16x32_bf16 v[4:7], v[84:87], v[104:107], v[4:7]
	s_add_u32 m0, s30, 0x12000
	v_lshl_add_u64 v[126:127], v[70:71], 0, s[24:25]
	global_load_lds_dwordx4 v[126:127], off
	v_mfma_f32_16x16x32_bf16 v[8:11], v[84:87], v[108:111], v[8:11]
	v_mfma_f32_16x16x32_bf16 v[12:15], v[84:87], v[112:115], v[12:15]
	v_mfma_f32_16x16x32_bf16 v[16:19], v[88:91], v[100:103], v[16:19]
	v_mfma_f32_16x16x32_bf16 v[20:23], v[88:91], v[104:107], v[20:23]
	v_mfma_f32_16x16x32_bf16 v[24:27], v[88:91], v[108:111], v[24:27]
	s_add_u32 m0, s30, 0x14000
	v_lshl_add_u64 v[124:125], v[72:73], 0, s[24:25]
	global_load_lds_dwordx4 v[124:125], off
	v_mfma_f32_16x16x32_bf16 v[28:31], v[88:91], v[112:115], v[28:31]
	v_mfma_f32_16x16x32_bf16 v[32:35], v[92:95], v[100:103], v[32:35]
	v_mfma_f32_16x16x32_bf16 v[36:39], v[92:95], v[104:107], v[36:39]
	v_mfma_f32_16x16x32_bf16 v[40:43], v[92:95], v[108:111], v[40:43]
	v_mfma_f32_16x16x32_bf16 v[44:47], v[92:95], v[112:115], v[44:47]
	s_add_u32 m0, s30, 0x16000
	v_lshl_add_u64 v[126:127], v[74:75], 0, s[24:25]
	global_load_lds_dwordx4 v[126:127], off
	v_mfma_f32_16x16x32_bf16 v[48:51], v[96:99], v[100:103], v[48:51]
	v_mfma_f32_16x16x32_bf16 v[52:55], v[96:99], v[104:107], v[52:55]
	v_mfma_f32_16x16x32_bf16 v[56:59], v[96:99], v[108:111], v[56:59]
	v_mfma_f32_16x16x32_bf16 v[60:63], v[96:99], v[112:115], v[60:63]
	s_waitcnt vmcnt(6) lgkmcnt(0)
	s_barrier
	ds_read_b128 v[84:87], v76
	ds_read_b128 v[88:91], v76 offset:2048
	ds_read_b128 v[92:95], v76 offset:4096
	ds_read_b128 v[96:99], v76 offset:6144
	ds_read_b128 v[100:103], v78
	ds_read_b128 v[104:107], v78 offset:2048
	ds_read_b128 v[108:111], v78 offset:4096
	ds_read_b128 v[112:115], v78 offset:6144
	v_mfma_f32_16x16x32_bf16 v[0:3], v[136:139], v[152:155], v[0:3]
	v_mfma_f32_16x16x32_bf16 v[4:7], v[136:139], v[156:159], v[4:7]
	s_mov_b32 s24, 0x680
	s_mov_b32 s25, 0
	s_add_u32 m0, s30, 0x18000
	v_lshl_add_u64 v[124:125], v[64:65], 0, s[24:25]
	global_load_lds_dwordx4 v[124:125], off
	v_mfma_f32_16x16x32_bf16 v[8:11], v[136:139], v[160:163], v[8:11]
	v_mfma_f32_16x16x32_bf16 v[12:15], v[136:139], v[164:167], v[12:15]
	v_mfma_f32_16x16x32_bf16 v[16:19], v[140:143], v[152:155], v[16:19]
	v_mfma_f32_16x16x32_bf16 v[20:23], v[140:143], v[156:159], v[20:23]
	v_mfma_f32_16x16x32_bf16 v[24:27], v[140:143], v[160:163], v[24:27]
	s_add_u32 m0, s30, 0x1a000
	v_lshl_add_u64 v[126:127], v[66:67], 0, s[24:25]
	global_load_lds_dwordx4 v[126:127], off
	v_mfma_f32_16x16x32_bf16 v[28:31], v[140:143], v[164:167], v[28:31]
	v_mfma_f32_16x16x32_bf16 v[32:35], v[144:147], v[152:155], v[32:35]
	v_mfma_f32_16x16x32_bf16 v[36:39], v[144:147], v[156:159], v[36:39]
	v_mfma_f32_16x16x32_bf16 v[40:43], v[144:147], v[160:163], v[40:43]
	v_mfma_f32_16x16x32_bf16 v[44:47], v[144:147], v[164:167], v[44:47]
	s_add_u32 m0, s30, 0x1c000
	v_lshl_add_u64 v[124:125], v[68:69], 0, s[24:25]
	global_load_lds_dwordx4 v[124:125], off
	v_mfma_f32_16x16x32_bf16 v[48:51], v[148:151], v[152:155], v[48:51]
	v_mfma_f32_16x16x32_bf16 v[52:55], v[148:151], v[156:159], v[52:55]
	v_mfma_f32_16x16x32_bf16 v[56:59], v[148:151], v[160:163], v[56:59]
	v_mfma_f32_16x16x32_bf16 v[60:63], v[148:151], v[164:167], v[60:63]
	ds_read_b128 v[136:139], v77
	ds_read_b128 v[140:143], v77 offset:2048
	ds_read_b128 v[144:147], v77 offset:4096
	ds_read_b128 v[148:151], v77 offset:6144
	ds_read_b128 v[152:155], v79
	ds_read_b128 v[156:159], v79 offset:2048
	ds_read_b128 v[160:163], v79 offset:4096
	ds_read_b128 v[164:167], v79 offset:6144
	s_waitcnt lgkmcnt(8)
;     ...
;   for (int kt = 0; kt < nk; ++kt) {
;     if (kt + 1 < nk) asm volatile("s_waitcnt vmcnt(6)" ::: "memory");
;     else asm volatile("s_waitcnt vmcnt(0)" ::: "memory");
;     __builtin_amdgcn_s_barrier();
;     asm volatile("" ::: "memory");
;     if (kt + 2 < nk) { const int st2 = (st >= 1) ? st - 1 : 2; GEMM_ISSUE(kt + 2, st2); }
;     const char* la = lds + st * STAGE_B;
;     const char* lb = la + 32768;
;     const unsigned sa_u = (unsigned)(size_t)la + arow_u, sb_u = (unsigned)(size_t)lb + brow_u;
;     const unsigned a0 = sa_u + co0, a1 = sa_u + co1, a2 = sa_u + co2, a3 = sa_u + co3;
;     const unsigned b0 = sb_u + co0, b1 = sb_u + co1, b2 = sb_u + co2, b3 = sb_u + co3;
;     {
;       bf16x8 p0, p1, q0, q1, u0, u1, w0, w1;
;       asm volatile(
;         "ds_read_b128 %4, %12\n\tds_read_b128 %5, %12 offset:4096\n\tds_read_b128 %6, %16\n\tds_read_b128 %7, %16 offset:4096\n\t"
;         "ds_read_b128 %8, %13\n\tds_read_b128 %9, %13 offset:4096\n\tds_read_b128 %10, %17\n\tds_read_b128 %11, %17 offset:4096\n\t"
;         "s_waitcnt lgkmcnt(4)\n\t"
;         "v_mfma_f32_32x32x16_bf16 %0, %4, %6, %0\n\tv_mfma_f32_32x32x16_bf16 %1, %4, %7, %1\n\tv_mfma_f32_32x32x16_bf16 %2, %5, %6, %2\n\tv_mfma_f32_32x32x16_bf16 %3, %5, %7, %3\n\t"
;         "ds_read_b128 %4, %14\n\tds_read_b128 %5, %14 offset:4096\n\tds_read_b128 %6, %18\n\tds_read_b128 %7, %18 offset:4096\n\t"
;         "s_waitcnt lgkmcnt(4)\n\t"
;         "v_mfma_f32_32x32x16_bf16 %0, %8, %10, %0\n\tv_mfma_f32_32x32x16_bf16 %1, %8, %11, %1\n\tv_mfma_f32_32x32x16_bf16 %2, %9, %10, %2\n\tv_mfma_f32_32x32x16_bf16 %3, %9, %11, %3\n\t"
;         "ds_read_b128 %8, %15\n\tds_read_b128 %9, %15 offset:4096\n\tds_read_b128 %10, %19\n\tds_read_b128 %11, %19 offset:4096\n\t"
;         "s_waitcnt lgkmcnt(4)\n\t"
;         "v_mfma_f32_32x32x16_bf16 %0, %4, %6, %0\n\tv_mfma_f32_32x32x16_bf16 %1, %4, %7, %1\n\tv_mfma_f32_32x32x16_bf16 %2, %5, %6, %2\n\tv_mfma_f32_32x32x16_bf16 %3, %5, %7, %3\n\t"
;         "s_waitcnt lgkmcnt(0)\n\t"
;         "v_mfma_f32_32x32x16_bf16 %0, %8, %10, %0\n\tv_mfma_f32_32x32x16_bf16 %1, %8, %11, %1\n\tv_mfma_f32_32x32x16_bf16 %2, %9, %10, %2\n\tv_mfma_f32_32x32x16_bf16 %3, %9, %11, %3"
;         : "+v"(acc[0][0]), "+v"(acc[0][1]), "+v"(acc[1][0]), "+v"(acc[1][1]),
;           "=&v"(p0), "=&v"(p1), "=&v"(q0), "=&v"(q1), "=&v"(u0), "=&v"(u1), "=&v"(w0), "=&v"(w1)
	v_mfma_f32_16x16x32_bf16 v[0:3], v[84:87], v[100:103], v[0:3]
	v_mfma_f32_16x16x32_bf16 v[4:7], v[84:87], v[104:107], v[4:7]
	s_add_u32 m0, s30, 0x1e000
	v_lshl_add_u64 v[126:127], v[70:71], 0, s[24:25]
	global_load_lds_dwordx4 v[126:127], off
	v_mfma_f32_16x16x32_bf16 v[8:11], v[84:87], v[108:111], v[8:11]
	v_mfma_f32_16x16x32_bf16 v[12:15], v[84:87], v[112:115], v[12:15]
	v_mfma_f32_16x16x32_bf16 v[16:19], v[88:91], v[100:103], v[16:19]
	v_mfma_f32_16x16x32_bf16 v[20:23], v[88:91], v[104:107], v[20:23]
	v_mfma_f32_16x16x32_bf16 v[24:27], v[88:91], v[108:111], v[24:27]
	s_add_u32 m0, s30, 0x20000
	v_lshl_add_u64 v[124:125], v[72:73], 0, s[24:25]
	global_load_lds_dwordx4 v[124:125], off
	v_mfma_f32_16x16x32_bf16 v[28:31], v[88:91], v[112:115], v[28:31]
	v_mfma_f32_16x16x32_bf16 v[32:35], v[92:95], v[100:103], v[32:35]
	v_mfma_f32_16x16x32_bf16 v[36:39], v[92:95], v[104:107], v[36:39]
	v_mfma_f32_16x16x32_bf16 v[40:43], v[92:95], v[108:111], v[40:43]
	v_mfma_f32_16x16x32_bf16 v[44:47], v[92:95], v[112:115], v[44:47]
	s_add_u32 m0, s30, 0x22000
	v_lshl_add_u64 v[126:127], v[74:75], 0, s[24:25]
	global_load_lds_dwordx4 v[126:127], off
	v_mfma_f32_16x16x32_bf16 v[48:51], v[96:99], v[100:103], v[48:51]
	v_mfma_f32_16x16x32_bf16 v[52:55], v[96:99], v[104:107], v[52:55]
	v_mfma_f32_16x16x32_bf16 v[56:59], v[96:99], v[108:111], v[56:59]
	v_mfma_f32_16x16x32_bf16 v[60:63], v[96:99], v[112:115], v[60:63]
	s_waitcnt vmcnt(6) lgkmcnt(0)
	s_barrier
	ds_read_b128 v[84:87], v76 offset:49152
	ds_read_b128 v[88:91], v76 offset:51200
	ds_read_b128 v[92:95], v76 offset:53248
	ds_read_b128 v[96:99], v76 offset:55296
	ds_read_b128 v[100:103], v78 offset:49152
	ds_read_b128 v[104:107], v78 offset:51200
	ds_read_b128 v[108:111], v78 offset:53248
	ds_read_b128 v[112:115], v78 offset:55296
	v_mfma_f32_16x16x32_bf16 v[0:3], v[136:139], v[152:155], v[0:3]
	v_mfma_f32_16x16x32_bf16 v[4:7], v[136:139], v[156:159], v[4:7]
	s_mov_b32 s24, 0x700
	s_mov_b32 s25, 0
	s_mov_b32 m0, s30
	v_lshl_add_u64 v[124:125], v[64:65], 0, s[24:25]
	global_load_lds_dwordx4 v[124:125], off
	v_mfma_f32_16x16x32_bf16 v[8:11], v[136:139], v[160:163], v[8:11]
	v_mfma_f32_16x16x32_bf16 v[12:15], v[136:139], v[164:167], v[12:15]
	v_mfma_f32_16x16x32_bf16 v[16:19], v[140:143], v[152:155], v[16:19]
	v_mfma_f32_16x16x32_bf16 v[20:23], v[140:143], v[156:159], v[20:23]
	v_mfma_f32_16x16x32_bf16 v[24:27], v[140:143], v[160:163], v[24:27]
	s_add_u32 m0, s30, 0x2000
	v_lshl_add_u64 v[126:127], v[66:67], 0, s[24:25]
	global_load_lds_dwordx4 v[126:127], off
	v_mfma_f32_16x16x32_bf16 v[28:31], v[140:143], v[164:167], v[28:31]
	v_mfma_f32_16x16x32_bf16 v[32:35], v[144:147], v[152:155], v[32:35]
	v_mfma_f32_16x16x32_bf16 v[36:39], v[144:147], v[156:159], v[36:39]
	v_mfma_f32_16x16x32_bf16 v[40:43], v[144:147], v[160:163], v[40:43]
	v_mfma_f32_16x16x32_bf16 v[44:47], v[144:147], v[164:167], v[44:47]
	s_add_u32 m0, s30, 0x4000
	v_lshl_add_u64 v[124:125], v[68:69], 0, s[24:25]
	global_load_lds_dwordx4 v[124:125], off
	v_mfma_f32_16x16x32_bf16 v[48:51], v[148:151], v[152:155], v[48:51]
	v_mfma_f32_16x16x32_bf16 v[52:55], v[148:151], v[156:159], v[52:55]
	v_mfma_f32_16x16x32_bf16 v[56:59], v[148:151], v[160:163], v[56:59]
	v_mfma_f32_16x16x32_bf16 v[60:63], v[148:151], v[164:167], v[60:63]
	ds_read_b128 v[136:139], v77 offset:49152
	ds_read_b128 v[140:143], v77 offset:51200
	ds_read_b128 v[144:147], v77 offset:53248
	ds_read_b128 v[148:151], v77 offset:55296
	ds_read_b128 v[152:155], v79 offset:49152
	ds_read_b128 v[156:159], v79 offset:51200
	ds_read_b128 v[160:163], v79 offset:53248
	ds_read_b128 v[164:167], v79 offset:55296
	s_waitcnt lgkmcnt(8)
	v_mfma_f32_16x16x32_bf16 v[0:3], v[84:87], v[100:103], v[0:3]
	v_mfma_f32_16x16x32_bf16 v[4:7], v[84:87], v[104:107], v[4:7]
	s_add_u32 m0, s30, 0x6000
	v_lshl_add_u64 v[126:127], v[70:71], 0, s[24:25]
	global_load_lds_dwordx4 v[126:127], off
	v_mfma_f32_16x16x32_bf16 v[8:11], v[84:87], v[108:111], v[8:11]
	v_mfma_f32_16x16x32_bf16 v[12:15], v[84:87], v[112:115], v[12:15]
	v_mfma_f32_16x16x32_bf16 v[16:19], v[88:91], v[100:103], v[16:19]
	v_mfma_f32_16x16x32_bf16 v[20:23], v[88:91], v[104:107], v[20:23]
	v_mfma_f32_16x16x32_bf16 v[24:27], v[88:91], v[108:111], v[24:27]
	s_add_u32 m0, s30, 0x8000
	v_lshl_add_u64 v[124:125], v[72:73], 0, s[24:25]
	global_load_lds_dwordx4 v[124:125], off
	v_mfma_f32_16x16x32_bf16 v[28:31], v[88:91], v[112:115], v[28:31]
	v_mfma_f32_16x16x32_bf16 v[32:35], v[92:95], v[100:103], v[32:35]
	v_mfma_f32_16x16x32_bf16 v[36:39], v[92:95], v[104:107], v[36:39]
	v_mfma_f32_16x16x32_bf16 v[40:43], v[92:95], v[108:111], v[40:43]
	v_mfma_f32_16x16x32_bf16 v[44:47], v[92:95], v[112:115], v[44:47]
	s_add_u32 m0, s30, 0xa000
	v_lshl_add_u64 v[126:127], v[74:75], 0, s[24:25]
	global_load_lds_dwordx4 v[126:127], off
	v_mfma_f32_16x16x32_bf16 v[48:51], v[96:99], v[100:103], v[48:51]
	v_mfma_f32_16x16x32_bf16 v[52:55], v[96:99], v[104:107], v[52:55]
	v_mfma_f32_16x16x32_bf16 v[56:59], v[96:99], v[108:111], v[56:59]
	v_mfma_f32_16x16x32_bf16 v[60:63], v[96:99], v[112:115], v[60:63]
	s_waitcnt vmcnt(6) lgkmcnt(0)
	s_barrier
;     ...
;   for (int kt = 0; kt < nk; ++kt) {
;     if (kt + 1 < nk) asm volatile("s_waitcnt vmcnt(6)" ::: "memory");
;     else asm volatile("s_waitcnt vmcnt(0)" ::: "memory");
;     __builtin_amdgcn_s_barrier();
;     asm volatile("" ::: "memory");
;     if (kt + 2 < nk) { const int st2 = (st >= 1) ? st - 1 : 2; GEMM_ISSUE(kt + 2, st2); }
;     const char* la = lds + st * STAGE_B;
;     const char* lb = la + 32768;
;     const unsigned sa_u = (unsigned)(size_t)la + arow_u, sb_u = (unsigned)(size_t)lb + brow_u;
;     const unsigned a0 = sa_u + co0, a1 = sa_u + co1, a2 = sa_u + co2, a3 = sa_u + co3;
;     const unsigned b0 = sb_u + co0, b1 = sb_u + co1, b2 = sb_u + co2, b3 = sb_u + co3;
;     {
;       bf16x8 p0, p1, q0, q1, u0, u1, w0, w1;
;       asm volatile(
;         "ds_read_b128 %4, %12\n\tds_read_b128 %5, %12 offset:4096\n\tds_read_b128 %6, %16\n\tds_read_b128 %7, %16 offset:4096\n\t"
;         "ds_read_b128 %8, %13\n\tds_read_b128 %9, %13 offset:4096\n\tds_read_b128 %10, %17\n\tds_read_b128 %11, %17 offset:4096\n\t"
;         "s_waitcnt lgkmcnt(4)\n\t"
;         "v_mfma_f32_32x32x16_bf16 %0, %4, %6, %0\n\tv_mfma_f32_32x32x16_bf16 %1, %4, %7, %1\n\tv_mfma_f32_32x32x16_bf16 %2, %5, %6, %2\n\tv_mfma_f32_32x32x16_bf16 %3, %5, %7, %3\n\t"
;         "ds_read_b128 %4, %14\n\tds_read_b128 %5, %14 offset:4096\n\tds_read_b128 %6, %18\n\tds_read_b128 %7, %18 offset:4096\n\t"
;         "s_waitcnt lgkmcnt(4)\n\t"
;         "v_mfma_f32_32x32x16_bf16 %0, %8, %10, %0\n\tv_mfma_f32_32x32x16_bf16 %1, %8, %11, %1\n\tv_mfma_f32_32x32x16_bf16 %2, %9, %10, %2\n\tv_mfma_f32_32x32x16_bf16 %3, %9, %11, %3\n\t"
;         "ds_read_b128 %8, %15\n\tds_read_b128 %9, %15 offset:4096\n\tds_read_b128 %10, %19\n\tds_read_b128 %11, %19 offset:4096\n\t"
;         "s_waitcnt lgkmcnt(4)\n\t"
;         "v_mfma_f32_32x32x16_bf16 %0, %4, %6, %0\n\tv_mfma_f32_32x32x16_bf16 %1, %4, %7, %1\n\tv_mfma_f32_32x32x16_bf16 %2, %5, %6, %2\n\tv_mfma_f32_32x32x16_bf16 %3, %5, %7, %3\n\t"
;         "s_waitcnt lgkmcnt(0)\n\t"
;         "v_mfma_f32_32x32x16_bf16 %0, %8, %10, %0\n\tv_mfma_f32_32x32x16_bf16 %1, %8, %11, %1\n\tv_mfma_f32_32x32x16_bf16 %2, %9, %10, %2\n\tv_mfma_f32_32x32x16_bf16 %3, %9, %11, %3"
;         : "+v"(acc[0][0]), "+v"(acc[0][1]), "+v"(acc[1][0]), "+v"(acc[1][1]),
;           "=&v"(p0), "=&v"(p1), "=&v"(q0), "=&v"(q1), "=&v"(u0), "=&v"(u1), "=&v"(w0), "=&v"(w1)
	ds_read_b128 v[84:87], v80
	ds_read_b128 v[88:91], v80 offset:2048
	ds_read_b128 v[92:95], v80 offset:4096
	ds_read_b128 v[96:99], v80 offset:6144
	ds_read_b128 v[100:103], v82
	ds_read_b128 v[104:107], v82 offset:2048
	ds_read_b128 v[108:111], v82 offset:4096
	ds_read_b128 v[112:115], v82 offset:6144
	v_mfma_f32_16x16x32_bf16 v[0:3], v[136:139], v[152:155], v[0:3]
	v_mfma_f32_16x16x32_bf16 v[4:7], v[136:139], v[156:159], v[4:7]
	s_mov_b32 s24, 0x780
	s_mov_b32 s25, 0
	s_add_u32 m0, s30, 0xc000
	v_lshl_add_u64 v[124:125], v[64:65], 0, s[24:25]
	global_load_lds_dwordx4 v[124:125], off
	v_mfma_f32_16x16x32_bf16 v[8:11], v[136:139], v[160:163], v[8:11]
	v_mfma_f32_16x16x32_bf16 v[12:15], v[136:139], v[164:167], v[12:15]
	v_mfma_f32_16x16x32_bf16 v[16:19], v[140:143], v[152:155], v[16:19]
	v_mfma_f32_16x16x32_bf16 v[20:23], v[140:143], v[156:159], v[20:23]
	v_mfma_f32_16x16x32_bf16 v[24:27], v[140:143], v[160:163], v[24:27]
	s_add_u32 m0, s30, 0xe000
	v_lshl_add_u64 v[126:127], v[66:67], 0, s[24:25]
	global_load_lds_dwordx4 v[126:127], off
	v_mfma_f32_16x16x32_bf16 v[28:31], v[140:143], v[164:167], v[28:31]
	v_mfma_f32_16x16x32_bf16 v[32:35], v[144:147], v[152:155], v[32:35]
	v_mfma_f32_16x16x32_bf16 v[36:39], v[144:147], v[156:159], v[36:39]
	v_mfma_f32_16x16x32_bf16 v[40:43], v[144:147], v[160:163], v[40:43]
	v_mfma_f32_16x16x32_bf16 v[44:47], v[144:147], v[164:167], v[44:47]
	s_add_u32 m0, s30, 0x10000
	v_lshl_add_u64 v[124:125], v[68:69], 0, s[24:25]
	global_load_lds_dwordx4 v[124:125], off
	v_mfma_f32_16x16x32_bf16 v[48:51], v[148:151], v[152:155], v[48:51]
	v_mfma_f32_16x16x32_bf16 v[52:55], v[148:151], v[156:159], v[52:55]
	v_mfma_f32_16x16x32_bf16 v[56:59], v[148:151], v[160:163], v[56:59]
	v_mfma_f32_16x16x32_bf16 v[60:63], v[148:151], v[164:167], v[60:63]
	ds_read_b128 v[136:139], v81
	ds_read_b128 v[140:143], v81 offset:2048
	ds_read_b128 v[144:147], v81 offset:4096
	ds_read_b128 v[148:151], v81 offset:6144
	ds_read_b128 v[152:155], v83
	ds_read_b128 v[156:159], v83 offset:2048
	ds_read_b128 v[160:163], v83 offset:4096
	ds_read_b128 v[164:167], v83 offset:6144
	s_waitcnt lgkmcnt(8)
	v_mfma_f32_16x16x32_bf16 v[0:3], v[84:87], v[100:103], v[0:3]
	v_mfma_f32_16x16x32_bf16 v[4:7], v[84:87], v[104:107], v[4:7]
	s_add_u32 m0, s30, 0x12000
	v_lshl_add_u64 v[126:127], v[70:71], 0, s[24:25]
	global_load_lds_dwordx4 v[126:127], off
	v_mfma_f32_16x16x32_bf16 v[8:11], v[84:87], v[108:111], v[8:11]
	v_mfma_f32_16x16x32_bf16 v[12:15], v[84:87], v[112:115], v[12:15]
	v_mfma_f32_16x16x32_bf16 v[16:19], v[88:91], v[100:103], v[16:19]
	v_mfma_f32_16x16x32_bf16 v[20:23], v[88:91], v[104:107], v[20:23]
	v_mfma_f32_16x16x32_bf16 v[24:27], v[88:91], v[108:111], v[24:27]
	s_add_u32 m0, s30, 0x14000
	v_lshl_add_u64 v[124:125], v[72:73], 0, s[24:25]
	global_load_lds_dwordx4 v[124:125], off
	v_mfma_f32_16x16x32_bf16 v[28:31], v[88:91], v[112:115], v[28:31]
	v_mfma_f32_16x16x32_bf16 v[32:35], v[92:95], v[100:103], v[32:35]
	v_mfma_f32_16x16x32_bf16 v[36:39], v[92:95], v[104:107], v[36:39]
	v_mfma_f32_16x16x32_bf16 v[40:43], v[92:95], v[108:111], v[40:43]
	v_mfma_f32_16x16x32_bf16 v[44:47], v[92:95], v[112:115], v[44:47]
	s_add_u32 m0, s30, 0x16000
	v_lshl_add_u64 v[126:127], v[74:75], 0, s[24:25]
	global_load_lds_dwordx4 v[126:127], off
	v_mfma_f32_16x16x32_bf16 v[48:51], v[96:99], v[100:103], v[48:51]
	v_mfma_f32_16x16x32_bf16 v[52:55], v[96:99], v[104:107], v[52:55]
	v_mfma_f32_16x16x32_bf16 v[56:59], v[96:99], v[108:111], v[56:59]
	v_mfma_f32_16x16x32_bf16 v[60:63], v[96:99], v[112:115], v[60:63]
	s_waitcnt vmcnt(6) lgkmcnt(0)
	s_barrier
	ds_read_b128 v[84:87], v76
	ds_read_b128 v[88:91], v76 offset:2048
	ds_read_b128 v[92:95], v76 offset:4096
	ds_read_b128 v[96:99], v76 offset:6144
	ds_read_b128 v[100:103], v78
	ds_read_b128 v[104:107], v78 offset:2048
	ds_read_b128 v[108:111], v78 offset:4096
	ds_read_b128 v[112:115], v78 offset:6144
	v_mfma_f32_16x16x32_bf16 v[0:3], v[136:139], v[152:155], v[0:3]
	v_mfma_f32_16x16x32_bf16 v[4:7], v[136:139], v[156:159], v[4:7]
	s_add_u32 s24, s56, 0x0
	s_addc_u32 s25, s57, 0
	s_add_u32 m0, s30, 0x18000
	v_lshl_add_u64 v[124:125], v[64:65], 0, s[24:25]
	global_load_lds_dwordx4 v[124:125], off
	v_mfma_f32_16x16x32_bf16 v[8:11], v[136:139], v[160:163], v[8:11]
	v_mfma_f32_16x16x32_bf16 v[12:15], v[136:139], v[164:167], v[12:15]
	v_mfma_f32_16x16x32_bf16 v[16:19], v[140:143], v[152:155], v[16:19]
	v_mfma_f32_16x16x32_bf16 v[20:23], v[140:143], v[156:159], v[20:23]
	v_mfma_f32_16x16x32_bf16 v[24:27], v[140:143], v[160:163], v[24:27]
	s_add_u32 m0, s30, 0x1a000
	v_lshl_add_u64 v[126:127], v[66:67], 0, s[24:25]
	global_load_lds_dwordx4 v[126:127], off
	v_mfma_f32_16x16x32_bf16 v[28:31], v[140:143], v[164:167], v[28:31]
	v_mfma_f32_16x16x32_bf16 v[32:35], v[144:147], v[152:155], v[32:35]
	v_mfma_f32_16x16x32_bf16 v[36:39], v[144:147], v[156:159], v[36:39]
	v_mfma_f32_16x16x32_bf16 v[40:43], v[144:147], v[160:163], v[40:43]
	v_mfma_f32_16x16x32_bf16 v[44:47], v[144:147], v[164:167], v[44:47]
	s_add_u32 m0, s30, 0x1c000
	v_lshl_add_u64 v[124:125], v[68:69], 0, s[24:25]
	global_load_lds_dwordx4 v[124:125], off
	v_mfma_f32_16x16x32_bf16 v[48:51], v[148:151], v[152:155], v[48:51]
	v_mfma_f32_16x16x32_bf16 v[52:55], v[148:151], v[156:159], v[52:55]
	v_mfma_f32_16x16x32_bf16 v[56:59], v[148:151], v[160:163], v[56:59]
	v_mfma_f32_16x16x32_bf16 v[60:63], v[148:151], v[164:167], v[60:63]
	ds_read_b128 v[136:139], v77
	ds_read_b128 v[140:143], v77 offset:2048
	ds_read_b128 v[144:147], v77 offset:4096
	ds_read_b128 v[148:151], v77 offset:6144
	ds_read_b128 v[152:155], v79
	ds_read_b128 v[156:159], v79 offset:2048
	ds_read_b128 v[160:163], v79 offset:4096
	ds_read_b128 v[164:167], v79 offset:6144
	s_waitcnt lgkmcnt(8)
;     ...
;   for (int kt = 0; kt < nk; ++kt) {
;     if (kt + 1 < nk) asm volatile("s_waitcnt vmcnt(6)" ::: "memory");
;     else asm volatile("s_waitcnt vmcnt(0)" ::: "memory");
;     __builtin_amdgcn_s_barrier();
;     asm volatile("" ::: "memory");
;     if (kt + 2 < nk) { const int st2 = (st >= 1) ? st - 1 : 2; GEMM_ISSUE(kt + 2, st2); }
;     const char* la = lds + st * STAGE_B;
;     const char* lb = la + 32768;
;     const unsigned sa_u = (unsigned)(size_t)la + arow_u, sb_u = (unsigned)(size_t)lb + brow_u;
;     const unsigned a0 = sa_u + co0, a1 = sa_u + co1, a2 = sa_u + co2, a3 = sa_u + co3;
;     const unsigned b0 = sb_u + co0, b1 = sb_u + co1, b2 = sb_u + co2, b3 = sb_u + co3;
;     {
;       bf16x8 p0, p1, q0, q1, u0, u1, w0, w1;
;       asm volatile(
;         "ds_read_b128 %4, %12\n\tds_read_b128 %5, %12 offset:4096\n\tds_read_b128 %6, %16\n\tds_read_b128 %7, %16 offset:4096\n\t"
;         "ds_read_b128 %8, %13\n\tds_read_b128 %9, %13 offset:4096\n\tds_read_b128 %10, %17\n\tds_read_b128 %11, %17 offset:4096\n\t"
;         "s_waitcnt lgkmcnt(4)\n\t"
;         "v_mfma_f32_32x32x16_bf16 %0, %4, %6, %0\n\tv_mfma_f32_32x32x16_bf16 %1, %4, %7, %1\n\tv_mfma_f32_32x32x16_bf16 %2, %5, %6, %2\n\tv_mfma_f32_32x32x16_bf16 %3, %5, %7, %3\n\t"
;         "ds_read_b128 %4, %14\n\tds_read_b128 %5, %14 offset:4096\n\tds_read_b128 %6, %18\n\tds_read_b128 %7, %18 offset:4096\n\t"
;         "s_waitcnt lgkmcnt(4)\n\t"
;         "v_mfma_f32_32x32x16_bf16 %0, %8, %10, %0\n\tv_mfma_f32_32x32x16_bf16 %1, %8, %11, %1\n\tv_mfma_f32_32x32x16_bf16 %2, %9, %10, %2\n\tv_mfma_f32_32x32x16_bf16 %3, %9, %11, %3\n\t"
;         "ds_read_b128 %8, %15\n\tds_read_b128 %9, %15 offset:4096\n\tds_read_b128 %10, %19\n\tds_read_b128 %11, %19 offset:4096\n\t"
;         "s_waitcnt lgkmcnt(4)\n\t"
;         "v_mfma_f32_32x32x16_bf16 %0, %4, %6, %0\n\tv_mfma_f32_32x32x16_bf16 %1, %4, %7, %1\n\tv_mfma_f32_32x32x16_bf16 %2, %5, %6, %2\n\tv_mfma_f32_32x32x16_bf16 %3, %5, %7, %3\n\t"
;         "s_waitcnt lgkmcnt(0)\n\t"
;         "v_mfma_f32_32x32x16_bf16 %0, %8, %10, %0\n\tv_mfma_f32_32x32x16_bf16 %1, %8, %11, %1\n\tv_mfma_f32_32x32x16_bf16 %2, %9, %10, %2\n\tv_mfma_f32_32x32x16_bf16 %3, %9, %11, %3"
;         : "+v"(acc[0][0]), "+v"(acc[0][1]), "+v"(acc[1][0]), "+v"(acc[1][1]),
;           "=&v"(p0), "=&v"(p1), "=&v"(q0), "=&v"(q1), "=&v"(u0), "=&v"(u1), "=&v"(w0), "=&v"(w1)
	v_mfma_f32_16x16x32_bf16 v[0:3], v[84:87], v[100:103], v[0:3]
	v_mfma_f32_16x16x32_bf16 v[4:7], v[84:87], v[104:107], v[4:7]
	s_add_u32 m0, s30, 0x1e000
	v_lshl_add_u64 v[126:127], v[70:71], 0, s[24:25]
	global_load_lds_dwordx4 v[126:127], off
	v_mfma_f32_16x16x32_bf16 v[8:11], v[84:87], v[108:111], v[8:11]
	v_mfma_f32_16x16x32_bf16 v[12:15], v[84:87], v[112:115], v[12:15]
	v_mfma_f32_16x16x32_bf16 v[16:19], v[88:91], v[100:103], v[16:19]
	v_mfma_f32_16x16x32_bf16 v[20:23], v[88:91], v[104:107], v[20:23]
	v_mfma_f32_16x16x32_bf16 v[24:27], v[88:91], v[108:111], v[24:27]
	s_add_u32 s24, s58, 0x0
	s_addc_u32 s25, s59, 0
	s_add_u32 m0, s30, 0x20000
	v_lshl_add_u64 v[124:125], v[72:73], 0, s[24:25]
	global_load_lds_dwordx4 v[124:125], off
	v_mfma_f32_16x16x32_bf16 v[28:31], v[88:91], v[112:115], v[28:31]
	v_mfma_f32_16x16x32_bf16 v[32:35], v[92:95], v[100:103], v[32:35]
	v_mfma_f32_16x16x32_bf16 v[36:39], v[92:95], v[104:107], v[36:39]
	v_mfma_f32_16x16x32_bf16 v[40:43], v[92:95], v[108:111], v[40:43]
	v_mfma_f32_16x16x32_bf16 v[44:47], v[92:95], v[112:115], v[44:47]
	s_add_u32 m0, s30, 0x22000
	v_lshl_add_u64 v[126:127], v[74:75], 0, s[24:25]
	global_load_lds_dwordx4 v[126:127], off
	v_mfma_f32_16x16x32_bf16 v[48:51], v[96:99], v[100:103], v[48:51]
	v_mfma_f32_16x16x32_bf16 v[52:55], v[96:99], v[104:107], v[52:55]
	v_mfma_f32_16x16x32_bf16 v[56:59], v[96:99], v[108:111], v[56:59]
	v_mfma_f32_16x16x32_bf16 v[60:63], v[96:99], v[112:115], v[60:63]
	s_waitcnt vmcnt(6) lgkmcnt(0)
	s_barrier
	ds_read_b128 v[84:87], v76 offset:49152
	ds_read_b128 v[88:91], v76 offset:51200
	ds_read_b128 v[92:95], v76 offset:53248
	ds_read_b128 v[96:99], v76 offset:55296
	ds_read_b128 v[100:103], v78 offset:49152
	ds_read_b128 v[104:107], v78 offset:51200
	ds_read_b128 v[108:111], v78 offset:53248
	ds_read_b128 v[112:115], v78 offset:55296
	v_mfma_f32_16x16x32_bf16 v[0:3], v[136:139], v[152:155], v[0:3]
	v_mfma_f32_16x16x32_bf16 v[4:7], v[136:139], v[156:159], v[4:7]
	s_add_u32 s24, s56, 0x80
	s_addc_u32 s25, s57, 0
	s_mov_b32 m0, s30
	v_lshl_add_u64 v[124:125], v[64:65], 0, s[24:25]
	global_load_lds_dwordx4 v[124:125], off
	v_mfma_f32_16x16x32_bf16 v[8:11], v[136:139], v[160:163], v[8:11]
	v_mfma_f32_16x16x32_bf16 v[12:15], v[136:139], v[164:167], v[12:15]
	v_mfma_f32_16x16x32_bf16 v[16:19], v[140:143], v[152:155], v[16:19]
	v_mfma_f32_16x16x32_bf16 v[20:23], v[140:143], v[156:159], v[20:23]
	v_mfma_f32_16x16x32_bf16 v[24:27], v[140:143], v[160:163], v[24:27]
	s_add_u32 m0, s30, 0x2000
	v_lshl_add_u64 v[126:127], v[66:67], 0, s[24:25]
	global_load_lds_dwordx4 v[126:127], off
	v_mfma_f32_16x16x32_bf16 v[28:31], v[140:143], v[164:167], v[28:31]
	v_mfma_f32_16x16x32_bf16 v[32:35], v[144:147], v[152:155], v[32:35]
	v_mfma_f32_16x16x32_bf16 v[36:39], v[144:147], v[156:159], v[36:39]
	v_mfma_f32_16x16x32_bf16 v[40:43], v[144:147], v[160:163], v[40:43]
	v_mfma_f32_16x16x32_bf16 v[44:47], v[144:147], v[164:167], v[44:47]
	s_add_u32 m0, s30, 0x4000
	v_lshl_add_u64 v[124:125], v[68:69], 0, s[24:25]
	global_load_lds_dwordx4 v[124:125], off
	v_mfma_f32_16x16x32_bf16 v[48:51], v[148:151], v[152:155], v[48:51]
	v_mfma_f32_16x16x32_bf16 v[52:55], v[148:151], v[156:159], v[52:55]
	v_mfma_f32_16x16x32_bf16 v[56:59], v[148:151], v[160:163], v[56:59]
	v_mfma_f32_16x16x32_bf16 v[60:63], v[148:151], v[164:167], v[60:63]
	ds_read_b128 v[136:139], v77 offset:49152
	ds_read_b128 v[140:143], v77 offset:51200
	ds_read_b128 v[144:147], v77 offset:53248
	ds_read_b128 v[148:151], v77 offset:55296
	ds_read_b128 v[152:155], v79 offset:49152
	ds_read_b128 v[156:159], v79 offset:51200
	ds_read_b128 v[160:163], v79 offset:53248
	ds_read_b128 v[164:167], v79 offset:55296
	s_waitcnt lgkmcnt(8)
	v_mfma_f32_16x16x32_bf16 v[0:3], v[84:87], v[100:103], v[0:3]
	v_mfma_f32_16x16x32_bf16 v[4:7], v[84:87], v[104:107], v[4:7]
	s_add_u32 m0, s30, 0x6000
	v_lshl_add_u64 v[126:127], v[70:71], 0, s[24:25]
	global_load_lds_dwordx4 v[126:127], off
	v_mfma_f32_16x16x32_bf16 v[8:11], v[84:87], v[108:111], v[8:11]
	v_mfma_f32_16x16x32_bf16 v[12:15], v[84:87], v[112:115], v[12:15]
	v_mfma_f32_16x16x32_bf16 v[16:19], v[88:91], v[100:103], v[16:19]
	v_mfma_f32_16x16x32_bf16 v[20:23], v[88:91], v[104:107], v[20:23]
	v_mfma_f32_16x16x32_bf16 v[24:27], v[88:91], v[108:111], v[24:27]
	s_add_u32 s24, s58, 0x80
	s_addc_u32 s25, s59, 0
	s_add_u32 m0, s30, 0x8000
	v_lshl_add_u64 v[124:125], v[72:73], 0, s[24:25]
	global_load_lds_dwordx4 v[124:125], off
	v_mfma_f32_16x16x32_bf16 v[28:31], v[88:91], v[112:115], v[28:31]
	v_mfma_f32_16x16x32_bf16 v[32:35], v[92:95], v[100:103], v[32:35]
	v_mfma_f32_16x16x32_bf16 v[36:39], v[92:95], v[104:107], v[36:39]
	v_mfma_f32_16x16x32_bf16 v[40:43], v[92:95], v[108:111], v[40:43]
	v_mfma_f32_16x16x32_bf16 v[44:47], v[92:95], v[112:115], v[44:47]
	s_add_u32 m0, s30, 0xa000
	v_lshl_add_u64 v[126:127], v[74:75], 0, s[24:25]
	global_load_lds_dwordx4 v[126:127], off
	v_mfma_f32_16x16x32_bf16 v[48:51], v[96:99], v[100:103], v[48:51]
	v_mfma_f32_16x16x32_bf16 v[52:55], v[96:99], v[104:107], v[52:55]
	v_mfma_f32_16x16x32_bf16 v[56:59], v[96:99], v[108:111], v[56:59]
	v_mfma_f32_16x16x32_bf16 v[60:63], v[96:99], v[112:115], v[60:63]
	s_waitcnt lgkmcnt(0)
	v_mfma_f32_16x16x32_bf16 v[0:3], v[136:139], v[152:155], v[0:3]
	v_mfma_f32_16x16x32_bf16 v[4:7], v[136:139], v[156:159], v[4:7]
	v_mfma_f32_16x16x32_bf16 v[8:11], v[136:139], v[160:163], v[8:11]
	v_mfma_f32_16x16x32_bf16 v[12:15], v[136:139], v[164:167], v[12:15]
	v_mfma_f32_16x16x32_bf16 v[16:19], v[140:143], v[152:155], v[16:19]
	v_mfma_f32_16x16x32_bf16 v[20:23], v[140:143], v[156:159], v[20:23]
	v_mfma_f32_16x16x32_bf16 v[24:27], v[140:143], v[160:163], v[24:27]
	v_mfma_f32_16x16x32_bf16 v[28:31], v[140:143], v[164:167], v[28:31]
	v_mfma_f32_16x16x32_bf16 v[32:35], v[144:147], v[152:155], v[32:35]
	v_mfma_f32_16x16x32_bf16 v[36:39], v[144:147], v[156:159], v[36:39]
	v_mfma_f32_16x16x32_bf16 v[40:43], v[144:147], v[160:163], v[40:43]
	v_mfma_f32_16x16x32_bf16 v[44:47], v[144:147], v[164:167], v[44:47]
	v_mfma_f32_16x16x32_bf16 v[48:51], v[148:151], v[152:155], v[48:51]
	v_mfma_f32_16x16x32_bf16 v[52:55], v[148:151], v[156:159], v[52:55]
	v_mfma_f32_16x16x32_bf16 v[56:59], v[148:151], v[160:163], v[56:59]
	v_mfma_f32_16x16x32_bf16 v[60:63], v[148:151], v[164:167], v[60:63]
	s_branch .Ly11_done
;     ...
;   for (int kt = 0; kt < nk; ++kt) {
;     if (kt + 1 < nk) asm volatile("s_waitcnt vmcnt(6)" ::: "memory");
;     else asm volatile("s_waitcnt vmcnt(0)" ::: "memory");
;     __builtin_amdgcn_s_barrier();
;     asm volatile("" ::: "memory");
;     if (kt + 2 < nk) { const int st2 = (st >= 1) ? st - 1 : 2; GEMM_ISSUE(kt + 2, st2); }
;     const char* la = lds + st * STAGE_B;
;     const char* lb = la + 32768;
;     const unsigned sa_u = (unsigned)(size_t)la + arow_u, sb_u = (unsigned)(size_t)lb + brow_u;
;     const unsigned a0 = sa_u + co0, a1 = sa_u + co1, a2 = sa_u + co2, a3 = sa_u + co3;
;     const unsigned b0 = sb_u + co0, b1 = sb_u + co1, b2 = sb_u + co2, b3 = sb_u + co3;
;     {
;       bf16x8 p0, p1, q0, q1, u0, u1, w0, w1;
;       asm volatile(
;         "ds_read_b128 %4, %12\n\tds_read_b128 %5, %12 offset:4096\n\tds_read_b128 %6, %16\n\tds_read_b128 %7, %16 offset:4096\n\t"
;         "ds_read_b128 %8, %13\n\tds_read_b128 %9, %13 offset:4096\n\tds_read_b128 %10, %17\n\tds_read_b128 %11, %17 offset:4096\n\t"
;         "s_waitcnt lgkmcnt(4)\n\t"
;         "v_mfma_f32_32x32x16_bf16 %0, %4, %6, %0\n\tv_mfma_f32_32x32x16_bf16 %1, %4, %7, %1\n\tv_mfma_f32_32x32x16_bf16 %2, %5, %6, %2\n\tv_mfma_f32_32x32x16_bf16 %3, %5, %7, %3\n\t"
;         "ds_read_b128 %4, %14\n\tds_read_b128 %5, %14 offset:4096\n\tds_read_b128 %6, %18\n\tds_read_b128 %7, %18 offset:4096\n\t"
;         "s_waitcnt lgkmcnt(4)\n\t"
;         "v_mfma_f32_32x32x16_bf16 %0, %8, %10, %0\n\tv_mfma_f32_32x32x16_bf16 %1, %8, %11, %1\n\tv_mfma_f32_32x32x16_bf16 %2, %9, %10, %2\n\tv_mfma_f32_32x32x16_bf16 %3, %9, %11, %3\n\t"
;         "ds_read_b128 %8, %15\n\tds_read_b128 %9, %15 offset:4096\n\tds_read_b128 %10, %19\n\tds_read_b128 %11, %19 offset:4096\n\t"
;         "s_waitcnt lgkmcnt(4)\n\t"
;         "v_mfma_f32_32x32x16_bf16 %0, %4, %6, %0\n\tv_mfma_f32_32x32x16_bf16 %1, %4, %7, %1\n\tv_mfma_f32_32x32x16_bf16 %2, %5, %6, %2\n\tv_mfma_f32_32x32x16_bf16 %3, %5, %7, %3\n\t"
;         "s_waitcnt lgkmcnt(0)\n\t"
;         "v_mfma_f32_32x32x16_bf16 %0, %8, %10, %0\n\tv_mfma_f32_32x32x16_bf16 %1, %8, %11, %1\n\tv_mfma_f32_32x32x16_bf16 %2, %9, %10, %2\n\tv_mfma_f32_32x32x16_bf16 %3, %9, %11, %3"
;         : "+v"(acc[0][0]), "+v"(acc[0][1]), "+v"(acc[1][0]), "+v"(acc[1][1]),
;           "=&v"(p0), "=&v"(p1), "=&v"(q0), "=&v"(q1), "=&v"(u0), "=&v"(u1), "=&v"(w0), "=&v"(w1)
.Ly11_v2:
	ds_read_b128 v[84:87], v80
	ds_read_b128 v[88:91], v80 offset:2048
	ds_read_b128 v[92:95], v80 offset:4096
	ds_read_b128 v[96:99], v80 offset:6144
	ds_read_b128 v[100:103], v82
	ds_read_b128 v[104:107], v82 offset:2048
	ds_read_b128 v[108:111], v82 offset:4096
	ds_read_b128 v[112:115], v82 offset:6144
	s_mov_b32 s24, 0x100
	s_mov_b32 s25, 0
	s_add_u32 m0, s30, 0xc000
	v_lshl_add_u64 v[124:125], v[64:65], 0, s[24:25]
	global_load_lds_dwordx4 v[124:125], off
	s_add_u32 m0, s30, 0xe000
	v_lshl_add_u64 v[126:127], v[66:67], 0, s[24:25]
	global_load_lds_dwordx4 v[126:127], off
	s_add_u32 m0, s30, 0x10000
	v_lshl_add_u64 v[124:125], v[68:69], 0, s[24:25]
	global_load_lds_dwordx4 v[124:125], off
	ds_read_b128 v[136:139], v81
	ds_read_b128 v[140:143], v81 offset:2048
	ds_read_b128 v[144:147], v81 offset:4096
	ds_read_b128 v[148:151], v81 offset:6144
	ds_read_b128 v[152:155], v83
	ds_read_b128 v[156:159], v83 offset:2048
	ds_read_b128 v[160:163], v83 offset:4096
	ds_read_b128 v[164:167], v83 offset:6144
	s_waitcnt lgkmcnt(8)
	v_mfma_f32_16x16x32_bf16 v[0:3], v[84:87], v[100:103], v[0:3]
	v_mfma_f32_16x16x32_bf16 v[4:7], v[84:87], v[104:107], v[4:7]
	s_add_u32 m0, s30, 0x12000
	v_lshl_add_u64 v[126:127], v[70:71], 0, s[24:25]
	global_load_lds_dwordx4 v[126:127], off
	v_mfma_f32_16x16x32_bf16 v[8:11], v[84:87], v[108:111], v[8:11]
	v_mfma_f32_16x16x32_bf16 v[12:15], v[84:87], v[112:115], v[12:15]
	v_mfma_f32_16x16x32_bf16 v[16:19], v[88:91], v[100:103], v[16:19]
	v_mfma_f32_16x16x32_bf16 v[20:23], v[88:91], v[104:107], v[20:23]
	v_mfma_f32_16x16x32_bf16 v[24:27], v[88:91], v[108:111], v[24:27]
	s_add_u32 m0, s30, 0x14000
	v_lshl_add_u64 v[124:125], v[72:73], 0, s[24:25]
	global_load_lds_dwordx4 v[124:125], off
	v_mfma_f32_16x16x32_bf16 v[28:31], v[88:91], v[112:115], v[28:31]
	v_mfma_f32_16x16x32_bf16 v[32:35], v[92:95], v[100:103], v[32:35]
	v_mfma_f32_16x16x32_bf16 v[36:39], v[92:95], v[104:107], v[36:39]
	v_mfma_f32_16x16x32_bf16 v[40:43], v[92:95], v[108:111], v[40:43]
	v_mfma_f32_16x16x32_bf16 v[44:47], v[92:95], v[112:115], v[44:47]
	s_add_u32 m0, s30, 0x16000
	v_lshl_add_u64 v[126:127], v[74:75], 0, s[24:25]
	global_load_lds_dwordx4 v[126:127], off
	v_mfma_f32_16x16x32_bf16 v[48:51], v[96:99], v[100:103], v[48:51]
	v_mfma_f32_16x16x32_bf16 v[52:55], v[96:99], v[104:107], v[52:55]
	v_mfma_f32_16x16x32_bf16 v[56:59], v[96:99], v[108:111], v[56:59]
	v_mfma_f32_16x16x32_bf16 v[60:63], v[96:99], v[112:115], v[60:63]
	s_waitcnt vmcnt(6) lgkmcnt(0)
	s_barrier
	ds_read_b128 v[84:87], v76
	ds_read_b128 v[88:91], v76 offset:2048
	ds_read_b128 v[92:95], v76 offset:4096
	ds_read_b128 v[96:99], v76 offset:6144
	ds_read_b128 v[100:103], v78
	ds_read_b128 v[104:107], v78 offset:2048
	ds_read_b128 v[108:111], v78 offset:4096
	ds_read_b128 v[112:115], v78 offset:6144
	v_mfma_f32_16x16x32_bf16 v[0:3], v[136:139], v[152:155], v[0:3]
	v_mfma_f32_16x16x32_bf16 v[4:7], v[136:139], v[156:159], v[4:7]
	s_mov_b32 s24, 0x180
	s_mov_b32 s25, 0
	s_add_u32 m0, s30, 0x18000
	v_lshl_add_u64 v[124:125], v[64:65], 0, s[24:25]
	global_load_lds_dwordx4 v[124:125], off
	v_mfma_f32_16x16x32_bf16 v[8:11], v[136:139], v[160:163], v[8:11]
	v_mfma_f32_16x16x32_bf16 v[12:15], v[136:139], v[164:167], v[12:15]
	v_mfma_f32_16x16x32_bf16 v[16:19], v[140:143], v[152:155], v[16:19]
	v_mfma_f32_16x16x32_bf16 v[20:23], v[140:143], v[156:159], v[20:23]
	v_mfma_f32_16x16x32_bf16 v[24:27], v[140:143], v[160:163], v[24:27]
	s_add_u32 m0, s30, 0x1a000
	v_lshl_add_u64 v[126:127], v[66:67], 0, s[24:25]
	global_load_lds_dwordx4 v[126:127], off
	v_mfma_f32_16x16x32_bf16 v[28:31], v[140:143], v[164:167], v[28:31]
	v_mfma_f32_16x16x32_bf16 v[32:35], v[144:147], v[152:155], v[32:35]
	v_mfma_f32_16x16x32_bf16 v[36:39], v[144:147], v[156:159], v[36:39]
	v_mfma_f32_16x16x32_bf16 v[40:43], v[144:147], v[160:163], v[40:43]
	v_mfma_f32_16x16x32_bf16 v[44:47], v[144:147], v[164:167], v[44:47]
	s_add_u32 m0, s30, 0x1c000
	v_lshl_add_u64 v[124:125], v[68:69], 0, s[24:25]
	global_load_lds_dwordx4 v[124:125], off
	v_mfma_f32_16x16x32_bf16 v[48:51], v[148:151], v[152:155], v[48:51]
	v_mfma_f32_16x16x32_bf16 v[52:55], v[148:151], v[156:159], v[52:55]
	v_mfma_f32_16x16x32_bf16 v[56:59], v[148:151], v[160:163], v[56:59]
	v_mfma_f32_16x16x32_bf16 v[60:63], v[148:151], v[164:167], v[60:63]
	ds_read_b128 v[136:139], v77
	ds_read_b128 v[140:143], v77 offset:2048
	ds_read_b128 v[144:147], v77 offset:4096
	ds_read_b128 v[148:151], v77 offset:6144
	ds_read_b128 v[152:155], v79
	ds_read_b128 v[156:159], v79 offset:2048
	ds_read_b128 v[160:163], v79 offset:4096
	ds_read_b128 v[164:167], v79 offset:6144
	s_waitcnt lgkmcnt(8)
	v_mfma_f32_16x16x32_bf16 v[0:3], v[84:87], v[100:103], v[0:3]
	v_mfma_f32_16x16x32_bf16 v[4:7], v[84:87], v[104:107], v[4:7]
	s_add_u32 m0, s30, 0x1e000
	v_lshl_add_u64 v[126:127], v[70:71], 0, s[24:25]
	global_load_lds_dwordx4 v[126:127], off
	v_mfma_f32_16x16x32_bf16 v[8:11], v[84:87], v[108:111], v[8:11]
	v_mfma_f32_16x16x32_bf16 v[12:15], v[84:87], v[112:115], v[12:15]
	v_mfma_f32_16x16x32_bf16 v[16:19], v[88:91], v[100:103], v[16:19]
	v_mfma_f32_16x16x32_bf16 v[20:23], v[88:91], v[104:107], v[20:23]
	v_mfma_f32_16x16x32_bf16 v[24:27], v[88:91], v[108:111], v[24:27]
	s_add_u32 m0, s30, 0x20000
	v_lshl_add_u64 v[124:125], v[72:73], 0, s[24:25]
	global_load_lds_dwordx4 v[124:125], off
	v_mfma_f32_16x16x32_bf16 v[28:31], v[88:91], v[112:115], v[28:31]
	v_mfma_f32_16x16x32_bf16 v[32:35], v[92:95], v[100:103], v[32:35]
	v_mfma_f32_16x16x32_bf16 v[36:39], v[92:95], v[104:107], v[36:39]
	v_mfma_f32_16x16x32_bf16 v[40:43], v[92:95], v[108:111], v[40:43]
	v_mfma_f32_16x16x32_bf16 v[44:47], v[92:95], v[112:115], v[44:47]
	s_add_u32 m0, s30, 0x22000
	v_lshl_add_u64 v[126:127], v[74:75], 0, s[24:25]
	global_load_lds_dwordx4 v[126:127], off
	v_mfma_f32_16x16x32_bf16 v[48:51], v[96:99], v[100:103], v[48:51]
	v_mfma_f32_16x16x32_bf16 v[52:55], v[96:99], v[104:107], v[52:55]
	v_mfma_f32_16x16x32_bf16 v[56:59], v[96:99], v[108:111], v[56:59]
	v_mfma_f32_16x16x32_bf16 v[60:63], v[96:99], v[112:115], v[60:63]
	s_waitcnt vmcnt(6) lgkmcnt(0)
	s_barrier
;     ...
;   for (int kt = 0; kt < nk; ++kt) {
;     if (kt + 1 < nk) asm volatile("s_waitcnt vmcnt(6)" ::: "memory");
;     else asm volatile("s_waitcnt vmcnt(0)" ::: "memory");
;     __builtin_amdgcn_s_barrier();
;     asm volatile("" ::: "memory");
;     if (kt + 2 < nk) { const int st2 = (st >= 1) ? st - 1 : 2; GEMM_ISSUE(kt + 2, st2); }
;     const char* la = lds + st * STAGE_B;
;     const char* lb = la + 32768;
;     const unsigned sa_u = (unsigned)(size_t)la + arow_u, sb_u = (unsigned)(size_t)lb + brow_u;
;     const unsigned a0 = sa_u + co0, a1 = sa_u + co1, a2 = sa_u + co2, a3 = sa_u + co3;
;     const unsigned b0 = sb_u + co0, b1 = sb_u + co1, b2 = sb_u + co2, b3 = sb_u + co3;
;     {
;       bf16x8 p0, p1, q0, q1, u0, u1, w0, w1;
;       asm volatile(
;         "ds_read_b128 %4, %12\n\tds_read_b128 %5, %12 offset:4096\n\tds_read_b128 %6, %16\n\tds_read_b128 %7, %16 offset:4096\n\t"
;         "ds_read_b128 %8, %13\n\tds_read_b128 %9, %13 offset:4096\n\tds_read_b128 %10, %17\n\tds_read_b128 %11, %17 offset:4096\n\t"
;         "s_waitcnt lgkmcnt(4)\n\t"
;         "v_mfma_f32_32x32x16_bf16 %0, %4, %6, %0\n\tv_mfma_f32_32x32x16_bf16 %1, %4, %7, %1\n\tv_mfma_f32_32x32x16_bf16 %2, %5, %6, %2\n\tv_mfma_f32_32x32x16_bf16 %3, %5, %7, %3\n\t"
;         "ds_read_b128 %4, %14\n\tds_read_b128 %5, %14 offset:4096\n\tds_read_b128 %6, %18\n\tds_read_b128 %7, %18 offset:4096\n\t"
;         "s_waitcnt lgkmcnt(4)\n\t"
;         "v_mfma_f32_32x32x16_bf16 %0, %8, %10, %0\n\tv_mfma_f32_32x32x16_bf16 %1, %8, %11, %1\n\tv_mfma_f32_32x32x16_bf16 %2, %9, %10, %2\n\tv_mfma_f32_32x32x16_bf16 %3, %9, %11, %3\n\t"
;         "ds_read_b128 %8, %15\n\tds_read_b128 %9, %15 offset:4096\n\tds_read_b128 %10, %19\n\tds_read_b128 %11, %19 offset:4096\n\t"
;         "s_waitcnt lgkmcnt(4)\n\t"
;         "v_mfma_f32_32x32x16_bf16 %0, %4, %6, %0\n\tv_mfma_f32_32x32x16_bf16 %1, %4, %7, %1\n\tv_mfma_f32_32x32x16_bf16 %2, %5, %6, %2\n\tv_mfma_f32_32x32x16_bf16 %3, %5, %7, %3\n\t"
;         "s_waitcnt lgkmcnt(0)\n\t"
;         "v_mfma_f32_32x32x16_bf16 %0, %8, %10, %0\n\tv_mfma_f32_32x32x16_bf16 %1, %8, %11, %1\n\tv_mfma_f32_32x32x16_bf16 %2, %9, %10, %2\n\tv_mfma_f32_32x32x16_bf16 %3, %9, %11, %3"
;         : "+v"(acc[0][0]), "+v"(acc[0][1]), "+v"(acc[1][0]), "+v"(acc[1][1]),
;           "=&v"(p0), "=&v"(p1), "=&v"(q0), "=&v"(q1), "=&v"(u0), "=&v"(u1), "=&v"(w0), "=&v"(w1)
	ds_read_b128 v[84:87], v76 offset:49152
	ds_read_b128 v[88:91], v76 offset:51200
	ds_read_b128 v[92:95], v76 offset:53248
	ds_read_b128 v[96:99], v76 offset:55296
	ds_read_b128 v[100:103], v78 offset:49152
	ds_read_b128 v[104:107], v78 offset:51200
	ds_read_b128 v[108:111], v78 offset:53248
	ds_read_b128 v[112:115], v78 offset:55296
	v_mfma_f32_16x16x32_bf16 v[0:3], v[136:139], v[152:155], v[0:3]
	v_mfma_f32_16x16x32_bf16 v[4:7], v[136:139], v[156:159], v[4:7]
	s_mov_b32 s24, 0x200
	s_mov_b32 s25, 0
	s_mov_b32 m0, s30
	v_lshl_add_u64 v[124:125], v[64:65], 0, s[24:25]
	global_load_lds_dwordx4 v[124:125], off
	v_mfma_f32_16x16x32_bf16 v[8:11], v[136:139], v[160:163], v[8:11]
	v_mfma_f32_16x16x32_bf16 v[12:15], v[136:139], v[164:167], v[12:15]
	v_mfma_f32_16x16x32_bf16 v[16:19], v[140:143], v[152:155], v[16:19]
	v_mfma_f32_16x16x32_bf16 v[20:23], v[140:143], v[156:159], v[20:23]
	v_mfma_f32_16x16x32_bf16 v[24:27], v[140:143], v[160:163], v[24:27]
	s_add_u32 m0, s30, 0x2000
	v_lshl_add_u64 v[126:127], v[66:67], 0, s[24:25]
	global_load_lds_dwordx4 v[126:127], off
	v_mfma_f32_16x16x32_bf16 v[28:31], v[140:143], v[164:167], v[28:31]
	v_mfma_f32_16x16x32_bf16 v[32:35], v[144:147], v[152:155], v[32:35]
	v_mfma_f32_16x16x32_bf16 v[36:39], v[144:147], v[156:159], v[36:39]
	v_mfma_f32_16x16x32_bf16 v[40:43], v[144:147], v[160:163], v[40:43]
	v_mfma_f32_16x16x32_bf16 v[44:47], v[144:147], v[164:167], v[44:47]
	s_add_u32 m0, s30, 0x4000
	v_lshl_add_u64 v[124:125], v[68:69], 0, s[24:25]
	global_load_lds_dwordx4 v[124:125], off
	v_mfma_f32_16x16x32_bf16 v[48:51], v[148:151], v[152:155], v[48:51]
	v_mfma_f32_16x16x32_bf16 v[52:55], v[148:151], v[156:159], v[52:55]
	v_mfma_f32_16x16x32_bf16 v[56:59], v[148:151], v[160:163], v[56:59]
	v_mfma_f32_16x16x32_bf16 v[60:63], v[148:151], v[164:167], v[60:63]
	ds_read_b128 v[136:139], v77 offset:49152
	ds_read_b128 v[140:143], v77 offset:51200
	ds_read_b128 v[144:147], v77 offset:53248
	ds_read_b128 v[148:151], v77 offset:55296
	ds_read_b128 v[152:155], v79 offset:49152
	ds_read_b128 v[156:159], v79 offset:51200
	ds_read_b128 v[160:163], v79 offset:53248
	ds_read_b128 v[164:167], v79 offset:55296
	s_waitcnt lgkmcnt(8)
	v_mfma_f32_16x16x32_bf16 v[0:3], v[84:87], v[100:103], v[0:3]
	v_mfma_f32_16x16x32_bf16 v[4:7], v[84:87], v[104:107], v[4:7]
	s_add_u32 m0, s30, 0x6000
	v_lshl_add_u64 v[126:127], v[70:71], 0, s[24:25]
	global_load_lds_dwordx4 v[126:127], off
	v_mfma_f32_16x16x32_bf16 v[8:11], v[84:87], v[108:111], v[8:11]
	v_mfma_f32_16x16x32_bf16 v[12:15], v[84:87], v[112:115], v[12:15]
	v_mfma_f32_16x16x32_bf16 v[16:19], v[88:91], v[100:103], v[16:19]
	v_mfma_f32_16x16x32_bf16 v[20:23], v[88:91], v[104:107], v[20:23]
	v_mfma_f32_16x16x32_bf16 v[24:27], v[88:91], v[108:111], v[24:27]
	s_add_u32 m0, s30, 0x8000
	v_lshl_add_u64 v[124:125], v[72:73], 0, s[24:25]
	global_load_lds_dwordx4 v[124:125], off
	v_mfma_f32_16x16x32_bf16 v[28:31], v[88:91], v[112:115], v[28:31]
	v_mfma_f32_16x16x32_bf16 v[32:35], v[92:95], v[100:103], v[32:35]
	v_mfma_f32_16x16x32_bf16 v[36:39], v[92:95], v[104:107], v[36:39]
	v_mfma_f32_16x16x32_bf16 v[40:43], v[92:95], v[108:111], v[40:43]
	v_mfma_f32_16x16x32_bf16 v[44:47], v[92:95], v[112:115], v[44:47]
	s_add_u32 m0, s30, 0xa000
	v_lshl_add_u64 v[126:127], v[74:75], 0, s[24:25]
	global_load_lds_dwordx4 v[126:127], off
	v_mfma_f32_16x16x32_bf16 v[48:51], v[96:99], v[100:103], v[48:51]
	v_mfma_f32_16x16x32_bf16 v[52:55], v[96:99], v[104:107], v[52:55]
	v_mfma_f32_16x16x32_bf16 v[56:59], v[96:99], v[108:111], v[56:59]
	v_mfma_f32_16x16x32_bf16 v[60:63], v[96:99], v[112:115], v[60:63]
	s_waitcnt vmcnt(6) lgkmcnt(0)
	s_barrier
	ds_read_b128 v[84:87], v80
	ds_read_b128 v[88:91], v80 offset:2048
	ds_read_b128 v[92:95], v80 offset:4096
	ds_read_b128 v[96:99], v80 offset:6144
	ds_read_b128 v[100:103], v82
	ds_read_b128 v[104:107], v82 offset:2048
	ds_read_b128 v[108:111], v82 offset:4096
	ds_read_b128 v[112:115], v82 offset:6144
	v_mfma_f32_16x16x32_bf16 v[0:3], v[136:139], v[152:155], v[0:3]
	v_mfma_f32_16x16x32_bf16 v[4:7], v[136:139], v[156:159], v[4:7]
	s_mov_b32 s24, 0x280
	s_mov_b32 s25, 0
	s_add_u32 m0, s30, 0xc000
	v_lshl_add_u64 v[124:125], v[64:65], 0, s[24:25]
	global_load_lds_dwordx4 v[124:125], off
	v_mfma_f32_16x16x32_bf16 v[8:11], v[136:139], v[160:163], v[8:11]
	v_mfma_f32_16x16x32_bf16 v[12:15], v[136:139], v[164:167], v[12:15]
	v_mfma_f32_16x16x32_bf16 v[16:19], v[140:143], v[152:155], v[16:19]
	v_mfma_f32_16x16x32_bf16 v[20:23], v[140:143], v[156:159], v[20:23]
	v_mfma_f32_16x16x32_bf16 v[24:27], v[140:143], v[160:163], v[24:27]
	s_add_u32 m0, s30, 0xe000
	v_lshl_add_u64 v[126:127], v[66:67], 0, s[24:25]
	global_load_lds_dwordx4 v[126:127], off
	v_mfma_f32_16x16x32_bf16 v[28:31], v[140:143], v[164:167], v[28:31]
	v_mfma_f32_16x16x32_bf16 v[32:35], v[144:147], v[152:155], v[32:35]
	v_mfma_f32_16x16x32_bf16 v[36:39], v[144:147], v[156:159], v[36:39]
	v_mfma_f32_16x16x32_bf16 v[40:43], v[144:147], v[160:163], v[40:43]
	v_mfma_f32_16x16x32_bf16 v[44:47], v[144:147], v[164:167], v[44:47]
	s_add_u32 m0, s30, 0x10000
	v_lshl_add_u64 v[124:125], v[68:69], 0, s[24:25]
	global_load_lds_dwordx4 v[124:125], off
	v_mfma_f32_16x16x32_bf16 v[48:51], v[148:151], v[152:155], v[48:51]
	v_mfma_f32_16x16x32_bf16 v[52:55], v[148:151], v[156:159], v[52:55]
	v_mfma_f32_16x16x32_bf16 v[56:59], v[148:151], v[160:163], v[56:59]
	v_mfma_f32_16x16x32_bf16 v[60:63], v[148:151], v[164:167], v[60:63]
	ds_read_b128 v[136:139], v81
	ds_read_b128 v[140:143], v81 offset:2048
	ds_read_b128 v[144:147], v81 offset:4096
	ds_read_b128 v[148:151], v81 offset:6144
	ds_read_b128 v[152:155], v83
	ds_read_b128 v[156:159], v83 offset:2048
	ds_read_b128 v[160:163], v83 offset:4096
	ds_read_b128 v[164:167], v83 offset:6144
	s_waitcnt lgkmcnt(8)
;     ...
;   for (int kt = 0; kt < nk; ++kt) {
;     if (kt + 1 < nk) asm volatile("s_waitcnt vmcnt(6)" ::: "memory");
;     else asm volatile("s_waitcnt vmcnt(0)" ::: "memory");
;     __builtin_amdgcn_s_barrier();
;     asm volatile("" ::: "memory");
;     if (kt + 2 < nk) { const int st2 = (st >= 1) ? st - 1 : 2; GEMM_ISSUE(kt + 2, st2); }
;     const char* la = lds + st * STAGE_B;
;     const char* lb = la + 32768;
;     const unsigned sa_u = (unsigned)(size_t)la + arow_u, sb_u = (unsigned)(size_t)lb + brow_u;
;     const unsigned a0 = sa_u + co0, a1 = sa_u + co1, a2 = sa_u + co2, a3 = sa_u + co3;
;     const unsigned b0 = sb_u + co0, b1 = sb_u + co1, b2 = sb_u + co2, b3 = sb_u + co3;
;     {
;       bf16x8 p0, p1, q0, q1, u0, u1, w0, w1;
;       asm volatile(
;         "ds_read_b128 %4, %12\n\tds_read_b128 %5, %12 offset:4096\n\tds_read_b128 %6, %16\n\tds_read_b128 %7, %16 offset:4096\n\t"
;         "ds_read_b128 %8, %13\n\tds_read_b128 %9, %13 offset:4096\n\tds_read_b128 %10, %17\n\tds_read_b128 %11, %17 offset:4096\n\t"
;         "s_waitcnt lgkmcnt(4)\n\t"
;         "v_mfma_f32_32x32x16_bf16 %0, %4, %6, %0\n\tv_mfma_f32_32x32x16_bf16 %1, %4, %7, %1\n\tv_mfma_f32_32x32x16_bf16 %2, %5, %6, %2\n\tv_mfma_f32_32x32x16_bf16 %3, %5, %7, %3\n\t"
;         "ds_read_b128 %4, %14\n\tds_read_b128 %5, %14 offset:4096\n\tds_read_b128 %6, %18\n\tds_read_b128 %7, %18 offset:4096\n\t"
;         "s_waitcnt lgkmcnt(4)\n\t"
;         "v_mfma_f32_32x32x16_bf16 %0, %8, %10, %0\n\tv_mfma_f32_32x32x16_bf16 %1, %8, %11, %1\n\tv_mfma_f32_32x32x16_bf16 %2, %9, %10, %2\n\tv_mfma_f32_32x32x16_bf16 %3, %9, %11, %3\n\t"
;         "ds_read_b128 %8, %15\n\tds_read_b128 %9, %15 offset:4096\n\tds_read_b128 %10, %19\n\tds_read_b128 %11, %19 offset:4096\n\t"
;         "s_waitcnt lgkmcnt(4)\n\t"
;         "v_mfma_f32_32x32x16_bf16 %0, %4, %6, %0\n\tv_mfma_f32_32x32x16_bf16 %1, %4, %7, %1\n\tv_mfma_f32_32x32x16_bf16 %2, %5, %6, %2\n\tv_mfma_f32_32x32x16_bf16 %3, %5, %7, %3\n\t"
;         "s_waitcnt lgkmcnt(0)\n\t"
;         "v_mfma_f32_32x32x16_bf16 %0, %8, %10, %0\n\tv_mfma_f32_32x32x16_bf16 %1, %8, %11, %1\n\tv_mfma_f32_32x32x16_bf16 %2, %9, %10, %2\n\tv_mfma_f32_32x32x16_bf16 %3, %9, %11, %3"
;         : "+v"(acc[0][0]), "+v"(acc[0][1]), "+v"(acc[1][0]), "+v"(acc[1][1]),
;           "=&v"(p0), "=&v"(p1), "=&v"(q0), "=&v"(q1), "=&v"(u0), "=&v"(u1), "=&v"(w0), "=&v"(w1)
	v_mfma_f32_16x16x32_bf16 v[0:3], v[84:87], v[100:103], v[0:3]
	v_mfma_f32_16x16x32_bf16 v[4:7], v[84:87], v[104:107], v[4:7]
	s_add_u32 m0, s30, 0x12000
	v_lshl_add_u64 v[126:127], v[70:71], 0, s[24:25]
	global_load_lds_dwordx4 v[126:127], off
	v_mfma_f32_16x16x32_bf16 v[8:11], v[84:87], v[108:111], v[8:11]
	v_mfma_f32_16x16x32_bf16 v[12:15], v[84:87], v[112:115], v[12:15]
	v_mfma_f32_16x16x32_bf16 v[16:19], v[88:91], v[100:103], v[16:19]
	v_mfma_f32_16x16x32_bf16 v[20:23], v[88:91], v[104:107], v[20:23]
	v_mfma_f32_16x16x32_bf16 v[24:27], v[88:91], v[108:111], v[24:27]
	s_add_u32 m0, s30, 0x14000
	v_lshl_add_u64 v[124:125], v[72:73], 0, s[24:25]
	global_load_lds_dwordx4 v[124:125], off
	v_mfma_f32_16x16x32_bf16 v[28:31], v[88:91], v[112:115], v[28:31]
	v_mfma_f32_16x16x32_bf16 v[32:35], v[92:95], v[100:103], v[32:35]
	v_mfma_f32_16x16x32_bf16 v[36:39], v[92:95], v[104:107], v[36:39]
	v_mfma_f32_16x16x32_bf16 v[40:43], v[92:95], v[108:111], v[40:43]
	v_mfma_f32_16x16x32_bf16 v[44:47], v[92:95], v[112:115], v[44:47]
	s_add_u32 m0, s30, 0x16000
	v_lshl_add_u64 v[126:127], v[74:75], 0, s[24:25]
	global_load_lds_dwordx4 v[126:127], off
	v_mfma_f32_16x16x32_bf16 v[48:51], v[96:99], v[100:103], v[48:51]
	v_mfma_f32_16x16x32_bf16 v[52:55], v[96:99], v[104:107], v[52:55]
	v_mfma_f32_16x16x32_bf16 v[56:59], v[96:99], v[108:111], v[56:59]
	v_mfma_f32_16x16x32_bf16 v[60:63], v[96:99], v[112:115], v[60:63]
	s_waitcnt vmcnt(6) lgkmcnt(0)
	s_barrier
	ds_read_b128 v[84:87], v76
	ds_read_b128 v[88:91], v76 offset:2048
	ds_read_b128 v[92:95], v76 offset:4096
	ds_read_b128 v[96:99], v76 offset:6144
	ds_read_b128 v[100:103], v78
	ds_read_b128 v[104:107], v78 offset:2048
	ds_read_b128 v[108:111], v78 offset:4096
	ds_read_b128 v[112:115], v78 offset:6144
	v_mfma_f32_16x16x32_bf16 v[0:3], v[136:139], v[152:155], v[0:3]
	v_mfma_f32_16x16x32_bf16 v[4:7], v[136:139], v[156:159], v[4:7]
	s_mov_b32 s24, 0x300
	s_mov_b32 s25, 0
	s_add_u32 m0, s30, 0x18000
	v_lshl_add_u64 v[124:125], v[64:65], 0, s[24:25]
	global_load_lds_dwordx4 v[124:125], off
	v_mfma_f32_16x16x32_bf16 v[8:11], v[136:139], v[160:163], v[8:11]
	v_mfma_f32_16x16x32_bf16 v[12:15], v[136:139], v[164:167], v[12:15]
	v_mfma_f32_16x16x32_bf16 v[16:19], v[140:143], v[152:155], v[16:19]
	v_mfma_f32_16x16x32_bf16 v[20:23], v[140:143], v[156:159], v[20:23]
	v_mfma_f32_16x16x32_bf16 v[24:27], v[140:143], v[160:163], v[24:27]
	s_add_u32 m0, s30, 0x1a000
	v_lshl_add_u64 v[126:127], v[66:67], 0, s[24:25]
	global_load_lds_dwordx4 v[126:127], off
	v_mfma_f32_16x16x32_bf16 v[28:31], v[140:143], v[164:167], v[28:31]
	v_mfma_f32_16x16x32_bf16 v[32:35], v[144:147], v[152:155], v[32:35]
	v_mfma_f32_16x16x32_bf16 v[36:39], v[144:147], v[156:159], v[36:39]
	v_mfma_f32_16x16x32_bf16 v[40:43], v[144:147], v[160:163], v[40:43]
	v_mfma_f32_16x16x32_bf16 v[44:47], v[144:147], v[164:167], v[44:47]
	s_add_u32 m0, s30, 0x1c000
	v_lshl_add_u64 v[124:125], v[68:69], 0, s[24:25]
	global_load_lds_dwordx4 v[124:125], off
	v_mfma_f32_16x16x32_bf16 v[48:51], v[148:151], v[152:155], v[48:51]
	v_mfma_f32_16x16x32_bf16 v[52:55], v[148:151], v[156:159], v[52:55]
	v_mfma_f32_16x16x32_bf16 v[56:59], v[148:151], v[160:163], v[56:59]
	v_mfma_f32_16x16x32_bf16 v[60:63], v[148:151], v[164:167], v[60:63]
	ds_read_b128 v[136:139], v77
	ds_read_b128 v[140:143], v77 offset:2048
	ds_read_b128 v[144:147], v77 offset:4096
	ds_read_b128 v[148:151], v77 offset:6144
	ds_read_b128 v[152:155], v79
	ds_read_b128 v[156:159], v79 offset:2048
	ds_read_b128 v[160:163], v79 offset:4096
	ds_read_b128 v[164:167], v79 offset:6144
	s_waitcnt lgkmcnt(8)
	v_mfma_f32_16x16x32_bf16 v[0:3], v[84:87], v[100:103], v[0:3]
	v_mfma_f32_16x16x32_bf16 v[4:7], v[84:87], v[104:107], v[4:7]
	s_add_u32 m0, s30, 0x1e000
	v_lshl_add_u64 v[126:127], v[70:71], 0, s[24:25]
	global_load_lds_dwordx4 v[126:127], off
	v_mfma_f32_16x16x32_bf16 v[8:11], v[84:87], v[108:111], v[8:11]
	v_mfma_f32_16x16x32_bf16 v[12:15], v[84:87], v[112:115], v[12:15]
	v_mfma_f32_16x16x32_bf16 v[16:19], v[88:91], v[100:103], v[16:19]
	v_mfma_f32_16x16x32_bf16 v[20:23], v[88:91], v[104:107], v[20:23]
	v_mfma_f32_16x16x32_bf16 v[24:27], v[88:91], v[108:111], v[24:27]
	s_add_u32 m0, s30, 0x20000
	v_lshl_add_u64 v[124:125], v[72:73], 0, s[24:25]
	global_load_lds_dwordx4 v[124:125], off
	v_mfma_f32_16x16x32_bf16 v[28:31], v[88:91], v[112:115], v[28:31]
	v_mfma_f32_16x16x32_bf16 v[32:35], v[92:95], v[100:103], v[32:35]
	v_mfma_f32_16x16x32_bf16 v[36:39], v[92:95], v[104:107], v[36:39]
	v_mfma_f32_16x16x32_bf16 v[40:43], v[92:95], v[108:111], v[40:43]
	v_mfma_f32_16x16x32_bf16 v[44:47], v[92:95], v[112:115], v[44:47]
	s_add_u32 m0, s30, 0x22000
	v_lshl_add_u64 v[126:127], v[74:75], 0, s[24:25]
	global_load_lds_dwordx4 v[126:127], off
	v_mfma_f32_16x16x32_bf16 v[48:51], v[96:99], v[100:103], v[48:51]
	v_mfma_f32_16x16x32_bf16 v[52:55], v[96:99], v[104:107], v[52:55]
	v_mfma_f32_16x16x32_bf16 v[56:59], v[96:99], v[108:111], v[56:59]
	v_mfma_f32_16x16x32_bf16 v[60:63], v[96:99], v[112:115], v[60:63]
	s_waitcnt vmcnt(6) lgkmcnt(0)
	s_barrier
;     ...
;   for (int kt = 0; kt < nk; ++kt) {
;     if (kt + 1 < nk) asm volatile("s_waitcnt vmcnt(6)" ::: "memory");
;     else asm volatile("s_waitcnt vmcnt(0)" ::: "memory");
;     __builtin_amdgcn_s_barrier();
;     asm volatile("" ::: "memory");
;     if (kt + 2 < nk) { const int st2 = (st >= 1) ? st - 1 : 2; GEMM_ISSUE(kt + 2, st2); }
;     const char* la = lds + st * STAGE_B;
;     const char* lb = la + 32768;
;     const unsigned sa_u = (unsigned)(size_t)la + arow_u, sb_u = (unsigned)(size_t)lb + brow_u;
;     const unsigned a0 = sa_u + co0, a1 = sa_u + co1, a2 = sa_u + co2, a3 = sa_u + co3;
;     const unsigned b0 = sb_u + co0, b1 = sb_u + co1, b2 = sb_u + co2, b3 = sb_u + co3;
;     {
;       bf16x8 p0, p1, q0, q1, u0, u1, w0, w1;
;       asm volatile(
;         "ds_read_b128 %4, %12\n\tds_read_b128 %5, %12 offset:4096\n\tds_read_b128 %6, %16\n\tds_read_b128 %7, %16 offset:4096\n\t"
;         "ds_read_b128 %8, %13\n\tds_read_b128 %9, %13 offset:4096\n\tds_read_b128 %10, %17\n\tds_read_b128 %11, %17 offset:4096\n\t"
;         "s_waitcnt lgkmcnt(4)\n\t"
;         "v_mfma_f32_32x32x16_bf16 %0, %4, %6, %0\n\tv_mfma_f32_32x32x16_bf16 %1, %4, %7, %1\n\tv_mfma_f32_32x32x16_bf16 %2, %5, %6, %2\n\tv_mfma_f32_32x32x16_bf16 %3, %5, %7, %3\n\t"
;         "ds_read_b128 %4, %14\n\tds_read_b128 %5, %14 offset:4096\n\tds_read_b128 %6, %18\n\tds_read_b128 %7, %18 offset:4096\n\t"
;         "s_waitcnt lgkmcnt(4)\n\t"
;         "v_mfma_f32_32x32x16_bf16 %0, %8, %10, %0\n\tv_mfma_f32_32x32x16_bf16 %1, %8, %11, %1\n\tv_mfma_f32_32x32x16_bf16 %2, %9, %10, %2\n\tv_mfma_f32_32x32x16_bf16 %3, %9, %11, %3\n\t"
;         "ds_read_b128 %8, %15\n\tds_read_b128 %9, %15 offset:4096\n\tds_read_b128 %10, %19\n\tds_read_b128 %11, %19 offset:4096\n\t"
;         "s_waitcnt lgkmcnt(4)\n\t"
;         "v_mfma_f32_32x32x16_bf16 %0, %4, %6, %0\n\tv_mfma_f32_32x32x16_bf16 %1, %4, %7, %1\n\tv_mfma_f32_32x32x16_bf16 %2, %5, %6, %2\n\tv_mfma_f32_32x32x16_bf16 %3, %5, %7, %3\n\t"
;         "s_waitcnt lgkmcnt(0)\n\t"
;         "v_mfma_f32_32x32x16_bf16 %0, %8, %10, %0\n\tv_mfma_f32_32x32x16_bf16 %1, %8, %11, %1\n\tv_mfma_f32_32x32x16_bf16 %2, %9, %10, %2\n\tv_mfma_f32_32x32x16_bf16 %3, %9, %11, %3"
;         : "+v"(acc[0][0]), "+v"(acc[0][1]), "+v"(acc[1][0]), "+v"(acc[1][1]),
;           "=&v"(p0), "=&v"(p1), "=&v"(q0), "=&v"(q1), "=&v"(u0), "=&v"(u1), "=&v"(w0), "=&v"(w1)
	ds_read_b128 v[84:87], v76 offset:49152
	ds_read_b128 v[88:91], v76 offset:51200
	ds_read_b128 v[92:95], v76 offset:53248
	ds_read_b128 v[96:99], v76 offset:55296
	ds_read_b128 v[100:103], v78 offset:49152
	ds_read_b128 v[104:107], v78 offset:51200
	ds_read_b128 v[108:111], v78 offset:53248
	ds_read_b128 v[112:115], v78 offset:55296
	v_mfma_f32_16x16x32_bf16 v[0:3], v[136:139], v[152:155], v[0:3]
	v_mfma_f32_16x16x32_bf16 v[4:7], v[136:139], v[156:159], v[4:7]
	s_mov_b32 s24, 0x380
	s_mov_b32 s25, 0
	s_mov_b32 m0, s30
	v_lshl_add_u64 v[124:125], v[64:65], 0, s[24:25]
	global_load_lds_dwordx4 v[124:125], off
	v_mfma_f32_16x16x32_bf16 v[8:11], v[136:139], v[160:163], v[8:11]
	v_mfma_f32_16x16x32_bf16 v[12:15], v[136:139], v[164:167], v[12:15]
	v_mfma_f32_16x16x32_bf16 v[16:19], v[140:143], v[152:155], v[16:19]
	v_mfma_f32_16x16x32_bf16 v[20:23], v[140:143], v[156:159], v[20:23]
	v_mfma_f32_16x16x32_bf16 v[24:27], v[140:143], v[160:163], v[24:27]
	s_add_u32 m0, s30, 0x2000
	v_lshl_add_u64 v[126:127], v[66:67], 0, s[24:25]
	global_load_lds_dwordx4 v[126:127], off
	v_mfma_f32_16x16x32_bf16 v[28:31], v[140:143], v[164:167], v[28:31]
	v_mfma_f32_16x16x32_bf16 v[32:35], v[144:147], v[152:155], v[32:35]
	v_mfma_f32_16x16x32_bf16 v[36:39], v[144:147], v[156:159], v[36:39]
	v_mfma_f32_16x16x32_bf16 v[40:43], v[144:147], v[160:163], v[40:43]
	v_mfma_f32_16x16x32_bf16 v[44:47], v[144:147], v[164:167], v[44:47]
	s_add_u32 m0, s30, 0x4000
	v_lshl_add_u64 v[124:125], v[68:69], 0, s[24:25]
	global_load_lds_dwordx4 v[124:125], off
	v_mfma_f32_16x16x32_bf16 v[48:51], v[148:151], v[152:155], v[48:51]
	v_mfma_f32_16x16x32_bf16 v[52:55], v[148:151], v[156:159], v[52:55]
	v_mfma_f32_16x16x32_bf16 v[56:59], v[148:151], v[160:163], v[56:59]
	v_mfma_f32_16x16x32_bf16 v[60:63], v[148:151], v[164:167], v[60:63]
	ds_read_b128 v[136:139], v77 offset:49152
	ds_read_b128 v[140:143], v77 offset:51200
	ds_read_b128 v[144:147], v77 offset:53248
	ds_read_b128 v[148:151], v77 offset:55296
	ds_read_b128 v[152:155], v79 offset:49152
	ds_read_b128 v[156:159], v79 offset:51200
	ds_read_b128 v[160:163], v79 offset:53248
	ds_read_b128 v[164:167], v79 offset:55296
	s_waitcnt lgkmcnt(8)
	v_mfma_f32_16x16x32_bf16 v[0:3], v[84:87], v[100:103], v[0:3]
	v_mfma_f32_16x16x32_bf16 v[4:7], v[84:87], v[104:107], v[4:7]
	s_add_u32 m0, s30, 0x6000
	v_lshl_add_u64 v[126:127], v[70:71], 0, s[24:25]
	global_load_lds_dwordx4 v[126:127], off
	v_mfma_f32_16x16x32_bf16 v[8:11], v[84:87], v[108:111], v[8:11]
	v_mfma_f32_16x16x32_bf16 v[12:15], v[84:87], v[112:115], v[12:15]
	v_mfma_f32_16x16x32_bf16 v[16:19], v[88:91], v[100:103], v[16:19]
	v_mfma_f32_16x16x32_bf16 v[20:23], v[88:91], v[104:107], v[20:23]
	v_mfma_f32_16x16x32_bf16 v[24:27], v[88:91], v[108:111], v[24:27]
	s_add_u32 m0, s30, 0x8000
	v_lshl_add_u64 v[124:125], v[72:73], 0, s[24:25]
	global_load_lds_dwordx4 v[124:125], off
	v_mfma_f32_16x16x32_bf16 v[28:31], v[88:91], v[112:115], v[28:31]
	v_mfma_f32_16x16x32_bf16 v[32:35], v[92:95], v[100:103], v[32:35]
	v_mfma_f32_16x16x32_bf16 v[36:39], v[92:95], v[104:107], v[36:39]
	v_mfma_f32_16x16x32_bf16 v[40:43], v[92:95], v[108:111], v[40:43]
	v_mfma_f32_16x16x32_bf16 v[44:47], v[92:95], v[112:115], v[44:47]
	s_add_u32 m0, s30, 0xa000
	v_lshl_add_u64 v[126:127], v[74:75], 0, s[24:25]
	global_load_lds_dwordx4 v[126:127], off
	v_mfma_f32_16x16x32_bf16 v[48:51], v[96:99], v[100:103], v[48:51]
	v_mfma_f32_16x16x32_bf16 v[52:55], v[96:99], v[104:107], v[52:55]
	v_mfma_f32_16x16x32_bf16 v[56:59], v[96:99], v[108:111], v[56:59]
	v_mfma_f32_16x16x32_bf16 v[60:63], v[96:99], v[112:115], v[60:63]
	s_waitcnt vmcnt(6) lgkmcnt(0)
	s_barrier
	ds_read_b128 v[84:87], v80
	ds_read_b128 v[88:91], v80 offset:2048
	ds_read_b128 v[92:95], v80 offset:4096
	ds_read_b128 v[96:99], v80 offset:6144
	ds_read_b128 v[100:103], v82
	ds_read_b128 v[104:107], v82 offset:2048
	ds_read_b128 v[108:111], v82 offset:4096
	ds_read_b128 v[112:115], v82 offset:6144
	v_mfma_f32_16x16x32_bf16 v[0:3], v[136:139], v[152:155], v[0:3]
	v_mfma_f32_16x16x32_bf16 v[4:7], v[136:139], v[156:159], v[4:7]
	s_mov_b32 s24, 0x400
	s_mov_b32 s25, 0
	s_add_u32 m0, s30, 0xc000
	v_lshl_add_u64 v[124:125], v[64:65], 0, s[24:25]
	global_load_lds_dwordx4 v[124:125], off
	v_mfma_f32_16x16x32_bf16 v[8:11], v[136:139], v[160:163], v[8:11]
	v_mfma_f32_16x16x32_bf16 v[12:15], v[136:139], v[164:167], v[12:15]
	v_mfma_f32_16x16x32_bf16 v[16:19], v[140:143], v[152:155], v[16:19]
	v_mfma_f32_16x16x32_bf16 v[20:23], v[140:143], v[156:159], v[20:23]
	v_mfma_f32_16x16x32_bf16 v[24:27], v[140:143], v[160:163], v[24:27]
	s_add_u32 m0, s30, 0xe000
	v_lshl_add_u64 v[126:127], v[66:67], 0, s[24:25]
	global_load_lds_dwordx4 v[126:127], off
	v_mfma_f32_16x16x32_bf16 v[28:31], v[140:143], v[164:167], v[28:31]
	v_mfma_f32_16x16x32_bf16 v[32:35], v[144:147], v[152:155], v[32:35]
	v_mfma_f32_16x16x32_bf16 v[36:39], v[144:147], v[156:159], v[36:39]
	v_mfma_f32_16x16x32_bf16 v[40:43], v[144:147], v[160:163], v[40:43]
	v_mfma_f32_16x16x32_bf16 v[44:47], v[144:147], v[164:167], v[44:47]
	s_add_u32 m0, s30, 0x10000
	v_lshl_add_u64 v[124:125], v[68:69], 0, s[24:25]
	global_load_lds_dwordx4 v[124:125], off
	v_mfma_f32_16x16x32_bf16 v[48:51], v[148:151], v[152:155], v[48:51]
	v_mfma_f32_16x16x32_bf16 v[52:55], v[148:151], v[156:159], v[52:55]
	v_mfma_f32_16x16x32_bf16 v[56:59], v[148:151], v[160:163], v[56:59]
	v_mfma_f32_16x16x32_bf16 v[60:63], v[148:151], v[164:167], v[60:63]
	ds_read_b128 v[136:139], v81
	ds_read_b128 v[140:143], v81 offset:2048
	ds_read_b128 v[144:147], v81 offset:4096
	ds_read_b128 v[148:151], v81 offset:6144
	ds_read_b128 v[152:155], v83
	ds_read_b128 v[156:159], v83 offset:2048
	ds_read_b128 v[160:163], v83 offset:4096
	ds_read_b128 v[164:167], v83 offset:6144
	s_waitcnt lgkmcnt(8)
;     ...
;   for (int kt = 0; kt < nk; ++kt) {
;     if (kt + 1 < nk) asm volatile("s_waitcnt vmcnt(6)" ::: "memory");
;     else asm volatile("s_waitcnt vmcnt(0)" ::: "memory");
;     __builtin_amdgcn_s_barrier();
;     asm volatile("" ::: "memory");
;     if (kt + 2 < nk) { const int st2 = (st >= 1) ? st - 1 : 2; GEMM_ISSUE(kt + 2, st2); }
;     const char* la = lds + st * STAGE_B;
;     const char* lb = la + 32768;
;     const unsigned sa_u = (unsigned)(size_t)la + arow_u, sb_u = (unsigned)(size_t)lb + brow_u;
;     const unsigned a0 = sa_u + co0, a1 = sa_u + co1, a2 = sa_u + co2, a3 = sa_u + co3;
;     const unsigned b0 = sb_u + co0, b1 = sb_u + co1, b2 = sb_u + co2, b3 = sb_u + co3;
;     {
;       bf16x8 p0, p1, q0, q1, u0, u1, w0, w1;
;       asm volatile(
;         "ds_read_b128 %4, %12\n\tds_read_b128 %5, %12 offset:4096\n\tds_read_b128 %6, %16\n\tds_read_b128 %7, %16 offset:4096\n\t"
;         "ds_read_b128 %8, %13\n\tds_read_b128 %9, %13 offset:4096\n\tds_read_b128 %10, %17\n\tds_read_b128 %11, %17 offset:4096\n\t"
;         "s_waitcnt lgkmcnt(4)\n\t"
;         "v_mfma_f32_32x32x16_bf16 %0, %4, %6, %0\n\tv_mfma_f32_32x32x16_bf16 %1, %4, %7, %1\n\tv_mfma_f32_32x32x16_bf16 %2, %5, %6, %2\n\tv_mfma_f32_32x32x16_bf16 %3, %5, %7, %3\n\t"
;         "ds_read_b128 %4, %14\n\tds_read_b128 %5, %14 offset:4096\n\tds_read_b128 %6, %18\n\tds_read_b128 %7, %18 offset:4096\n\t"
;         "s_waitcnt lgkmcnt(4)\n\t"
;         "v_mfma_f32_32x32x16_bf16 %0, %8, %10, %0\n\tv_mfma_f32_32x32x16_bf16 %1, %8, %11, %1\n\tv_mfma_f32_32x32x16_bf16 %2, %9, %10, %2\n\tv_mfma_f32_32x32x16_bf16 %3, %9, %11, %3\n\t"
;         "ds_read_b128 %8, %15\n\tds_read_b128 %9, %15 offset:4096\n\tds_read_b128 %10, %19\n\tds_read_b128 %11, %19 offset:4096\n\t"
;         "s_waitcnt lgkmcnt(4)\n\t"
;         "v_mfma_f32_32x32x16_bf16 %0, %4, %6, %0\n\tv_mfma_f32_32x32x16_bf16 %1, %4, %7, %1\n\tv_mfma_f32_32x32x16_bf16 %2, %5, %6, %2\n\tv_mfma_f32_32x32x16_bf16 %3, %5, %7, %3\n\t"
;         "s_waitcnt lgkmcnt(0)\n\t"
;         "v_mfma_f32_32x32x16_bf16 %0, %8, %10, %0\n\tv_mfma_f32_32x32x16_bf16 %1, %8, %11, %1\n\tv_mfma_f32_32x32x16_bf16 %2, %9, %10, %2\n\tv_mfma_f32_32x32x16_bf16 %3, %9, %11, %3"
;         : "+v"(acc[0][0]), "+v"(acc[0][1]), "+v"(acc[1][0]), "+v"(acc[1][1]),
;           "=&v"(p0), "=&v"(p1), "=&v"(q0), "=&v"(q1), "=&v"(u0), "=&v"(u1), "=&v"(w0), "=&v"(w1)
	v_mfma_f32_16x16x32_bf16 v[0:3], v[84:87], v[100:103], v[0:3]
	v_mfma_f32_16x16x32_bf16 v[4:7], v[84:87], v[104:107], v[4:7]
	s_add_u32 m0, s30, 0x12000
	v_lshl_add_u64 v[126:127], v[70:71], 0, s[24:25]
	global_load_lds_dwordx4 v[126:127], off
	v_mfma_f32_16x16x32_bf16 v[8:11], v[84:87], v[108:111], v[8:11]
	v_mfma_f32_16x16x32_bf16 v[12:15], v[84:87], v[112:115], v[12:15]
	v_mfma_f32_16x16x32_bf16 v[16:19], v[88:91], v[100:103], v[16:19]
	v_mfma_f32_16x16x32_bf16 v[20:23], v[88:91], v[104:107], v[20:23]
	v_mfma_f32_16x16x32_bf16 v[24:27], v[88:91], v[108:111], v[24:27]
	s_add_u32 m0, s30, 0x14000
	v_lshl_add_u64 v[124:125], v[72:73], 0, s[24:25]
	global_load_lds_dwordx4 v[124:125], off
	v_mfma_f32_16x16x32_bf16 v[28:31], v[88:91], v[112:115], v[28:31]
	v_mfma_f32_16x16x32_bf16 v[32:35], v[92:95], v[100:103], v[32:35]
	v_mfma_f32_16x16x32_bf16 v[36:39], v[92:95], v[104:107], v[36:39]
	v_mfma_f32_16x16x32_bf16 v[40:43], v[92:95], v[108:111], v[40:43]
	v_mfma_f32_16x16x32_bf16 v[44:47], v[92:95], v[112:115], v[44:47]
	s_add_u32 m0, s30, 0x16000
	v_lshl_add_u64 v[126:127], v[74:75], 0, s[24:25]
	global_load_lds_dwordx4 v[126:127], off
	v_mfma_f32_16x16x32_bf16 v[48:51], v[96:99], v[100:103], v[48:51]
	v_mfma_f32_16x16x32_bf16 v[52:55], v[96:99], v[104:107], v[52:55]
	v_mfma_f32_16x16x32_bf16 v[56:59], v[96:99], v[108:111], v[56:59]
	v_mfma_f32_16x16x32_bf16 v[60:63], v[96:99], v[112:115], v[60:63]
	s_waitcnt vmcnt(6) lgkmcnt(0)
	s_barrier
	ds_read_b128 v[84:87], v76
	ds_read_b128 v[88:91], v76 offset:2048
	ds_read_b128 v[92:95], v76 offset:4096
	ds_read_b128 v[96:99], v76 offset:6144
	ds_read_b128 v[100:103], v78
	ds_read_b128 v[104:107], v78 offset:2048
	ds_read_b128 v[108:111], v78 offset:4096
	ds_read_b128 v[112:115], v78 offset:6144
	v_mfma_f32_16x16x32_bf16 v[0:3], v[136:139], v[152:155], v[0:3]
	v_mfma_f32_16x16x32_bf16 v[4:7], v[136:139], v[156:159], v[4:7]
	s_mov_b32 s24, 0x480
	s_mov_b32 s25, 0
	s_add_u32 m0, s30, 0x18000
	v_lshl_add_u64 v[124:125], v[64:65], 0, s[24:25]
	global_load_lds_dwordx4 v[124:125], off
	v_mfma_f32_16x16x32_bf16 v[8:11], v[136:139], v[160:163], v[8:11]
	v_mfma_f32_16x16x32_bf16 v[12:15], v[136:139], v[164:167], v[12:15]
	v_mfma_f32_16x16x32_bf16 v[16:19], v[140:143], v[152:155], v[16:19]
	v_mfma_f32_16x16x32_bf16 v[20:23], v[140:143], v[156:159], v[20:23]
	v_mfma_f32_16x16x32_bf16 v[24:27], v[140:143], v[160:163], v[24:27]
	s_add_u32 m0, s30, 0x1a000
	v_lshl_add_u64 v[126:127], v[66:67], 0, s[24:25]
	global_load_lds_dwordx4 v[126:127], off
	v_mfma_f32_16x16x32_bf16 v[28:31], v[140:143], v[164:167], v[28:31]
	v_mfma_f32_16x16x32_bf16 v[32:35], v[144:147], v[152:155], v[32:35]
	v_mfma_f32_16x16x32_bf16 v[36:39], v[144:147], v[156:159], v[36:39]
	v_mfma_f32_16x16x32_bf16 v[40:43], v[144:147], v[160:163], v[40:43]
	v_mfma_f32_16x16x32_bf16 v[44:47], v[144:147], v[164:167], v[44:47]
	s_add_u32 m0, s30, 0x1c000
	v_lshl_add_u64 v[124:125], v[68:69], 0, s[24:25]
	global_load_lds_dwordx4 v[124:125], off
	v_mfma_f32_16x16x32_bf16 v[48:51], v[148:151], v[152:155], v[48:51]
	v_mfma_f32_16x16x32_bf16 v[52:55], v[148:151], v[156:159], v[52:55]
	v_mfma_f32_16x16x32_bf16 v[56:59], v[148:151], v[160:163], v[56:59]
	v_mfma_f32_16x16x32_bf16 v[60:63], v[148:151], v[164:167], v[60:63]
	ds_read_b128 v[136:139], v77
	ds_read_b128 v[140:143], v77 offset:2048
	ds_read_b128 v[144:147], v77 offset:4096
	ds_read_b128 v[148:151], v77 offset:6144
	ds_read_b128 v[152:155], v79
	ds_read_b128 v[156:159], v79 offset:2048
	ds_read_b128 v[160:163], v79 offset:4096
	ds_read_b128 v[164:167], v79 offset:6144
	s_waitcnt lgkmcnt(8)
	v_mfma_f32_16x16x32_bf16 v[0:3], v[84:87], v[100:103], v[0:3]
	v_mfma_f32_16x16x32_bf16 v[4:7], v[84:87], v[104:107], v[4:7]
	s_add_u32 m0, s30, 0x1e000
	v_lshl_add_u64 v[126:127], v[70:71], 0, s[24:25]
	global_load_lds_dwordx4 v[126:127], off
	v_mfma_f32_16x16x32_bf16 v[8:11], v[84:87], v[108:111], v[8:11]
	v_mfma_f32_16x16x32_bf16 v[12:15], v[84:87], v[112:115], v[12:15]
	v_mfma_f32_16x16x32_bf16 v[16:19], v[88:91], v[100:103], v[16:19]
	v_mfma_f32_16x16x32_bf16 v[20:23], v[88:91], v[104:107], v[20:23]
	v_mfma_f32_16x16x32_bf16 v[24:27], v[88:91], v[108:111], v[24:27]
	s_add_u32 m0, s30, 0x20000
	v_lshl_add_u64 v[124:125], v[72:73], 0, s[24:25]
	global_load_lds_dwordx4 v[124:125], off
	v_mfma_f32_16x16x32_bf16 v[28:31], v[88:91], v[112:115], v[28:31]
	v_mfma_f32_16x16x32_bf16 v[32:35], v[92:95], v[100:103], v[32:35]
	v_mfma_f32_16x16x32_bf16 v[36:39], v[92:95], v[104:107], v[36:39]
	v_mfma_f32_16x16x32_bf16 v[40:43], v[92:95], v[108:111], v[40:43]
	v_mfma_f32_16x16x32_bf16 v[44:47], v[92:95], v[112:115], v[44:47]
	s_add_u32 m0, s30, 0x22000
	v_lshl_add_u64 v[126:127], v[74:75], 0, s[24:25]
	global_load_lds_dwordx4 v[126:127], off
	v_mfma_f32_16x16x32_bf16 v[48:51], v[96:99], v[100:103], v[48:51]
	v_mfma_f32_16x16x32_bf16 v[52:55], v[96:99], v[104:107], v[52:55]
	v_mfma_f32_16x16x32_bf16 v[56:59], v[96:99], v[108:111], v[56:59]
	v_mfma_f32_16x16x32_bf16 v[60:63], v[96:99], v[112:115], v[60:63]
	s_waitcnt vmcnt(6) lgkmcnt(0)
	s_barrier
;     ...
;   for (int kt = 0; kt < nk; ++kt) {
;     if (kt + 1 < nk) asm volatile("s_waitcnt vmcnt(6)" ::: "memory");
;     else asm volatile("s_waitcnt vmcnt(0)" ::: "memory");
;     __builtin_amdgcn_s_barrier();
;     asm volatile("" ::: "memory");
;     if (kt + 2 < nk) { const int st2 = (st >= 1) ? st - 1 : 2; GEMM_ISSUE(kt + 2, st2); }
;     const char* la = lds + st * STAGE_B;
;     const char* lb = la + 32768;
;     const unsigned sa_u = (unsigned)(size_t)la + arow_u, sb_u = (unsigned)(size_t)lb + brow_u;
;     const unsigned a0 = sa_u + co0, a1 = sa_u + co1, a2 = sa_u + co2, a3 = sa_u + co3;
;     const unsigned b0 = sb_u + co0, b1 = sb_u + co1, b2 = sb_u + co2, b3 = sb_u + co3;
;     {
;       bf16x8 p0, p1, q0, q1, u0, u1, w0, w1;
;       asm volatile(
;         "ds_read_b128 %4, %12\n\tds_read_b128 %5, %12 offset:4096\n\tds_read_b128 %6, %16\n\tds_read_b128 %7, %16 offset:4096\n\t"
;         "ds_read_b128 %8, %13\n\tds_read_b128 %9, %13 offset:4096\n\tds_read_b128 %10, %17\n\tds_read_b128 %11, %17 offset:4096\n\t"
;         "s_waitcnt lgkmcnt(4)\n\t"
;         "v_mfma_f32_32x32x16_bf16 %0, %4, %6, %0\n\tv_mfma_f32_32x32x16_bf16 %1, %4, %7, %1\n\tv_mfma_f32_32x32x16_bf16 %2, %5, %6, %2\n\tv_mfma_f32_32x32x16_bf16 %3, %5, %7, %3\n\t"
;         "ds_read_b128 %4, %14\n\tds_read_b128 %5, %14 offset:4096\n\tds_read_b128 %6, %18\n\tds_read_b128 %7, %18 offset:4096\n\t"
;         "s_waitcnt lgkmcnt(4)\n\t"
;         "v_mfma_f32_32x32x16_bf16 %0, %8, %10, %0\n\tv_mfma_f32_32x32x16_bf16 %1, %8, %11, %1\n\tv_mfma_f32_32x32x16_bf16 %2, %9, %10, %2\n\tv_mfma_f32_32x32x16_bf16 %3, %9, %11, %3\n\t"
;         "ds_read_b128 %8, %15\n\tds_read_b128 %9, %15 offset:4096\n\tds_read_b128 %10, %19\n\tds_read_b128 %11, %19 offset:4096\n\t"
;         "s_waitcnt lgkmcnt(4)\n\t"
;         "v_mfma_f32_32x32x16_bf16 %0, %4, %6, %0\n\tv_mfma_f32_32x32x16_bf16 %1, %4, %7, %1\n\tv_mfma_f32_32x32x16_bf16 %2, %5, %6, %2\n\tv_mfma_f32_32x32x16_bf16 %3, %5, %7, %3\n\t"
;         "s_waitcnt lgkmcnt(0)\n\t"
;         "v_mfma_f32_32x32x16_bf16 %0, %8, %10, %0\n\tv_mfma_f32_32x32x16_bf16 %1, %8, %11, %1\n\tv_mfma_f32_32x32x16_bf16 %2, %9, %10, %2\n\tv_mfma_f32_32x32x16_bf16 %3, %9, %11, %3"
;         : "+v"(acc[0][0]), "+v"(acc[0][1]), "+v"(acc[1][0]), "+v"(acc[1][1]),
;           "=&v"(p0), "=&v"(p1), "=&v"(q0), "=&v"(q1), "=&v"(u0), "=&v"(u1), "=&v"(w0), "=&v"(w1)
	ds_read_b128 v[84:87], v76 offset:49152
	ds_read_b128 v[88:91], v76 offset:51200
	ds_read_b128 v[92:95], v76 offset:53248
	ds_read_b128 v[96:99], v76 offset:55296
	ds_read_b128 v[100:103], v78 offset:49152
	ds_read_b128 v[104:107], v78 offset:51200
	ds_read_b128 v[108:111], v78 offset:53248
	ds_read_b128 v[112:115], v78 offset:55296
	v_mfma_f32_16x16x32_bf16 v[0:3], v[136:139], v[152:155], v[0:3]
	v_mfma_f32_16x16x32_bf16 v[4:7], v[136:139], v[156:159], v[4:7]
	s_mov_b32 s24, 0x500
	s_mov_b32 s25, 0
	s_mov_b32 m0, s30
	v_lshl_add_u64 v[124:125], v[64:65], 0, s[24:25]
	global_load_lds_dwordx4 v[124:125], off
	v_mfma_f32_16x16x32_bf16 v[8:11], v[136:139], v[160:163], v[8:11]
	v_mfma_f32_16x16x32_bf16 v[12:15], v[136:139], v[164:167], v[12:15]
	v_mfma_f32_16x16x32_bf16 v[16:19], v[140:143], v[152:155], v[16:19]
	v_mfma_f32_16x16x32_bf16 v[20:23], v[140:143], v[156:159], v[20:23]
	v_mfma_f32_16x16x32_bf16 v[24:27], v[140:143], v[160:163], v[24:27]
	s_add_u32 m0, s30, 0x2000
	v_lshl_add_u64 v[126:127], v[66:67], 0, s[24:25]
	global_load_lds_dwordx4 v[126:127], off
	v_mfma_f32_16x16x32_bf16 v[28:31], v[140:143], v[164:167], v[28:31]
	v_mfma_f32_16x16x32_bf16 v[32:35], v[144:147], v[152:155], v[32:35]
	v_mfma_f32_16x16x32_bf16 v[36:39], v[144:147], v[156:159], v[36:39]
	v_mfma_f32_16x16x32_bf16 v[40:43], v[144:147], v[160:163], v[40:43]
	v_mfma_f32_16x16x32_bf16 v[44:47], v[144:147], v[164:167], v[44:47]
	s_add_u32 m0, s30, 0x4000
	v_lshl_add_u64 v[124:125], v[68:69], 0, s[24:25]
	global_load_lds_dwordx4 v[124:125], off
	v_mfma_f32_16x16x32_bf16 v[48:51], v[148:151], v[152:155], v[48:51]
	v_mfma_f32_16x16x32_bf16 v[52:55], v[148:151], v[156:159], v[52:55]
	v_mfma_f32_16x16x32_bf16 v[56:59], v[148:151], v[160:163], v[56:59]
	v_mfma_f32_16x16x32_bf16 v[60:63], v[148:151], v[164:167], v[60:63]
	ds_read_b128 v[136:139], v77 offset:49152
	ds_read_b128 v[140:143], v77 offset:51200
	ds_read_b128 v[144:147], v77 offset:53248
	ds_read_b128 v[148:151], v77 offset:55296
	ds_read_b128 v[152:155], v79 offset:49152
	ds_read_b128 v[156:159], v79 offset:51200
	ds_read_b128 v[160:163], v79 offset:53248
	ds_read_b128 v[164:167], v79 offset:55296
	s_waitcnt lgkmcnt(8)
	v_mfma_f32_16x16x32_bf16 v[0:3], v[84:87], v[100:103], v[0:3]
	v_mfma_f32_16x16x32_bf16 v[4:7], v[84:87], v[104:107], v[4:7]
	s_add_u32 m0, s30, 0x6000
	v_lshl_add_u64 v[126:127], v[70:71], 0, s[24:25]
	global_load_lds_dwordx4 v[126:127], off
	v_mfma_f32_16x16x32_bf16 v[8:11], v[84:87], v[108:111], v[8:11]
	v_mfma_f32_16x16x32_bf16 v[12:15], v[84:87], v[112:115], v[12:15]
	v_mfma_f32_16x16x32_bf16 v[16:19], v[88:91], v[100:103], v[16:19]
	v_mfma_f32_16x16x32_bf16 v[20:23], v[88:91], v[104:107], v[20:23]
	v_mfma_f32_16x16x32_bf16 v[24:27], v[88:91], v[108:111], v[24:27]
	s_add_u32 m0, s30, 0x8000
	v_lshl_add_u64 v[124:125], v[72:73], 0, s[24:25]
	global_load_lds_dwordx4 v[124:125], off
	v_mfma_f32_16x16x32_bf16 v[28:31], v[88:91], v[112:115], v[28:31]
	v_mfma_f32_16x16x32_bf16 v[32:35], v[92:95], v[100:103], v[32:35]
	v_mfma_f32_16x16x32_bf16 v[36:39], v[92:95], v[104:107], v[36:39]
	v_mfma_f32_16x16x32_bf16 v[40:43], v[92:95], v[108:111], v[40:43]
	v_mfma_f32_16x16x32_bf16 v[44:47], v[92:95], v[112:115], v[44:47]
	s_add_u32 m0, s30, 0xa000
	v_lshl_add_u64 v[126:127], v[74:75], 0, s[24:25]
	global_load_lds_dwordx4 v[126:127], off
	v_mfma_f32_16x16x32_bf16 v[48:51], v[96:99], v[100:103], v[48:51]
	v_mfma_f32_16x16x32_bf16 v[52:55], v[96:99], v[104:107], v[52:55]
	v_mfma_f32_16x16x32_bf16 v[56:59], v[96:99], v[108:111], v[56:59]
	v_mfma_f32_16x16x32_bf16 v[60:63], v[96:99], v[112:115], v[60:63]
	s_waitcnt vmcnt(6) lgkmcnt(0)
	s_barrier
	ds_read_b128 v[84:87], v80
	ds_read_b128 v[88:91], v80 offset:2048
	ds_read_b128 v[92:95], v80 offset:4096
	ds_read_b128 v[96:99], v80 offset:6144
	ds_read_b128 v[100:103], v82
	ds_read_b128 v[104:107], v82 offset:2048
	ds_read_b128 v[108:111], v82 offset:4096
	ds_read_b128 v[112:115], v82 offset:6144
	v_mfma_f32_16x16x32_bf16 v[0:3], v[136:139], v[152:155], v[0:3]
	v_mfma_f32_16x16x32_bf16 v[4:7], v[136:139], v[156:159], v[4:7]
	s_mov_b32 s24, 0x580
	s_mov_b32 s25, 0
	s_add_u32 m0, s30, 0xc000
	v_lshl_add_u64 v[124:125], v[64:65], 0, s[24:25]
	global_load_lds_dwordx4 v[124:125], off
	v_mfma_f32_16x16x32_bf16 v[8:11], v[136:139], v[160:163], v[8:11]
	v_mfma_f32_16x16x32_bf16 v[12:15], v[136:139], v[164:167], v[12:15]
	v_mfma_f32_16x16x32_bf16 v[16:19], v[140:143], v[152:155], v[16:19]
	v_mfma_f32_16x16x32_bf16 v[20:23], v[140:143], v[156:159], v[20:23]
	v_mfma_f32_16x16x32_bf16 v[24:27], v[140:143], v[160:163], v[24:27]
	s_add_u32 m0, s30, 0xe000
	v_lshl_add_u64 v[126:127], v[66:67], 0, s[24:25]
	global_load_lds_dwordx4 v[126:127], off
	v_mfma_f32_16x16x32_bf16 v[28:31], v[140:143], v[164:167], v[28:31]
	v_mfma_f32_16x16x32_bf16 v[32:35], v[144:147], v[152:155], v[32:35]
	v_mfma_f32_16x16x32_bf16 v[36:39], v[144:147], v[156:159], v[36:39]
	v_mfma_f32_16x16x32_bf16 v[40:43], v[144:147], v[160:163], v[40:43]
	v_mfma_f32_16x16x32_bf16 v[44:47], v[144:147], v[164:167], v[44:47]
	s_add_u32 m0, s30, 0x10000
	v_lshl_add_u64 v[124:125], v[68:69], 0, s[24:25]
	global_load_lds_dwordx4 v[124:125], off
	v_mfma_f32_16x16x32_bf16 v[48:51], v[148:151], v[152:155], v[48:51]
	v_mfma_f32_16x16x32_bf16 v[52:55], v[148:151], v[156:159], v[52:55]
	v_mfma_f32_16x16x32_bf16 v[56:59], v[148:151], v[160:163], v[56:59]
	v_mfma_f32_16x16x32_bf16 v[60:63], v[148:151], v[164:167], v[60:63]
	ds_read_b128 v[136:139], v81
	ds_read_b128 v[140:143], v81 offset:2048
	ds_read_b128 v[144:147], v81 offset:4096
	ds_read_b128 v[148:151], v81 offset:6144
	ds_read_b128 v[152:155], v83
	ds_read_b128 v[156:159], v83 offset:2048
	ds_read_b128 v[160:163], v83 offset:4096
	ds_read_b128 v[164:167], v83 offset:6144
	s_waitcnt lgkmcnt(8)
;     ...
;   for (int kt = 0; kt < nk; ++kt) {
;     if (kt + 1 < nk) asm volatile("s_waitcnt vmcnt(6)" ::: "memory");
;     else asm volatile("s_waitcnt vmcnt(0)" ::: "memory");
;     __builtin_amdgcn_s_barrier();
;     asm volatile("" ::: "memory");
;     if (kt + 2 < nk) { const int st2 = (st >= 1) ? st - 1 : 2; GEMM_ISSUE(kt + 2, st2); }
;     const char* la = lds + st * STAGE_B;
;     const char* lb = la + 32768;
;     const unsigned sa_u = (unsigned)(size_t)la + arow_u, sb_u = (unsigned)(size_t)lb + brow_u;
;     const unsigned a0 = sa_u + co0, a1 = sa_u + co1, a2 = sa_u + co2, a3 = sa_u + co3;
;     const unsigned b0 = sb_u + co0, b1 = sb_u + co1, b2 = sb_u + co2, b3 = sb_u + co3;
;     {
;       bf16x8 p0, p1, q0, q1, u0, u1, w0, w1;
;       asm volatile(
;         "ds_read_b128 %4, %12\n\tds_read_b128 %5, %12 offset:4096\n\tds_read_b128 %6, %16\n\tds_read_b128 %7, %16 offset:4096\n\t"
;         "ds_read_b128 %8, %13\n\tds_read_b128 %9, %13 offset:4096\n\tds_read_b128 %10, %17\n\tds_read_b128 %11, %17 offset:4096\n\t"
;         "s_waitcnt lgkmcnt(4)\n\t"
;         "v_mfma_f32_32x32x16_bf16 %0, %4, %6, %0\n\tv_mfma_f32_32x32x16_bf16 %1, %4, %7, %1\n\tv_mfma_f32_32x32x16_bf16 %2, %5, %6, %2\n\tv_mfma_f32_32x32x16_bf16 %3, %5, %7, %3\n\t"
;         "ds_read_b128 %4, %14\n\tds_read_b128 %5, %14 offset:4096\n\tds_read_b128 %6, %18\n\tds_read_b128 %7, %18 offset:4096\n\t"
;         "s_waitcnt lgkmcnt(4)\n\t"
;         "v_mfma_f32_32x32x16_bf16 %0, %8, %10, %0\n\tv_mfma_f32_32x32x16_bf16 %1, %8, %11, %1\n\tv_mfma_f32_32x32x16_bf16 %2, %9, %10, %2\n\tv_mfma_f32_32x32x16_bf16 %3, %9, %11, %3\n\t"
;         "ds_read_b128 %8, %15\n\tds_read_b128 %9, %15 offset:4096\n\tds_read_b128 %10, %19\n\tds_read_b128 %11, %19 offset:4096\n\t"
;         "s_waitcnt lgkmcnt(4)\n\t"
;         "v_mfma_f32_32x32x16_bf16 %0, %4, %6, %0\n\tv_mfma_f32_32x32x16_bf16 %1, %4, %7, %1\n\tv_mfma_f32_32x32x16_bf16 %2, %5, %6, %2\n\tv_mfma_f32_32x32x16_bf16 %3, %5, %7, %3\n\t"
;         "s_waitcnt lgkmcnt(0)\n\t"
;         "v_mfma_f32_32x32x16_bf16 %0, %8, %10, %0\n\tv_mfma_f32_32x32x16_bf16 %1, %8, %11, %1\n\tv_mfma_f32_32x32x16_bf16 %2, %9, %10, %2\n\tv_mfma_f32_32x32x16_bf16 %3, %9, %11, %3"
;         : "+v"(acc[0][0]), "+v"(acc[0][1]), "+v"(acc[1][0]), "+v"(acc[1][1]),
;           "=&v"(p0), "=&v"(p1), "=&v"(q0), "=&v"(q1), "=&v"(u0), "=&v"(u1), "=&v"(w0), "=&v"(w1)
	v_mfma_f32_16x16x32_bf16 v[0:3], v[84:87], v[100:103], v[0:3]
	v_mfma_f32_16x16x32_bf16 v[4:7], v[84:87], v[104:107], v[4:7]
	s_add_u32 m0, s30, 0x12000
	v_lshl_add_u64 v[126:127], v[70:71], 0, s[24:25]
	global_load_lds_dwordx4 v[126:127], off
	v_mfma_f32_16x16x32_bf16 v[8:11], v[84:87], v[108:111], v[8:11]
	v_mfma_f32_16x16x32_bf16 v[12:15], v[84:87], v[112:115], v[12:15]
	v_mfma_f32_16x16x32_bf16 v[16:19], v[88:91], v[100:103], v[16:19]
	v_mfma_f32_16x16x32_bf16 v[20:23], v[88:91], v[104:107], v[20:23]
	v_mfma_f32_16x16x32_bf16 v[24:27], v[88:91], v[108:111], v[24:27]
	s_add_u32 m0, s30, 0x14000
	v_lshl_add_u64 v[124:125], v[72:73], 0, s[24:25]
	global_load_lds_dwordx4 v[124:125], off
	v_mfma_f32_16x16x32_bf16 v[28:31], v[88:91], v[112:115], v[28:31]
	v_mfma_f32_16x16x32_bf16 v[32:35], v[92:95], v[100:103], v[32:35]
	v_mfma_f32_16x16x32_bf16 v[36:39], v[92:95], v[104:107], v[36:39]
	v_mfma_f32_16x16x32_bf16 v[40:43], v[92:95], v[108:111], v[40:43]
	v_mfma_f32_16x16x32_bf16 v[44:47], v[92:95], v[112:115], v[44:47]
	s_add_u32 m0, s30, 0x16000
	v_lshl_add_u64 v[126:127], v[74:75], 0, s[24:25]
	global_load_lds_dwordx4 v[126:127], off
	v_mfma_f32_16x16x32_bf16 v[48:51], v[96:99], v[100:103], v[48:51]
	v_mfma_f32_16x16x32_bf16 v[52:55], v[96:99], v[104:107], v[52:55]
	v_mfma_f32_16x16x32_bf16 v[56:59], v[96:99], v[108:111], v[56:59]
	v_mfma_f32_16x16x32_bf16 v[60:63], v[96:99], v[112:115], v[60:63]
	s_waitcnt vmcnt(6) lgkmcnt(0)
	s_barrier
	ds_read_b128 v[84:87], v76
	ds_read_b128 v[88:91], v76 offset:2048
	ds_read_b128 v[92:95], v76 offset:4096
	ds_read_b128 v[96:99], v76 offset:6144
	ds_read_b128 v[100:103], v78
	ds_read_b128 v[104:107], v78 offset:2048
	ds_read_b128 v[108:111], v78 offset:4096
	ds_read_b128 v[112:115], v78 offset:6144
	v_mfma_f32_16x16x32_bf16 v[0:3], v[136:139], v[152:155], v[0:3]
	v_mfma_f32_16x16x32_bf16 v[4:7], v[136:139], v[156:159], v[4:7]
	s_mov_b32 s24, 0x600
	s_mov_b32 s25, 0
	s_add_u32 m0, s30, 0x18000
	v_lshl_add_u64 v[124:125], v[64:65], 0, s[24:25]
	global_load_lds_dwordx4 v[124:125], off
	v_mfma_f32_16x16x32_bf16 v[8:11], v[136:139], v[160:163], v[8:11]
	v_mfma_f32_16x16x32_bf16 v[12:15], v[136:139], v[164:167], v[12:15]
	v_mfma_f32_16x16x32_bf16 v[16:19], v[140:143], v[152:155], v[16:19]
	v_mfma_f32_16x16x32_bf16 v[20:23], v[140:143], v[156:159], v[20:23]
	v_mfma_f32_16x16x32_bf16 v[24:27], v[140:143], v[160:163], v[24:27]
	s_add_u32 m0, s30, 0x1a000
	v_lshl_add_u64 v[126:127], v[66:67], 0, s[24:25]
	global_load_lds_dwordx4 v[126:127], off
	v_mfma_f32_16x16x32_bf16 v[28:31], v[140:143], v[164:167], v[28:31]
	v_mfma_f32_16x16x32_bf16 v[32:35], v[144:147], v[152:155], v[32:35]
	v_mfma_f32_16x16x32_bf16 v[36:39], v[144:147], v[156:159], v[36:39]
	v_mfma_f32_16x16x32_bf16 v[40:43], v[144:147], v[160:163], v[40:43]
	v_mfma_f32_16x16x32_bf16 v[44:47], v[144:147], v[164:167], v[44:47]
	s_add_u32 m0, s30, 0x1c000
	v_lshl_add_u64 v[124:125], v[68:69], 0, s[24:25]
	global_load_lds_dwordx4 v[124:125], off
	v_mfma_f32_16x16x32_bf16 v[48:51], v[148:151], v[152:155], v[48:51]
	v_mfma_f32_16x16x32_bf16 v[52:55], v[148:151], v[156:159], v[52:55]
	v_mfma_f32_16x16x32_bf16 v[56:59], v[148:151], v[160:163], v[56:59]
	v_mfma_f32_16x16x32_bf16 v[60:63], v[148:151], v[164:167], v[60:63]
	ds_read_b128 v[136:139], v77
	ds_read_b128 v[140:143], v77 offset:2048
	ds_read_b128 v[144:147], v77 offset:4096
	ds_read_b128 v[148:151], v77 offset:6144
	ds_read_b128 v[152:155], v79
	ds_read_b128 v[156:159], v79 offset:2048
	ds_read_b128 v[160:163], v79 offset:4096
	ds_read_b128 v[164:167], v79 offset:6144
	s_waitcnt lgkmcnt(8)
	v_mfma_f32_16x16x32_bf16 v[0:3], v[84:87], v[100:103], v[0:3]
	v_mfma_f32_16x16x32_bf16 v[4:7], v[84:87], v[104:107], v[4:7]
	s_add_u32 m0, s30, 0x1e000
	v_lshl_add_u64 v[126:127], v[70:71], 0, s[24:25]
	global_load_lds_dwordx4 v[126:127], off
	v_mfma_f32_16x16x32_bf16 v[8:11], v[84:87], v[108:111], v[8:11]
	v_mfma_f32_16x16x32_bf16 v[12:15], v[84:87], v[112:115], v[12:15]
	v_mfma_f32_16x16x32_bf16 v[16:19], v[88:91], v[100:103], v[16:19]
	v_mfma_f32_16x16x32_bf16 v[20:23], v[88:91], v[104:107], v[20:23]
	v_mfma_f32_16x16x32_bf16 v[24:27], v[88:91], v[108:111], v[24:27]
	s_add_u32 m0, s30, 0x20000
	v_lshl_add_u64 v[124:125], v[72:73], 0, s[24:25]
	global_load_lds_dwordx4 v[124:125], off
	v_mfma_f32_16x16x32_bf16 v[28:31], v[88:91], v[112:115], v[28:31]
	v_mfma_f32_16x16x32_bf16 v[32:35], v[92:95], v[100:103], v[32:35]
	v_mfma_f32_16x16x32_bf16 v[36:39], v[92:95], v[104:107], v[36:39]
	v_mfma_f32_16x16x32_bf16 v[40:43], v[92:95], v[108:111], v[40:43]
	v_mfma_f32_16x16x32_bf16 v[44:47], v[92:95], v[112:115], v[44:47]
	s_add_u32 m0, s30, 0x22000
	v_lshl_add_u64 v[126:127], v[74:75], 0, s[24:25]
	global_load_lds_dwordx4 v[126:127], off
	v_mfma_f32_16x16x32_bf16 v[48:51], v[96:99], v[100:103], v[48:51]
	v_mfma_f32_16x16x32_bf16 v[52:55], v[96:99], v[104:107], v[52:55]
	v_mfma_f32_16x16x32_bf16 v[56:59], v[96:99], v[108:111], v[56:59]
	v_mfma_f32_16x16x32_bf16 v[60:63], v[96:99], v[112:115], v[60:63]
	s_waitcnt vmcnt(6) lgkmcnt(0)
	s_barrier
;     ...
;   for (int kt = 0; kt < nk; ++kt) {
;     if (kt + 1 < nk) asm volatile("s_waitcnt vmcnt(6)" ::: "memory");
;     else asm volatile("s_waitcnt vmcnt(0)" ::: "memory");
;     __builtin_amdgcn_s_barrier();
;     asm volatile("" ::: "memory");
;     if (kt + 2 < nk) { const int st2 = (st >= 1) ? st - 1 : 2; GEMM_ISSUE(kt + 2, st2); }
;     const char* la = lds + st * STAGE_B;
;     const char* lb = la + 32768;
;     const unsigned sa_u = (unsigned)(size_t)la + arow_u, sb_u = (unsigned)(size_t)lb + brow_u;
;     const unsigned a0 = sa_u + co0, a1 = sa_u + co1, a2 = sa_u + co2, a3 = sa_u + co3;
;     const unsigned b0 = sb_u + co0, b1 = sb_u + co1, b2 = sb_u + co2, b3 = sb_u + co3;
;     {
;       bf16x8 p0, p1, q0, q1, u0, u1, w0, w1;
;       asm volatile(
;         "ds_read_b128 %4, %12\n\tds_read_b128 %5, %12 offset:4096\n\tds_read_b128 %6, %16\n\tds_read_b128 %7, %16 offset:4096\n\t"
;         "ds_read_b128 %8, %13\n\tds_read_b128 %9, %13 offset:4096\n\tds_read_b128 %10, %17\n\tds_read_b128 %11, %17 offset:4096\n\t"
;         "s_waitcnt lgkmcnt(4)\n\t"
;         "v_mfma_f32_32x32x16_bf16 %0, %4, %6, %0\n\tv_mfma_f32_32x32x16_bf16 %1, %4, %7, %1\n\tv_mfma_f32_32x32x16_bf16 %2, %5, %6, %2\n\tv_mfma_f32_32x32x16_bf16 %3, %5, %7, %3\n\t"
;         "ds_read_b128 %4, %14\n\tds_read_b128 %5, %14 offset:4096\n\tds_read_b128 %6, %18\n\tds_read_b128 %7, %18 offset:4096\n\t"
;         "s_waitcnt lgkmcnt(4)\n\t"
;         "v_mfma_f32_32x32x16_bf16 %0, %8, %10, %0\n\tv_mfma_f32_32x32x16_bf16 %1, %8, %11, %1\n\tv_mfma_f32_32x32x16_bf16 %2, %9, %10, %2\n\tv_mfma_f32_32x32x16_bf16 %3, %9, %11, %3\n\t"
;         "ds_read_b128 %8, %15\n\tds_read_b128 %9, %15 offset:4096\n\tds_read_b128 %10, %19\n\tds_read_b128 %11, %19 offset:4096\n\t"
;         "s_waitcnt lgkmcnt(4)\n\t"
;         "v_mfma_f32_32x32x16_bf16 %0, %4, %6, %0\n\tv_mfma_f32_32x32x16_bf16 %1, %4, %7, %1\n\tv_mfma_f32_32x32x16_bf16 %2, %5, %6, %2\n\tv_mfma_f32_32x32x16_bf16 %3, %5, %7, %3\n\t"
;         "s_waitcnt lgkmcnt(0)\n\t"
;         "v_mfma_f32_32x32x16_bf16 %0, %8, %10, %0\n\tv_mfma_f32_32x32x16_bf16 %1, %8, %11, %1\n\tv_mfma_f32_32x32x16_bf16 %2, %9, %10, %2\n\tv_mfma_f32_32x32x16_bf16 %3, %9, %11, %3"
;         : "+v"(acc[0][0]), "+v"(acc[0][1]), "+v"(acc[1][0]), "+v"(acc[1][1]),
;           "=&v"(p0), "=&v"(p1), "=&v"(q0), "=&v"(q1), "=&v"(u0), "=&v"(u1), "=&v"(w0), "=&v"(w1)
	ds_read_b128 v[84:87], v76 offset:49152
	ds_read_b128 v[88:91], v76 offset:51200
	ds_read_b128 v[92:95], v76 offset:53248
	ds_read_b128 v[96:99], v76 offset:55296
	ds_read_b128 v[100:103], v78 offset:49152
	ds_read_b128 v[104:107], v78 offset:51200
	ds_read_b128 v[108:111], v78 offset:53248
	ds_read_b128 v[112:115], v78 offset:55296
	v_mfma_f32_16x16x32_bf16 v[0:3], v[136:139], v[152:155], v[0:3]
	v_mfma_f32_16x16x32_bf16 v[4:7], v[136:139], v[156:159], v[4:7]
	s_mov_b32 s24, 0x680
	s_mov_b32 s25, 0
	s_mov_b32 m0, s30
	v_lshl_add_u64 v[124:125], v[64:65], 0, s[24:25]
	global_load_lds_dwordx4 v[124:125], off
	v_mfma_f32_16x16x32_bf16 v[8:11], v[136:139], v[160:163], v[8:11]
	v_mfma_f32_16x16x32_bf16 v[12:15], v[136:139], v[164:167], v[12:15]
	v_mfma_f32_16x16x32_bf16 v[16:19], v[140:143], v[152:155], v[16:19]
	v_mfma_f32_16x16x32_bf16 v[20:23], v[140:143], v[156:159], v[20:23]
	v_mfma_f32_16x16x32_bf16 v[24:27], v[140:143], v[160:163], v[24:27]
	s_add_u32 m0, s30, 0x2000
	v_lshl_add_u64 v[126:127], v[66:67], 0, s[24:25]
	global_load_lds_dwordx4 v[126:127], off
	v_mfma_f32_16x16x32_bf16 v[28:31], v[140:143], v[164:167], v[28:31]
	v_mfma_f32_16x16x32_bf16 v[32:35], v[144:147], v[152:155], v[32:35]
	v_mfma_f32_16x16x32_bf16 v[36:39], v[144:147], v[156:159], v[36:39]
	v_mfma_f32_16x16x32_bf16 v[40:43], v[144:147], v[160:163], v[40:43]
	v_mfma_f32_16x16x32_bf16 v[44:47], v[144:147], v[164:167], v[44:47]
	s_add_u32 m0, s30, 0x4000
	v_lshl_add_u64 v[124:125], v[68:69], 0, s[24:25]
	global_load_lds_dwordx4 v[124:125], off
	v_mfma_f32_16x16x32_bf16 v[48:51], v[148:151], v[152:155], v[48:51]
	v_mfma_f32_16x16x32_bf16 v[52:55], v[148:151], v[156:159], v[52:55]
	v_mfma_f32_16x16x32_bf16 v[56:59], v[148:151], v[160:163], v[56:59]
	v_mfma_f32_16x16x32_bf16 v[60:63], v[148:151], v[164:167], v[60:63]
	ds_read_b128 v[136:139], v77 offset:49152
	ds_read_b128 v[140:143], v77 offset:51200
	ds_read_b128 v[144:147], v77 offset:53248
	ds_read_b128 v[148:151], v77 offset:55296
	ds_read_b128 v[152:155], v79 offset:49152
	ds_read_b128 v[156:159], v79 offset:51200
	ds_read_b128 v[160:163], v79 offset:53248
	ds_read_b128 v[164:167], v79 offset:55296
	s_waitcnt lgkmcnt(8)
	v_mfma_f32_16x16x32_bf16 v[0:3], v[84:87], v[100:103], v[0:3]
	v_mfma_f32_16x16x32_bf16 v[4:7], v[84:87], v[104:107], v[4:7]
	s_add_u32 m0, s30, 0x6000
	v_lshl_add_u64 v[126:127], v[70:71], 0, s[24:25]
	global_load_lds_dwordx4 v[126:127], off
	v_mfma_f32_16x16x32_bf16 v[8:11], v[84:87], v[108:111], v[8:11]
	v_mfma_f32_16x16x32_bf16 v[12:15], v[84:87], v[112:115], v[12:15]
	v_mfma_f32_16x16x32_bf16 v[16:19], v[88:91], v[100:103], v[16:19]
	v_mfma_f32_16x16x32_bf16 v[20:23], v[88:91], v[104:107], v[20:23]
	v_mfma_f32_16x16x32_bf16 v[24:27], v[88:91], v[108:111], v[24:27]
	s_add_u32 m0, s30, 0x8000
	v_lshl_add_u64 v[124:125], v[72:73], 0, s[24:25]
	global_load_lds_dwordx4 v[124:125], off
	v_mfma_f32_16x16x32_bf16 v[28:31], v[88:91], v[112:115], v[28:31]
	v_mfma_f32_16x16x32_bf16 v[32:35], v[92:95], v[100:103], v[32:35]
	v_mfma_f32_16x16x32_bf16 v[36:39], v[92:95], v[104:107], v[36:39]
	v_mfma_f32_16x16x32_bf16 v[40:43], v[92:95], v[108:111], v[40:43]
	v_mfma_f32_16x16x32_bf16 v[44:47], v[92:95], v[112:115], v[44:47]
	s_add_u32 m0, s30, 0xa000
	v_lshl_add_u64 v[126:127], v[74:75], 0, s[24:25]
	global_load_lds_dwordx4 v[126:127], off
	v_mfma_f32_16x16x32_bf16 v[48:51], v[96:99], v[100:103], v[48:51]
	v_mfma_f32_16x16x32_bf16 v[52:55], v[96:99], v[104:107], v[52:55]
	v_mfma_f32_16x16x32_bf16 v[56:59], v[96:99], v[108:111], v[56:59]
	v_mfma_f32_16x16x32_bf16 v[60:63], v[96:99], v[112:115], v[60:63]
	s_waitcnt vmcnt(6) lgkmcnt(0)
	s_barrier
	ds_read_b128 v[84:87], v80
	ds_read_b128 v[88:91], v80 offset:2048
	ds_read_b128 v[92:95], v80 offset:4096
	ds_read_b128 v[96:99], v80 offset:6144
	ds_read_b128 v[100:103], v82
	ds_read_b128 v[104:107], v82 offset:2048
	ds_read_b128 v[108:111], v82 offset:4096
	ds_read_b128 v[112:115], v82 offset:6144
	v_mfma_f32_16x16x32_bf16 v[0:3], v[136:139], v[152:155], v[0:3]
	v_mfma_f32_16x16x32_bf16 v[4:7], v[136:139], v[156:159], v[4:7]
	s_mov_b32 s24, 0x700
	s_mov_b32 s25, 0
	s_add_u32 m0, s30, 0xc000
	v_lshl_add_u64 v[124:125], v[64:65], 0, s[24:25]
	global_load_lds_dwordx4 v[124:125], off
	v_mfma_f32_16x16x32_bf16 v[8:11], v[136:139], v[160:163], v[8:11]
	v_mfma_f32_16x16x32_bf16 v[12:15], v[136:139], v[164:167], v[12:15]
	v_mfma_f32_16x16x32_bf16 v[16:19], v[140:143], v[152:155], v[16:19]
	v_mfma_f32_16x16x32_bf16 v[20:23], v[140:143], v[156:159], v[20:23]
	v_mfma_f32_16x16x32_bf16 v[24:27], v[140:143], v[160:163], v[24:27]
	s_add_u32 m0, s30, 0xe000
	v_lshl_add_u64 v[126:127], v[66:67], 0, s[24:25]
	global_load_lds_dwordx4 v[126:127], off
	v_mfma_f32_16x16x32_bf16 v[28:31], v[140:143], v[164:167], v[28:31]
	v_mfma_f32_16x16x32_bf16 v[32:35], v[144:147], v[152:155], v[32:35]
	v_mfma_f32_16x16x32_bf16 v[36:39], v[144:147], v[156:159], v[36:39]
	v_mfma_f32_16x16x32_bf16 v[40:43], v[144:147], v[160:163], v[40:43]
	v_mfma_f32_16x16x32_bf16 v[44:47], v[144:147], v[164:167], v[44:47]
	s_add_u32 m0, s30, 0x10000
	v_lshl_add_u64 v[124:125], v[68:69], 0, s[24:25]
	global_load_lds_dwordx4 v[124:125], off
	v_mfma_f32_16x16x32_bf16 v[48:51], v[148:151], v[152:155], v[48:51]
	v_mfma_f32_16x16x32_bf16 v[52:55], v[148:151], v[156:159], v[52:55]
	v_mfma_f32_16x16x32_bf16 v[56:59], v[148:151], v[160:163], v[56:59]
	v_mfma_f32_16x16x32_bf16 v[60:63], v[148:151], v[164:167], v[60:63]
	ds_read_b128 v[136:139], v81
	ds_read_b128 v[140:143], v81 offset:2048
	ds_read_b128 v[144:147], v81 offset:4096
	ds_read_b128 v[148:151], v81 offset:6144
	ds_read_b128 v[152:155], v83
	ds_read_b128 v[156:159], v83 offset:2048
	ds_read_b128 v[160:163], v83 offset:4096
	ds_read_b128 v[164:167], v83 offset:6144
	s_waitcnt lgkmcnt(8)
;     ...
;   for (int kt = 0; kt < nk; ++kt) {
;     if (kt + 1 < nk) asm volatile("s_waitcnt vmcnt(6)" ::: "memory");
;     else asm volatile("s_waitcnt vmcnt(0)" ::: "memory");
;     __builtin_amdgcn_s_barrier();
;     asm volatile("" ::: "memory");
;     if (kt + 2 < nk) { const int st2 = (st >= 1) ? st - 1 : 2; GEMM_ISSUE(kt + 2, st2); }
;     const char* la = lds + st * STAGE_B;
;     const char* lb = la + 32768;
;     const unsigned sa_u = (unsigned)(size_t)la + arow_u, sb_u = (unsigned)(size_t)lb + brow_u;
;     const unsigned a0 = sa_u + co0, a1 = sa_u + co1, a2 = sa_u + co2, a3 = sa_u + co3;
;     const unsigned b0 = sb_u + co0, b1 = sb_u + co1, b2 = sb_u + co2, b3 = sb_u + co3;
;     {
;       bf16x8 p0, p1, q0, q1, u0, u1, w0, w1;
;       asm volatile(
;         "ds_read_b128 %4, %12\n\tds_read_b128 %5, %12 offset:4096\n\tds_read_b128 %6, %16\n\tds_read_b128 %7, %16 offset:4096\n\t"
;         "ds_read_b128 %8, %13\n\tds_read_b128 %9, %13 offset:4096\n\tds_read_b128 %10, %17\n\tds_read_b128 %11, %17 offset:4096\n\t"
;         "s_waitcnt lgkmcnt(4)\n\t"
;         "v_mfma_f32_32x32x16_bf16 %0, %4, %6, %0\n\tv_mfma_f32_32x32x16_bf16 %1, %4, %7, %1\n\tv_mfma_f32_32x32x16_bf16 %2, %5, %6, %2\n\tv_mfma_f32_32x32x16_bf16 %3, %5, %7, %3\n\t"
;         "ds_read_b128 %4, %14\n\tds_read_b128 %5, %14 offset:4096\n\tds_read_b128 %6, %18\n\tds_read_b128 %7, %18 offset:4096\n\t"
;         "s_waitcnt lgkmcnt(4)\n\t"
;         "v_mfma_f32_32x32x16_bf16 %0, %8, %10, %0\n\tv_mfma_f32_32x32x16_bf16 %1, %8, %11, %1\n\tv_mfma_f32_32x32x16_bf16 %2, %9, %10, %2\n\tv_mfma_f32_32x32x16_bf16 %3, %9, %11, %3\n\t"
;         "ds_read_b128 %8, %15\n\tds_read_b128 %9, %15 offset:4096\n\tds_read_b128 %10, %19\n\tds_read_b128 %11, %19 offset:4096\n\t"
;         "s_waitcnt lgkmcnt(4)\n\t"
;         "v_mfma_f32_32x32x16_bf16 %0, %4, %6, %0\n\tv_mfma_f32_32x32x16_bf16 %1, %4, %7, %1\n\tv_mfma_f32_32x32x16_bf16 %2, %5, %6, %2\n\tv_mfma_f32_32x32x16_bf16 %3, %5, %7, %3\n\t"
;         "s_waitcnt lgkmcnt(0)\n\t"
;         "v_mfma_f32_32x32x16_bf16 %0, %8, %10, %0\n\tv_mfma_f32_32x32x16_bf16 %1, %8, %11, %1\n\tv_mfma_f32_32x32x16_bf16 %2, %9, %10, %2\n\tv_mfma_f32_32x32x16_bf16 %3, %9, %11, %3"
;         : "+v"(acc[0][0]), "+v"(acc[0][1]), "+v"(acc[1][0]), "+v"(acc[1][1]),
;           "=&v"(p0), "=&v"(p1), "=&v"(q0), "=&v"(q1), "=&v"(u0), "=&v"(u1), "=&v"(w0), "=&v"(w1)
	v_mfma_f32_16x16x32_bf16 v[0:3], v[84:87], v[100:103], v[0:3]
	v_mfma_f32_16x16x32_bf16 v[4:7], v[84:87], v[104:107], v[4:7]
	s_add_u32 m0, s30, 0x12000
	v_lshl_add_u64 v[126:127], v[70:71], 0, s[24:25]
	global_load_lds_dwordx4 v[126:127], off
	v_mfma_f32_16x16x32_bf16 v[8:11], v[84:87], v[108:111], v[8:11]
	v_mfma_f32_16x16x32_bf16 v[12:15], v[84:87], v[112:115], v[12:15]
	v_mfma_f32_16x16x32_bf16 v[16:19], v[88:91], v[100:103], v[16:19]
	v_mfma_f32_16x16x32_bf16 v[20:23], v[88:91], v[104:107], v[20:23]
	v_mfma_f32_16x16x32_bf16 v[24:27], v[88:91], v[108:111], v[24:27]
	s_add_u32 m0, s30, 0x14000
	v_lshl_add_u64 v[124:125], v[72:73], 0, s[24:25]
	global_load_lds_dwordx4 v[124:125], off
	v_mfma_f32_16x16x32_bf16 v[28:31], v[88:91], v[112:115], v[28:31]
	v_mfma_f32_16x16x32_bf16 v[32:35], v[92:95], v[100:103], v[32:35]
	v_mfma_f32_16x16x32_bf16 v[36:39], v[92:95], v[104:107], v[36:39]
	v_mfma_f32_16x16x32_bf16 v[40:43], v[92:95], v[108:111], v[40:43]
	v_mfma_f32_16x16x32_bf16 v[44:47], v[92:95], v[112:115], v[44:47]
	s_add_u32 m0, s30, 0x16000
	v_lshl_add_u64 v[126:127], v[74:75], 0, s[24:25]
	global_load_lds_dwordx4 v[126:127], off
	v_mfma_f32_16x16x32_bf16 v[48:51], v[96:99], v[100:103], v[48:51]
	v_mfma_f32_16x16x32_bf16 v[52:55], v[96:99], v[104:107], v[52:55]
	v_mfma_f32_16x16x32_bf16 v[56:59], v[96:99], v[108:111], v[56:59]
	v_mfma_f32_16x16x32_bf16 v[60:63], v[96:99], v[112:115], v[60:63]
	s_waitcnt vmcnt(6) lgkmcnt(0)
	s_barrier
	ds_read_b128 v[84:87], v76
	ds_read_b128 v[88:91], v76 offset:2048
	ds_read_b128 v[92:95], v76 offset:4096
	ds_read_b128 v[96:99], v76 offset:6144
	ds_read_b128 v[100:103], v78
	ds_read_b128 v[104:107], v78 offset:2048
	ds_read_b128 v[108:111], v78 offset:4096
	ds_read_b128 v[112:115], v78 offset:6144
	v_mfma_f32_16x16x32_bf16 v[0:3], v[136:139], v[152:155], v[0:3]
	v_mfma_f32_16x16x32_bf16 v[4:7], v[136:139], v[156:159], v[4:7]
	s_mov_b32 s24, 0x780
	s_mov_b32 s25, 0
	s_add_u32 m0, s30, 0x18000
	v_lshl_add_u64 v[124:125], v[64:65], 0, s[24:25]
	global_load_lds_dwordx4 v[124:125], off
	v_mfma_f32_16x16x32_bf16 v[8:11], v[136:139], v[160:163], v[8:11]
	v_mfma_f32_16x16x32_bf16 v[12:15], v[136:139], v[164:167], v[12:15]
	v_mfma_f32_16x16x32_bf16 v[16:19], v[140:143], v[152:155], v[16:19]
	v_mfma_f32_16x16x32_bf16 v[20:23], v[140:143], v[156:159], v[20:23]
	v_mfma_f32_16x16x32_bf16 v[24:27], v[140:143], v[160:163], v[24:27]
	s_add_u32 m0, s30, 0x1a000
	v_lshl_add_u64 v[126:127], v[66:67], 0, s[24:25]
	global_load_lds_dwordx4 v[126:127], off
	v_mfma_f32_16x16x32_bf16 v[28:31], v[140:143], v[164:167], v[28:31]
	v_mfma_f32_16x16x32_bf16 v[32:35], v[144:147], v[152:155], v[32:35]
	v_mfma_f32_16x16x32_bf16 v[36:39], v[144:147], v[156:159], v[36:39]
	v_mfma_f32_16x16x32_bf16 v[40:43], v[144:147], v[160:163], v[40:43]
	v_mfma_f32_16x16x32_bf16 v[44:47], v[144:147], v[164:167], v[44:47]
	s_add_u32 m0, s30, 0x1c000
	v_lshl_add_u64 v[124:125], v[68:69], 0, s[24:25]
	global_load_lds_dwordx4 v[124:125], off
	v_mfma_f32_16x16x32_bf16 v[48:51], v[148:151], v[152:155], v[48:51]
	v_mfma_f32_16x16x32_bf16 v[52:55], v[148:151], v[156:159], v[52:55]
	v_mfma_f32_16x16x32_bf16 v[56:59], v[148:151], v[160:163], v[56:59]
	v_mfma_f32_16x16x32_bf16 v[60:63], v[148:151], v[164:167], v[60:63]
	ds_read_b128 v[136:139], v77
	ds_read_b128 v[140:143], v77 offset:2048
	ds_read_b128 v[144:147], v77 offset:4096
	ds_read_b128 v[148:151], v77 offset:6144
	ds_read_b128 v[152:155], v79
	ds_read_b128 v[156:159], v79 offset:2048
	ds_read_b128 v[160:163], v79 offset:4096
	ds_read_b128 v[164:167], v79 offset:6144
	s_waitcnt lgkmcnt(8)
	v_mfma_f32_16x16x32_bf16 v[0:3], v[84:87], v[100:103], v[0:3]
	v_mfma_f32_16x16x32_bf16 v[4:7], v[84:87], v[104:107], v[4:7]
	s_add_u32 m0, s30, 0x1e000
	v_lshl_add_u64 v[126:127], v[70:71], 0, s[24:25]
	global_load_lds_dwordx4 v[126:127], off
	v_mfma_f32_16x16x32_bf16 v[8:11], v[84:87], v[108:111], v[8:11]
	v_mfma_f32_16x16x32_bf16 v[12:15], v[84:87], v[112:115], v[12:15]
	v_mfma_f32_16x16x32_bf16 v[16:19], v[88:91], v[100:103], v[16:19]
	v_mfma_f32_16x16x32_bf16 v[20:23], v[88:91], v[104:107], v[20:23]
	v_mfma_f32_16x16x32_bf16 v[24:27], v[88:91], v[108:111], v[24:27]
	s_add_u32 m0, s30, 0x20000
	v_lshl_add_u64 v[124:125], v[72:73], 0, s[24:25]
	global_load_lds_dwordx4 v[124:125], off
	v_mfma_f32_16x16x32_bf16 v[28:31], v[88:91], v[112:115], v[28:31]
	v_mfma_f32_16x16x32_bf16 v[32:35], v[92:95], v[100:103], v[32:35]
	v_mfma_f32_16x16x32_bf16 v[36:39], v[92:95], v[104:107], v[36:39]
	v_mfma_f32_16x16x32_bf16 v[40:43], v[92:95], v[108:111], v[40:43]
	v_mfma_f32_16x16x32_bf16 v[44:47], v[92:95], v[112:115], v[44:47]
	s_add_u32 m0, s30, 0x22000
	v_lshl_add_u64 v[126:127], v[74:75], 0, s[24:25]
	global_load_lds_dwordx4 v[126:127], off
	v_mfma_f32_16x16x32_bf16 v[48:51], v[96:99], v[100:103], v[48:51]
	v_mfma_f32_16x16x32_bf16 v[52:55], v[96:99], v[104:107], v[52:55]
	v_mfma_f32_16x16x32_bf16 v[56:59], v[96:99], v[108:111], v[56:59]
	v_mfma_f32_16x16x32_bf16 v[60:63], v[96:99], v[112:115], v[60:63]
	s_waitcnt vmcnt(6) lgkmcnt(0)
	s_barrier
;     ...
;   for (int kt = 0; kt < nk; ++kt) {
;     if (kt + 1 < nk) asm volatile("s_waitcnt vmcnt(6)" ::: "memory");
;     else asm volatile("s_waitcnt vmcnt(0)" ::: "memory");
;     __builtin_amdgcn_s_barrier();
;     asm volatile("" ::: "memory");
;     if (kt + 2 < nk) { const int st2 = (st >= 1) ? st - 1 : 2; GEMM_ISSUE(kt + 2, st2); }
;     const char* la = lds + st * STAGE_B;
;     const char* lb = la + 32768;
;     const unsigned sa_u = (unsigned)(size_t)la + arow_u, sb_u = (unsigned)(size_t)lb + brow_u;
;     const unsigned a0 = sa_u + co0, a1 = sa_u + co1, a2 = sa_u + co2, a3 = sa_u + co3;
;     const unsigned b0 = sb_u + co0, b1 = sb_u + co1, b2 = sb_u + co2, b3 = sb_u + co3;
;     {
;       bf16x8 p0, p1, q0, q1, u0, u1, w0, w1;
;       asm volatile(
;         "ds_read_b128 %4, %12\n\tds_read_b128 %5, %12 offset:4096\n\tds_read_b128 %6, %16\n\tds_read_b128 %7, %16 offset:4096\n\t"
;         "ds_read_b128 %8, %13\n\tds_read_b128 %9, %13 offset:4096\n\tds_read_b128 %10, %17\n\tds_read_b128 %11, %17 offset:4096\n\t"
;         "s_waitcnt lgkmcnt(4)\n\t"
;         "v_mfma_f32_32x32x16_bf16 %0, %4, %6, %0\n\tv_mfma_f32_32x32x16_bf16 %1, %4, %7, %1\n\tv_mfma_f32_32x32x16_bf16 %2, %5, %6, %2\n\tv_mfma_f32_32x32x16_bf16 %3, %5, %7, %3\n\t"
;         "ds_read_b128 %4, %14\n\tds_read_b128 %5, %14 offset:4096\n\tds_read_b128 %6, %18\n\tds_read_b128 %7, %18 offset:4096\n\t"
;         "s_waitcnt lgkmcnt(4)\n\t"
;         "v_mfma_f32_32x32x16_bf16 %0, %8, %10, %0\n\tv_mfma_f32_32x32x16_bf16 %1, %8, %11, %1\n\tv_mfma_f32_32x32x16_bf16 %2, %9, %10, %2\n\tv_mfma_f32_32x32x16_bf16 %3, %9, %11, %3\n\t"
;         "ds_read_b128 %8, %15\n\tds_read_b128 %9, %15 offset:4096\n\tds_read_b128 %10, %19\n\tds_read_b128 %11, %19 offset:4096\n\t"
;         "s_waitcnt lgkmcnt(4)\n\t"
;         "v_mfma_f32_32x32x16_bf16 %0, %4, %6, %0\n\tv_mfma_f32_32x32x16_bf16 %1, %4, %7, %1\n\tv_mfma_f32_32x32x16_bf16 %2, %5, %6, %2\n\tv_mfma_f32_32x32x16_bf16 %3, %5, %7, %3\n\t"
;         "s_waitcnt lgkmcnt(0)\n\t"
;         "v_mfma_f32_32x32x16_bf16 %0, %8, %10, %0\n\tv_mfma_f32_32x32x16_bf16 %1, %8, %11, %1\n\tv_mfma_f32_32x32x16_bf16 %2, %9, %10, %2\n\tv_mfma_f32_32x32x16_bf16 %3, %9, %11, %3"
;         : "+v"(acc[0][0]), "+v"(acc[0][1]), "+v"(acc[1][0]), "+v"(acc[1][1]),
;           "=&v"(p0), "=&v"(p1), "=&v"(q0), "=&v"(q1), "=&v"(u0), "=&v"(u1), "=&v"(w0), "=&v"(w1)
	ds_read_b128 v[84:87], v76 offset:49152
	ds_read_b128 v[88:91], v76 offset:51200
	ds_read_b128 v[92:95], v76 offset:53248
	ds_read_b128 v[96:99], v76 offset:55296
	ds_read_b128 v[100:103], v78 offset:49152
	ds_read_b128 v[104:107], v78 offset:51200
	ds_read_b128 v[108:111], v78 offset:53248
	ds_read_b128 v[112:115], v78 offset:55296
	v_mfma_f32_16x16x32_bf16 v[0:3], v[136:139], v[152:155], v[0:3]
	v_mfma_f32_16x16x32_bf16 v[4:7], v[136:139], v[156:159], v[4:7]
	s_add_u32 s24, s56, 0x0
	s_addc_u32 s25, s57, 0
	s_mov_b32 m0, s30
	v_lshl_add_u64 v[124:125], v[64:65], 0, s[24:25]
	global_load_lds_dwordx4 v[124:125], off
	v_mfma_f32_16x16x32_bf16 v[8:11], v[136:139], v[160:163], v[8:11]
	v_mfma_f32_16x16x32_bf16 v[12:15], v[136:139], v[164:167], v[12:15]
	v_mfma_f32_16x16x32_bf16 v[16:19], v[140:143], v[152:155], v[16:19]
	v_mfma_f32_16x16x32_bf16 v[20:23], v[140:143], v[156:159], v[20:23]
	v_mfma_f32_16x16x32_bf16 v[24:27], v[140:143], v[160:163], v[24:27]
	s_add_u32 m0, s30, 0x2000
	v_lshl_add_u64 v[126:127], v[66:67], 0, s[24:25]
	global_load_lds_dwordx4 v[126:127], off
	v_mfma_f32_16x16x32_bf16 v[28:31], v[140:143], v[164:167], v[28:31]
	v_mfma_f32_16x16x32_bf16 v[32:35], v[144:147], v[152:155], v[32:35]
	v_mfma_f32_16x16x32_bf16 v[36:39], v[144:147], v[156:159], v[36:39]
	v_mfma_f32_16x16x32_bf16 v[40:43], v[144:147], v[160:163], v[40:43]
	v_mfma_f32_16x16x32_bf16 v[44:47], v[144:147], v[164:167], v[44:47]
	s_add_u32 m0, s30, 0x4000
	v_lshl_add_u64 v[124:125], v[68:69], 0, s[24:25]
	global_load_lds_dwordx4 v[124:125], off
	v_mfma_f32_16x16x32_bf16 v[48:51], v[148:151], v[152:155], v[48:51]
	v_mfma_f32_16x16x32_bf16 v[52:55], v[148:151], v[156:159], v[52:55]
	v_mfma_f32_16x16x32_bf16 v[56:59], v[148:151], v[160:163], v[56:59]
	v_mfma_f32_16x16x32_bf16 v[60:63], v[148:151], v[164:167], v[60:63]
	ds_read_b128 v[136:139], v77 offset:49152
	ds_read_b128 v[140:143], v77 offset:51200
	ds_read_b128 v[144:147], v77 offset:53248
	ds_read_b128 v[148:151], v77 offset:55296
	ds_read_b128 v[152:155], v79 offset:49152
	ds_read_b128 v[156:159], v79 offset:51200
	ds_read_b128 v[160:163], v79 offset:53248
	ds_read_b128 v[164:167], v79 offset:55296
	s_waitcnt lgkmcnt(8)
	v_mfma_f32_16x16x32_bf16 v[0:3], v[84:87], v[100:103], v[0:3]
	v_mfma_f32_16x16x32_bf16 v[4:7], v[84:87], v[104:107], v[4:7]
	s_add_u32 m0, s30, 0x6000
	v_lshl_add_u64 v[126:127], v[70:71], 0, s[24:25]
	global_load_lds_dwordx4 v[126:127], off
	v_mfma_f32_16x16x32_bf16 v[8:11], v[84:87], v[108:111], v[8:11]
	v_mfma_f32_16x16x32_bf16 v[12:15], v[84:87], v[112:115], v[12:15]
	v_mfma_f32_16x16x32_bf16 v[16:19], v[88:91], v[100:103], v[16:19]
	v_mfma_f32_16x16x32_bf16 v[20:23], v[88:91], v[104:107], v[20:23]
	v_mfma_f32_16x16x32_bf16 v[24:27], v[88:91], v[108:111], v[24:27]
	s_add_u32 s24, s58, 0x0
	s_addc_u32 s25, s59, 0
	s_add_u32 m0, s30, 0x8000
	v_lshl_add_u64 v[124:125], v[72:73], 0, s[24:25]
	global_load_lds_dwordx4 v[124:125], off
	v_mfma_f32_16x16x32_bf16 v[28:31], v[88:91], v[112:115], v[28:31]
	v_mfma_f32_16x16x32_bf16 v[32:35], v[92:95], v[100:103], v[32:35]
	v_mfma_f32_16x16x32_bf16 v[36:39], v[92:95], v[104:107], v[36:39]
	v_mfma_f32_16x16x32_bf16 v[40:43], v[92:95], v[108:111], v[40:43]
	v_mfma_f32_16x16x32_bf16 v[44:47], v[92:95], v[112:115], v[44:47]
	s_add_u32 m0, s30, 0xa000
	v_lshl_add_u64 v[126:127], v[74:75], 0, s[24:25]
	global_load_lds_dwordx4 v[126:127], off
	v_mfma_f32_16x16x32_bf16 v[48:51], v[96:99], v[100:103], v[48:51]
	v_mfma_f32_16x16x32_bf16 v[52:55], v[96:99], v[104:107], v[52:55]
	v_mfma_f32_16x16x32_bf16 v[56:59], v[96:99], v[108:111], v[56:59]
	v_mfma_f32_16x16x32_bf16 v[60:63], v[96:99], v[112:115], v[60:63]
	s_waitcnt vmcnt(6) lgkmcnt(0)
	s_barrier
;     ...
;   for (int kt = 0; kt < nk; ++kt) {
;     if (kt + 1 < nk) asm volatile("s_waitcnt vmcnt(6)" ::: "memory");
;     else asm volatile("s_waitcnt vmcnt(0)" ::: "memory");
;     __builtin_amdgcn_s_barrier();
;     asm volatile("" ::: "memory");
;     if (kt + 2 < nk) { const int st2 = (st >= 1) ? st - 1 : 2; GEMM_ISSUE(kt + 2, st2); }
;     const char* la = lds + st * STAGE_B;
;     const char* lb = la + 32768;
;     const unsigned sa_u = (unsigned)(size_t)la + arow_u, sb_u = (unsigned)(size_t)lb + brow_u;
;     const unsigned a0 = sa_u + co0, a1 = sa_u + co1, a2 = sa_u + co2, a3 = sa_u + co3;
;     const unsigned b0 = sb_u + co0, b1 = sb_u + co1, b2 = sb_u + co2, b3 = sb_u + co3;
;     {
;       bf16x8 p0, p1, q0, q1, u0, u1, w0, w1;
;       asm volatile(
;         "ds_read_b128 %4, %12\n\tds_read_b128 %5, %12 offset:4096\n\tds_read_b128 %6, %16\n\tds_read_b128 %7, %16 offset:4096\n\t"
;         "ds_read_b128 %8, %13\n\tds_read_b128 %9, %13 offset:4096\n\tds_read_b128 %10, %17\n\tds_read_b128 %11, %17 offset:4096\n\t"
;         "s_waitcnt lgkmcnt(4)\n\t"
;         "v_mfma_f32_32x32x16_bf16 %0, %4, %6, %0\n\tv_mfma_f32_32x32x16_bf16 %1, %4, %7, %1\n\tv_mfma_f32_32x32x16_bf16 %2, %5, %6, %2\n\tv_mfma_f32_32x32x16_bf16 %3, %5, %7, %3\n\t"
;         "ds_read_b128 %4, %14\n\tds_read_b128 %5, %14 offset:4096\n\tds_read_b128 %6, %18\n\tds_read_b128 %7, %18 offset:4096\n\t"
;         "s_waitcnt lgkmcnt(4)\n\t"
;         "v_mfma_f32_32x32x16_bf16 %0, %8, %10, %0\n\tv_mfma_f32_32x32x16_bf16 %1, %8, %11, %1\n\tv_mfma_f32_32x32x16_bf16 %2, %9, %10, %2\n\tv_mfma_f32_32x32x16_bf16 %3, %9, %11, %3\n\t"
;         "ds_read_b128 %8, %15\n\tds_read_b128 %9, %15 offset:4096\n\tds_read_b128 %10, %19\n\tds_read_b128 %11, %19 offset:4096\n\t"
;         "s_waitcnt lgkmcnt(4)\n\t"
;         "v_mfma_f32_32x32x16_bf16 %0, %4, %6, %0\n\tv_mfma_f32_32x32x16_bf16 %1, %4, %7, %1\n\tv_mfma_f32_32x32x16_bf16 %2, %5, %6, %2\n\tv_mfma_f32_32x32x16_bf16 %3, %5, %7, %3\n\t"
;         "s_waitcnt lgkmcnt(0)\n\t"
;         "v_mfma_f32_32x32x16_bf16 %0, %8, %10, %0\n\tv_mfma_f32_32x32x16_bf16 %1, %8, %11, %1\n\tv_mfma_f32_32x32x16_bf16 %2, %9, %10, %2\n\tv_mfma_f32_32x32x16_bf16 %3, %9, %11, %3"
;         : "+v"(acc[0][0]), "+v"(acc[0][1]), "+v"(acc[1][0]), "+v"(acc[1][1]),
;           "=&v"(p0), "=&v"(p1), "=&v"(q0), "=&v"(q1), "=&v"(u0), "=&v"(u1), "=&v"(w0), "=&v"(w1)
	ds_read_b128 v[84:87], v80
	ds_read_b128 v[88:91], v80 offset:2048
	ds_read_b128 v[92:95], v80 offset:4096
	ds_read_b128 v[96:99], v80 offset:6144
	ds_read_b128 v[100:103], v82
	ds_read_b128 v[104:107], v82 offset:2048
	ds_read_b128 v[108:111], v82 offset:4096
	ds_read_b128 v[112:115], v82 offset:6144
	v_mfma_f32_16x16x32_bf16 v[0:3], v[136:139], v[152:155], v[0:3]
	v_mfma_f32_16x16x32_bf16 v[4:7], v[136:139], v[156:159], v[4:7]
	s_add_u32 s24, s56, 0x80
	s_addc_u32 s25, s57, 0
	s_add_u32 m0, s30, 0xc000
	v_lshl_add_u64 v[124:125], v[64:65], 0, s[24:25]
	global_load_lds_dwordx4 v[124:125], off
	v_mfma_f32_16x16x32_bf16 v[8:11], v[136:139], v[160:163], v[8:11]
	v_mfma_f32_16x16x32_bf16 v[12:15], v[136:139], v[164:167], v[12:15]
	v_mfma_f32_16x16x32_bf16 v[16:19], v[140:143], v[152:155], v[16:19]
	v_mfma_f32_16x16x32_bf16 v[20:23], v[140:143], v[156:159], v[20:23]
	v_mfma_f32_16x16x32_bf16 v[24:27], v[140:143], v[160:163], v[24:27]
	s_add_u32 m0, s30, 0xe000
	v_lshl_add_u64 v[126:127], v[66:67], 0, s[24:25]
	global_load_lds_dwordx4 v[126:127], off
	v_mfma_f32_16x16x32_bf16 v[28:31], v[140:143], v[164:167], v[28:31]
	v_mfma_f32_16x16x32_bf16 v[32:35], v[144:147], v[152:155], v[32:35]
	v_mfma_f32_16x16x32_bf16 v[36:39], v[144:147], v[156:159], v[36:39]
	v_mfma_f32_16x16x32_bf16 v[40:43], v[144:147], v[160:163], v[40:43]
	v_mfma_f32_16x16x32_bf16 v[44:47], v[144:147], v[164:167], v[44:47]
	s_add_u32 m0, s30, 0x10000
	v_lshl_add_u64 v[124:125], v[68:69], 0, s[24:25]
	global_load_lds_dwordx4 v[124:125], off
	v_mfma_f32_16x16x32_bf16 v[48:51], v[148:151], v[152:155], v[48:51]
	v_mfma_f32_16x16x32_bf16 v[52:55], v[148:151], v[156:159], v[52:55]
	v_mfma_f32_16x16x32_bf16 v[56:59], v[148:151], v[160:163], v[56:59]
	v_mfma_f32_16x16x32_bf16 v[60:63], v[148:151], v[164:167], v[60:63]
	ds_read_b128 v[136:139], v81
	ds_read_b128 v[140:143], v81 offset:2048
	ds_read_b128 v[144:147], v81 offset:4096
	ds_read_b128 v[148:151], v81 offset:6144
	ds_read_b128 v[152:155], v83
	ds_read_b128 v[156:159], v83 offset:2048
	ds_read_b128 v[160:163], v83 offset:4096
	ds_read_b128 v[164:167], v83 offset:6144
	s_waitcnt lgkmcnt(8)
	v_mfma_f32_16x16x32_bf16 v[0:3], v[84:87], v[100:103], v[0:3]
	v_mfma_f32_16x16x32_bf16 v[4:7], v[84:87], v[104:107], v[4:7]
	s_add_u32 m0, s30, 0x12000
	v_lshl_add_u64 v[126:127], v[70:71], 0, s[24:25]
	global_load_lds_dwordx4 v[126:127], off
	v_mfma_f32_16x16x32_bf16 v[8:11], v[84:87], v[108:111], v[8:11]
	v_mfma_f32_16x16x32_bf16 v[12:15], v[84:87], v[112:115], v[12:15]
	v_mfma_f32_16x16x32_bf16 v[16:19], v[88:91], v[100:103], v[16:19]
	v_mfma_f32_16x16x32_bf16 v[20:23], v[88:91], v[104:107], v[20:23]
	v_mfma_f32_16x16x32_bf16 v[24:27], v[88:91], v[108:111], v[24:27]
	s_add_u32 s24, s58, 0x80
	s_addc_u32 s25, s59, 0
	s_add_u32 m0, s30, 0x14000
	v_lshl_add_u64 v[124:125], v[72:73], 0, s[24:25]
	global_load_lds_dwordx4 v[124:125], off
	v_mfma_f32_16x16x32_bf16 v[28:31], v[88:91], v[112:115], v[28:31]
	v_mfma_f32_16x16x32_bf16 v[32:35], v[92:95], v[100:103], v[32:35]
	v_mfma_f32_16x16x32_bf16 v[36:39], v[92:95], v[104:107], v[36:39]
	v_mfma_f32_16x16x32_bf16 v[40:43], v[92:95], v[108:111], v[40:43]
	v_mfma_f32_16x16x32_bf16 v[44:47], v[92:95], v[112:115], v[44:47]
	s_add_u32 m0, s30, 0x16000
	v_lshl_add_u64 v[126:127], v[74:75], 0, s[24:25]
	global_load_lds_dwordx4 v[126:127], off
	v_mfma_f32_16x16x32_bf16 v[48:51], v[96:99], v[100:103], v[48:51]
	v_mfma_f32_16x16x32_bf16 v[52:55], v[96:99], v[104:107], v[52:55]
	v_mfma_f32_16x16x32_bf16 v[56:59], v[96:99], v[108:111], v[56:59]
	v_mfma_f32_16x16x32_bf16 v[60:63], v[96:99], v[112:115], v[60:63]
	s_waitcnt lgkmcnt(0)
	v_mfma_f32_16x16x32_bf16 v[0:3], v[136:139], v[152:155], v[0:3]
	v_mfma_f32_16x16x32_bf16 v[4:7], v[136:139], v[156:159], v[4:7]
	v_mfma_f32_16x16x32_bf16 v[8:11], v[136:139], v[160:163], v[8:11]
	v_mfma_f32_16x16x32_bf16 v[12:15], v[136:139], v[164:167], v[12:15]
	v_mfma_f32_16x16x32_bf16 v[16:19], v[140:143], v[152:155], v[16:19]
	v_mfma_f32_16x16x32_bf16 v[20:23], v[140:143], v[156:159], v[20:23]
	v_mfma_f32_16x16x32_bf16 v[24:27], v[140:143], v[160:163], v[24:27]
	v_mfma_f32_16x16x32_bf16 v[28:31], v[140:143], v[164:167], v[28:31]
	v_mfma_f32_16x16x32_bf16 v[32:35], v[144:147], v[152:155], v[32:35]
	v_mfma_f32_16x16x32_bf16 v[36:39], v[144:147], v[156:159], v[36:39]
	v_mfma_f32_16x16x32_bf16 v[40:43], v[144:147], v[160:163], v[40:43]
	v_mfma_f32_16x16x32_bf16 v[44:47], v[144:147], v[164:167], v[44:47]
	v_mfma_f32_16x16x32_bf16 v[48:51], v[148:151], v[152:155], v[48:51]
	v_mfma_f32_16x16x32_bf16 v[52:55], v[148:151], v[156:159], v[52:55]
	v_mfma_f32_16x16x32_bf16 v[56:59], v[148:151], v[160:163], v[56:59]
	v_mfma_f32_16x16x32_bf16 v[60:63], v[148:151], v[164:167], v[60:63]
.Ly11_done:
	s_add_u32 s100, s100, 1
	s_cmp_ge_u32 s100, 3
	s_cselect_b32 s101, 3, 0
	s_sub_u32 s100, s100, s101
	s_mov_b32 s101, 0
	s_mov_b32 s53, 0x8000
	s_nop 15
	s_nop 15
	s_nop 7
	s_barrier
	s_branch .LBB0_56

; __global__ void __launch_bounds__(NTHREADS) mega_kernel(Params p) {
;     ...
;   for (int ph = 0; ph < NPHASE; ++ph) {
;     ...
;     const int nrep = (REPQ >= 100) ? ((ph == REPQ - 100) ? 2 : 1) : ((ph > 0 && ph < NPHASE - 1 && (ph - 1) % 14 == REPQ) ? 2 : 1);
;     ...
;     const int nrep = 1;
;     ...
;     if (ph == NPHASE - 2) continue;
;     for (int rep = 0; rep < nrep; ++rep) {
;       run_phase(p, ph, lds, rep);
;       if (ph + 1 < NPHASE) {
;         if (ph == 0) grid.sync();
;         else { ++bar_gen; grid_barrier((unsigned*)(p.ws + OFF_MISC + 6144), bar_gen * gridDim.x); }
;       }
;     }
.LBB0_735:
	s_or_b64 exec, exec, s[54:55]
	s_mov_b64 s[40:41], -1
	s_barrier
	s_and_b64 vcc, exec, s[44:45]
	s_cbranch_vccz .LBB0_178
	s_branch .LBB0_122
.Ltramp_956:
	s_branch .LBB0_956
.LBB0_736:
	s_mov_b32 s46, s62
	s_mov_b64 s[48:49], s[64:65]

; #define TIDX get_tid_()
; DI bf16_t f2bf(float x) { unsigned r; asm("v_cvt_pk_bf16_f32 %0, %1, %1" : "=v"(r) : "v"(x)); return (bf16_t)(r & 0xffffu); }
; DI int crow(int i, int h) { return (i & 3) + 8 * (i >> 2) + 4 * h; }
; DI float sigmoidf_(float x) { return 1.f / (1.f + __expf(-x)); }
; #define GEMM_ISSUE(kt_, st_) do { char* sb_ = lw + (st_) * STAGE_B; const char* ak_ = Ab + (size_t)(kt_) * 128; const char* bk_ = Bb + (size_t)(kt_) * 128; \
;     _Pragma("unroll") for (int i_ = 0; i_ < 4; ++i_) glds16(ak_ + avo[i_], sb_ + i_ * 8192); \
;     _Pragma("unroll") for (int i_ = 0; i_ < 2; ++i_) glds16(bk_ + bvo[i_], sb_ + 32768 + i_ * 8192); } while (0)
;     ...
;   if (PART != 2) {
;     GEMM_ISSUE(0, 0);
;     if (nk > 1) GEMM_ISSUE(1, 1);
;   }
;   DI void operator()(const f32x16 (&acc)[2][2], int m0, int n0) const {
;     const int tid = TIDX, lane = tid & 63, wid = tid >> 6, wr = wid >> 1, wc = wid & 1, r = lane & 31, h = lane >> 5;
;     const int hid = (n0 >> 7) * 64 + wc * 32 + r;
; #pragma unroll
;     for (int mi = 0; mi < 2; ++mi)
; #pragma unroll
;       for (int i = 0; i < 16; ++i) {
;         const int row = m0 + wr * 64 + mi * 32 + crow(i, h);
;         const float g = acc[mi][0][i], u = acc[mi][1][i];
;         ffh[(size_t)row * DFF + hid] = f2bf(g * sigmoidf_(g) * u);
;       }
;   }
.LBB0_755:
	s_andn2_b64 vcc, exec, s[14:15]
	s_cbranch_vccnz .LBB0_767
	v_mov_b32_e32 v0, v129
	s_ashr_i32 s9, s8, 31
	v_lshlrev_b32_e32 v1, 4, v0
	v_xor_b32_e32 v2, v1, v0
	v_lshlrev_b32_e32 v0, 8, v0
	s_lshl_b64 s[14:15], s[8:9], 19
	v_and_b32_e32 v0, 0xfffff800, v0
	s_movk_i32 s9, 0x70
	v_add_u32_e32 v14, 0, v1
	s_add_u32 s14, s88, s14
	v_and_or_b32 v130, v2, s9, v0
	v_readfirstlane_b32 s9, v14
	v_add_u32_e32 v3, 0x2000, v14
	s_addc_u32 s15, s89, s15
	v_add_u32_e32 v2, 0x40000, v130
	s_mov_b32 m0, s9
	v_readfirstlane_b32 s9, v3
	v_mov_b32_e32 v3, v131
	v_lshl_add_u64 v[10:11], s[14:15], 0, v[2:3]
	v_add_u32_e32 v3, 0x4000, v14
	s_ashr_i32 s11, s10, 31
	v_add_u32_e32 v0, 0x20000, v130
	global_load_lds_dwordx4 v130, s[14:15]
	s_mov_b32 m0, s9
	v_readfirstlane_b32 s9, v3
	s_lshl_b64 s[26:27], s[10:11], 18
	v_add_u32_e32 v4, 0x60000, v130
	global_load_lds_dwordx4 v0, s[14:15]
	s_mov_b32 m0, s9
	v_mov_b32_e32 v5, v131
	s_add_u32 s26, s4, s26
	global_load_lds_dwordx4 v2, s[14:15]
	v_lshl_add_u64 v[2:3], s[14:15], 0, v[4:5]
	v_add_u32_e32 v5, 0x6000, v14
	s_addc_u32 s27, s22, s27
	v_mov_b32_e32 v1, v131
	v_readfirstlane_b32 s9, v5
	v_add_u32_e32 v12, 0x8000, v14
	v_lshl_add_u64 v[8:9], s[14:15], 0, v[0:1]
	s_mov_b32 m0, s9
	v_readfirstlane_b32 s9, v12
	v_lshl_add_u64 v[12:13], s[26:27], 0, v[0:1]
	v_add_u32_e32 v1, 0xa000, v14
	global_load_lds_dwordx4 v4, s[14:15]
	s_mov_b32 m0, s9
	v_readfirstlane_b32 s9, v1
	v_lshl_add_u64 v[6:7], s[14:15], 0, v[130:131]
	global_load_lds_dwordx4 v130, s[26:27]
	s_mov_b32 m0, s9
	v_add_u32_e32 v15, 0xc000, v14
	global_load_lds_dwordx4 v0, s[26:27]
	v_lshl_add_u64 v[0:1], v[6:7], 0, s[92:93]
	v_readfirstlane_b32 s9, v15
	v_add_u32_e32 v6, 0xe000, v14
	s_mov_b32 m0, s9
	v_readfirstlane_b32 s9, v6
	v_add_u32_e32 v6, 0x10000, v14
	global_load_lds_dwordx4 v[0:1], off
	v_lshl_add_u64 v[0:1], v[8:9], 0, s[92:93]
	s_mov_b32 m0, s9
	v_readfirstlane_b32 s9, v6
	global_load_lds_dwordx4 v[0:1], off
	v_lshl_add_u64 v[0:1], v[10:11], 0, s[92:93]
	s_mov_b32 m0, s9
	v_lshl_add_u64 v[4:5], s[26:27], 0, v[130:131]
	global_load_lds_dwordx4 v[0:1], off
	v_lshl_add_u64 v[0:1], v[2:3], 0, s[92:93]
	v_add_u32_e32 v2, 0x12000, v14
	s_nop 0
	v_readfirstlane_b32 s9, v2
	v_add_u32_e32 v2, 0x14000, v14
	s_mov_b32 m0, s9
	v_readfirstlane_b32 s9, v2
	v_add_u32_e32 v2, 0x16000, v14
	global_load_lds_dwordx4 v[0:1], off
	v_lshl_add_u64 v[0:1], v[4:5], 0, s[92:93]
	s_mov_b32 m0, s9
	v_readfirstlane_b32 s9, v2
	global_load_lds_dwordx4 v[0:1], off
	v_lshl_add_u64 v[0:1], v[12:13], 0, s[92:93]
	s_mov_b32 m0, s9
	s_nop 0
	global_load_lds_dwordx4 v[0:1], off
	s_waitcnt vmcnt(0)
	s_mov_b32 s100, 0
	s_mov_b32 s101, 1
	s_branch .LBB0_758
.LBB0_757:
	v_lshrrev_b32_e32 v64, 7, v129
	v_bfe_u32 v65, v129, 4, 2
	v_lshlrev_b32_e32 v64, 6, v64
	v_lshl_add_u32 v64, v65, 2, v64
	v_mul_u32_u24_e32 v64, 0x1600, v64
	v_bfe_u32 v65, v129, 6, 1
	v_and_b32_e32 v66, 15, v129
	v_lshl_add_u32 v65, v65, 5, v66
	v_lshl_add_u32 v72, v65, 1, v64
	v_add_u32_e32 v73, 0x1600, v72
	v_add_u32_e32 v74, 0x2c00, v72
	v_add_u32_e32 v75, 0x4200, v72
	v_readlane_b32 s24, v253, 13
	v_readlane_b32 s25, v253, 14
	s_mul_i32 s26, s68, 0x160000
	s_lshl_b32 s27, s70, 7
	s_add_u32 s26, s26, s27
	s_add_u32 s24, s24, s26
	s_addc_u32 s25, s25, 0
	v_mul_f32_e32 v64, 0xbfb8aa3b, v0
	v_mul_f32_e32 v65, 0xbfb8aa3b, v1
	v_mul_f32_e32 v66, 0xbfb8aa3b, v2
	v_mul_f32_e32 v67, 0xbfb8aa3b, v3
	v_exp_f32_e32 v64, v64
	v_exp_f32_e32 v65, v65
	v_exp_f32_e32 v66, v66
	v_exp_f32_e32 v67, v67
	v_add_f32_e32 v64, 1.0, v64
	v_add_f32_e32 v65, 1.0, v65
	v_add_f32_e32 v66, 1.0, v66
	v_add_f32_e32 v67, 1.0, v67
	v_rcp_f32_e32 v64, v64
	v_rcp_f32_e32 v65, v65
	v_rcp_f32_e32 v66, v66
	v_rcp_f32_e32 v67, v67
	v_mul_f32_e32 v0, v0, v64
	v_mul_f32_e32 v1, v1, v65
	v_mul_f32_e32 v2, v2, v66
	v_mul_f32_e32 v3, v3, v67
	v_mul_f32_e32 v0, v8, v0
	v_mul_f32_e32 v1, v9, v1
	v_mul_f32_e32 v2, v10, v2
	v_mul_f32_e32 v3, v11, v3
	v_cvt_pk_bf16_f32 v64, v0, v1
	v_cvt_pk_bf16_f32 v65, v2, v3
	global_store_short v72, v64, s[24:25]
	global_store_short_d16_hi v73, v64, s[24:25]
	global_store_short v74, v65, s[24:25]
	global_store_short_d16_hi v75, v65, s[24:25]
	v_mul_f32_e32 v68, 0xbfb8aa3b, v4
	v_mul_f32_e32 v69, 0xbfb8aa3b, v5
	v_mul_f32_e32 v70, 0xbfb8aa3b, v6
	v_mul_f32_e32 v71, 0xbfb8aa3b, v7
	v_exp_f32_e32 v68, v68
	v_exp_f32_e32 v69, v69
	v_exp_f32_e32 v70, v70
	v_exp_f32_e32 v71, v71
	v_add_f32_e32 v68, 1.0, v68
	v_add_f32_e32 v69, 1.0, v69
	v_add_f32_e32 v70, 1.0, v70
	v_add_f32_e32 v71, 1.0, v71
	v_rcp_f32_e32 v68, v68
	v_rcp_f32_e32 v69, v69
	v_rcp_f32_e32 v70, v70
	v_rcp_f32_e32 v71, v71
	v_mul_f32_e32 v4, v4, v68
	v_mul_f32_e32 v5, v5, v69
	v_mul_f32_e32 v6, v6, v70
	v_mul_f32_e32 v7, v7, v71
	v_mul_f32_e32 v4, v12, v4
	v_mul_f32_e32 v5, v13, v5
	v_mul_f32_e32 v6, v14, v6
	v_mul_f32_e32 v7, v15, v7
	v_cvt_pk_bf16_f32 v68, v4, v5
	v_cvt_pk_bf16_f32 v69, v6, v7
	global_store_short v72, v68, s[24:25] offset:32
	global_store_short_d16_hi v73, v68, s[24:25] offset:32
	global_store_short v74, v69, s[24:25] offset:32
	global_store_short_d16_hi v75, v69, s[24:25] offset:32
	s_add_u32 s24, s24, 0x16000
	s_addc_u32 s25, s25, 0
	v_mul_f32_e32 v64, 0xbfb8aa3b, v16
	v_mul_f32_e32 v65, 0xbfb8aa3b, v17
	v_mul_f32_e32 v66, 0xbfb8aa3b, v18
	v_mul_f32_e32 v67, 0xbfb8aa3b, v19
	v_exp_f32_e32 v64, v64
	v_exp_f32_e32 v65, v65
	v_exp_f32_e32 v66, v66
	v_exp_f32_e32 v67, v67
	v_add_f32_e32 v64, 1.0, v64
	v_add_f32_e32 v65, 1.0, v65
	v_add_f32_e32 v66, 1.0, v66
	v_add_f32_e32 v67, 1.0, v67
	v_rcp_f32_e32 v64, v64
	v_rcp_f32_e32 v65, v65
	v_rcp_f32_e32 v66, v66
	v_rcp_f32_e32 v67, v67
	v_mul_f32_e32 v16, v16, v64
	v_mul_f32_e32 v17, v17, v65
; #define TIDX get_tid_()
; DI bf16_t f2bf(float x) { unsigned r; asm("v_cvt_pk_bf16_f32 %0, %1, %1" : "=v"(r) : "v"(x)); return (bf16_t)(r & 0xffffu); }
; DI int crow(int i, int h) { return (i & 3) + 8 * (i >> 2) + 4 * h; }
; DI float sigmoidf_(float x) { return 1.f / (1.f + __expf(-x)); }
;   DI void operator()(const f32x16 (&acc)[2][2], int m0, int n0) const {
;     const int tid = TIDX, lane = tid & 63, wid = tid >> 6, wr = wid >> 1, wc = wid & 1, r = lane & 31, h = lane >> 5;
;     const int hid = (n0 >> 7) * 64 + wc * 32 + r;
; #pragma unroll
;     for (int mi = 0; mi < 2; ++mi)
; #pragma unroll
;       for (int i = 0; i < 16; ++i) {
;         const int row = m0 + wr * 64 + mi * 32 + crow(i, h);
;         const float g = acc[mi][0][i], u = acc[mi][1][i];
;         ffh[(size_t)row * DFF + hid] = f2bf(g * sigmoidf_(g) * u);
;       }
;   }
	v_mul_f32_e32 v18, v18, v66
	v_mul_f32_e32 v19, v19, v67
	v_mul_f32_e32 v16, v24, v16
	v_mul_f32_e32 v17, v25, v17
	v_mul_f32_e32 v18, v26, v18
	v_mul_f32_e32 v19, v27, v19
	v_cvt_pk_bf16_f32 v64, v16, v17
	v_cvt_pk_bf16_f32 v65, v18, v19
	global_store_short v72, v64, s[24:25]
	global_store_short_d16_hi v73, v64, s[24:25]
	global_store_short v74, v65, s[24:25]
	global_store_short_d16_hi v75, v65, s[24:25]
	v_mul_f32_e32 v68, 0xbfb8aa3b, v20
	v_mul_f32_e32 v69, 0xbfb8aa3b, v21
	v_mul_f32_e32 v70, 0xbfb8aa3b, v22
	v_mul_f32_e32 v71, 0xbfb8aa3b, v23
	v_exp_f32_e32 v68, v68
	v_exp_f32_e32 v69, v69
	v_exp_f32_e32 v70, v70
	v_exp_f32_e32 v71, v71
	v_add_f32_e32 v68, 1.0, v68
	v_add_f32_e32 v69, 1.0, v69
	v_add_f32_e32 v70, 1.0, v70
	v_add_f32_e32 v71, 1.0, v71
	v_rcp_f32_e32 v68, v68
	v_rcp_f32_e32 v69, v69
	v_rcp_f32_e32 v70, v70
	v_rcp_f32_e32 v71, v71
	v_mul_f32_e32 v20, v20, v68
	v_mul_f32_e32 v21, v21, v69
	v_mul_f32_e32 v22, v22, v70
	v_mul_f32_e32 v23, v23, v71
	v_mul_f32_e32 v20, v28, v20
	v_mul_f32_e32 v21, v29, v21
	v_mul_f32_e32 v22, v30, v22
	v_mul_f32_e32 v23, v31, v23
	v_cvt_pk_bf16_f32 v68, v20, v21
	v_cvt_pk_bf16_f32 v69, v22, v23
	global_store_short v72, v68, s[24:25] offset:32
	global_store_short_d16_hi v73, v68, s[24:25] offset:32
	global_store_short v74, v69, s[24:25] offset:32
	global_store_short_d16_hi v75, v69, s[24:25] offset:32
	s_add_u32 s24, s24, 0x16000
	s_addc_u32 s25, s25, 0
	v_mul_f32_e32 v64, 0xbfb8aa3b, v32
	v_mul_f32_e32 v65, 0xbfb8aa3b, v33
	v_mul_f32_e32 v66, 0xbfb8aa3b, v34
	v_mul_f32_e32 v67, 0xbfb8aa3b, v35
	v_exp_f32_e32 v64, v64
	v_exp_f32_e32 v65, v65
	v_exp_f32_e32 v66, v66
	v_exp_f32_e32 v67, v67
	v_add_f32_e32 v64, 1.0, v64
	v_add_f32_e32 v65, 1.0, v65
	v_add_f32_e32 v66, 1.0, v66
	v_add_f32_e32 v67, 1.0, v67
	v_rcp_f32_e32 v64, v64
	v_rcp_f32_e32 v65, v65
	v_rcp_f32_e32 v66, v66
	v_rcp_f32_e32 v67, v67
	v_mul_f32_e32 v32, v32, v64
	v_mul_f32_e32 v33, v33, v65
	v_mul_f32_e32 v34, v34, v66
	v_mul_f32_e32 v35, v35, v67
	v_mul_f32_e32 v32, v40, v32
	v_mul_f32_e32 v33, v41, v33
	v_mul_f32_e32 v34, v42, v34
	v_mul_f32_e32 v35, v43, v35
	v_cvt_pk_bf16_f32 v64, v32, v33
	v_cvt_pk_bf16_f32 v65, v34, v35
	global_store_short v72, v64, s[24:25]
	global_store_short_d16_hi v73, v64, s[24:25]
	global_store_short v74, v65, s[24:25]
	global_store_short_d16_hi v75, v65, s[24:25]
	v_mul_f32_e32 v68, 0xbfb8aa3b, v36
	v_mul_f32_e32 v69, 0xbfb8aa3b, v37
	v_mul_f32_e32 v70, 0xbfb8aa3b, v38
	v_mul_f32_e32 v71, 0xbfb8aa3b, v39
	v_exp_f32_e32 v68, v68
	v_exp_f32_e32 v69, v69
	v_exp_f32_e32 v70, v70
	v_exp_f32_e32 v71, v71
	v_add_f32_e32 v68, 1.0, v68
	v_add_f32_e32 v69, 1.0, v69
	v_add_f32_e32 v70, 1.0, v70
	v_add_f32_e32 v71, 1.0, v71
	v_rcp_f32_e32 v68, v68
	v_rcp_f32_e32 v69, v69
	v_rcp_f32_e32 v70, v70
	v_rcp_f32_e32 v71, v71
	v_mul_f32_e32 v36, v36, v68
	v_mul_f32_e32 v37, v37, v69
	v_mul_f32_e32 v38, v38, v70
	v_mul_f32_e32 v39, v39, v71
	v_mul_f32_e32 v36, v44, v36
	v_mul_f32_e32 v37, v45, v37
	v_mul_f32_e32 v38, v46, v38
	v_mul_f32_e32 v39, v47, v39
	v_cvt_pk_bf16_f32 v68, v36, v37
	v_cvt_pk_bf16_f32 v69, v38, v39
	global_store_short v72, v68, s[24:25] offset:32
	global_store_short_d16_hi v73, v68, s[24:25] offset:32
	global_store_short v74, v69, s[24:25] offset:32
	global_store_short_d16_hi v75, v69, s[24:25] offset:32
	s_add_u32 s24, s24, 0x16000
	s_addc_u32 s25, s25, 0
	v_mul_f32_e32 v64, 0xbfb8aa3b, v48
	v_mul_f32_e32 v65, 0xbfb8aa3b, v49
	v_mul_f32_e32 v66, 0xbfb8aa3b, v50
	v_mul_f32_e32 v67, 0xbfb8aa3b, v51
	v_exp_f32_e32 v64, v64
	v_exp_f32_e32 v65, v65
	v_exp_f32_e32 v66, v66
	v_exp_f32_e32 v67, v67
	v_add_f32_e32 v64, 1.0, v64
	v_add_f32_e32 v65, 1.0, v65
	v_add_f32_e32 v66, 1.0, v66
	v_add_f32_e32 v67, 1.0, v67
	v_rcp_f32_e32 v64, v64
	v_rcp_f32_e32 v65, v65
	v_rcp_f32_e32 v66, v66
	v_rcp_f32_e32 v67, v67
	v_mul_f32_e32 v48, v48, v64
	v_mul_f32_e32 v49, v49, v65
	v_mul_f32_e32 v50, v50, v66
	v_mul_f32_e32 v51, v51, v67
	v_mul_f32_e32 v48, v56, v48
	v_mul_f32_e32 v49, v57, v49
	v_mul_f32_e32 v50, v58, v50
	v_mul_f32_e32 v51, v59, v51
	v_cvt_pk_bf16_f32 v64, v48, v49
	v_cvt_pk_bf16_f32 v65, v50, v51
	global_store_short v72, v64, s[24:25]
	global_store_short_d16_hi v73, v64, s[24:25]
	global_store_short v74, v65, s[24:25]
	global_store_short_d16_hi v75, v65, s[24:25]
	v_mul_f32_e32 v68, 0xbfb8aa3b, v52
	v_mul_f32_e32 v69, 0xbfb8aa3b, v53
	v_mul_f32_e32 v70, 0xbfb8aa3b, v54
	v_mul_f32_e32 v71, 0xbfb8aa3b, v55
	v_exp_f32_e32 v68, v68
	v_exp_f32_e32 v69, v69
	v_exp_f32_e32 v70, v70
	v_exp_f32_e32 v71, v71
	v_add_f32_e32 v68, 1.0, v68
	v_add_f32_e32 v69, 1.0, v69
	v_add_f32_e32 v70, 1.0, v70
	v_add_f32_e32 v71, 1.0, v71
	v_rcp_f32_e32 v68, v68
	v_rcp_f32_e32 v69, v69
	v_rcp_f32_e32 v70, v70
	v_rcp_f32_e32 v71, v71
	v_mul_f32_e32 v52, v52, v68
	v_mul_f32_e32 v53, v53, v69
	v_mul_f32_e32 v54, v54, v70
	v_mul_f32_e32 v55, v55, v71
	v_mul_f32_e32 v52, v60, v52
	v_mul_f32_e32 v53, v61, v53
	v_mul_f32_e32 v54, v62, v54
	v_mul_f32_e32 v55, v63, v55
	v_cvt_pk_bf16_f32 v68, v52, v53
	v_cvt_pk_bf16_f32 v69, v54, v55
	global_store_short v72, v68, s[24:25] offset:32
	global_store_short_d16_hi v73, v68, s[24:25] offset:32
	global_store_short v74, v69, s[24:25] offset:32
	global_store_short_d16_hi v75, v69, s[24:25] offset:32
	s_xor_b64 s[14:15], s[14:15], -1
	s_and_b64 vcc, exec, s[14:15]
	s_cbranch_vccnz .LBB0_766
; #define TIDX get_tid_()
;   const int tid = TIDX, lane = tid & 63, wid = tid >> 6, wr = wid >> 1, wc = wid & 1, r = lane & 31, h = lane >> 5;
;   const int ch = (tid & 7) ^ ((tid >> 4) & 7);
;   unsigned avo[4], bvo[2];
; #pragma unroll
;   for (int i = 0; i < 4; ++i) avo[i] = (unsigned)(((tid >> 3) + 64 * i) * lda * 2 + ch * 16);
; #pragma unroll
;   for (int i = 0; i < 2; ++i) bvo[i] = (unsigned)(((tid >> 3) + 64 * i) * ldb * 2 + ch * 16);
;   const char* Ab = (const char*)A; const char* Bb = (const char*)Bt;
;   char* lw = lds + tid * 16;
;   const int nk = K >> 6;
;   const unsigned swz = (unsigned)((r >> 1) & 7);
;   const unsigned arow_u = (unsigned)((wr * 64 + r) * 128), brow_u = (unsigned)((wc * 64 + r) * 128);
;   const unsigned co0 = ((0u + h) ^ swz) << 4, co1 = ((2u + h) ^ swz) << 4, co2 = ((4u + h) ^ swz) << 4, co3 = ((6u + h) ^ swz) << 4;
; template <class Epi>
; DI void gemm_phase(const bf16_t* A, int lda, const bf16_t* Bt, int ldb, int K, int MT, int NTl, int SN, const Epi& epi, char* lds, bool rev = false) {
;     ...
;     for (L += gridDim.x; L < lmax; L += gridDim.x) if (tile_map(L, MT, NTl, SN, mt, nt)) { have = true; if (rev) mt = MT - 1 - mt; break; }
.LBB0_758:
	v_mov_b32_e32 v1, v129
	s_mov_b32 s68, s8
	v_lshlrev_b32_e32 v5, 4, v1
	v_lshrrev_b32_e32 v3, 5, v1
	v_xor_b32_e32 v0, v5, v1
	v_lshlrev_b32_e32 v2, 8, v1
	v_and_b32_e32 v6, 31, v1
	v_bfe_u32 v7, v1, 5, 1
	v_add_u32_e32 v116, 0, v5
	v_lshrrev_b32_e32 v5, 1, v1
	v_bfe_u32 v8, v1, 1, 3
	v_lshlrev_b32_e32 v1, 7, v1
	s_ashr_i32 s69, s8, 31
	v_and_b32_e32 v118, 0x2f80, v1
	v_bitop3_b32 v1, v3, v8, 1 bitop3:0x6c
	s_lshl_b64 s[14:15], s[68:69], 19
	v_lshlrev_b32_e32 v119, 4, v1
	v_bitop3_b32 v1, v7, v8, 2 bitop3:0x36
	s_add_u32 s26, s88, s14
	v_and_b32_e32 v2, 0xfffff800, v2
	s_movk_i32 s9, 0x70
	v_lshlrev_b32_e32 v120, 4, v1
	v_bitop3_b32 v1, v7, v8, 4 bitop3:0x36
	s_addc_u32 s27, s89, s15
	v_and_or_b32 v130, v0, s9, v2
	s_mov_b32 s9, 0x1ffffc0
	v_lshlrev_b32_e32 v121, 4, v1
	v_bitop3_b32 v1, v7, v8, 6 bitop3:0x36
	v_add_u32_e32 v8, 0x18000, v116
	v_add_u32_e32 v0, 0x20000, v130
	v_and_or_b32 v5, v5, s9, v6
	v_lshlrev_b32_e32 v122, 4, v1
	v_mov_b32_e32 v1, v131
	v_lshl_add_u64 v[64:65], s[26:27], 0, v[130:131]
	v_readfirstlane_b32 s9, v8
	v_add_u32_e32 v8, 0x1a000, v116
	v_lshl_add_u64 v[6:7], v[64:65], 0, s[78:79]
	v_lshl_add_u64 v[66:67], s[26:27], 0, v[0:1]
	v_readfirstlane_b32 s11, v8
	s_mov_b32 s70, s10
	s_ashr_i32 s71, s10, 31
	v_lshl_add_u64 v[6:7], v[66:67], 0, s[78:79]
	s_lshl_b64 s[14:15], s[70:71], 18
	v_add_u32_e32 v2, 0x40000, v130
	v_add_u32_e32 v4, 0x60000, v130
	v_lshlrev_b32_e32 v117, 7, v5
	v_mov_b32_e32 v3, v131
	v_mov_b32_e32 v5, v131
	v_add_u32_e32 v6, 0x1c000, v116
	s_add_u32 s30, s4, s14
	v_lshl_add_u64 v[68:69], s[26:27], 0, v[2:3]
	v_readfirstlane_b32 s14, v6
	v_lshl_add_u64 v[70:71], s[26:27], 0, v[4:5]
	v_add_u32_e32 v4, 0x1e000, v116
	s_addc_u32 s31, s22, s15
	v_lshl_add_u64 v[2:3], v[68:69], 0, s[78:79]
	v_readfirstlane_b32 s15, v4
	v_add_u32_e32 v4, 0x20000, v116
	v_lshl_add_u64 v[2:3], v[70:71], 0, s[78:79]
	v_lshl_add_u64 v[72:73], s[30:31], 0, v[130:131]
	v_readfirstlane_b32 s26, v4
	v_lshl_add_u64 v[2:3], v[72:73], 0, s[78:79]
	v_lshl_add_u64 v[74:75], s[30:31], 0, v[0:1]
	v_add_u32_e32 v2, 0x22000, v116
	s_cmp_lg_u32 0, -1
	v_readfirstlane_b32 s27, v2
	v_lshl_add_u64 v[0:1], v[74:75], 0, s[78:79]
	s_cselect_b32 s30, 0, 0
	s_mov_b32 s53, s52
	v_add_u32_e32 v0, s30, v117
	s_add_i32 s30, s30, 0x8000
	s_mov_b32 s54, s52
	s_mov_b32 s55, s52
	s_mov_b32 s56, s52
	s_mov_b32 s57, s52
	s_mov_b32 s58, s52
	s_mov_b32 s59, s52
	s_mov_b32 s60, s52
	s_mov_b32 s61, s52
	s_mov_b32 s62, s52
	s_mov_b32 s63, s52
	s_mov_b32 s64, s52
	s_mov_b32 s65, s52
	s_mov_b32 s66, s52
	s_mov_b32 s67, s52
	v_mov_b64_e32 v[32:33], s[52:53]
	v_add_u32_e32 v1, s30, v118
	v_mov_b64_e32 v[46:47], s[66:67]
	v_add_u32_e32 v76, v0, v119
	v_add_u32_e32 v77, v0, v120
	v_add_u32_e32 v78, v0, v121
	v_add_u32_e32 v79, v0, v122
	v_add_u32_e32 v80, v119, v1
	v_add_u32_e32 v81, v120, v1
	v_add_u32_e32 v82, v121, v1
	v_add_u32_e32 v83, v122, v1
	v_mov_b64_e32 v[34:35], s[54:55]
	v_mov_b64_e32 v[36:37], s[56:57]
	v_mov_b64_e32 v[38:39], s[58:59]
	v_mov_b64_e32 v[40:41], s[60:61]
	v_mov_b64_e32 v[42:43], s[62:63]
	v_mov_b64_e32 v[44:45], s[64:65]
	v_mov_b64_e32 v[62:63], v[46:47]
	v_mov_b64_e32 v[0:1], v[32:33]
	v_mov_b64_e32 v[16:17], v[32:33]
	v_mov_b64_e32 v[60:61], v[44:45]
	v_mov_b64_e32 v[58:59], v[42:43]
	v_mov_b64_e32 v[56:57], v[40:41]
	v_mov_b64_e32 v[54:55], v[38:39]
	v_mov_b64_e32 v[52:53], v[36:37]
	v_mov_b64_e32 v[50:51], v[34:35]
	v_mov_b64_e32 v[48:49], v[32:33]
	v_mov_b64_e32 v[2:3], v[34:35]
	v_mov_b64_e32 v[4:5], v[36:37]
	v_mov_b64_e32 v[6:7], v[38:39]
	v_mov_b64_e32 v[8:9], v[40:41]
	v_mov_b64_e32 v[10:11], v[42:43]
	v_mov_b64_e32 v[12:13], v[44:45]
	v_mov_b64_e32 v[14:15], v[46:47]
	v_mov_b64_e32 v[18:19], v[34:35]
	v_mov_b64_e32 v[20:21], v[36:37]
	v_mov_b64_e32 v[22:23], v[38:39]
	v_mov_b64_e32 v[24:25], v[40:41]
	v_mov_b64_e32 v[26:27], v[42:43]
	v_mov_b64_e32 v[28:29], v[44:45]
	v_mov_b64_e32 v[30:31], v[46:47]
	s_load_dword s9, s[0:1], 0x10
	s_waitcnt lgkmcnt(0)
	s_lshr_b32 s9, s9, 16
	s_cmp_lg_u32 s9, 0
	s_cselect_b64 s[14:15], -1, 0
	s_cmp_lg_u64 s[14:15], 0
	s_addc_u32 s9, s33, 0
	s_cmp_lg_u64 s[14:15], 0
	s_addc_u32 s23, s23, s33
	s_cmpk_gt_i32 s23, 0x15ff
	s_cbranch_scc0 .LBB0_760

; #define TIDX get_tid_()
;   const int tid = TIDX, lane = tid & 63, wid = tid >> 6, wr = wid >> 1, wc = wid & 1, r = lane & 31, h = lane >> 5;
;   const int ch = (tid & 7) ^ ((tid >> 4) & 7);
;   unsigned avo[4], bvo[2];
; #pragma unroll
;   for (int i = 0; i < 4; ++i) avo[i] = (unsigned)(((tid >> 3) + 64 * i) * lda * 2 + ch * 16);
; #pragma unroll
;   for (int i = 0; i < 2; ++i) bvo[i] = (unsigned)(((tid >> 3) + 64 * i) * ldb * 2 + ch * 16);
;   const char* Ab = (const char*)A; const char* Bb = (const char*)Bt;
;   char* lw = lds + tid * 16;
;   const int nk = K >> 6;
;   const unsigned swz = (unsigned)((r >> 1) & 7);
;   const unsigned arow_u = (unsigned)((wr * 64 + r) * 128), brow_u = (unsigned)((wc * 64 + r) * 128);
;   const unsigned co0 = ((0u + h) ^ swz) << 4, co1 = ((2u + h) ^ swz) << 4, co2 = ((4u + h) ^ swz) << 4, co3 = ((6u + h) ^ swz) << 4;
; template <class Epi>
; DI void gemm_phase(const bf16_t* A, int lda, const bf16_t* Bt, int ldb, int K, int MT, int NTl, int SN, const Epi& epi, char* lds, bool rev = false) {
;     ...
;     for (L += gridDim.x; L < lmax; L += gridDim.x) if (tile_map(L, MT, NTl, SN, mt, nt)) { have = true; if (rev) mt = MT - 1 - mt; break; }
;     if (have) gemm_core<1>(A + (size_t)mt * 256 * lda, lda, Bt + (size_t)nt * 128 * ldb, ldb, K, dummy, lds);
.Ly0_go:
	s_sub_i32 s56, s8, s68
	s_ashr_i32 s57, s56, 31
	s_lshl_b64 s[56:57], s[56:57], 19
	s_and_b64 s[56:57], s[56:57], s[14:15]
	s_sub_i32 s58, s10, s70
	s_ashr_i32 s59, s58, 31
	s_lshl_b64 s[58:59], s[58:59], 18
	s_and_b64 s[58:59], s[58:59], s[14:15]
	v_and_b32_e32 v84, 15, v129
	v_bfe_u32 v85, v129, 4, 2
	v_lshrrev_b32_e32 v86, 6, v129
	v_bfe_u32 v88, v129, 1, 3
	v_lshrrev_b32_e32 v87, 1, v86
	v_and_b32_e32 v86, 1, v86
	v_xor_b32_e32 v85, v85, v88
	v_lshl_add_u32 v87, v87, 6, v84
	v_lshl_add_u32 v86, v86, 6, v84
	v_lshlrev_b32_e32 v85, 4, v85
	v_lshlrev_b32_e32 v87, 7, v87
	v_lshlrev_b32_e32 v86, 7, v86
	v_add_u32_e32 v86, 0x8000, v86
	v_xor_b32_e32 v88, 0x40, v85
	v_add_u32_e32 v76, v87, v85
	v_add_u32_e32 v77, v87, v88
	v_add_u32_e32 v78, v86, v85
	v_add_u32_e32 v79, v86, v88
	v_add_u32_e32 v80, 0x18000, v76
	v_add_u32_e32 v82, 0x18000, v78
	v_add_u32_e32 v81, 0x18000, v77
	v_add_u32_e32 v83, 0x18000, v79
	v_lshlrev_b32_e32 v84, 4, v129
	s_nop 0
	v_readfirstlane_b32 s30, v84
	s_mov_b32 s25, 0
	s_cmp_eq_u32 s101, 1
	s_cbranch_scc1 .Ly0_first
	s_waitcnt vmcnt(38)
	s_branch .Ly0_w0

;     ...
;     st = (st == 2) ? 0 : st + 1;
;   }
;   asm volatile("s_nop 15\n\ts_nop 15\n\ts_nop 7" ::: "memory");
;   __builtin_amdgcn_s_barrier();
;   asm volatile("" ::: "memory");
.Ly0_done:
	s_add_u32 s100, s100, 1
	s_cmp_ge_u32 s100, 3
	s_cselect_b32 s101, 3, 0
	s_sub_u32 s100, s100, s101
	s_mov_b32 s101, 0
	s_nop 15
	s_nop 15
	s_nop 7
	s_barrier
	s_branch .LBB0_757

; __global__ void __launch_bounds__(NTHREADS) mega_kernel(Params p) {
;   extern __shared__ __attribute__((aligned(16))) char lds[];
;   cg::grid_group grid = cg::this_grid();
;   unsigned bar_gen = 0;
;   for (int ph = 0; ph < NPHASE; ++ph) {
;     ...
;     const int nrep = (REPQ >= 100) ? ((ph == REPQ - 100) ? 2 : 1) : ((ph > 0 && ph < NPHASE - 1 && (ph - 1) % 14 == REPQ) ? 2 : 1);
;     ...
;     const int nrep = 1;
;     ...
;     if (ph == NPHASE - 2) continue;
;     for (int rep = 0; rep < nrep; ++rep) {
;       run_phase(p, ph, lds, rep);
;       if (ph + 1 < NPHASE) {
;         if (ph == 0) grid.sync();
;         else { ++bar_gen; grid_barrier((unsigned*)(p.ws + OFF_MISC + 6144), bar_gen * gridDim.x); }
;       }
;     }
;   }
; }
	.amdhsa_kernel _Z11mega_kernel6Params
		.amdhsa_group_segment_fixed_size 0
		.amdhsa_private_segment_fixed_size 0
		.amdhsa_kernarg_size 456
		.amdhsa_user_sgpr_count 2
		.amdhsa_user_sgpr_dispatch_ptr 0
		.amdhsa_user_sgpr_queue_ptr 0
		.amdhsa_user_sgpr_kernarg_segment_ptr 1
		.amdhsa_user_sgpr_dispatch_id 0
		.amdhsa_user_sgpr_kernarg_preload_length 0
		.amdhsa_user_sgpr_kernarg_preload_offset 0
		.amdhsa_user_sgpr_private_segment_size 0
		.amdhsa_uses_dynamic_stack 0
		.amdhsa_enable_private_segment 0
		.amdhsa_system_sgpr_workgroup_id_x 1
		.amdhsa_system_sgpr_workgroup_id_y 0
		.amdhsa_system_sgpr_workgroup_id_z 0
		.amdhsa_system_sgpr_workgroup_info 0
		.amdhsa_system_vgpr_workitem_id 2
		.amdhsa_next_free_vgpr 255
		.amdhsa_next_free_sgpr 102
		.amdhsa_accum_offset 256
		.amdhsa_reserve_vcc 1
		.amdhsa_float_round_mode_32 0
		.amdhsa_float_round_mode_16_64 0
		.amdhsa_float_denorm_mode_32 3
		.amdhsa_float_denorm_mode_16_64 3
		.amdhsa_dx10_clamp 1
		.amdhsa_ieee_mode 1
		.amdhsa_fp16_overflow 0
		.amdhsa_tg_split 0
		.amdhsa_exception_fp_ieee_invalid_op 0
		.amdhsa_exception_fp_denorm_src 0
		.amdhsa_exception_fp_ieee_div_zero 0
		.amdhsa_exception_fp_ieee_overflow 0
		.amdhsa_exception_fp_ieee_underflow 0
		.amdhsa_exception_fp_ieee_inexact 0
		.amdhsa_exception_int_div_zero 0
	.end_amdhsa_kernel

; __global__ void __launch_bounds__(NTHREADS) mega_kernel(Params p) {
;   extern __shared__ __attribute__((aligned(16))) char lds[];
;   cg::grid_group grid = cg::this_grid();
;   unsigned bar_gen = 0;
;   for (int ph = 0; ph < NPHASE; ++ph) {
;     ...
;     const int nrep = (REPQ >= 100) ? ((ph == REPQ - 100) ? 2 : 1) : ((ph > 0 && ph < NPHASE - 1 && (ph - 1) % 14 == REPQ) ? 2 : 1);
;     ...
;     const int nrep = 1;
;     ...
;     if (ph == NPHASE - 2) continue;
;     for (int rep = 0; rep < nrep; ++rep) {
;       run_phase(p, ph, lds, rep);
;       if (ph + 1 < NPHASE) {
;         if (ph == 0) grid.sync();
;         else { ++bar_gen; grid_barrier((unsigned*)(p.ws + OFF_MISC + 6144), bar_gen * gridDim.x); }
;       }
;     }
;   }
; }
amdhsa.kernels:
  - .agpr_count:     0
    .args:
      - .offset:         0
        .size:           200
        .value_kind:     by_value
      - .offset:         200
        .size:           4
        .value_kind:     hidden_block_count_x
      - .offset:         204
        .size:           4
        .value_kind:     hidden_block_count_y
      - .offset:         208
        .size:           4
        .value_kind:     hidden_block_count_z
      - .offset:         212
        .size:           2
        .value_kind:     hidden_group_size_x
      - .offset:         214
        .size:           2
        .value_kind:     hidden_group_size_y
      - .offset:         216
        .size:           2
        .value_kind:     hidden_group_size_z
      - .offset:         218
        .size:           2
        .value_kind:     hidden_remainder_x
      - .offset:         220
        .size:           2
        .value_kind:     hidden_remainder_y
      - .offset:         222
        .size:           2
        .value_kind:     hidden_remainder_z
      - .offset:         240
        .size:           8
        .value_kind:     hidden_global_offset_x
      - .offset:         248
        .size:           8
        .value_kind:     hidden_global_offset_y
      - .offset:         256
        .size:           8
        .value_kind:     hidden_global_offset_z
      - .offset:         264
        .size:           2
        .value_kind:     hidden_grid_dims
      - .offset:         288
        .size:           8
        .value_kind:     hidden_multigrid_sync_arg
      - .offset:         320
        .size:           4
        .value_kind:     hidden_dynamic_lds_size
    .group_segment_fixed_size: 0
    .kernarg_segment_align: 8
    .kernarg_segment_size: 456
    .language:       OpenCL C
    .language_version:
      - 2
      - 0
    .max_flat_workgroup_size: 512
    .name:           _Z11mega_kernel6Params
    .private_segment_fixed_size: 0
    .sgpr_count:     108
    .sgpr_spill_count: 136
    .symbol:         _Z11mega_kernel6Params.kd
    .uniform_work_group_size: 1
    .uses_dynamic_stack: false
    .vgpr_count:     255
    .vgpr_spill_count: 0
    .wavefront_size: 64
